# adds nt (non-temporal) policy on read-once streams: transposer f32 loads, row-phase x/y loads and out stores
# speedup vs baseline: 1.0115x; 1.0115x over previous
.Ltra_dec_done1:
	s_mul_i32 s26, s41, s37
	s_lshl_b32 s27, s43, 6
	s_mul_i32 s27, s27, s36
	s_add_u32 s26, s26, s27
	s_lshl_b32 s27, s44, 7
	s_add_u32 s26, s26, s27
	s_add_u32 s14, s14, s26
	s_addc_u32 s15, s15, 0
	s_mul_i32 s26, s41, s39
	s_add_u32 s26, s26, s38
	s_lshl_b32 s27, s44, 5
	s_mul_i32 s27, s27, s40
	s_add_u32 s26, s26, s27
	s_lshl_b32 s27, s43, 7
	s_add_u32 s26, s26, s27
	s_add_u32 s18, s90, s26
	s_addc_u32 s19, s91, 0
	s_mov_b32 s22, s40
	v_mad_u32_u24 v7, v5, s36, v6
	s_lshl_b32 s45, s36, 3
	global_load_dwordx4 v[10:13], v7, s[14:15] nt
	s_add_u32 s14, s14, s45
	s_addc_u32 s15, s15, 0
	global_load_dwordx4 v[14:17], v7, s[14:15] nt
	s_add_u32 s14, s14, s45
	s_addc_u32 s15, s15, 0
	global_load_dwordx4 v[18:21], v7, s[14:15] nt
	s_add_u32 s14, s14, s45
	s_addc_u32 s15, s15, 0
	global_load_dwordx4 v[22:25], v7, s[14:15] nt
	s_add_u32 s14, s14, s45
	s_addc_u32 s15, s15, 0
	global_load_dwordx4 v[26:29], v7, s[14:15] nt
	s_add_u32 s14, s14, s45
	s_addc_u32 s15, s15, 0
	global_load_dwordx4 v[30:33], v7, s[14:15] nt
	s_add_u32 s14, s14, s45
	s_addc_u32 s15, s15, 0
	global_load_dwordx4 v[34:37], v7, s[14:15] nt
	s_add_u32 s14, s14, s45
	s_addc_u32 s15, s15, 0
	global_load_dwordx4 v[38:41], v7, s[14:15] nt

.Ltra_dec_done10:
	s_mul_i32 s26, s41, s37
	s_lshl_b32 s27, s43, 6
	s_mul_i32 s27, s27, s36
	s_add_u32 s26, s26, s27
	s_lshl_b32 s27, s44, 7
	s_add_u32 s26, s26, s27
	s_add_u32 s16, s16, s26
	s_addc_u32 s17, s17, 0
	s_mul_i32 s26, s41, s39
	s_add_u32 s26, s26, s38
	s_lshl_b32 s27, s44, 5
	s_mul_i32 s27, s27, s40
	s_add_u32 s26, s26, s27
	s_lshl_b32 s27, s43, 7
	s_add_u32 s26, s26, s27
	s_add_u32 s20, s90, s26
	s_addc_u32 s21, s91, 0
	s_mov_b32 s23, s40
	v_mad_u32_u24 v8, v5, s36, v6
	s_lshl_b32 s45, s36, 3
	global_load_dwordx4 v[42:45], v8, s[16:17] nt
	s_add_u32 s16, s16, s45
	s_addc_u32 s17, s17, 0
	global_load_dwordx4 v[46:49], v8, s[16:17] nt
	s_add_u32 s16, s16, s45
	s_addc_u32 s17, s17, 0
	global_load_dwordx4 v[50:53], v8, s[16:17] nt
	s_add_u32 s16, s16, s45
	s_addc_u32 s17, s17, 0
	global_load_dwordx4 v[54:57], v8, s[16:17] nt
	s_add_u32 s16, s16, s45
	s_addc_u32 s17, s17, 0
	global_load_dwordx4 v[58:61], v8, s[16:17] nt
	s_add_u32 s16, s16, s45
	s_addc_u32 s17, s17, 0
	global_load_dwordx4 v[62:65], v8, s[16:17] nt
	s_add_u32 s16, s16, s45
	s_addc_u32 s17, s17, 0
	global_load_dwordx4 v[66:69], v8, s[16:17] nt
	s_add_u32 s16, s16, s45
	s_addc_u32 s17, s17, 0
	global_load_dwordx4 v[70:73], v8, s[16:17] nt
	s_waitcnt vmcnt(8)
	s_branch .Ltra_after9

.Ltra_dec_done19:
	s_mul_i32 s26, s41, s37
	s_lshl_b32 s27, s43, 6
	s_mul_i32 s27, s27, s36
	s_add_u32 s26, s26, s27
	s_lshl_b32 s27, s44, 7
	s_add_u32 s26, s26, s27
	s_add_u32 s14, s14, s26
	s_addc_u32 s15, s15, 0
	s_mul_i32 s26, s41, s39
	s_add_u32 s26, s26, s38
	s_lshl_b32 s27, s44, 5
	s_mul_i32 s27, s27, s40
	s_add_u32 s26, s26, s27
	s_lshl_b32 s27, s43, 7
	s_add_u32 s26, s26, s27
	s_add_u32 s18, s90, s26
	s_addc_u32 s19, s91, 0
	s_mov_b32 s22, s40
	v_mad_u32_u24 v7, v5, s36, v6
	s_lshl_b32 s45, s36, 3
	global_load_dwordx4 v[10:13], v7, s[14:15] nt
	s_add_u32 s14, s14, s45
	s_addc_u32 s15, s15, 0
	global_load_dwordx4 v[14:17], v7, s[14:15] nt
	s_add_u32 s14, s14, s45
	s_addc_u32 s15, s15, 0
	global_load_dwordx4 v[18:21], v7, s[14:15] nt
	s_add_u32 s14, s14, s45
	s_addc_u32 s15, s15, 0
	global_load_dwordx4 v[22:25], v7, s[14:15] nt
	s_add_u32 s14, s14, s45
	s_addc_u32 s15, s15, 0
	global_load_dwordx4 v[26:29], v7, s[14:15] nt
	s_add_u32 s14, s14, s45
	s_addc_u32 s15, s15, 0
	global_load_dwordx4 v[30:33], v7, s[14:15] nt
	s_add_u32 s14, s14, s45
	s_addc_u32 s15, s15, 0
	global_load_dwordx4 v[34:37], v7, s[14:15] nt
	s_add_u32 s14, s14, s45
	s_addc_u32 s15, s15, 0
	global_load_dwordx4 v[38:41], v7, s[14:15] nt
	s_waitcnt vmcnt(8)
	s_branch .Ltra_after18

.LBB0_223:
.LBB0_224:
	s_waitcnt vmcnt(0) lgkmcnt(0)
	s_load_dwordx2 s[0:1], s[92:93], 0x40
	s_load_dwordx2 s[2:3], s[92:93], 0x38
	s_load_dwordx2 s[4:5], s[92:93], 0xf0
	s_load_dwordx2 s[6:7], s[92:93], 0x0
	s_load_dwordx2 s[8:9], s[92:93], 0x8
	v_and_b32_e32 v2, 63, v154
	v_lshlrev_b32_e32 v1, 4, v2
	v_lshlrev_b32_e32 v2, 3, v2
	v_mov_b32_e32 v6, 1.0
	v_mov_b32_e32 v7, 1.0
	s_mov_b32 s40, 0x3a000000
	s_mov_b32 s41, 0x358637bd
	v_readfirstlane_b32 s10, v154
	s_lshr_b32 s10, s10, 6
	s_lshl_b32 s12, s96, 3
	s_add_u32 s10, s10, s12
	s_waitcnt lgkmcnt(0)
	s_add_u32 s12, s10, 0
	s_lshl_b32 s13, s12, 13
	s_lshl_b32 s14, s12, 12
	s_add_u32 s20, s6, s13
	s_addc_u32 s21, s7, 0
	s_add_u32 s22, s90, 0x21918000
	s_addc_u32 s23, s91, 0
	s_add_u32 s22, s22, s14
	s_addc_u32 s23, s23, 0
	s_add_u32 s36, s20, 0x1000
	s_addc_u32 s37, s21, 0
	global_load_dwordx4 v[34:37], v1, s[20:21] nt
	global_load_dwordx4 v[38:41], v1, s[20:21] offset:1024 nt
	global_load_dwordx4 v[42:45], v1, s[20:21] offset:2048 nt
	global_load_dwordx4 v[46:49], v1, s[20:21] offset:3072 nt
	global_load_dwordx4 v[50:53], v1, s[36:37] nt
	global_load_dwordx4 v[54:57], v1, s[36:37] offset:1024 nt
	global_load_dwordx4 v[58:61], v1, s[36:37] offset:2048 nt
	global_load_dwordx4 v[62:65], v1, s[36:37] offset:3072 nt
	s_mov_b32 s16, 4
	s_add_u32 s17, s16, 0
	s_mul_i32 s17, s17, 49152
	s_add_u32 s17, s17, 0x10404000
	s_add_u32 s28, s90, s17
	s_addc_u32 s29, s91, 0
	s_add_u32 s17, s16, 0
	s_mul_i32 s17, s17, 49152
	s_add_u32 s17, s17, 0x10400000
	s_add_u32 s30, s90, s17
	s_addc_u32 s31, s91, 0
	s_add_u32 s32, s30, 0x2000
	s_addc_u32 s33, s31, 0
	s_add_u32 s18, s2, 0x1000
	s_addc_u32 s19, s3, 0
	global_load_dwordx4 v[130:133], v1, s[2:3]
	global_load_dwordx4 v[134:137], v1, s[2:3] offset:1024
	global_load_dwordx4 v[138:141], v1, s[2:3] offset:2048
	global_load_dwordx4 v[142:145], v1, s[2:3] offset:3072
	global_load_dwordx4 v[146:149], v1, s[18:19]
	global_load_dwordx4 v[150:153], v1, s[18:19] offset:1024
	global_load_dwordx4 v[156:159], v1, s[18:19] offset:2048
	global_load_dwordx4 v[160:163], v1, s[18:19] offset:3072
	s_add_u32 s18, s30, 0x1000
	s_addc_u32 s19, s31, 0
	global_load_dwordx4 v[164:167], v1, s[30:31]
	global_load_dwordx4 v[168:171], v1, s[30:31] offset:1024
	global_load_dwordx4 v[172:175], v1, s[30:31] offset:2048
	global_load_dwordx4 v[176:179], v1, s[30:31] offset:3072
	global_load_dwordx4 v[180:183], v1, s[18:19]
	global_load_dwordx4 v[184:187], v1, s[18:19] offset:1024
	global_load_dwordx4 v[188:191], v1, s[18:19] offset:2048
	global_load_dwordx4 v[192:195], v1, s[18:19] offset:3072
	s_add_u32 s18, s32, 0x1000
	s_addc_u32 s19, s33, 0
	global_load_dwordx4 v[196:199], v1, s[32:33]
	global_load_dwordx4 v[200:203], v1, s[32:33] offset:1024
	global_load_dwordx4 v[204:207], v1, s[32:33] offset:2048
	global_load_dwordx4 v[208:211], v1, s[32:33] offset:3072
	global_load_dwordx4 v[212:215], v1, s[18:19]
	global_load_dwordx4 v[216:219], v1, s[18:19] offset:1024
	global_load_dwordx4 v[220:223], v1, s[18:19] offset:2048
	global_load_dwordx4 v[224:227], v1, s[18:19] offset:3072
	s_add_u32 s12, s10, 2048
	s_lshl_b32 s13, s12, 13
	s_lshl_b32 s14, s12, 12
	s_add_u32 s20, s6, s13
	s_addc_u32 s21, s7, 0
	s_add_u32 s22, s90, 0x21918000
	s_addc_u32 s23, s91, 0
	s_add_u32 s22, s22, s14
	s_addc_u32 s23, s23, 0
	s_add_u32 s36, s20, 0x1000
	s_addc_u32 s37, s21, 0
	global_load_dwordx4 v[66:69], v1, s[20:21] nt
	global_load_dwordx4 v[70:73], v1, s[20:21] offset:1024 nt
	global_load_dwordx4 v[74:77], v1, s[20:21] offset:2048 nt
	global_load_dwordx4 v[78:81], v1, s[20:21] offset:3072 nt
	global_load_dwordx4 v[82:85], v1, s[36:37] nt
	global_load_dwordx4 v[86:89], v1, s[36:37] offset:1024 nt
	global_load_dwordx4 v[90:93], v1, s[36:37] offset:2048 nt
	global_load_dwordx4 v[94:97], v1, s[36:37] offset:3072 nt
	s_add_u32 s12, s10, 0
	s_lshl_b32 s14, s12, 12
	s_add_u32 s26, s90, 0x11918000
	s_addc_u32 s27, s91, 0
	s_add_u32 s26, s26, s14
	s_addc_u32 s27, s27, 0
	s_waitcnt vmcnt(32)
	v_mov_b32_e32 v8, 0
	v_fmac_f32_e32 v8, v34, v34
	v_fmac_f32_e32 v8, v35, v35
	v_fmac_f32_e32 v8, v36, v36
	v_fmac_f32_e32 v8, v37, v37
	v_fmac_f32_e32 v8, v38, v38
	v_fmac_f32_e32 v8, v39, v39
	v_fmac_f32_e32 v8, v40, v40
	v_fmac_f32_e32 v8, v41, v41
	v_fmac_f32_e32 v8, v42, v42
	v_fmac_f32_e32 v8, v43, v43
	v_fmac_f32_e32 v8, v44, v44
	v_fmac_f32_e32 v8, v45, v45
	v_fmac_f32_e32 v8, v46, v46
	v_fmac_f32_e32 v8, v47, v47
	v_fmac_f32_e32 v8, v48, v48
	v_fmac_f32_e32 v8, v49, v49
	v_fmac_f32_e32 v8, v50, v50
	v_fmac_f32_e32 v8, v51, v51
	v_fmac_f32_e32 v8, v52, v52
	v_fmac_f32_e32 v8, v53, v53
	v_fmac_f32_e32 v8, v54, v54
	v_fmac_f32_e32 v8, v55, v55
	v_fmac_f32_e32 v8, v56, v56
	v_fmac_f32_e32 v8, v57, v57
	v_fmac_f32_e32 v8, v58, v58
	v_fmac_f32_e32 v8, v59, v59
	v_fmac_f32_e32 v8, v60, v60
	v_fmac_f32_e32 v8, v61, v61
	v_fmac_f32_e32 v8, v62, v62
	v_fmac_f32_e32 v8, v63, v63
	v_fmac_f32_e32 v8, v64, v64
	v_fmac_f32_e32 v8, v65, v65
	s_nop 1
	v_add_f32_dpp v8, v8, v8 quad_perm:[1,0,3,2] row_mask:0xf bank_mask:0xf
	s_nop 1
	v_add_f32_dpp v8, v8, v8 quad_perm:[2,3,0,1] row_mask:0xf bank_mask:0xf
	s_nop 1
	v_add_f32_dpp v8, v8, v8 row_ror:4 row_mask:0xf bank_mask:0xf
	s_nop 1
	v_add_f32_dpp v8, v8, v8 row_ror:8 row_mask:0xf bank_mask:0xf
	s_nop 1
	v_readlane_b32 s42, v8, 0
	v_readlane_b32 s43, v8, 16
	v_readlane_b32 s44, v8, 32
	v_readlane_b32 s45, v8, 48
	s_nop 1
	v_mov_b32_e32 v8, s42
	v_add_f32_e32 v8, s43, v8
	v_add_f32_e32 v8, s44, v8
	v_add_f32_e32 v8, s45, v8
	v_mov_b32_e32 v4, s41
	v_fmac_f32_e32 v4, s40, v8
	v_rsq_f32_e32 v4, v4
	s_nop 0
	v_mov_b32_e32 v5, v4
	s_waitcnt vmcnt(8)
	v_pk_mul_f32 v[10:11], v[34:35], v[4:5]
	v_pk_mul_f32 v[10:11], v[10:11], v[130:131]
	v_pk_add_f32 v[12:13], v[196:197], v[6:7]
	v_pk_fma_f32 v[14:15], v[10:11], v[12:13], v[164:165]
	v_pk_mul_f32 v[10:11], v[36:37], v[4:5]
	v_pk_mul_f32 v[10:11], v[10:11], v[132:133]
	v_pk_add_f32 v[12:13], v[198:199], v[6:7]
	v_pk_fma_f32 v[16:17], v[10:11], v[12:13], v[166:167]
	v_cvt_pk_bf16_f32 v26, v14, v15
	v_cvt_pk_bf16_f32 v27, v16, v17
	global_store_dwordx2 v2, v[26:27], s[26:27]
	v_pk_mul_f32 v[10:11], v[38:39], v[4:5]
	v_pk_mul_f32 v[10:11], v[10:11], v[134:135]
	v_pk_add_f32 v[12:13], v[200:201], v[6:7]
	v_pk_fma_f32 v[14:15], v[10:11], v[12:13], v[168:169]
	v_pk_mul_f32 v[10:11], v[40:41], v[4:5]
	v_pk_mul_f32 v[10:11], v[10:11], v[136:137]
	v_pk_add_f32 v[12:13], v[202:203], v[6:7]
	v_pk_fma_f32 v[16:17], v[10:11], v[12:13], v[170:171]
	v_cvt_pk_bf16_f32 v28, v14, v15
	v_cvt_pk_bf16_f32 v29, v16, v17
	global_store_dwordx2 v2, v[28:29], s[26:27] offset:512
	v_pk_mul_f32 v[10:11], v[42:43], v[4:5]
	v_pk_mul_f32 v[10:11], v[10:11], v[138:139]
	v_pk_add_f32 v[12:13], v[204:205], v[6:7]
	v_pk_fma_f32 v[14:15], v[10:11], v[12:13], v[172:173]
	v_pk_mul_f32 v[10:11], v[44:45], v[4:5]
	v_pk_mul_f32 v[10:11], v[10:11], v[140:141]
	v_pk_add_f32 v[12:13], v[206:207], v[6:7]
	v_pk_fma_f32 v[16:17], v[10:11], v[12:13], v[174:175]
	v_cvt_pk_bf16_f32 v30, v14, v15
	v_cvt_pk_bf16_f32 v31, v16, v17
	global_store_dwordx2 v2, v[30:31], s[26:27] offset:1024
	v_pk_mul_f32 v[10:11], v[46:47], v[4:5]
	v_pk_mul_f32 v[10:11], v[10:11], v[142:143]
	v_pk_add_f32 v[12:13], v[208:209], v[6:7]
	v_pk_fma_f32 v[14:15], v[10:11], v[12:13], v[176:177]
	v_pk_mul_f32 v[10:11], v[48:49], v[4:5]
	v_pk_mul_f32 v[10:11], v[10:11], v[144:145]
	v_pk_add_f32 v[12:13], v[210:211], v[6:7]
	v_pk_fma_f32 v[16:17], v[10:11], v[12:13], v[178:179]
	v_cvt_pk_bf16_f32 v32, v14, v15
	v_cvt_pk_bf16_f32 v33, v16, v17
	global_store_dwordx2 v2, v[32:33], s[26:27] offset:1536
	v_pk_mul_f32 v[10:11], v[50:51], v[4:5]
	v_pk_mul_f32 v[10:11], v[10:11], v[146:147]
	v_pk_add_f32 v[12:13], v[212:213], v[6:7]
	v_pk_fma_f32 v[14:15], v[10:11], v[12:13], v[180:181]
	v_pk_mul_f32 v[10:11], v[52:53], v[4:5]
	v_pk_mul_f32 v[10:11], v[10:11], v[148:149]
	v_pk_add_f32 v[12:13], v[214:215], v[6:7]
	v_pk_fma_f32 v[16:17], v[10:11], v[12:13], v[182:183]
	v_cvt_pk_bf16_f32 v26, v14, v15
	v_cvt_pk_bf16_f32 v27, v16, v17
	global_store_dwordx2 v2, v[26:27], s[26:27] offset:2048
	v_pk_mul_f32 v[10:11], v[54:55], v[4:5]
	v_pk_mul_f32 v[10:11], v[10:11], v[150:151]
	v_pk_add_f32 v[12:13], v[216:217], v[6:7]
	v_pk_fma_f32 v[14:15], v[10:11], v[12:13], v[184:185]
	v_pk_mul_f32 v[10:11], v[56:57], v[4:5]
	v_pk_mul_f32 v[10:11], v[10:11], v[152:153]
	v_pk_add_f32 v[12:13], v[218:219], v[6:7]
	v_pk_fma_f32 v[16:17], v[10:11], v[12:13], v[186:187]
	v_cvt_pk_bf16_f32 v28, v14, v15
	v_cvt_pk_bf16_f32 v29, v16, v17
	global_store_dwordx2 v2, v[28:29], s[26:27] offset:2560
	v_pk_mul_f32 v[10:11], v[58:59], v[4:5]
	v_pk_mul_f32 v[10:11], v[10:11], v[156:157]
	v_pk_add_f32 v[12:13], v[220:221], v[6:7]
	v_pk_fma_f32 v[14:15], v[10:11], v[12:13], v[188:189]
	v_pk_mul_f32 v[10:11], v[60:61], v[4:5]
	v_pk_mul_f32 v[10:11], v[10:11], v[158:159]
	v_pk_add_f32 v[12:13], v[222:223], v[6:7]
	v_pk_fma_f32 v[16:17], v[10:11], v[12:13], v[190:191]
	v_cvt_pk_bf16_f32 v30, v14, v15
	v_cvt_pk_bf16_f32 v31, v16, v17
	global_store_dwordx2 v2, v[30:31], s[26:27] offset:3072
	v_pk_mul_f32 v[10:11], v[62:63], v[4:5]
	v_pk_mul_f32 v[10:11], v[10:11], v[160:161]
	v_pk_add_f32 v[12:13], v[224:225], v[6:7]
	v_pk_fma_f32 v[14:15], v[10:11], v[12:13], v[192:193]
	v_pk_mul_f32 v[10:11], v[64:65], v[4:5]
	v_pk_mul_f32 v[10:11], v[10:11], v[162:163]
	v_pk_add_f32 v[12:13], v[226:227], v[6:7]
	v_pk_fma_f32 v[16:17], v[10:11], v[12:13], v[194:195]
	v_cvt_pk_bf16_f32 v32, v14, v15
	v_cvt_pk_bf16_f32 v33, v16, v17
	global_store_dwordx2 v2, v[32:33], s[26:27] offset:3584
	s_mov_b32 s16, 4
	s_add_u32 s17, s16, 0
	s_mul_i32 s17, s17, 49152
	s_add_u32 s17, s17, 0x10404000
	s_add_u32 s28, s90, s17
	s_addc_u32 s29, s91, 0
	s_add_u32 s17, s16, 0
	s_mul_i32 s17, s17, 49152
	s_add_u32 s17, s17, 0x10400000
	s_add_u32 s30, s90, s17
	s_addc_u32 s31, s91, 0
	s_add_u32 s32, s30, 0x2000
	s_addc_u32 s33, s31, 0
	s_add_u32 s18, s2, 0x1000
	s_addc_u32 s19, s3, 0
	global_load_dwordx4 v[130:133], v1, s[2:3]
	global_load_dwordx4 v[134:137], v1, s[2:3] offset:1024
	global_load_dwordx4 v[138:141], v1, s[2:3] offset:2048
	global_load_dwordx4 v[142:145], v1, s[2:3] offset:3072
	global_load_dwordx4 v[146:149], v1, s[18:19]
	global_load_dwordx4 v[150:153], v1, s[18:19] offset:1024
	global_load_dwordx4 v[156:159], v1, s[18:19] offset:2048
	global_load_dwordx4 v[160:163], v1, s[18:19] offset:3072
	s_add_u32 s18, s30, 0x1000
	s_addc_u32 s19, s31, 0
	global_load_dwordx4 v[164:167], v1, s[30:31]
	global_load_dwordx4 v[168:171], v1, s[30:31] offset:1024
	global_load_dwordx4 v[172:175], v1, s[30:31] offset:2048
	global_load_dwordx4 v[176:179], v1, s[30:31] offset:3072
	global_load_dwordx4 v[180:183], v1, s[18:19]
	global_load_dwordx4 v[184:187], v1, s[18:19] offset:1024
	global_load_dwordx4 v[188:191], v1, s[18:19] offset:2048
	global_load_dwordx4 v[192:195], v1, s[18:19] offset:3072
	s_add_u32 s18, s32, 0x1000
	s_addc_u32 s19, s33, 0
	global_load_dwordx4 v[196:199], v1, s[32:33]
	global_load_dwordx4 v[200:203], v1, s[32:33] offset:1024
	global_load_dwordx4 v[204:207], v1, s[32:33] offset:2048
	global_load_dwordx4 v[208:211], v1, s[32:33] offset:3072
	global_load_dwordx4 v[212:215], v1, s[18:19]
	global_load_dwordx4 v[216:219], v1, s[18:19] offset:1024
	global_load_dwordx4 v[220:223], v1, s[18:19] offset:2048
	global_load_dwordx4 v[224:227], v1, s[18:19] offset:3072
	s_add_u32 s12, s10, 4096
	s_lshl_b32 s13, s12, 13
	s_lshl_b32 s14, s12, 12
	s_sub_u32 s15, s13, 0x2000000
	s_add_u32 s20, s8, s15
	s_addc_u32 s21, s9, 0
	s_add_u32 s22, s90, 0x21918000
	s_addc_u32 s23, s91, 0
	s_add_u32 s22, s22, s14
	s_addc_u32 s23, s23, 0
	s_add_u32 s36, s20, 0x1000
	s_addc_u32 s37, s21, 0
	global_load_dwordx4 v[34:37], v1, s[20:21] nt
	global_load_dwordx4 v[38:41], v1, s[20:21] offset:1024 nt
	global_load_dwordx4 v[42:45], v1, s[20:21] offset:2048 nt
	global_load_dwordx4 v[46:49], v1, s[20:21] offset:3072 nt
	global_load_dwordx4 v[50:53], v1, s[36:37] nt
	global_load_dwordx4 v[54:57], v1, s[36:37] offset:1024 nt
	global_load_dwordx4 v[58:61], v1, s[36:37] offset:2048 nt
	global_load_dwordx4 v[62:65], v1, s[36:37] offset:3072 nt
	s_add_u32 s12, s10, 2048
	s_lshl_b32 s14, s12, 12
	s_add_u32 s26, s90, 0x11918000
	s_addc_u32 s27, s91, 0
	s_add_u32 s26, s26, s14
	s_addc_u32 s27, s27, 0
	s_waitcnt vmcnt(40)
	v_mov_b32_e32 v8, 0
	v_fmac_f32_e32 v8, v66, v66
	v_fmac_f32_e32 v8, v67, v67
	v_fmac_f32_e32 v8, v68, v68
	v_fmac_f32_e32 v8, v69, v69
	v_fmac_f32_e32 v8, v70, v70
	v_fmac_f32_e32 v8, v71, v71
	v_fmac_f32_e32 v8, v72, v72
	v_fmac_f32_e32 v8, v73, v73
	v_fmac_f32_e32 v8, v74, v74
	v_fmac_f32_e32 v8, v75, v75
	v_fmac_f32_e32 v8, v76, v76
	v_fmac_f32_e32 v8, v77, v77
	v_fmac_f32_e32 v8, v78, v78
	v_fmac_f32_e32 v8, v79, v79
	v_fmac_f32_e32 v8, v80, v80
	v_fmac_f32_e32 v8, v81, v81
	v_fmac_f32_e32 v8, v82, v82
	v_fmac_f32_e32 v8, v83, v83
	v_fmac_f32_e32 v8, v84, v84
	v_fmac_f32_e32 v8, v85, v85
	v_fmac_f32_e32 v8, v86, v86
	v_fmac_f32_e32 v8, v87, v87
	v_fmac_f32_e32 v8, v88, v88
	v_fmac_f32_e32 v8, v89, v89
	v_fmac_f32_e32 v8, v90, v90
	v_fmac_f32_e32 v8, v91, v91
	v_fmac_f32_e32 v8, v92, v92
	v_fmac_f32_e32 v8, v93, v93
	v_fmac_f32_e32 v8, v94, v94
	v_fmac_f32_e32 v8, v95, v95
	v_fmac_f32_e32 v8, v96, v96
	v_fmac_f32_e32 v8, v97, v97
	s_nop 1
	v_add_f32_dpp v8, v8, v8 quad_perm:[1,0,3,2] row_mask:0xf bank_mask:0xf
	s_nop 1
	v_add_f32_dpp v8, v8, v8 quad_perm:[2,3,0,1] row_mask:0xf bank_mask:0xf
	s_nop 1
	v_add_f32_dpp v8, v8, v8 row_ror:4 row_mask:0xf bank_mask:0xf
	s_nop 1
	v_add_f32_dpp v8, v8, v8 row_ror:8 row_mask:0xf bank_mask:0xf
	s_nop 1
	v_readlane_b32 s42, v8, 0
	v_readlane_b32 s43, v8, 16
	v_readlane_b32 s44, v8, 32
	v_readlane_b32 s45, v8, 48
	s_nop 1
	v_mov_b32_e32 v8, s42
	v_add_f32_e32 v8, s43, v8
	v_add_f32_e32 v8, s44, v8
	v_add_f32_e32 v8, s45, v8
	v_mov_b32_e32 v4, s41
	v_fmac_f32_e32 v4, s40, v8
	v_rsq_f32_e32 v4, v4
	s_nop 0
	v_mov_b32_e32 v5, v4
	s_waitcnt vmcnt(8)
	v_pk_mul_f32 v[10:11], v[66:67], v[4:5]
	v_pk_mul_f32 v[10:11], v[10:11], v[130:131]
	v_pk_add_f32 v[12:13], v[196:197], v[6:7]
	v_pk_fma_f32 v[14:15], v[10:11], v[12:13], v[164:165]
	v_pk_mul_f32 v[10:11], v[68:69], v[4:5]
	v_pk_mul_f32 v[10:11], v[10:11], v[132:133]
	v_pk_add_f32 v[12:13], v[198:199], v[6:7]
	v_pk_fma_f32 v[16:17], v[10:11], v[12:13], v[166:167]
	v_cvt_pk_bf16_f32 v26, v14, v15
	v_cvt_pk_bf16_f32 v27, v16, v17
	global_store_dwordx2 v2, v[26:27], s[26:27]
	v_pk_mul_f32 v[10:11], v[70:71], v[4:5]
	v_pk_mul_f32 v[10:11], v[10:11], v[134:135]
	v_pk_add_f32 v[12:13], v[200:201], v[6:7]
	v_pk_fma_f32 v[14:15], v[10:11], v[12:13], v[168:169]
	v_pk_mul_f32 v[10:11], v[72:73], v[4:5]
	v_pk_mul_f32 v[10:11], v[10:11], v[136:137]
	v_pk_add_f32 v[12:13], v[202:203], v[6:7]
	v_pk_fma_f32 v[16:17], v[10:11], v[12:13], v[170:171]
	v_cvt_pk_bf16_f32 v28, v14, v15
	v_cvt_pk_bf16_f32 v29, v16, v17
	global_store_dwordx2 v2, v[28:29], s[26:27] offset:512
	v_pk_mul_f32 v[10:11], v[74:75], v[4:5]
	v_pk_mul_f32 v[10:11], v[10:11], v[138:139]
	v_pk_add_f32 v[12:13], v[204:205], v[6:7]
	v_pk_fma_f32 v[14:15], v[10:11], v[12:13], v[172:173]
	v_pk_mul_f32 v[10:11], v[76:77], v[4:5]
	v_pk_mul_f32 v[10:11], v[10:11], v[140:141]
	v_pk_add_f32 v[12:13], v[206:207], v[6:7]
	v_pk_fma_f32 v[16:17], v[10:11], v[12:13], v[174:175]
	v_cvt_pk_bf16_f32 v30, v14, v15
	v_cvt_pk_bf16_f32 v31, v16, v17
	global_store_dwordx2 v2, v[30:31], s[26:27] offset:1024
	v_pk_mul_f32 v[10:11], v[78:79], v[4:5]
	v_pk_mul_f32 v[10:11], v[10:11], v[142:143]
	v_pk_add_f32 v[12:13], v[208:209], v[6:7]
	v_pk_fma_f32 v[14:15], v[10:11], v[12:13], v[176:177]
	v_pk_mul_f32 v[10:11], v[80:81], v[4:5]
	v_pk_mul_f32 v[10:11], v[10:11], v[144:145]
	v_pk_add_f32 v[12:13], v[210:211], v[6:7]
	v_pk_fma_f32 v[16:17], v[10:11], v[12:13], v[178:179]
	v_cvt_pk_bf16_f32 v32, v14, v15
	v_cvt_pk_bf16_f32 v33, v16, v17
	global_store_dwordx2 v2, v[32:33], s[26:27] offset:1536
	v_pk_mul_f32 v[10:11], v[82:83], v[4:5]
	v_pk_mul_f32 v[10:11], v[10:11], v[146:147]
	v_pk_add_f32 v[12:13], v[212:213], v[6:7]
	v_pk_fma_f32 v[14:15], v[10:11], v[12:13], v[180:181]
	v_pk_mul_f32 v[10:11], v[84:85], v[4:5]
	v_pk_mul_f32 v[10:11], v[10:11], v[148:149]
	v_pk_add_f32 v[12:13], v[214:215], v[6:7]
	v_pk_fma_f32 v[16:17], v[10:11], v[12:13], v[182:183]
	v_cvt_pk_bf16_f32 v26, v14, v15
	v_cvt_pk_bf16_f32 v27, v16, v17
	global_store_dwordx2 v2, v[26:27], s[26:27] offset:2048
	v_pk_mul_f32 v[10:11], v[86:87], v[4:5]
	v_pk_mul_f32 v[10:11], v[10:11], v[150:151]
	v_pk_add_f32 v[12:13], v[216:217], v[6:7]
	v_pk_fma_f32 v[14:15], v[10:11], v[12:13], v[184:185]
	v_pk_mul_f32 v[10:11], v[88:89], v[4:5]
	v_pk_mul_f32 v[10:11], v[10:11], v[152:153]
	v_pk_add_f32 v[12:13], v[218:219], v[6:7]
	v_pk_fma_f32 v[16:17], v[10:11], v[12:13], v[186:187]
	v_cvt_pk_bf16_f32 v28, v14, v15
	v_cvt_pk_bf16_f32 v29, v16, v17
	global_store_dwordx2 v2, v[28:29], s[26:27] offset:2560
	v_pk_mul_f32 v[10:11], v[90:91], v[4:5]
	v_pk_mul_f32 v[10:11], v[10:11], v[156:157]
	v_pk_add_f32 v[12:13], v[220:221], v[6:7]
	v_pk_fma_f32 v[14:15], v[10:11], v[12:13], v[188:189]
	v_pk_mul_f32 v[10:11], v[92:93], v[4:5]
	v_pk_mul_f32 v[10:11], v[10:11], v[158:159]
	v_pk_add_f32 v[12:13], v[222:223], v[6:7]
	v_pk_fma_f32 v[16:17], v[10:11], v[12:13], v[190:191]
	v_cvt_pk_bf16_f32 v30, v14, v15
	v_cvt_pk_bf16_f32 v31, v16, v17
	global_store_dwordx2 v2, v[30:31], s[26:27] offset:3072
	v_pk_mul_f32 v[10:11], v[94:95], v[4:5]
	v_pk_mul_f32 v[10:11], v[10:11], v[160:161]
	v_pk_add_f32 v[12:13], v[224:225], v[6:7]
	v_pk_fma_f32 v[14:15], v[10:11], v[12:13], v[192:193]
	v_pk_mul_f32 v[10:11], v[96:97], v[4:5]
	v_pk_mul_f32 v[10:11], v[10:11], v[162:163]
	v_pk_add_f32 v[12:13], v[226:227], v[6:7]
	v_pk_fma_f32 v[16:17], v[10:11], v[12:13], v[194:195]
	v_cvt_pk_bf16_f32 v32, v14, v15
	v_cvt_pk_bf16_f32 v33, v16, v17
	global_store_dwordx2 v2, v[32:33], s[26:27] offset:3584
	s_lshr_b32 s16, s10, 10
	s_add_u32 s17, s16, 0
	s_mul_i32 s17, s17, 49152
	s_add_u32 s17, s17, 0x10404000
	s_add_u32 s28, s90, s17
	s_addc_u32 s29, s91, 0
	s_add_u32 s17, s16, 0
	s_mul_i32 s17, s17, 49152
	s_add_u32 s17, s17, 0x10400000
	s_add_u32 s30, s90, s17
	s_addc_u32 s31, s91, 0
	s_add_u32 s32, s30, 0x2000
	s_addc_u32 s33, s31, 0
	s_add_u32 s18, s2, 0x1000
	s_addc_u32 s19, s3, 0
	global_load_dwordx4 v[130:133], v1, s[2:3]
	global_load_dwordx4 v[134:137], v1, s[2:3] offset:1024
	global_load_dwordx4 v[138:141], v1, s[2:3] offset:2048
	global_load_dwordx4 v[142:145], v1, s[2:3] offset:3072
	global_load_dwordx4 v[146:149], v1, s[18:19]
	global_load_dwordx4 v[150:153], v1, s[18:19] offset:1024
	global_load_dwordx4 v[156:159], v1, s[18:19] offset:2048
	global_load_dwordx4 v[160:163], v1, s[18:19] offset:3072
	s_add_u32 s18, s30, 0x1000
	s_addc_u32 s19, s31, 0
	global_load_dwordx4 v[164:167], v1, s[30:31]
	global_load_dwordx4 v[168:171], v1, s[30:31] offset:1024
	global_load_dwordx4 v[172:175], v1, s[30:31] offset:2048
	global_load_dwordx4 v[176:179], v1, s[30:31] offset:3072
	global_load_dwordx4 v[180:183], v1, s[18:19]
	global_load_dwordx4 v[184:187], v1, s[18:19] offset:1024
	global_load_dwordx4 v[188:191], v1, s[18:19] offset:2048
	global_load_dwordx4 v[192:195], v1, s[18:19] offset:3072
	s_add_u32 s18, s32, 0x1000
	s_addc_u32 s19, s33, 0
	global_load_dwordx4 v[196:199], v1, s[32:33]
	global_load_dwordx4 v[200:203], v1, s[32:33] offset:1024
	global_load_dwordx4 v[204:207], v1, s[32:33] offset:2048
	global_load_dwordx4 v[208:211], v1, s[32:33] offset:3072
	global_load_dwordx4 v[212:215], v1, s[18:19]
	global_load_dwordx4 v[216:219], v1, s[18:19] offset:1024
	global_load_dwordx4 v[220:223], v1, s[18:19] offset:2048
	global_load_dwordx4 v[224:227], v1, s[18:19] offset:3072
	s_add_u32 s12, s10, 6144
	s_lshl_b32 s13, s12, 13
	s_lshl_b32 s14, s12, 12
	s_sub_u32 s15, s13, 0x2000000
	s_add_u32 s20, s8, s15
	s_addc_u32 s21, s9, 0
	s_add_u32 s22, s90, 0x21918000
	s_addc_u32 s23, s91, 0
	s_add_u32 s22, s22, s14
	s_addc_u32 s23, s23, 0
	s_add_u32 s36, s20, 0x1000
	s_addc_u32 s37, s21, 0
	global_load_dwordx4 v[66:69], v1, s[20:21] nt
	global_load_dwordx4 v[70:73], v1, s[20:21] offset:1024 nt
	global_load_dwordx4 v[74:77], v1, s[20:21] offset:2048 nt
	global_load_dwordx4 v[78:81], v1, s[20:21] offset:3072 nt
	global_load_dwordx4 v[82:85], v1, s[36:37] nt
	global_load_dwordx4 v[86:89], v1, s[36:37] offset:1024 nt
	global_load_dwordx4 v[90:93], v1, s[36:37] offset:2048 nt
	global_load_dwordx4 v[94:97], v1, s[36:37] offset:3072 nt
	s_add_u32 s12, s10, 4096
	s_lshl_b32 s14, s12, 12
	s_add_u32 s26, s90, 0x11918000
	s_addc_u32 s27, s91, 0
	s_add_u32 s26, s26, s14
	s_addc_u32 s27, s27, 0
	s_waitcnt vmcnt(40)
	v_mov_b32_e32 v8, 0
	v_fmac_f32_e32 v8, v34, v34
	v_fmac_f32_e32 v8, v35, v35
	v_fmac_f32_e32 v8, v36, v36
	v_fmac_f32_e32 v8, v37, v37
	v_fmac_f32_e32 v8, v38, v38
	v_fmac_f32_e32 v8, v39, v39
	v_fmac_f32_e32 v8, v40, v40
	v_fmac_f32_e32 v8, v41, v41
	v_fmac_f32_e32 v8, v42, v42
	v_fmac_f32_e32 v8, v43, v43
	v_fmac_f32_e32 v8, v44, v44
	v_fmac_f32_e32 v8, v45, v45
	v_fmac_f32_e32 v8, v46, v46
	v_fmac_f32_e32 v8, v47, v47
	v_fmac_f32_e32 v8, v48, v48
	v_fmac_f32_e32 v8, v49, v49
	v_fmac_f32_e32 v8, v50, v50
	v_fmac_f32_e32 v8, v51, v51
	v_fmac_f32_e32 v8, v52, v52
	v_fmac_f32_e32 v8, v53, v53
	v_fmac_f32_e32 v8, v54, v54
	v_fmac_f32_e32 v8, v55, v55
	v_fmac_f32_e32 v8, v56, v56
	v_fmac_f32_e32 v8, v57, v57
	v_fmac_f32_e32 v8, v58, v58
	v_fmac_f32_e32 v8, v59, v59
	v_fmac_f32_e32 v8, v60, v60
	v_fmac_f32_e32 v8, v61, v61
	v_fmac_f32_e32 v8, v62, v62
	v_fmac_f32_e32 v8, v63, v63
	v_fmac_f32_e32 v8, v64, v64
	v_fmac_f32_e32 v8, v65, v65
	s_nop 1
	v_add_f32_dpp v8, v8, v8 quad_perm:[1,0,3,2] row_mask:0xf bank_mask:0xf
	s_nop 1
	v_add_f32_dpp v8, v8, v8 quad_perm:[2,3,0,1] row_mask:0xf bank_mask:0xf
	s_nop 1
	v_add_f32_dpp v8, v8, v8 row_ror:4 row_mask:0xf bank_mask:0xf
	s_nop 1
	v_add_f32_dpp v8, v8, v8 row_ror:8 row_mask:0xf bank_mask:0xf
	s_nop 1
	v_readlane_b32 s42, v8, 0
	v_readlane_b32 s43, v8, 16
	v_readlane_b32 s44, v8, 32
	v_readlane_b32 s45, v8, 48
	s_nop 1
	v_mov_b32_e32 v8, s42
	v_add_f32_e32 v8, s43, v8
	v_add_f32_e32 v8, s44, v8
	v_add_f32_e32 v8, s45, v8
	v_mov_b32_e32 v4, s41
	v_fmac_f32_e32 v4, s40, v8
	v_rsq_f32_e32 v4, v4
	s_nop 0
	v_mov_b32_e32 v5, v4
	s_waitcnt vmcnt(8)
	v_pk_mul_f32 v[10:11], v[34:35], v[4:5]
	v_pk_mul_f32 v[10:11], v[10:11], v[130:131]
	v_pk_add_f32 v[12:13], v[196:197], v[6:7]
	v_pk_fma_f32 v[14:15], v[10:11], v[12:13], v[164:165]
	v_pk_mul_f32 v[10:11], v[36:37], v[4:5]
	v_pk_mul_f32 v[10:11], v[10:11], v[132:133]
	v_pk_add_f32 v[12:13], v[198:199], v[6:7]
	v_pk_fma_f32 v[16:17], v[10:11], v[12:13], v[166:167]
	v_cvt_pk_bf16_f32 v26, v14, v15
	v_cvt_pk_bf16_f32 v27, v16, v17
	global_store_dwordx2 v2, v[26:27], s[26:27]
	v_pk_mul_f32 v[10:11], v[38:39], v[4:5]
	v_pk_mul_f32 v[10:11], v[10:11], v[134:135]
	v_pk_add_f32 v[12:13], v[200:201], v[6:7]
	v_pk_fma_f32 v[14:15], v[10:11], v[12:13], v[168:169]
	v_pk_mul_f32 v[10:11], v[40:41], v[4:5]
	v_pk_mul_f32 v[10:11], v[10:11], v[136:137]
	v_pk_add_f32 v[12:13], v[202:203], v[6:7]
	v_pk_fma_f32 v[16:17], v[10:11], v[12:13], v[170:171]
	v_cvt_pk_bf16_f32 v28, v14, v15
	v_cvt_pk_bf16_f32 v29, v16, v17
	global_store_dwordx2 v2, v[28:29], s[26:27] offset:512
	v_pk_mul_f32 v[10:11], v[42:43], v[4:5]
	v_pk_mul_f32 v[10:11], v[10:11], v[138:139]
	v_pk_add_f32 v[12:13], v[204:205], v[6:7]
	v_pk_fma_f32 v[14:15], v[10:11], v[12:13], v[172:173]
	v_pk_mul_f32 v[10:11], v[44:45], v[4:5]
	v_pk_mul_f32 v[10:11], v[10:11], v[140:141]
	v_pk_add_f32 v[12:13], v[206:207], v[6:7]
	v_pk_fma_f32 v[16:17], v[10:11], v[12:13], v[174:175]
	v_cvt_pk_bf16_f32 v30, v14, v15
	v_cvt_pk_bf16_f32 v31, v16, v17
	global_store_dwordx2 v2, v[30:31], s[26:27] offset:1024
	v_pk_mul_f32 v[10:11], v[46:47], v[4:5]
	v_pk_mul_f32 v[10:11], v[10:11], v[142:143]
	v_pk_add_f32 v[12:13], v[208:209], v[6:7]
	v_pk_fma_f32 v[14:15], v[10:11], v[12:13], v[176:177]
	v_pk_mul_f32 v[10:11], v[48:49], v[4:5]
	v_pk_mul_f32 v[10:11], v[10:11], v[144:145]
	v_pk_add_f32 v[12:13], v[210:211], v[6:7]
	v_pk_fma_f32 v[16:17], v[10:11], v[12:13], v[178:179]
	v_cvt_pk_bf16_f32 v32, v14, v15
	v_cvt_pk_bf16_f32 v33, v16, v17
	global_store_dwordx2 v2, v[32:33], s[26:27] offset:1536
	v_pk_mul_f32 v[10:11], v[50:51], v[4:5]
	v_pk_mul_f32 v[10:11], v[10:11], v[146:147]
	v_pk_add_f32 v[12:13], v[212:213], v[6:7]
	v_pk_fma_f32 v[14:15], v[10:11], v[12:13], v[180:181]
	v_pk_mul_f32 v[10:11], v[52:53], v[4:5]
	v_pk_mul_f32 v[10:11], v[10:11], v[148:149]
	v_pk_add_f32 v[12:13], v[214:215], v[6:7]
	v_pk_fma_f32 v[16:17], v[10:11], v[12:13], v[182:183]
	v_cvt_pk_bf16_f32 v26, v14, v15
	v_cvt_pk_bf16_f32 v27, v16, v17
	global_store_dwordx2 v2, v[26:27], s[26:27] offset:2048
	v_pk_mul_f32 v[10:11], v[54:55], v[4:5]
	v_pk_mul_f32 v[10:11], v[10:11], v[150:151]
	v_pk_add_f32 v[12:13], v[216:217], v[6:7]
	v_pk_fma_f32 v[14:15], v[10:11], v[12:13], v[184:185]
	v_pk_mul_f32 v[10:11], v[56:57], v[4:5]
	v_pk_mul_f32 v[10:11], v[10:11], v[152:153]
	v_pk_add_f32 v[12:13], v[218:219], v[6:7]
	v_pk_fma_f32 v[16:17], v[10:11], v[12:13], v[186:187]
	v_cvt_pk_bf16_f32 v28, v14, v15
	v_cvt_pk_bf16_f32 v29, v16, v17
	global_store_dwordx2 v2, v[28:29], s[26:27] offset:2560
	v_pk_mul_f32 v[10:11], v[58:59], v[4:5]
	v_pk_mul_f32 v[10:11], v[10:11], v[156:157]
	v_pk_add_f32 v[12:13], v[220:221], v[6:7]
	v_pk_fma_f32 v[14:15], v[10:11], v[12:13], v[188:189]
	v_pk_mul_f32 v[10:11], v[60:61], v[4:5]
	v_pk_mul_f32 v[10:11], v[10:11], v[158:159]
	v_pk_add_f32 v[12:13], v[222:223], v[6:7]
	v_pk_fma_f32 v[16:17], v[10:11], v[12:13], v[190:191]
	v_cvt_pk_bf16_f32 v30, v14, v15
	v_cvt_pk_bf16_f32 v31, v16, v17
	global_store_dwordx2 v2, v[30:31], s[26:27] offset:3072
	v_pk_mul_f32 v[10:11], v[62:63], v[4:5]
	v_pk_mul_f32 v[10:11], v[10:11], v[160:161]
	v_pk_add_f32 v[12:13], v[224:225], v[6:7]
	v_pk_fma_f32 v[14:15], v[10:11], v[12:13], v[192:193]
	v_pk_mul_f32 v[10:11], v[64:65], v[4:5]
	v_pk_mul_f32 v[10:11], v[10:11], v[162:163]
	v_pk_add_f32 v[12:13], v[226:227], v[6:7]
	v_pk_fma_f32 v[16:17], v[10:11], v[12:13], v[194:195]
	v_cvt_pk_bf16_f32 v32, v14, v15
	v_cvt_pk_bf16_f32 v33, v16, v17
	global_store_dwordx2 v2, v[32:33], s[26:27] offset:3584
	s_lshr_b32 s16, s10, 10
	s_add_u32 s16, s16, 2
	s_add_u32 s17, s16, 0
	s_mul_i32 s17, s17, 49152
	s_add_u32 s17, s17, 0x10404000
	s_add_u32 s28, s90, s17
	s_addc_u32 s29, s91, 0
	s_add_u32 s17, s16, 0
	s_mul_i32 s17, s17, 49152
	s_add_u32 s17, s17, 0x10400000
	s_add_u32 s30, s90, s17
	s_addc_u32 s31, s91, 0
	s_add_u32 s32, s30, 0x2000
	s_addc_u32 s33, s31, 0
	s_add_u32 s18, s2, 0x1000
	s_addc_u32 s19, s3, 0
	global_load_dwordx4 v[130:133], v1, s[2:3]
	global_load_dwordx4 v[134:137], v1, s[2:3] offset:1024
	global_load_dwordx4 v[138:141], v1, s[2:3] offset:2048
	global_load_dwordx4 v[142:145], v1, s[2:3] offset:3072
	global_load_dwordx4 v[146:149], v1, s[18:19]
	global_load_dwordx4 v[150:153], v1, s[18:19] offset:1024
	global_load_dwordx4 v[156:159], v1, s[18:19] offset:2048
	global_load_dwordx4 v[160:163], v1, s[18:19] offset:3072
	s_add_u32 s18, s30, 0x1000
	s_addc_u32 s19, s31, 0
	global_load_dwordx4 v[164:167], v1, s[30:31]
	global_load_dwordx4 v[168:171], v1, s[30:31] offset:1024
	global_load_dwordx4 v[172:175], v1, s[30:31] offset:2048
	global_load_dwordx4 v[176:179], v1, s[30:31] offset:3072
	global_load_dwordx4 v[180:183], v1, s[18:19]
	global_load_dwordx4 v[184:187], v1, s[18:19] offset:1024
	global_load_dwordx4 v[188:191], v1, s[18:19] offset:2048
	global_load_dwordx4 v[192:195], v1, s[18:19] offset:3072
	s_add_u32 s18, s32, 0x1000
	s_addc_u32 s19, s33, 0
	global_load_dwordx4 v[196:199], v1, s[32:33]
	global_load_dwordx4 v[200:203], v1, s[32:33] offset:1024
	global_load_dwordx4 v[204:207], v1, s[32:33] offset:2048
	global_load_dwordx4 v[208:211], v1, s[32:33] offset:3072
	global_load_dwordx4 v[212:215], v1, s[18:19]
	global_load_dwordx4 v[216:219], v1, s[18:19] offset:1024
	global_load_dwordx4 v[220:223], v1, s[18:19] offset:2048
	global_load_dwordx4 v[224:227], v1, s[18:19] offset:3072
	s_add_u32 s12, s10, 6144
	s_lshl_b32 s14, s12, 12
	s_add_u32 s26, s90, 0x11918000
	s_addc_u32 s27, s91, 0
	s_add_u32 s26, s26, s14
	s_addc_u32 s27, s27, 0
	s_waitcnt vmcnt(32)
	v_mov_b32_e32 v8, 0
	v_fmac_f32_e32 v8, v66, v66
	v_fmac_f32_e32 v8, v67, v67
	v_fmac_f32_e32 v8, v68, v68
	v_fmac_f32_e32 v8, v69, v69
	v_fmac_f32_e32 v8, v70, v70
	v_fmac_f32_e32 v8, v71, v71
	v_fmac_f32_e32 v8, v72, v72
	v_fmac_f32_e32 v8, v73, v73
	v_fmac_f32_e32 v8, v74, v74
	v_fmac_f32_e32 v8, v75, v75
	v_fmac_f32_e32 v8, v76, v76
	v_fmac_f32_e32 v8, v77, v77
	v_fmac_f32_e32 v8, v78, v78
	v_fmac_f32_e32 v8, v79, v79
	v_fmac_f32_e32 v8, v80, v80
	v_fmac_f32_e32 v8, v81, v81
	v_fmac_f32_e32 v8, v82, v82
	v_fmac_f32_e32 v8, v83, v83
	v_fmac_f32_e32 v8, v84, v84
	v_fmac_f32_e32 v8, v85, v85
	v_fmac_f32_e32 v8, v86, v86
	v_fmac_f32_e32 v8, v87, v87
	v_fmac_f32_e32 v8, v88, v88
	v_fmac_f32_e32 v8, v89, v89
	v_fmac_f32_e32 v8, v90, v90
	v_fmac_f32_e32 v8, v91, v91
	v_fmac_f32_e32 v8, v92, v92
	v_fmac_f32_e32 v8, v93, v93
	v_fmac_f32_e32 v8, v94, v94
	v_fmac_f32_e32 v8, v95, v95
	v_fmac_f32_e32 v8, v96, v96
	v_fmac_f32_e32 v8, v97, v97
	s_nop 1
	v_add_f32_dpp v8, v8, v8 quad_perm:[1,0,3,2] row_mask:0xf bank_mask:0xf
	s_nop 1
	v_add_f32_dpp v8, v8, v8 quad_perm:[2,3,0,1] row_mask:0xf bank_mask:0xf
	s_nop 1
	v_add_f32_dpp v8, v8, v8 row_ror:4 row_mask:0xf bank_mask:0xf
	s_nop 1
	v_add_f32_dpp v8, v8, v8 row_ror:8 row_mask:0xf bank_mask:0xf
	s_nop 1
	v_readlane_b32 s42, v8, 0
	v_readlane_b32 s43, v8, 16
	v_readlane_b32 s44, v8, 32
	v_readlane_b32 s45, v8, 48
	s_nop 1
	v_mov_b32_e32 v8, s42
	v_add_f32_e32 v8, s43, v8
	v_add_f32_e32 v8, s44, v8
	v_add_f32_e32 v8, s45, v8
	v_mov_b32_e32 v4, s41
	v_fmac_f32_e32 v4, s40, v8
	v_rsq_f32_e32 v4, v4
	s_nop 0
	v_mov_b32_e32 v5, v4
	s_waitcnt vmcnt(0)
	v_pk_mul_f32 v[10:11], v[66:67], v[4:5]
	v_pk_mul_f32 v[10:11], v[10:11], v[130:131]
	v_pk_add_f32 v[12:13], v[196:197], v[6:7]
	v_pk_fma_f32 v[14:15], v[10:11], v[12:13], v[164:165]
	v_pk_mul_f32 v[10:11], v[68:69], v[4:5]
	v_pk_mul_f32 v[10:11], v[10:11], v[132:133]
	v_pk_add_f32 v[12:13], v[198:199], v[6:7]
	v_pk_fma_f32 v[16:17], v[10:11], v[12:13], v[166:167]
	v_cvt_pk_bf16_f32 v26, v14, v15
	v_cvt_pk_bf16_f32 v27, v16, v17
	global_store_dwordx2 v2, v[26:27], s[26:27]
	v_pk_mul_f32 v[10:11], v[70:71], v[4:5]
	v_pk_mul_f32 v[10:11], v[10:11], v[134:135]
	v_pk_add_f32 v[12:13], v[200:201], v[6:7]
	v_pk_fma_f32 v[14:15], v[10:11], v[12:13], v[168:169]
	v_pk_mul_f32 v[10:11], v[72:73], v[4:5]
	v_pk_mul_f32 v[10:11], v[10:11], v[136:137]
	v_pk_add_f32 v[12:13], v[202:203], v[6:7]
	v_pk_fma_f32 v[16:17], v[10:11], v[12:13], v[170:171]
	v_cvt_pk_bf16_f32 v28, v14, v15
	v_cvt_pk_bf16_f32 v29, v16, v17
	global_store_dwordx2 v2, v[28:29], s[26:27] offset:512
	v_pk_mul_f32 v[10:11], v[74:75], v[4:5]
	v_pk_mul_f32 v[10:11], v[10:11], v[138:139]
	v_pk_add_f32 v[12:13], v[204:205], v[6:7]
	v_pk_fma_f32 v[14:15], v[10:11], v[12:13], v[172:173]
	v_pk_mul_f32 v[10:11], v[76:77], v[4:5]
	v_pk_mul_f32 v[10:11], v[10:11], v[140:141]
	v_pk_add_f32 v[12:13], v[206:207], v[6:7]
	v_pk_fma_f32 v[16:17], v[10:11], v[12:13], v[174:175]
	v_cvt_pk_bf16_f32 v30, v14, v15
	v_cvt_pk_bf16_f32 v31, v16, v17
	global_store_dwordx2 v2, v[30:31], s[26:27] offset:1024
	v_pk_mul_f32 v[10:11], v[78:79], v[4:5]
	v_pk_mul_f32 v[10:11], v[10:11], v[142:143]
	v_pk_add_f32 v[12:13], v[208:209], v[6:7]
	v_pk_fma_f32 v[14:15], v[10:11], v[12:13], v[176:177]
	v_pk_mul_f32 v[10:11], v[80:81], v[4:5]
	v_pk_mul_f32 v[10:11], v[10:11], v[144:145]
	v_pk_add_f32 v[12:13], v[210:211], v[6:7]
	v_pk_fma_f32 v[16:17], v[10:11], v[12:13], v[178:179]
	v_cvt_pk_bf16_f32 v32, v14, v15
	v_cvt_pk_bf16_f32 v33, v16, v17
	global_store_dwordx2 v2, v[32:33], s[26:27] offset:1536
	v_pk_mul_f32 v[10:11], v[82:83], v[4:5]
	v_pk_mul_f32 v[10:11], v[10:11], v[146:147]
	v_pk_add_f32 v[12:13], v[212:213], v[6:7]
	v_pk_fma_f32 v[14:15], v[10:11], v[12:13], v[180:181]
	v_pk_mul_f32 v[10:11], v[84:85], v[4:5]
	v_pk_mul_f32 v[10:11], v[10:11], v[148:149]
	v_pk_add_f32 v[12:13], v[214:215], v[6:7]
	v_pk_fma_f32 v[16:17], v[10:11], v[12:13], v[182:183]
	v_cvt_pk_bf16_f32 v26, v14, v15
	v_cvt_pk_bf16_f32 v27, v16, v17
	global_store_dwordx2 v2, v[26:27], s[26:27] offset:2048
	v_pk_mul_f32 v[10:11], v[86:87], v[4:5]
	v_pk_mul_f32 v[10:11], v[10:11], v[150:151]
	v_pk_add_f32 v[12:13], v[216:217], v[6:7]
	v_pk_fma_f32 v[14:15], v[10:11], v[12:13], v[184:185]
	v_pk_mul_f32 v[10:11], v[88:89], v[4:5]
	v_pk_mul_f32 v[10:11], v[10:11], v[152:153]
	v_pk_add_f32 v[12:13], v[218:219], v[6:7]
	v_pk_fma_f32 v[16:17], v[10:11], v[12:13], v[186:187]
	v_cvt_pk_bf16_f32 v28, v14, v15
	v_cvt_pk_bf16_f32 v29, v16, v17
	global_store_dwordx2 v2, v[28:29], s[26:27] offset:2560
	v_pk_mul_f32 v[10:11], v[90:91], v[4:5]
	v_pk_mul_f32 v[10:11], v[10:11], v[156:157]
	v_pk_add_f32 v[12:13], v[220:221], v[6:7]
	v_pk_fma_f32 v[14:15], v[10:11], v[12:13], v[188:189]
	v_pk_mul_f32 v[10:11], v[92:93], v[4:5]
	v_pk_mul_f32 v[10:11], v[10:11], v[158:159]
	v_pk_add_f32 v[12:13], v[222:223], v[6:7]
	v_pk_fma_f32 v[16:17], v[10:11], v[12:13], v[190:191]
	v_cvt_pk_bf16_f32 v30, v14, v15
	v_cvt_pk_bf16_f32 v31, v16, v17
	global_store_dwordx2 v2, v[30:31], s[26:27] offset:3072
	v_pk_mul_f32 v[10:11], v[94:95], v[4:5]
	v_pk_mul_f32 v[10:11], v[10:11], v[160:161]
	v_pk_add_f32 v[12:13], v[224:225], v[6:7]
	v_pk_fma_f32 v[14:15], v[10:11], v[12:13], v[192:193]
	v_pk_mul_f32 v[10:11], v[96:97], v[4:5]
	v_pk_mul_f32 v[10:11], v[10:11], v[162:163]
	v_pk_add_f32 v[12:13], v[226:227], v[6:7]
	v_pk_fma_f32 v[16:17], v[10:11], v[12:13], v[194:195]
	v_cvt_pk_bf16_f32 v32, v14, v15
	v_cvt_pk_bf16_f32 v33, v16, v17
	global_store_dwordx2 v2, v[32:33], s[26:27] offset:3584
	s_waitcnt vmcnt(0)
	s_branch .LBB0_231

.LBB0_1085:
.LBB0_1086:
	s_waitcnt vmcnt(0) lgkmcnt(0)
	s_load_dwordx2 s[0:1], s[92:93], 0x40
	s_load_dwordx2 s[2:3], s[92:93], 0x48
	s_load_dwordx2 s[4:5], s[92:93], 0xf0
	s_load_dwordx2 s[6:7], s[92:93], 0x0
	s_load_dwordx2 s[8:9], s[92:93], 0x8
	v_and_b32_e32 v2, 63, v154
	v_lshlrev_b32_e32 v1, 4, v2
	v_lshlrev_b32_e32 v2, 3, v2
	v_mov_b32_e32 v6, 1.0
	v_mov_b32_e32 v7, 1.0
	s_mov_b32 s40, 0x3a000000
	s_mov_b32 s41, 0x358637bd
	v_readfirstlane_b32 s10, v154
	s_lshr_b32 s10, s10, 6
	s_lshl_b32 s12, s96, 3
	s_add_u32 s10, s10, s12
	s_waitcnt lgkmcnt(0)
	s_add_u32 s12, s10, 0
	s_lshl_b32 s13, s12, 13
	s_lshl_b32 s14, s12, 12
	s_add_u32 s20, s6, s13
	s_addc_u32 s21, s7, 0
	s_add_u32 s22, s90, 0x21918000
	s_addc_u32 s23, s91, 0
	s_add_u32 s22, s22, s14
	s_addc_u32 s23, s23, 0
	global_load_dwordx2 v[98:99], v2, s[22:23] nt
	global_load_dwordx2 v[100:101], v2, s[22:23] offset:512 nt
	global_load_dwordx2 v[102:103], v2, s[22:23] offset:1024 nt
	global_load_dwordx2 v[104:105], v2, s[22:23] offset:1536 nt
	global_load_dwordx2 v[106:107], v2, s[22:23] offset:2048 nt
	global_load_dwordx2 v[108:109], v2, s[22:23] offset:2560 nt
	global_load_dwordx2 v[110:111], v2, s[22:23] offset:3072 nt
	global_load_dwordx2 v[112:113], v2, s[22:23] offset:3584 nt
	s_add_u32 s36, s20, 0x1000
	s_addc_u32 s37, s21, 0
	global_load_dwordx4 v[34:37], v1, s[20:21] nt
	global_load_dwordx4 v[38:41], v1, s[20:21] offset:1024 nt
	global_load_dwordx4 v[42:45], v1, s[20:21] offset:2048 nt
	global_load_dwordx4 v[46:49], v1, s[20:21] offset:3072 nt
	global_load_dwordx4 v[50:53], v1, s[36:37] nt
	global_load_dwordx4 v[54:57], v1, s[36:37] offset:1024 nt
	global_load_dwordx4 v[58:61], v1, s[36:37] offset:2048 nt
	global_load_dwordx4 v[62:65], v1, s[36:37] offset:3072 nt
	s_mov_b32 s16, 4
	s_add_u32 s17, s16, 0
	s_mul_i32 s17, s17, 49152
	s_add_u32 s17, s17, 0x10404000
	s_add_u32 s28, s90, s17
	s_addc_u32 s29, s91, 0
	s_add_u32 s17, s16, 0
	s_mul_i32 s17, s17, 49152
	s_add_u32 s17, s17, 0x10406000
	s_add_u32 s30, s90, s17
	s_addc_u32 s31, s91, 0
	s_add_u32 s32, s30, 0x2000
	s_addc_u32 s33, s31, 0
	s_add_u32 s18, s0, 0x1000
	s_addc_u32 s19, s1, 0
	global_load_dwordx4 v[130:133], v1, s[0:1]
	global_load_dwordx4 v[134:137], v1, s[0:1] offset:1024
	global_load_dwordx4 v[138:141], v1, s[0:1] offset:2048
	global_load_dwordx4 v[142:145], v1, s[0:1] offset:3072
	global_load_dwordx4 v[146:149], v1, s[18:19]
	global_load_dwordx4 v[150:153], v1, s[18:19] offset:1024
	global_load_dwordx4 v[156:159], v1, s[18:19] offset:2048
	global_load_dwordx4 v[160:163], v1, s[18:19] offset:3072
	s_add_u32 s18, s28, 0x1000
	s_addc_u32 s19, s29, 0
	global_load_dwordx4 v[164:167], v1, s[28:29]
	global_load_dwordx4 v[168:171], v1, s[28:29] offset:1024
	global_load_dwordx4 v[172:175], v1, s[28:29] offset:2048
	global_load_dwordx4 v[176:179], v1, s[28:29] offset:3072
	global_load_dwordx4 v[180:183], v1, s[18:19]
	global_load_dwordx4 v[184:187], v1, s[18:19] offset:1024
	global_load_dwordx4 v[188:191], v1, s[18:19] offset:2048
	global_load_dwordx4 v[192:195], v1, s[18:19] offset:3072
	s_add_u32 s12, s10, 2048
	s_lshl_b32 s13, s12, 13
	s_lshl_b32 s14, s12, 12
	s_add_u32 s20, s6, s13
	s_addc_u32 s21, s7, 0
	s_add_u32 s22, s90, 0x21918000
	s_addc_u32 s23, s91, 0
	s_add_u32 s22, s22, s14
	s_addc_u32 s23, s23, 0
	global_load_dwordx2 v[114:115], v2, s[22:23] nt
	global_load_dwordx2 v[116:117], v2, s[22:23] offset:512 nt
	global_load_dwordx2 v[118:119], v2, s[22:23] offset:1024 nt
	global_load_dwordx2 v[120:121], v2, s[22:23] offset:1536 nt
	global_load_dwordx2 v[122:123], v2, s[22:23] offset:2048 nt
	global_load_dwordx2 v[124:125], v2, s[22:23] offset:2560 nt
	global_load_dwordx2 v[126:127], v2, s[22:23] offset:3072 nt
	global_load_dwordx2 v[128:129], v2, s[22:23] offset:3584 nt
	s_add_u32 s36, s20, 0x1000
	s_addc_u32 s37, s21, 0
	global_load_dwordx4 v[66:69], v1, s[20:21] nt
	global_load_dwordx4 v[70:73], v1, s[20:21] offset:1024 nt
	global_load_dwordx4 v[74:77], v1, s[20:21] offset:2048 nt
	global_load_dwordx4 v[78:81], v1, s[20:21] offset:3072 nt
	global_load_dwordx4 v[82:85], v1, s[36:37] nt
	global_load_dwordx4 v[86:89], v1, s[36:37] offset:1024 nt
	global_load_dwordx4 v[90:93], v1, s[36:37] offset:2048 nt
	global_load_dwordx4 v[94:97], v1, s[36:37] offset:3072 nt
	s_add_u32 s12, s10, 0
	s_lshl_b32 s13, s12, 13
	s_lshl_b32 s14, s12, 12
	s_add_u32 s24, s4, s13
	s_addc_u32 s25, s5, 0
	s_add_u32 s34, s24, 0x1000
	s_addc_u32 s35, s25, 0
	s_add_u32 s26, s90, 0x11918000
	s_addc_u32 s27, s91, 0
	s_add_u32 s26, s26, s14
	s_addc_u32 s27, s27, 0
	s_waitcnt vmcnt(40)
	v_mov_b32_e32 v8, 0
	v_lshlrev_b32_e32 v10, 16, v98
	v_and_b32_e32 v11, 0xffff0000, v98
	v_fmac_f32_e32 v8, v10, v10
	v_fmac_f32_e32 v8, v11, v11
	v_lshlrev_b32_e32 v10, 16, v99
	v_and_b32_e32 v11, 0xffff0000, v99
	v_fmac_f32_e32 v8, v10, v10
	v_fmac_f32_e32 v8, v11, v11
	v_lshlrev_b32_e32 v10, 16, v100
	v_and_b32_e32 v11, 0xffff0000, v100
	v_fmac_f32_e32 v8, v10, v10
	v_fmac_f32_e32 v8, v11, v11
	v_lshlrev_b32_e32 v10, 16, v101
	v_and_b32_e32 v11, 0xffff0000, v101
	v_fmac_f32_e32 v8, v10, v10
	v_fmac_f32_e32 v8, v11, v11
	v_lshlrev_b32_e32 v10, 16, v102
	v_and_b32_e32 v11, 0xffff0000, v102
	v_fmac_f32_e32 v8, v10, v10
	v_fmac_f32_e32 v8, v11, v11
	v_lshlrev_b32_e32 v10, 16, v103
	v_and_b32_e32 v11, 0xffff0000, v103
	v_fmac_f32_e32 v8, v10, v10
	v_fmac_f32_e32 v8, v11, v11
	v_lshlrev_b32_e32 v10, 16, v104
	v_and_b32_e32 v11, 0xffff0000, v104
	v_fmac_f32_e32 v8, v10, v10
	v_fmac_f32_e32 v8, v11, v11
	v_lshlrev_b32_e32 v10, 16, v105
	v_and_b32_e32 v11, 0xffff0000, v105
	v_fmac_f32_e32 v8, v10, v10
	v_fmac_f32_e32 v8, v11, v11
	v_lshlrev_b32_e32 v10, 16, v106
	v_and_b32_e32 v11, 0xffff0000, v106
	v_fmac_f32_e32 v8, v10, v10
	v_fmac_f32_e32 v8, v11, v11
	v_lshlrev_b32_e32 v10, 16, v107
	v_and_b32_e32 v11, 0xffff0000, v107
	v_fmac_f32_e32 v8, v10, v10
	v_fmac_f32_e32 v8, v11, v11
	v_lshlrev_b32_e32 v10, 16, v108
	v_and_b32_e32 v11, 0xffff0000, v108
	v_fmac_f32_e32 v8, v10, v10
	v_fmac_f32_e32 v8, v11, v11
	v_lshlrev_b32_e32 v10, 16, v109
	v_and_b32_e32 v11, 0xffff0000, v109
	v_fmac_f32_e32 v8, v10, v10
	v_fmac_f32_e32 v8, v11, v11
	v_lshlrev_b32_e32 v10, 16, v110
	v_and_b32_e32 v11, 0xffff0000, v110
	v_fmac_f32_e32 v8, v10, v10
	v_fmac_f32_e32 v8, v11, v11
	v_lshlrev_b32_e32 v10, 16, v111
	v_and_b32_e32 v11, 0xffff0000, v111
	v_fmac_f32_e32 v8, v10, v10
	v_fmac_f32_e32 v8, v11, v11
	v_lshlrev_b32_e32 v10, 16, v112
	v_and_b32_e32 v11, 0xffff0000, v112
	v_fmac_f32_e32 v8, v10, v10
	v_fmac_f32_e32 v8, v11, v11
	v_lshlrev_b32_e32 v10, 16, v113
	v_and_b32_e32 v11, 0xffff0000, v113
	v_fmac_f32_e32 v8, v10, v10
	v_fmac_f32_e32 v8, v11, v11
	s_nop 1
	v_add_f32_dpp v8, v8, v8 quad_perm:[1,0,3,2] row_mask:0xf bank_mask:0xf
	s_nop 1
	v_add_f32_dpp v8, v8, v8 quad_perm:[2,3,0,1] row_mask:0xf bank_mask:0xf
	s_nop 1
	v_add_f32_dpp v8, v8, v8 row_ror:4 row_mask:0xf bank_mask:0xf
	s_nop 1
	v_add_f32_dpp v8, v8, v8 row_ror:8 row_mask:0xf bank_mask:0xf
	s_nop 1
	v_readlane_b32 s42, v8, 0
	v_readlane_b32 s43, v8, 16
	v_readlane_b32 s44, v8, 32
	v_readlane_b32 s45, v8, 48
	s_nop 1
	v_mov_b32_e32 v8, s42
	v_add_f32_e32 v8, s43, v8
	v_add_f32_e32 v8, s44, v8
	v_add_f32_e32 v8, s45, v8
	v_mov_b32_e32 v4, s41
	v_fmac_f32_e32 v4, s40, v8
	v_rsq_f32_e32 v4, v4
	s_nop 0
	v_mov_b32_e32 v5, v4
	s_waitcnt vmcnt(32)
	s_waitcnt vmcnt(16)
	v_mov_b32_e32 v8, 0
	v_lshlrev_b32_e32 v10, 16, v98
	v_and_b32_e32 v11, 0xffff0000, v98
	v_pk_mul_f32 v[10:11], v[10:11], v[4:5]
	v_pk_mul_f32 v[10:11], v[10:11], v[130:131]
	v_pk_fma_f32 v[34:35], v[164:165], v[10:11], v[34:35]
	v_lshlrev_b32_e32 v10, 16, v99
	v_and_b32_e32 v11, 0xffff0000, v99
	v_pk_mul_f32 v[10:11], v[10:11], v[4:5]
	v_pk_mul_f32 v[10:11], v[10:11], v[132:133]
	v_pk_fma_f32 v[36:37], v[166:167], v[10:11], v[36:37]
	global_store_dwordx4 v1, v[34:37], s[24:25] nt
	v_fmac_f32_e32 v8, v34, v34
	v_fmac_f32_e32 v8, v35, v35
	v_fmac_f32_e32 v8, v36, v36
	v_fmac_f32_e32 v8, v37, v37
	v_lshlrev_b32_e32 v10, 16, v100
	v_and_b32_e32 v11, 0xffff0000, v100
	v_pk_mul_f32 v[10:11], v[10:11], v[4:5]
	v_pk_mul_f32 v[10:11], v[10:11], v[134:135]
	v_pk_fma_f32 v[38:39], v[168:169], v[10:11], v[38:39]
	v_lshlrev_b32_e32 v10, 16, v101
	v_and_b32_e32 v11, 0xffff0000, v101
	v_pk_mul_f32 v[10:11], v[10:11], v[4:5]
	v_pk_mul_f32 v[10:11], v[10:11], v[136:137]
	v_pk_fma_f32 v[40:41], v[170:171], v[10:11], v[40:41]
	global_store_dwordx4 v1, v[38:41], s[24:25] offset:1024 nt
	v_fmac_f32_e32 v8, v38, v38
	v_fmac_f32_e32 v8, v39, v39
	v_fmac_f32_e32 v8, v40, v40
	v_fmac_f32_e32 v8, v41, v41
	v_lshlrev_b32_e32 v10, 16, v102
	v_and_b32_e32 v11, 0xffff0000, v102
	v_pk_mul_f32 v[10:11], v[10:11], v[4:5]
	v_pk_mul_f32 v[10:11], v[10:11], v[138:139]
	v_pk_fma_f32 v[42:43], v[172:173], v[10:11], v[42:43]
	v_lshlrev_b32_e32 v10, 16, v103
	v_and_b32_e32 v11, 0xffff0000, v103
	v_pk_mul_f32 v[10:11], v[10:11], v[4:5]
	v_pk_mul_f32 v[10:11], v[10:11], v[140:141]
	v_pk_fma_f32 v[44:45], v[174:175], v[10:11], v[44:45]
	global_store_dwordx4 v1, v[42:45], s[24:25] offset:2048 nt
	v_fmac_f32_e32 v8, v42, v42
	v_fmac_f32_e32 v8, v43, v43
	v_fmac_f32_e32 v8, v44, v44
	v_fmac_f32_e32 v8, v45, v45
	v_lshlrev_b32_e32 v10, 16, v104
	v_and_b32_e32 v11, 0xffff0000, v104
	v_pk_mul_f32 v[10:11], v[10:11], v[4:5]
	v_pk_mul_f32 v[10:11], v[10:11], v[142:143]
	v_pk_fma_f32 v[46:47], v[176:177], v[10:11], v[46:47]
	v_lshlrev_b32_e32 v10, 16, v105
	v_and_b32_e32 v11, 0xffff0000, v105
	v_pk_mul_f32 v[10:11], v[10:11], v[4:5]
	v_pk_mul_f32 v[10:11], v[10:11], v[144:145]
	v_pk_fma_f32 v[48:49], v[178:179], v[10:11], v[48:49]
	global_store_dwordx4 v1, v[46:49], s[24:25] offset:3072 nt
	v_fmac_f32_e32 v8, v46, v46
	v_fmac_f32_e32 v8, v47, v47
	v_fmac_f32_e32 v8, v48, v48
	v_fmac_f32_e32 v8, v49, v49
	v_lshlrev_b32_e32 v10, 16, v106
	v_and_b32_e32 v11, 0xffff0000, v106
	v_pk_mul_f32 v[10:11], v[10:11], v[4:5]
	v_pk_mul_f32 v[10:11], v[10:11], v[146:147]
	v_pk_fma_f32 v[50:51], v[180:181], v[10:11], v[50:51]
	v_lshlrev_b32_e32 v10, 16, v107
	v_and_b32_e32 v11, 0xffff0000, v107
	v_pk_mul_f32 v[10:11], v[10:11], v[4:5]
	v_pk_mul_f32 v[10:11], v[10:11], v[148:149]
	v_pk_fma_f32 v[52:53], v[182:183], v[10:11], v[52:53]
	global_store_dwordx4 v1, v[50:53], s[34:35] nt
	v_fmac_f32_e32 v8, v50, v50
	v_fmac_f32_e32 v8, v51, v51
	v_fmac_f32_e32 v8, v52, v52
	v_fmac_f32_e32 v8, v53, v53
	v_lshlrev_b32_e32 v10, 16, v108
	v_and_b32_e32 v11, 0xffff0000, v108
	v_pk_mul_f32 v[10:11], v[10:11], v[4:5]
	v_pk_mul_f32 v[10:11], v[10:11], v[150:151]
	v_pk_fma_f32 v[54:55], v[184:185], v[10:11], v[54:55]
	v_lshlrev_b32_e32 v10, 16, v109
	v_and_b32_e32 v11, 0xffff0000, v109
	v_pk_mul_f32 v[10:11], v[10:11], v[4:5]
	v_pk_mul_f32 v[10:11], v[10:11], v[152:153]
	v_pk_fma_f32 v[56:57], v[186:187], v[10:11], v[56:57]
	global_store_dwordx4 v1, v[54:57], s[34:35] offset:1024 nt
	v_fmac_f32_e32 v8, v54, v54
	v_fmac_f32_e32 v8, v55, v55
	v_fmac_f32_e32 v8, v56, v56
	v_fmac_f32_e32 v8, v57, v57
	v_lshlrev_b32_e32 v10, 16, v110
	v_and_b32_e32 v11, 0xffff0000, v110
	v_pk_mul_f32 v[10:11], v[10:11], v[4:5]
	v_pk_mul_f32 v[10:11], v[10:11], v[156:157]
	v_pk_fma_f32 v[58:59], v[188:189], v[10:11], v[58:59]
	v_lshlrev_b32_e32 v10, 16, v111
	v_and_b32_e32 v11, 0xffff0000, v111
	v_pk_mul_f32 v[10:11], v[10:11], v[4:5]
	v_pk_mul_f32 v[10:11], v[10:11], v[158:159]
	v_pk_fma_f32 v[60:61], v[190:191], v[10:11], v[60:61]
	global_store_dwordx4 v1, v[58:61], s[34:35] offset:2048 nt
	v_fmac_f32_e32 v8, v58, v58
	v_fmac_f32_e32 v8, v59, v59
	v_fmac_f32_e32 v8, v60, v60
	v_fmac_f32_e32 v8, v61, v61
	v_lshlrev_b32_e32 v10, 16, v112
	v_and_b32_e32 v11, 0xffff0000, v112
	v_pk_mul_f32 v[10:11], v[10:11], v[4:5]
	v_pk_mul_f32 v[10:11], v[10:11], v[160:161]
	v_pk_fma_f32 v[62:63], v[192:193], v[10:11], v[62:63]
	v_lshlrev_b32_e32 v10, 16, v113
	v_and_b32_e32 v11, 0xffff0000, v113
	v_pk_mul_f32 v[10:11], v[10:11], v[4:5]
	v_pk_mul_f32 v[10:11], v[10:11], v[162:163]
	v_pk_fma_f32 v[64:65], v[194:195], v[10:11], v[64:65]
	global_store_dwordx4 v1, v[62:65], s[34:35] offset:3072 nt
	v_fmac_f32_e32 v8, v62, v62
	v_fmac_f32_e32 v8, v63, v63
	v_fmac_f32_e32 v8, v64, v64
	v_fmac_f32_e32 v8, v65, v65
	s_add_u32 s18, s2, 0x1000
	s_addc_u32 s19, s3, 0
	global_load_dwordx4 v[130:133], v1, s[2:3]
	global_load_dwordx4 v[134:137], v1, s[2:3] offset:1024
	global_load_dwordx4 v[138:141], v1, s[2:3] offset:2048
	global_load_dwordx4 v[142:145], v1, s[2:3] offset:3072
	global_load_dwordx4 v[146:149], v1, s[18:19]
	global_load_dwordx4 v[150:153], v1, s[18:19] offset:1024
	global_load_dwordx4 v[156:159], v1, s[18:19] offset:2048
	global_load_dwordx4 v[160:163], v1, s[18:19] offset:3072
	s_add_u32 s18, s30, 0x1000
	s_addc_u32 s19, s31, 0
	global_load_dwordx4 v[164:167], v1, s[30:31]
	global_load_dwordx4 v[168:171], v1, s[30:31] offset:1024
	global_load_dwordx4 v[172:175], v1, s[30:31] offset:2048
	global_load_dwordx4 v[176:179], v1, s[30:31] offset:3072
	global_load_dwordx4 v[180:183], v1, s[18:19]
	global_load_dwordx4 v[184:187], v1, s[18:19] offset:1024
	global_load_dwordx4 v[188:191], v1, s[18:19] offset:2048
	global_load_dwordx4 v[192:195], v1, s[18:19] offset:3072
	s_add_u32 s18, s32, 0x1000
	s_addc_u32 s19, s33, 0
	global_load_dwordx4 v[196:199], v1, s[32:33]
	global_load_dwordx4 v[200:203], v1, s[32:33] offset:1024
	global_load_dwordx4 v[204:207], v1, s[32:33] offset:2048
	global_load_dwordx4 v[208:211], v1, s[32:33] offset:3072
	global_load_dwordx4 v[212:215], v1, s[18:19]
	global_load_dwordx4 v[216:219], v1, s[18:19] offset:1024
	global_load_dwordx4 v[220:223], v1, s[18:19] offset:2048
	global_load_dwordx4 v[224:227], v1, s[18:19] offset:3072
	s_nop 1
	v_add_f32_dpp v8, v8, v8 quad_perm:[1,0,3,2] row_mask:0xf bank_mask:0xf
	s_nop 1
	v_add_f32_dpp v8, v8, v8 quad_perm:[2,3,0,1] row_mask:0xf bank_mask:0xf
	s_nop 1
	v_add_f32_dpp v8, v8, v8 row_ror:4 row_mask:0xf bank_mask:0xf
	s_nop 1
	v_add_f32_dpp v8, v8, v8 row_ror:8 row_mask:0xf bank_mask:0xf
	s_nop 1
	v_readlane_b32 s42, v8, 0
	v_readlane_b32 s43, v8, 16
	v_readlane_b32 s44, v8, 32
	v_readlane_b32 s45, v8, 48
	s_nop 1
	v_mov_b32_e32 v8, s42
	v_add_f32_e32 v8, s43, v8
	v_add_f32_e32 v8, s44, v8
	v_add_f32_e32 v8, s45, v8
	v_mov_b32_e32 v4, s41
	v_fmac_f32_e32 v4, s40, v8
	v_rsq_f32_e32 v4, v4
	s_nop 0
	v_mov_b32_e32 v5, v4
	s_waitcnt vmcnt(0)
	v_pk_mul_f32 v[10:11], v[34:35], v[4:5]
	v_pk_mul_f32 v[10:11], v[10:11], v[130:131]
	v_pk_add_f32 v[12:13], v[196:197], v[6:7]
	v_pk_fma_f32 v[14:15], v[10:11], v[12:13], v[164:165]
	v_pk_mul_f32 v[10:11], v[36:37], v[4:5]
	v_pk_mul_f32 v[10:11], v[10:11], v[132:133]
	v_pk_add_f32 v[12:13], v[198:199], v[6:7]
	v_pk_fma_f32 v[16:17], v[10:11], v[12:13], v[166:167]
	v_cvt_pk_bf16_f32 v26, v14, v15
	v_cvt_pk_bf16_f32 v27, v16, v17
	global_store_dwordx2 v2, v[26:27], s[26:27]
	v_pk_mul_f32 v[10:11], v[38:39], v[4:5]
	v_pk_mul_f32 v[10:11], v[10:11], v[134:135]
	v_pk_add_f32 v[12:13], v[200:201], v[6:7]
	v_pk_fma_f32 v[14:15], v[10:11], v[12:13], v[168:169]
	v_pk_mul_f32 v[10:11], v[40:41], v[4:5]
	v_pk_mul_f32 v[10:11], v[10:11], v[136:137]
	v_pk_add_f32 v[12:13], v[202:203], v[6:7]
	v_pk_fma_f32 v[16:17], v[10:11], v[12:13], v[170:171]
	v_cvt_pk_bf16_f32 v28, v14, v15
	v_cvt_pk_bf16_f32 v29, v16, v17
	global_store_dwordx2 v2, v[28:29], s[26:27] offset:512
	v_pk_mul_f32 v[10:11], v[42:43], v[4:5]
	v_pk_mul_f32 v[10:11], v[10:11], v[138:139]
	v_pk_add_f32 v[12:13], v[204:205], v[6:7]
	v_pk_fma_f32 v[14:15], v[10:11], v[12:13], v[172:173]
	v_pk_mul_f32 v[10:11], v[44:45], v[4:5]
	v_pk_mul_f32 v[10:11], v[10:11], v[140:141]
	v_pk_add_f32 v[12:13], v[206:207], v[6:7]
	v_pk_fma_f32 v[16:17], v[10:11], v[12:13], v[174:175]
	v_cvt_pk_bf16_f32 v30, v14, v15
	v_cvt_pk_bf16_f32 v31, v16, v17
	global_store_dwordx2 v2, v[30:31], s[26:27] offset:1024
	v_pk_mul_f32 v[10:11], v[46:47], v[4:5]
	v_pk_mul_f32 v[10:11], v[10:11], v[142:143]
	v_pk_add_f32 v[12:13], v[208:209], v[6:7]
	v_pk_fma_f32 v[14:15], v[10:11], v[12:13], v[176:177]
	v_pk_mul_f32 v[10:11], v[48:49], v[4:5]
	v_pk_mul_f32 v[10:11], v[10:11], v[144:145]
	v_pk_add_f32 v[12:13], v[210:211], v[6:7]
	v_pk_fma_f32 v[16:17], v[10:11], v[12:13], v[178:179]
	v_cvt_pk_bf16_f32 v32, v14, v15
	v_cvt_pk_bf16_f32 v33, v16, v17
	global_store_dwordx2 v2, v[32:33], s[26:27] offset:1536
	v_pk_mul_f32 v[10:11], v[50:51], v[4:5]
	v_pk_mul_f32 v[10:11], v[10:11], v[146:147]
	v_pk_add_f32 v[12:13], v[212:213], v[6:7]
	v_pk_fma_f32 v[14:15], v[10:11], v[12:13], v[180:181]
	v_pk_mul_f32 v[10:11], v[52:53], v[4:5]
	v_pk_mul_f32 v[10:11], v[10:11], v[148:149]
	v_pk_add_f32 v[12:13], v[214:215], v[6:7]
	v_pk_fma_f32 v[16:17], v[10:11], v[12:13], v[182:183]
	v_cvt_pk_bf16_f32 v26, v14, v15
	v_cvt_pk_bf16_f32 v27, v16, v17
	global_store_dwordx2 v2, v[26:27], s[26:27] offset:2048
	v_pk_mul_f32 v[10:11], v[54:55], v[4:5]
	v_pk_mul_f32 v[10:11], v[10:11], v[150:151]
	v_pk_add_f32 v[12:13], v[216:217], v[6:7]
	v_pk_fma_f32 v[14:15], v[10:11], v[12:13], v[184:185]
	v_pk_mul_f32 v[10:11], v[56:57], v[4:5]
	v_pk_mul_f32 v[10:11], v[10:11], v[152:153]
	v_pk_add_f32 v[12:13], v[218:219], v[6:7]
	v_pk_fma_f32 v[16:17], v[10:11], v[12:13], v[186:187]
	v_cvt_pk_bf16_f32 v28, v14, v15
	v_cvt_pk_bf16_f32 v29, v16, v17
	global_store_dwordx2 v2, v[28:29], s[26:27] offset:2560
	v_pk_mul_f32 v[10:11], v[58:59], v[4:5]
	v_pk_mul_f32 v[10:11], v[10:11], v[156:157]
	v_pk_add_f32 v[12:13], v[220:221], v[6:7]
	v_pk_fma_f32 v[14:15], v[10:11], v[12:13], v[188:189]
	v_pk_mul_f32 v[10:11], v[60:61], v[4:5]
	v_pk_mul_f32 v[10:11], v[10:11], v[158:159]
	v_pk_add_f32 v[12:13], v[222:223], v[6:7]
	v_pk_fma_f32 v[16:17], v[10:11], v[12:13], v[190:191]
	v_cvt_pk_bf16_f32 v30, v14, v15
	v_cvt_pk_bf16_f32 v31, v16, v17
	global_store_dwordx2 v2, v[30:31], s[26:27] offset:3072
	v_pk_mul_f32 v[10:11], v[62:63], v[4:5]
	v_pk_mul_f32 v[10:11], v[10:11], v[160:161]
	v_pk_add_f32 v[12:13], v[224:225], v[6:7]
	v_pk_fma_f32 v[14:15], v[10:11], v[12:13], v[192:193]
	v_pk_mul_f32 v[10:11], v[64:65], v[4:5]
	v_pk_mul_f32 v[10:11], v[10:11], v[162:163]
	v_pk_add_f32 v[12:13], v[226:227], v[6:7]
	v_pk_fma_f32 v[16:17], v[10:11], v[12:13], v[194:195]
	v_cvt_pk_bf16_f32 v32, v14, v15
	v_cvt_pk_bf16_f32 v33, v16, v17
	global_store_dwordx2 v2, v[32:33], s[26:27] offset:3584
	s_mov_b32 s16, 4
	s_add_u32 s17, s16, 0
	s_mul_i32 s17, s17, 49152
	s_add_u32 s17, s17, 0x10404000
	s_add_u32 s28, s90, s17
	s_addc_u32 s29, s91, 0
	s_add_u32 s17, s16, 0
	s_mul_i32 s17, s17, 49152
	s_add_u32 s17, s17, 0x10406000
	s_add_u32 s30, s90, s17
	s_addc_u32 s31, s91, 0
	s_add_u32 s32, s30, 0x2000
	s_addc_u32 s33, s31, 0
	s_add_u32 s18, s0, 0x1000
	s_addc_u32 s19, s1, 0
	global_load_dwordx4 v[130:133], v1, s[0:1]
	global_load_dwordx4 v[134:137], v1, s[0:1] offset:1024
	global_load_dwordx4 v[138:141], v1, s[0:1] offset:2048
	global_load_dwordx4 v[142:145], v1, s[0:1] offset:3072
	global_load_dwordx4 v[146:149], v1, s[18:19]
	global_load_dwordx4 v[150:153], v1, s[18:19] offset:1024
	global_load_dwordx4 v[156:159], v1, s[18:19] offset:2048
	global_load_dwordx4 v[160:163], v1, s[18:19] offset:3072
	s_add_u32 s18, s28, 0x1000
	s_addc_u32 s19, s29, 0
	global_load_dwordx4 v[164:167], v1, s[28:29]
	global_load_dwordx4 v[168:171], v1, s[28:29] offset:1024
	global_load_dwordx4 v[172:175], v1, s[28:29] offset:2048
	global_load_dwordx4 v[176:179], v1, s[28:29] offset:3072
	global_load_dwordx4 v[180:183], v1, s[18:19]
	global_load_dwordx4 v[184:187], v1, s[18:19] offset:1024
	global_load_dwordx4 v[188:191], v1, s[18:19] offset:2048
	global_load_dwordx4 v[192:195], v1, s[18:19] offset:3072
	s_add_u32 s12, s10, 4096
	s_lshl_b32 s13, s12, 13
	s_lshl_b32 s14, s12, 12
	s_sub_u32 s15, s13, 0x2000000
	s_add_u32 s20, s8, s15
	s_addc_u32 s21, s9, 0
	s_add_u32 s22, s90, 0x21918000
	s_addc_u32 s23, s91, 0
	s_add_u32 s22, s22, s14
	s_addc_u32 s23, s23, 0
	global_load_dwordx2 v[98:99], v2, s[22:23] nt
	global_load_dwordx2 v[100:101], v2, s[22:23] offset:512 nt
	global_load_dwordx2 v[102:103], v2, s[22:23] offset:1024 nt
	global_load_dwordx2 v[104:105], v2, s[22:23] offset:1536 nt
	global_load_dwordx2 v[106:107], v2, s[22:23] offset:2048 nt
	global_load_dwordx2 v[108:109], v2, s[22:23] offset:2560 nt
	global_load_dwordx2 v[110:111], v2, s[22:23] offset:3072 nt
	global_load_dwordx2 v[112:113], v2, s[22:23] offset:3584 nt
	s_add_u32 s36, s20, 0x1000
	s_addc_u32 s37, s21, 0
	global_load_dwordx4 v[34:37], v1, s[20:21] nt
	global_load_dwordx4 v[38:41], v1, s[20:21] offset:1024 nt
	global_load_dwordx4 v[42:45], v1, s[20:21] offset:2048 nt
	global_load_dwordx4 v[46:49], v1, s[20:21] offset:3072 nt
	global_load_dwordx4 v[50:53], v1, s[36:37] nt
	global_load_dwordx4 v[54:57], v1, s[36:37] offset:1024 nt
	global_load_dwordx4 v[58:61], v1, s[36:37] offset:2048 nt
	global_load_dwordx4 v[62:65], v1, s[36:37] offset:3072 nt
	s_add_u32 s12, s10, 2048
	s_lshl_b32 s13, s12, 13
	s_lshl_b32 s14, s12, 12
	s_add_u32 s24, s4, s13
	s_addc_u32 s25, s5, 0
	s_add_u32 s34, s24, 0x1000
	s_addc_u32 s35, s25, 0
	s_add_u32 s26, s90, 0x11918000
	s_addc_u32 s27, s91, 0
	s_add_u32 s26, s26, s14
	s_addc_u32 s27, s27, 0
	s_waitcnt vmcnt(63)
	v_mov_b32_e32 v8, 0
	v_lshlrev_b32_e32 v10, 16, v114
	v_and_b32_e32 v11, 0xffff0000, v114
	v_fmac_f32_e32 v8, v10, v10
	v_fmac_f32_e32 v8, v11, v11
	v_lshlrev_b32_e32 v10, 16, v115
	v_and_b32_e32 v11, 0xffff0000, v115
	v_fmac_f32_e32 v8, v10, v10
	v_fmac_f32_e32 v8, v11, v11
	v_lshlrev_b32_e32 v10, 16, v116
	v_and_b32_e32 v11, 0xffff0000, v116
	v_fmac_f32_e32 v8, v10, v10
	v_fmac_f32_e32 v8, v11, v11
	v_lshlrev_b32_e32 v10, 16, v117
	v_and_b32_e32 v11, 0xffff0000, v117
	v_fmac_f32_e32 v8, v10, v10
	v_fmac_f32_e32 v8, v11, v11
	v_lshlrev_b32_e32 v10, 16, v118
	v_and_b32_e32 v11, 0xffff0000, v118
	v_fmac_f32_e32 v8, v10, v10
	v_fmac_f32_e32 v8, v11, v11
	v_lshlrev_b32_e32 v10, 16, v119
	v_and_b32_e32 v11, 0xffff0000, v119
	v_fmac_f32_e32 v8, v10, v10
	v_fmac_f32_e32 v8, v11, v11
	v_lshlrev_b32_e32 v10, 16, v120
	v_and_b32_e32 v11, 0xffff0000, v120
	v_fmac_f32_e32 v8, v10, v10
	v_fmac_f32_e32 v8, v11, v11
	v_lshlrev_b32_e32 v10, 16, v121
	v_and_b32_e32 v11, 0xffff0000, v121
	v_fmac_f32_e32 v8, v10, v10
	v_fmac_f32_e32 v8, v11, v11
	v_lshlrev_b32_e32 v10, 16, v122
	v_and_b32_e32 v11, 0xffff0000, v122
	v_fmac_f32_e32 v8, v10, v10
	v_fmac_f32_e32 v8, v11, v11
	v_lshlrev_b32_e32 v10, 16, v123
	v_and_b32_e32 v11, 0xffff0000, v123
	v_fmac_f32_e32 v8, v10, v10
	v_fmac_f32_e32 v8, v11, v11
	v_lshlrev_b32_e32 v10, 16, v124
	v_and_b32_e32 v11, 0xffff0000, v124
	v_fmac_f32_e32 v8, v10, v10
	v_fmac_f32_e32 v8, v11, v11
	v_lshlrev_b32_e32 v10, 16, v125
	v_and_b32_e32 v11, 0xffff0000, v125
	v_fmac_f32_e32 v8, v10, v10
	v_fmac_f32_e32 v8, v11, v11
	v_lshlrev_b32_e32 v10, 16, v126
	v_and_b32_e32 v11, 0xffff0000, v126
	v_fmac_f32_e32 v8, v10, v10
	v_fmac_f32_e32 v8, v11, v11
	v_lshlrev_b32_e32 v10, 16, v127
	v_and_b32_e32 v11, 0xffff0000, v127
	v_fmac_f32_e32 v8, v10, v10
	v_fmac_f32_e32 v8, v11, v11
	v_lshlrev_b32_e32 v10, 16, v128
	v_and_b32_e32 v11, 0xffff0000, v128
	v_fmac_f32_e32 v8, v10, v10
	v_fmac_f32_e32 v8, v11, v11
	v_lshlrev_b32_e32 v10, 16, v129
	v_and_b32_e32 v11, 0xffff0000, v129
	v_fmac_f32_e32 v8, v10, v10
	v_fmac_f32_e32 v8, v11, v11
	s_nop 1
	v_add_f32_dpp v8, v8, v8 quad_perm:[1,0,3,2] row_mask:0xf bank_mask:0xf
	s_nop 1
	v_add_f32_dpp v8, v8, v8 quad_perm:[2,3,0,1] row_mask:0xf bank_mask:0xf
	s_nop 1
	v_add_f32_dpp v8, v8, v8 row_ror:4 row_mask:0xf bank_mask:0xf
	s_nop 1
	v_add_f32_dpp v8, v8, v8 row_ror:8 row_mask:0xf bank_mask:0xf
	s_nop 1
	v_readlane_b32 s42, v8, 0
	v_readlane_b32 s43, v8, 16
	v_readlane_b32 s44, v8, 32
	v_readlane_b32 s45, v8, 48
	s_nop 1
	v_mov_b32_e32 v8, s42
	v_add_f32_e32 v8, s43, v8
	v_add_f32_e32 v8, s44, v8
	v_add_f32_e32 v8, s45, v8
	v_mov_b32_e32 v4, s41
	v_fmac_f32_e32 v4, s40, v8
	v_rsq_f32_e32 v4, v4
	s_nop 0
	v_mov_b32_e32 v5, v4
	s_waitcnt vmcnt(63)
	s_waitcnt vmcnt(16)
	v_mov_b32_e32 v8, 0
	v_lshlrev_b32_e32 v10, 16, v114
	v_and_b32_e32 v11, 0xffff0000, v114
	v_pk_mul_f32 v[10:11], v[10:11], v[4:5]
	v_pk_mul_f32 v[10:11], v[10:11], v[130:131]
	v_pk_fma_f32 v[66:67], v[164:165], v[10:11], v[66:67]
	v_lshlrev_b32_e32 v10, 16, v115
	v_and_b32_e32 v11, 0xffff0000, v115
	v_pk_mul_f32 v[10:11], v[10:11], v[4:5]
	v_pk_mul_f32 v[10:11], v[10:11], v[132:133]
	v_pk_fma_f32 v[68:69], v[166:167], v[10:11], v[68:69]
	global_store_dwordx4 v1, v[66:69], s[24:25] nt
	v_fmac_f32_e32 v8, v66, v66
	v_fmac_f32_e32 v8, v67, v67
	v_fmac_f32_e32 v8, v68, v68
	v_fmac_f32_e32 v8, v69, v69
	v_lshlrev_b32_e32 v10, 16, v116
	v_and_b32_e32 v11, 0xffff0000, v116
	v_pk_mul_f32 v[10:11], v[10:11], v[4:5]
	v_pk_mul_f32 v[10:11], v[10:11], v[134:135]
	v_pk_fma_f32 v[70:71], v[168:169], v[10:11], v[70:71]
	v_lshlrev_b32_e32 v10, 16, v117
	v_and_b32_e32 v11, 0xffff0000, v117
	v_pk_mul_f32 v[10:11], v[10:11], v[4:5]
	v_pk_mul_f32 v[10:11], v[10:11], v[136:137]
	v_pk_fma_f32 v[72:73], v[170:171], v[10:11], v[72:73]
	global_store_dwordx4 v1, v[70:73], s[24:25] offset:1024 nt
	v_fmac_f32_e32 v8, v70, v70
	v_fmac_f32_e32 v8, v71, v71
	v_fmac_f32_e32 v8, v72, v72
	v_fmac_f32_e32 v8, v73, v73
	v_lshlrev_b32_e32 v10, 16, v118
	v_and_b32_e32 v11, 0xffff0000, v118
	v_pk_mul_f32 v[10:11], v[10:11], v[4:5]
	v_pk_mul_f32 v[10:11], v[10:11], v[138:139]
	v_pk_fma_f32 v[74:75], v[172:173], v[10:11], v[74:75]
	v_lshlrev_b32_e32 v10, 16, v119
	v_and_b32_e32 v11, 0xffff0000, v119
	v_pk_mul_f32 v[10:11], v[10:11], v[4:5]
	v_pk_mul_f32 v[10:11], v[10:11], v[140:141]
	v_pk_fma_f32 v[76:77], v[174:175], v[10:11], v[76:77]
	global_store_dwordx4 v1, v[74:77], s[24:25] offset:2048 nt
	v_fmac_f32_e32 v8, v74, v74
	v_fmac_f32_e32 v8, v75, v75
	v_fmac_f32_e32 v8, v76, v76
	v_fmac_f32_e32 v8, v77, v77
	v_lshlrev_b32_e32 v10, 16, v120
	v_and_b32_e32 v11, 0xffff0000, v120
	v_pk_mul_f32 v[10:11], v[10:11], v[4:5]
	v_pk_mul_f32 v[10:11], v[10:11], v[142:143]
	v_pk_fma_f32 v[78:79], v[176:177], v[10:11], v[78:79]
	v_lshlrev_b32_e32 v10, 16, v121
	v_and_b32_e32 v11, 0xffff0000, v121
	v_pk_mul_f32 v[10:11], v[10:11], v[4:5]
	v_pk_mul_f32 v[10:11], v[10:11], v[144:145]
	v_pk_fma_f32 v[80:81], v[178:179], v[10:11], v[80:81]
	global_store_dwordx4 v1, v[78:81], s[24:25] offset:3072 nt
	v_fmac_f32_e32 v8, v78, v78
	v_fmac_f32_e32 v8, v79, v79
	v_fmac_f32_e32 v8, v80, v80
	v_fmac_f32_e32 v8, v81, v81
	v_lshlrev_b32_e32 v10, 16, v122
	v_and_b32_e32 v11, 0xffff0000, v122
	v_pk_mul_f32 v[10:11], v[10:11], v[4:5]
	v_pk_mul_f32 v[10:11], v[10:11], v[146:147]
	v_pk_fma_f32 v[82:83], v[180:181], v[10:11], v[82:83]
	v_lshlrev_b32_e32 v10, 16, v123
	v_and_b32_e32 v11, 0xffff0000, v123
	v_pk_mul_f32 v[10:11], v[10:11], v[4:5]
	v_pk_mul_f32 v[10:11], v[10:11], v[148:149]
	v_pk_fma_f32 v[84:85], v[182:183], v[10:11], v[84:85]
	global_store_dwordx4 v1, v[82:85], s[34:35] nt
	v_fmac_f32_e32 v8, v82, v82
	v_fmac_f32_e32 v8, v83, v83
	v_fmac_f32_e32 v8, v84, v84
	v_fmac_f32_e32 v8, v85, v85
	v_lshlrev_b32_e32 v10, 16, v124
	v_and_b32_e32 v11, 0xffff0000, v124
	v_pk_mul_f32 v[10:11], v[10:11], v[4:5]
	v_pk_mul_f32 v[10:11], v[10:11], v[150:151]
	v_pk_fma_f32 v[86:87], v[184:185], v[10:11], v[86:87]
	v_lshlrev_b32_e32 v10, 16, v125
	v_and_b32_e32 v11, 0xffff0000, v125
	v_pk_mul_f32 v[10:11], v[10:11], v[4:5]
	v_pk_mul_f32 v[10:11], v[10:11], v[152:153]
	v_pk_fma_f32 v[88:89], v[186:187], v[10:11], v[88:89]
	global_store_dwordx4 v1, v[86:89], s[34:35] offset:1024 nt
	v_fmac_f32_e32 v8, v86, v86
	v_fmac_f32_e32 v8, v87, v87
	v_fmac_f32_e32 v8, v88, v88
	v_fmac_f32_e32 v8, v89, v89
	v_lshlrev_b32_e32 v10, 16, v126
	v_and_b32_e32 v11, 0xffff0000, v126
	v_pk_mul_f32 v[10:11], v[10:11], v[4:5]
	v_pk_mul_f32 v[10:11], v[10:11], v[156:157]
	v_pk_fma_f32 v[90:91], v[188:189], v[10:11], v[90:91]
	v_lshlrev_b32_e32 v10, 16, v127
	v_and_b32_e32 v11, 0xffff0000, v127
	v_pk_mul_f32 v[10:11], v[10:11], v[4:5]
	v_pk_mul_f32 v[10:11], v[10:11], v[158:159]
	v_pk_fma_f32 v[92:93], v[190:191], v[10:11], v[92:93]
	global_store_dwordx4 v1, v[90:93], s[34:35] offset:2048 nt
	v_fmac_f32_e32 v8, v90, v90
	v_fmac_f32_e32 v8, v91, v91
	v_fmac_f32_e32 v8, v92, v92
	v_fmac_f32_e32 v8, v93, v93
	v_lshlrev_b32_e32 v10, 16, v128
	v_and_b32_e32 v11, 0xffff0000, v128
	v_pk_mul_f32 v[10:11], v[10:11], v[4:5]
	v_pk_mul_f32 v[10:11], v[10:11], v[160:161]
	v_pk_fma_f32 v[94:95], v[192:193], v[10:11], v[94:95]
	v_lshlrev_b32_e32 v10, 16, v129
	v_and_b32_e32 v11, 0xffff0000, v129
	v_pk_mul_f32 v[10:11], v[10:11], v[4:5]
	v_pk_mul_f32 v[10:11], v[10:11], v[162:163]
	v_pk_fma_f32 v[96:97], v[194:195], v[10:11], v[96:97]
	global_store_dwordx4 v1, v[94:97], s[34:35] offset:3072 nt
	v_fmac_f32_e32 v8, v94, v94
	v_fmac_f32_e32 v8, v95, v95
	v_fmac_f32_e32 v8, v96, v96
	v_fmac_f32_e32 v8, v97, v97
	s_add_u32 s18, s2, 0x1000
	s_addc_u32 s19, s3, 0
	global_load_dwordx4 v[130:133], v1, s[2:3]
	global_load_dwordx4 v[134:137], v1, s[2:3] offset:1024
	global_load_dwordx4 v[138:141], v1, s[2:3] offset:2048
	global_load_dwordx4 v[142:145], v1, s[2:3] offset:3072
	global_load_dwordx4 v[146:149], v1, s[18:19]
	global_load_dwordx4 v[150:153], v1, s[18:19] offset:1024
	global_load_dwordx4 v[156:159], v1, s[18:19] offset:2048
	global_load_dwordx4 v[160:163], v1, s[18:19] offset:3072
	s_add_u32 s18, s30, 0x1000
	s_addc_u32 s19, s31, 0
	global_load_dwordx4 v[164:167], v1, s[30:31]
	global_load_dwordx4 v[168:171], v1, s[30:31] offset:1024
	global_load_dwordx4 v[172:175], v1, s[30:31] offset:2048
	global_load_dwordx4 v[176:179], v1, s[30:31] offset:3072
	global_load_dwordx4 v[180:183], v1, s[18:19]
	global_load_dwordx4 v[184:187], v1, s[18:19] offset:1024
	global_load_dwordx4 v[188:191], v1, s[18:19] offset:2048
	global_load_dwordx4 v[192:195], v1, s[18:19] offset:3072
	s_add_u32 s18, s32, 0x1000
	s_addc_u32 s19, s33, 0
	global_load_dwordx4 v[196:199], v1, s[32:33]
	global_load_dwordx4 v[200:203], v1, s[32:33] offset:1024
	global_load_dwordx4 v[204:207], v1, s[32:33] offset:2048
	global_load_dwordx4 v[208:211], v1, s[32:33] offset:3072
	global_load_dwordx4 v[212:215], v1, s[18:19]
	global_load_dwordx4 v[216:219], v1, s[18:19] offset:1024
	global_load_dwordx4 v[220:223], v1, s[18:19] offset:2048
	global_load_dwordx4 v[224:227], v1, s[18:19] offset:3072
	s_nop 1
	v_add_f32_dpp v8, v8, v8 quad_perm:[1,0,3,2] row_mask:0xf bank_mask:0xf
	s_nop 1
	v_add_f32_dpp v8, v8, v8 quad_perm:[2,3,0,1] row_mask:0xf bank_mask:0xf
	s_nop 1
	v_add_f32_dpp v8, v8, v8 row_ror:4 row_mask:0xf bank_mask:0xf
	s_nop 1
	v_add_f32_dpp v8, v8, v8 row_ror:8 row_mask:0xf bank_mask:0xf
	s_nop 1
	v_readlane_b32 s42, v8, 0
	v_readlane_b32 s43, v8, 16
	v_readlane_b32 s44, v8, 32
	v_readlane_b32 s45, v8, 48
	s_nop 1
	v_mov_b32_e32 v8, s42
	v_add_f32_e32 v8, s43, v8
	v_add_f32_e32 v8, s44, v8
	v_add_f32_e32 v8, s45, v8
	v_mov_b32_e32 v4, s41
	v_fmac_f32_e32 v4, s40, v8
	v_rsq_f32_e32 v4, v4
	s_nop 0
	v_mov_b32_e32 v5, v4
	s_waitcnt vmcnt(0)
	v_pk_mul_f32 v[10:11], v[66:67], v[4:5]
	v_pk_mul_f32 v[10:11], v[10:11], v[130:131]
	v_pk_add_f32 v[12:13], v[196:197], v[6:7]
	v_pk_fma_f32 v[14:15], v[10:11], v[12:13], v[164:165]
	v_pk_mul_f32 v[10:11], v[68:69], v[4:5]
	v_pk_mul_f32 v[10:11], v[10:11], v[132:133]
	v_pk_add_f32 v[12:13], v[198:199], v[6:7]
	v_pk_fma_f32 v[16:17], v[10:11], v[12:13], v[166:167]
	v_cvt_pk_bf16_f32 v26, v14, v15
	v_cvt_pk_bf16_f32 v27, v16, v17
	global_store_dwordx2 v2, v[26:27], s[26:27]
	v_pk_mul_f32 v[10:11], v[70:71], v[4:5]
	v_pk_mul_f32 v[10:11], v[10:11], v[134:135]
	v_pk_add_f32 v[12:13], v[200:201], v[6:7]
	v_pk_fma_f32 v[14:15], v[10:11], v[12:13], v[168:169]
	v_pk_mul_f32 v[10:11], v[72:73], v[4:5]
	v_pk_mul_f32 v[10:11], v[10:11], v[136:137]
	v_pk_add_f32 v[12:13], v[202:203], v[6:7]
	v_pk_fma_f32 v[16:17], v[10:11], v[12:13], v[170:171]
	v_cvt_pk_bf16_f32 v28, v14, v15
	v_cvt_pk_bf16_f32 v29, v16, v17
	global_store_dwordx2 v2, v[28:29], s[26:27] offset:512
	v_pk_mul_f32 v[10:11], v[74:75], v[4:5]
	v_pk_mul_f32 v[10:11], v[10:11], v[138:139]
	v_pk_add_f32 v[12:13], v[204:205], v[6:7]
	v_pk_fma_f32 v[14:15], v[10:11], v[12:13], v[172:173]
	v_pk_mul_f32 v[10:11], v[76:77], v[4:5]
	v_pk_mul_f32 v[10:11], v[10:11], v[140:141]
	v_pk_add_f32 v[12:13], v[206:207], v[6:7]
	v_pk_fma_f32 v[16:17], v[10:11], v[12:13], v[174:175]
	v_cvt_pk_bf16_f32 v30, v14, v15
	v_cvt_pk_bf16_f32 v31, v16, v17
	global_store_dwordx2 v2, v[30:31], s[26:27] offset:1024
	v_pk_mul_f32 v[10:11], v[78:79], v[4:5]
	v_pk_mul_f32 v[10:11], v[10:11], v[142:143]
	v_pk_add_f32 v[12:13], v[208:209], v[6:7]
	v_pk_fma_f32 v[14:15], v[10:11], v[12:13], v[176:177]
	v_pk_mul_f32 v[10:11], v[80:81], v[4:5]
	v_pk_mul_f32 v[10:11], v[10:11], v[144:145]
	v_pk_add_f32 v[12:13], v[210:211], v[6:7]
	v_pk_fma_f32 v[16:17], v[10:11], v[12:13], v[178:179]
	v_cvt_pk_bf16_f32 v32, v14, v15
	v_cvt_pk_bf16_f32 v33, v16, v17
	global_store_dwordx2 v2, v[32:33], s[26:27] offset:1536
	v_pk_mul_f32 v[10:11], v[82:83], v[4:5]
	v_pk_mul_f32 v[10:11], v[10:11], v[146:147]
	v_pk_add_f32 v[12:13], v[212:213], v[6:7]
	v_pk_fma_f32 v[14:15], v[10:11], v[12:13], v[180:181]
	v_pk_mul_f32 v[10:11], v[84:85], v[4:5]
	v_pk_mul_f32 v[10:11], v[10:11], v[148:149]
	v_pk_add_f32 v[12:13], v[214:215], v[6:7]
	v_pk_fma_f32 v[16:17], v[10:11], v[12:13], v[182:183]
	v_cvt_pk_bf16_f32 v26, v14, v15
	v_cvt_pk_bf16_f32 v27, v16, v17
	global_store_dwordx2 v2, v[26:27], s[26:27] offset:2048
	v_pk_mul_f32 v[10:11], v[86:87], v[4:5]
	v_pk_mul_f32 v[10:11], v[10:11], v[150:151]
	v_pk_add_f32 v[12:13], v[216:217], v[6:7]
	v_pk_fma_f32 v[14:15], v[10:11], v[12:13], v[184:185]
	v_pk_mul_f32 v[10:11], v[88:89], v[4:5]
	v_pk_mul_f32 v[10:11], v[10:11], v[152:153]
	v_pk_add_f32 v[12:13], v[218:219], v[6:7]
	v_pk_fma_f32 v[16:17], v[10:11], v[12:13], v[186:187]
	v_cvt_pk_bf16_f32 v28, v14, v15
	v_cvt_pk_bf16_f32 v29, v16, v17
	global_store_dwordx2 v2, v[28:29], s[26:27] offset:2560
	v_pk_mul_f32 v[10:11], v[90:91], v[4:5]
	v_pk_mul_f32 v[10:11], v[10:11], v[156:157]
	v_pk_add_f32 v[12:13], v[220:221], v[6:7]
	v_pk_fma_f32 v[14:15], v[10:11], v[12:13], v[188:189]
	v_pk_mul_f32 v[10:11], v[92:93], v[4:5]
	v_pk_mul_f32 v[10:11], v[10:11], v[158:159]
	v_pk_add_f32 v[12:13], v[222:223], v[6:7]
	v_pk_fma_f32 v[16:17], v[10:11], v[12:13], v[190:191]
	v_cvt_pk_bf16_f32 v30, v14, v15
	v_cvt_pk_bf16_f32 v31, v16, v17
	global_store_dwordx2 v2, v[30:31], s[26:27] offset:3072
	v_pk_mul_f32 v[10:11], v[94:95], v[4:5]
	v_pk_mul_f32 v[10:11], v[10:11], v[160:161]
	v_pk_add_f32 v[12:13], v[224:225], v[6:7]
	v_pk_fma_f32 v[14:15], v[10:11], v[12:13], v[192:193]
	v_pk_mul_f32 v[10:11], v[96:97], v[4:5]
	v_pk_mul_f32 v[10:11], v[10:11], v[162:163]
	v_pk_add_f32 v[12:13], v[226:227], v[6:7]
	v_pk_fma_f32 v[16:17], v[10:11], v[12:13], v[194:195]
	v_cvt_pk_bf16_f32 v32, v14, v15
	v_cvt_pk_bf16_f32 v33, v16, v17
	global_store_dwordx2 v2, v[32:33], s[26:27] offset:3584
	s_lshr_b32 s16, s10, 10
	s_add_u32 s17, s16, 0
	s_mul_i32 s17, s17, 49152
	s_add_u32 s17, s17, 0x10404000
	s_add_u32 s28, s90, s17
	s_addc_u32 s29, s91, 0
	s_add_u32 s17, s16, 0
	s_mul_i32 s17, s17, 49152
	s_add_u32 s17, s17, 0x10406000
	s_add_u32 s30, s90, s17
	s_addc_u32 s31, s91, 0
	s_add_u32 s32, s30, 0x2000
	s_addc_u32 s33, s31, 0
	s_add_u32 s18, s0, 0x1000
	s_addc_u32 s19, s1, 0
	global_load_dwordx4 v[130:133], v1, s[0:1]
	global_load_dwordx4 v[134:137], v1, s[0:1] offset:1024
	global_load_dwordx4 v[138:141], v1, s[0:1] offset:2048
	global_load_dwordx4 v[142:145], v1, s[0:1] offset:3072
	global_load_dwordx4 v[146:149], v1, s[18:19]
	global_load_dwordx4 v[150:153], v1, s[18:19] offset:1024
	global_load_dwordx4 v[156:159], v1, s[18:19] offset:2048
	global_load_dwordx4 v[160:163], v1, s[18:19] offset:3072
	s_add_u32 s18, s28, 0x1000
	s_addc_u32 s19, s29, 0
	global_load_dwordx4 v[164:167], v1, s[28:29]
	global_load_dwordx4 v[168:171], v1, s[28:29] offset:1024
	global_load_dwordx4 v[172:175], v1, s[28:29] offset:2048
	global_load_dwordx4 v[176:179], v1, s[28:29] offset:3072
	global_load_dwordx4 v[180:183], v1, s[18:19]
	global_load_dwordx4 v[184:187], v1, s[18:19] offset:1024
	global_load_dwordx4 v[188:191], v1, s[18:19] offset:2048
	global_load_dwordx4 v[192:195], v1, s[18:19] offset:3072
	s_add_u32 s12, s10, 6144
	s_lshl_b32 s13, s12, 13
	s_lshl_b32 s14, s12, 12
	s_sub_u32 s15, s13, 0x2000000
	s_add_u32 s20, s8, s15
	s_addc_u32 s21, s9, 0
	s_add_u32 s22, s90, 0x21918000
	s_addc_u32 s23, s91, 0
	s_add_u32 s22, s22, s14
	s_addc_u32 s23, s23, 0
	global_load_dwordx2 v[114:115], v2, s[22:23] nt
	global_load_dwordx2 v[116:117], v2, s[22:23] offset:512 nt
	global_load_dwordx2 v[118:119], v2, s[22:23] offset:1024 nt
	global_load_dwordx2 v[120:121], v2, s[22:23] offset:1536 nt
	global_load_dwordx2 v[122:123], v2, s[22:23] offset:2048 nt
	global_load_dwordx2 v[124:125], v2, s[22:23] offset:2560 nt
	global_load_dwordx2 v[126:127], v2, s[22:23] offset:3072 nt
	global_load_dwordx2 v[128:129], v2, s[22:23] offset:3584 nt
	s_add_u32 s36, s20, 0x1000
	s_addc_u32 s37, s21, 0
	global_load_dwordx4 v[66:69], v1, s[20:21] nt
	global_load_dwordx4 v[70:73], v1, s[20:21] offset:1024 nt
	global_load_dwordx4 v[74:77], v1, s[20:21] offset:2048 nt
	global_load_dwordx4 v[78:81], v1, s[20:21] offset:3072 nt
	global_load_dwordx4 v[82:85], v1, s[36:37] nt
	global_load_dwordx4 v[86:89], v1, s[36:37] offset:1024 nt
	global_load_dwordx4 v[90:93], v1, s[36:37] offset:2048 nt
	global_load_dwordx4 v[94:97], v1, s[36:37] offset:3072 nt
	s_add_u32 s12, s10, 4096
	s_lshl_b32 s13, s12, 13
	s_lshl_b32 s14, s12, 12
	s_add_u32 s24, s4, s13
	s_addc_u32 s25, s5, 0
	s_add_u32 s34, s24, 0x1000
	s_addc_u32 s35, s25, 0
	s_add_u32 s26, s90, 0x11918000
	s_addc_u32 s27, s91, 0
	s_add_u32 s26, s26, s14
	s_addc_u32 s27, s27, 0
	s_waitcnt vmcnt(63)
	v_mov_b32_e32 v8, 0
	v_lshlrev_b32_e32 v10, 16, v98
	v_and_b32_e32 v11, 0xffff0000, v98
	v_fmac_f32_e32 v8, v10, v10
	v_fmac_f32_e32 v8, v11, v11
	v_lshlrev_b32_e32 v10, 16, v99
	v_and_b32_e32 v11, 0xffff0000, v99
	v_fmac_f32_e32 v8, v10, v10
	v_fmac_f32_e32 v8, v11, v11
	v_lshlrev_b32_e32 v10, 16, v100
	v_and_b32_e32 v11, 0xffff0000, v100
	v_fmac_f32_e32 v8, v10, v10
	v_fmac_f32_e32 v8, v11, v11
	v_lshlrev_b32_e32 v10, 16, v101
	v_and_b32_e32 v11, 0xffff0000, v101
	v_fmac_f32_e32 v8, v10, v10
	v_fmac_f32_e32 v8, v11, v11
	v_lshlrev_b32_e32 v10, 16, v102
	v_and_b32_e32 v11, 0xffff0000, v102
	v_fmac_f32_e32 v8, v10, v10
	v_fmac_f32_e32 v8, v11, v11
	v_lshlrev_b32_e32 v10, 16, v103
	v_and_b32_e32 v11, 0xffff0000, v103
	v_fmac_f32_e32 v8, v10, v10
	v_fmac_f32_e32 v8, v11, v11
	v_lshlrev_b32_e32 v10, 16, v104
	v_and_b32_e32 v11, 0xffff0000, v104
	v_fmac_f32_e32 v8, v10, v10
	v_fmac_f32_e32 v8, v11, v11
	v_lshlrev_b32_e32 v10, 16, v105
	v_and_b32_e32 v11, 0xffff0000, v105
	v_fmac_f32_e32 v8, v10, v10
	v_fmac_f32_e32 v8, v11, v11
	v_lshlrev_b32_e32 v10, 16, v106
	v_and_b32_e32 v11, 0xffff0000, v106
	v_fmac_f32_e32 v8, v10, v10
	v_fmac_f32_e32 v8, v11, v11
	v_lshlrev_b32_e32 v10, 16, v107
	v_and_b32_e32 v11, 0xffff0000, v107
	v_fmac_f32_e32 v8, v10, v10
	v_fmac_f32_e32 v8, v11, v11
	v_lshlrev_b32_e32 v10, 16, v108
	v_and_b32_e32 v11, 0xffff0000, v108
	v_fmac_f32_e32 v8, v10, v10
	v_fmac_f32_e32 v8, v11, v11
	v_lshlrev_b32_e32 v10, 16, v109
	v_and_b32_e32 v11, 0xffff0000, v109
	v_fmac_f32_e32 v8, v10, v10
	v_fmac_f32_e32 v8, v11, v11
	v_lshlrev_b32_e32 v10, 16, v110
	v_and_b32_e32 v11, 0xffff0000, v110
	v_fmac_f32_e32 v8, v10, v10
	v_fmac_f32_e32 v8, v11, v11
	v_lshlrev_b32_e32 v10, 16, v111
	v_and_b32_e32 v11, 0xffff0000, v111
	v_fmac_f32_e32 v8, v10, v10
	v_fmac_f32_e32 v8, v11, v11
	v_lshlrev_b32_e32 v10, 16, v112
	v_and_b32_e32 v11, 0xffff0000, v112
	v_fmac_f32_e32 v8, v10, v10
	v_fmac_f32_e32 v8, v11, v11
	v_lshlrev_b32_e32 v10, 16, v113
	v_and_b32_e32 v11, 0xffff0000, v113
	v_fmac_f32_e32 v8, v10, v10
	v_fmac_f32_e32 v8, v11, v11
	s_nop 1
	v_add_f32_dpp v8, v8, v8 quad_perm:[1,0,3,2] row_mask:0xf bank_mask:0xf
	s_nop 1
	v_add_f32_dpp v8, v8, v8 quad_perm:[2,3,0,1] row_mask:0xf bank_mask:0xf
	s_nop 1
	v_add_f32_dpp v8, v8, v8 row_ror:4 row_mask:0xf bank_mask:0xf
	s_nop 1
	v_add_f32_dpp v8, v8, v8 row_ror:8 row_mask:0xf bank_mask:0xf
	s_nop 1
	v_readlane_b32 s42, v8, 0
	v_readlane_b32 s43, v8, 16
	v_readlane_b32 s44, v8, 32
	v_readlane_b32 s45, v8, 48
	s_nop 1
	v_mov_b32_e32 v8, s42
	v_add_f32_e32 v8, s43, v8
	v_add_f32_e32 v8, s44, v8
	v_add_f32_e32 v8, s45, v8
	v_mov_b32_e32 v4, s41
	v_fmac_f32_e32 v4, s40, v8
	v_rsq_f32_e32 v4, v4
	s_nop 0
	v_mov_b32_e32 v5, v4
	s_waitcnt vmcnt(63)
	s_waitcnt vmcnt(16)
	v_mov_b32_e32 v8, 0
	v_lshlrev_b32_e32 v10, 16, v98
	v_and_b32_e32 v11, 0xffff0000, v98
	v_pk_mul_f32 v[10:11], v[10:11], v[4:5]
	v_pk_mul_f32 v[10:11], v[10:11], v[130:131]
	v_pk_fma_f32 v[34:35], v[164:165], v[10:11], v[34:35]
	v_lshlrev_b32_e32 v10, 16, v99
	v_and_b32_e32 v11, 0xffff0000, v99
	v_pk_mul_f32 v[10:11], v[10:11], v[4:5]
	v_pk_mul_f32 v[10:11], v[10:11], v[132:133]
	v_pk_fma_f32 v[36:37], v[166:167], v[10:11], v[36:37]
	global_store_dwordx4 v1, v[34:37], s[24:25] nt
	v_fmac_f32_e32 v8, v34, v34
	v_fmac_f32_e32 v8, v35, v35
	v_fmac_f32_e32 v8, v36, v36
	v_fmac_f32_e32 v8, v37, v37
	v_lshlrev_b32_e32 v10, 16, v100
	v_and_b32_e32 v11, 0xffff0000, v100
	v_pk_mul_f32 v[10:11], v[10:11], v[4:5]
	v_pk_mul_f32 v[10:11], v[10:11], v[134:135]
	v_pk_fma_f32 v[38:39], v[168:169], v[10:11], v[38:39]
	v_lshlrev_b32_e32 v10, 16, v101
	v_and_b32_e32 v11, 0xffff0000, v101
	v_pk_mul_f32 v[10:11], v[10:11], v[4:5]
	v_pk_mul_f32 v[10:11], v[10:11], v[136:137]
	v_pk_fma_f32 v[40:41], v[170:171], v[10:11], v[40:41]
	global_store_dwordx4 v1, v[38:41], s[24:25] offset:1024 nt
	v_fmac_f32_e32 v8, v38, v38
	v_fmac_f32_e32 v8, v39, v39
	v_fmac_f32_e32 v8, v40, v40
	v_fmac_f32_e32 v8, v41, v41
	v_lshlrev_b32_e32 v10, 16, v102
	v_and_b32_e32 v11, 0xffff0000, v102
	v_pk_mul_f32 v[10:11], v[10:11], v[4:5]
	v_pk_mul_f32 v[10:11], v[10:11], v[138:139]
	v_pk_fma_f32 v[42:43], v[172:173], v[10:11], v[42:43]
	v_lshlrev_b32_e32 v10, 16, v103
	v_and_b32_e32 v11, 0xffff0000, v103
	v_pk_mul_f32 v[10:11], v[10:11], v[4:5]
	v_pk_mul_f32 v[10:11], v[10:11], v[140:141]
	v_pk_fma_f32 v[44:45], v[174:175], v[10:11], v[44:45]
	global_store_dwordx4 v1, v[42:45], s[24:25] offset:2048 nt
	v_fmac_f32_e32 v8, v42, v42
	v_fmac_f32_e32 v8, v43, v43
	v_fmac_f32_e32 v8, v44, v44
	v_fmac_f32_e32 v8, v45, v45
	v_lshlrev_b32_e32 v10, 16, v104
	v_and_b32_e32 v11, 0xffff0000, v104
	v_pk_mul_f32 v[10:11], v[10:11], v[4:5]
	v_pk_mul_f32 v[10:11], v[10:11], v[142:143]
	v_pk_fma_f32 v[46:47], v[176:177], v[10:11], v[46:47]
	v_lshlrev_b32_e32 v10, 16, v105
	v_and_b32_e32 v11, 0xffff0000, v105
	v_pk_mul_f32 v[10:11], v[10:11], v[4:5]
	v_pk_mul_f32 v[10:11], v[10:11], v[144:145]
	v_pk_fma_f32 v[48:49], v[178:179], v[10:11], v[48:49]
	global_store_dwordx4 v1, v[46:49], s[24:25] offset:3072 nt
	v_fmac_f32_e32 v8, v46, v46
	v_fmac_f32_e32 v8, v47, v47
	v_fmac_f32_e32 v8, v48, v48
	v_fmac_f32_e32 v8, v49, v49
	v_lshlrev_b32_e32 v10, 16, v106
	v_and_b32_e32 v11, 0xffff0000, v106
	v_pk_mul_f32 v[10:11], v[10:11], v[4:5]
	v_pk_mul_f32 v[10:11], v[10:11], v[146:147]
	v_pk_fma_f32 v[50:51], v[180:181], v[10:11], v[50:51]
	v_lshlrev_b32_e32 v10, 16, v107
	v_and_b32_e32 v11, 0xffff0000, v107
	v_pk_mul_f32 v[10:11], v[10:11], v[4:5]
	v_pk_mul_f32 v[10:11], v[10:11], v[148:149]
	v_pk_fma_f32 v[52:53], v[182:183], v[10:11], v[52:53]
	global_store_dwordx4 v1, v[50:53], s[34:35] nt
	v_fmac_f32_e32 v8, v50, v50
	v_fmac_f32_e32 v8, v51, v51
	v_fmac_f32_e32 v8, v52, v52
	v_fmac_f32_e32 v8, v53, v53
	v_lshlrev_b32_e32 v10, 16, v108
	v_and_b32_e32 v11, 0xffff0000, v108
	v_pk_mul_f32 v[10:11], v[10:11], v[4:5]
	v_pk_mul_f32 v[10:11], v[10:11], v[150:151]
	v_pk_fma_f32 v[54:55], v[184:185], v[10:11], v[54:55]
	v_lshlrev_b32_e32 v10, 16, v109
	v_and_b32_e32 v11, 0xffff0000, v109
	v_pk_mul_f32 v[10:11], v[10:11], v[4:5]
	v_pk_mul_f32 v[10:11], v[10:11], v[152:153]
	v_pk_fma_f32 v[56:57], v[186:187], v[10:11], v[56:57]
	global_store_dwordx4 v1, v[54:57], s[34:35] offset:1024 nt
	v_fmac_f32_e32 v8, v54, v54
	v_fmac_f32_e32 v8, v55, v55
	v_fmac_f32_e32 v8, v56, v56
	v_fmac_f32_e32 v8, v57, v57
	v_lshlrev_b32_e32 v10, 16, v110
	v_and_b32_e32 v11, 0xffff0000, v110
	v_pk_mul_f32 v[10:11], v[10:11], v[4:5]
	v_pk_mul_f32 v[10:11], v[10:11], v[156:157]
	v_pk_fma_f32 v[58:59], v[188:189], v[10:11], v[58:59]
	v_lshlrev_b32_e32 v10, 16, v111
	v_and_b32_e32 v11, 0xffff0000, v111
	v_pk_mul_f32 v[10:11], v[10:11], v[4:5]
	v_pk_mul_f32 v[10:11], v[10:11], v[158:159]
	v_pk_fma_f32 v[60:61], v[190:191], v[10:11], v[60:61]
	global_store_dwordx4 v1, v[58:61], s[34:35] offset:2048 nt
	v_fmac_f32_e32 v8, v58, v58
	v_fmac_f32_e32 v8, v59, v59
	v_fmac_f32_e32 v8, v60, v60
	v_fmac_f32_e32 v8, v61, v61
	v_lshlrev_b32_e32 v10, 16, v112
	v_and_b32_e32 v11, 0xffff0000, v112
	v_pk_mul_f32 v[10:11], v[10:11], v[4:5]
	v_pk_mul_f32 v[10:11], v[10:11], v[160:161]
	v_pk_fma_f32 v[62:63], v[192:193], v[10:11], v[62:63]
	v_lshlrev_b32_e32 v10, 16, v113
	v_and_b32_e32 v11, 0xffff0000, v113
	v_pk_mul_f32 v[10:11], v[10:11], v[4:5]
	v_pk_mul_f32 v[10:11], v[10:11], v[162:163]
	v_pk_fma_f32 v[64:65], v[194:195], v[10:11], v[64:65]
	global_store_dwordx4 v1, v[62:65], s[34:35] offset:3072 nt
	v_fmac_f32_e32 v8, v62, v62
	v_fmac_f32_e32 v8, v63, v63
	v_fmac_f32_e32 v8, v64, v64
	v_fmac_f32_e32 v8, v65, v65
	s_add_u32 s18, s2, 0x1000
	s_addc_u32 s19, s3, 0
	global_load_dwordx4 v[130:133], v1, s[2:3]
	global_load_dwordx4 v[134:137], v1, s[2:3] offset:1024
	global_load_dwordx4 v[138:141], v1, s[2:3] offset:2048
	global_load_dwordx4 v[142:145], v1, s[2:3] offset:3072
	global_load_dwordx4 v[146:149], v1, s[18:19]
	global_load_dwordx4 v[150:153], v1, s[18:19] offset:1024
	global_load_dwordx4 v[156:159], v1, s[18:19] offset:2048
	global_load_dwordx4 v[160:163], v1, s[18:19] offset:3072
	s_add_u32 s18, s30, 0x1000
	s_addc_u32 s19, s31, 0
	global_load_dwordx4 v[164:167], v1, s[30:31]
	global_load_dwordx4 v[168:171], v1, s[30:31] offset:1024
	global_load_dwordx4 v[172:175], v1, s[30:31] offset:2048
	global_load_dwordx4 v[176:179], v1, s[30:31] offset:3072
	global_load_dwordx4 v[180:183], v1, s[18:19]
	global_load_dwordx4 v[184:187], v1, s[18:19] offset:1024
	global_load_dwordx4 v[188:191], v1, s[18:19] offset:2048
	global_load_dwordx4 v[192:195], v1, s[18:19] offset:3072
	s_add_u32 s18, s32, 0x1000
	s_addc_u32 s19, s33, 0
	global_load_dwordx4 v[196:199], v1, s[32:33]
	global_load_dwordx4 v[200:203], v1, s[32:33] offset:1024
	global_load_dwordx4 v[204:207], v1, s[32:33] offset:2048
	global_load_dwordx4 v[208:211], v1, s[32:33] offset:3072
	global_load_dwordx4 v[212:215], v1, s[18:19]
	global_load_dwordx4 v[216:219], v1, s[18:19] offset:1024
	global_load_dwordx4 v[220:223], v1, s[18:19] offset:2048
	global_load_dwordx4 v[224:227], v1, s[18:19] offset:3072
	s_nop 1
	v_add_f32_dpp v8, v8, v8 quad_perm:[1,0,3,2] row_mask:0xf bank_mask:0xf
	s_nop 1
	v_add_f32_dpp v8, v8, v8 quad_perm:[2,3,0,1] row_mask:0xf bank_mask:0xf
	s_nop 1
	v_add_f32_dpp v8, v8, v8 row_ror:4 row_mask:0xf bank_mask:0xf
	s_nop 1
	v_add_f32_dpp v8, v8, v8 row_ror:8 row_mask:0xf bank_mask:0xf
	s_nop 1
	v_readlane_b32 s42, v8, 0
	v_readlane_b32 s43, v8, 16
	v_readlane_b32 s44, v8, 32
	v_readlane_b32 s45, v8, 48
	s_nop 1
	v_mov_b32_e32 v8, s42
	v_add_f32_e32 v8, s43, v8
	v_add_f32_e32 v8, s44, v8
	v_add_f32_e32 v8, s45, v8
	v_mov_b32_e32 v4, s41
	v_fmac_f32_e32 v4, s40, v8
	v_rsq_f32_e32 v4, v4
	s_nop 0
	v_mov_b32_e32 v5, v4
	s_waitcnt vmcnt(0)
	v_pk_mul_f32 v[10:11], v[34:35], v[4:5]
	v_pk_mul_f32 v[10:11], v[10:11], v[130:131]
	v_pk_add_f32 v[12:13], v[196:197], v[6:7]
	v_pk_fma_f32 v[14:15], v[10:11], v[12:13], v[164:165]
	v_pk_mul_f32 v[10:11], v[36:37], v[4:5]
	v_pk_mul_f32 v[10:11], v[10:11], v[132:133]
	v_pk_add_f32 v[12:13], v[198:199], v[6:7]
	v_pk_fma_f32 v[16:17], v[10:11], v[12:13], v[166:167]
	v_cvt_pk_bf16_f32 v26, v14, v15
	v_cvt_pk_bf16_f32 v27, v16, v17
	global_store_dwordx2 v2, v[26:27], s[26:27]
	v_pk_mul_f32 v[10:11], v[38:39], v[4:5]
	v_pk_mul_f32 v[10:11], v[10:11], v[134:135]
	v_pk_add_f32 v[12:13], v[200:201], v[6:7]
	v_pk_fma_f32 v[14:15], v[10:11], v[12:13], v[168:169]
	v_pk_mul_f32 v[10:11], v[40:41], v[4:5]
	v_pk_mul_f32 v[10:11], v[10:11], v[136:137]
	v_pk_add_f32 v[12:13], v[202:203], v[6:7]
	v_pk_fma_f32 v[16:17], v[10:11], v[12:13], v[170:171]
	v_cvt_pk_bf16_f32 v28, v14, v15
	v_cvt_pk_bf16_f32 v29, v16, v17
	global_store_dwordx2 v2, v[28:29], s[26:27] offset:512
	v_pk_mul_f32 v[10:11], v[42:43], v[4:5]
	v_pk_mul_f32 v[10:11], v[10:11], v[138:139]
	v_pk_add_f32 v[12:13], v[204:205], v[6:7]
	v_pk_fma_f32 v[14:15], v[10:11], v[12:13], v[172:173]
	v_pk_mul_f32 v[10:11], v[44:45], v[4:5]
	v_pk_mul_f32 v[10:11], v[10:11], v[140:141]
	v_pk_add_f32 v[12:13], v[206:207], v[6:7]
	v_pk_fma_f32 v[16:17], v[10:11], v[12:13], v[174:175]
	v_cvt_pk_bf16_f32 v30, v14, v15
	v_cvt_pk_bf16_f32 v31, v16, v17
	global_store_dwordx2 v2, v[30:31], s[26:27] offset:1024
	v_pk_mul_f32 v[10:11], v[46:47], v[4:5]
	v_pk_mul_f32 v[10:11], v[10:11], v[142:143]
	v_pk_add_f32 v[12:13], v[208:209], v[6:7]
	v_pk_fma_f32 v[14:15], v[10:11], v[12:13], v[176:177]
	v_pk_mul_f32 v[10:11], v[48:49], v[4:5]
	v_pk_mul_f32 v[10:11], v[10:11], v[144:145]
	v_pk_add_f32 v[12:13], v[210:211], v[6:7]
	v_pk_fma_f32 v[16:17], v[10:11], v[12:13], v[178:179]
	v_cvt_pk_bf16_f32 v32, v14, v15
	v_cvt_pk_bf16_f32 v33, v16, v17
	global_store_dwordx2 v2, v[32:33], s[26:27] offset:1536
	v_pk_mul_f32 v[10:11], v[50:51], v[4:5]
	v_pk_mul_f32 v[10:11], v[10:11], v[146:147]
	v_pk_add_f32 v[12:13], v[212:213], v[6:7]
	v_pk_fma_f32 v[14:15], v[10:11], v[12:13], v[180:181]
	v_pk_mul_f32 v[10:11], v[52:53], v[4:5]
	v_pk_mul_f32 v[10:11], v[10:11], v[148:149]
	v_pk_add_f32 v[12:13], v[214:215], v[6:7]
	v_pk_fma_f32 v[16:17], v[10:11], v[12:13], v[182:183]
	v_cvt_pk_bf16_f32 v26, v14, v15
	v_cvt_pk_bf16_f32 v27, v16, v17
	global_store_dwordx2 v2, v[26:27], s[26:27] offset:2048
	v_pk_mul_f32 v[10:11], v[54:55], v[4:5]
	v_pk_mul_f32 v[10:11], v[10:11], v[150:151]
	v_pk_add_f32 v[12:13], v[216:217], v[6:7]
	v_pk_fma_f32 v[14:15], v[10:11], v[12:13], v[184:185]
	v_pk_mul_f32 v[10:11], v[56:57], v[4:5]
	v_pk_mul_f32 v[10:11], v[10:11], v[152:153]
	v_pk_add_f32 v[12:13], v[218:219], v[6:7]
	v_pk_fma_f32 v[16:17], v[10:11], v[12:13], v[186:187]
	v_cvt_pk_bf16_f32 v28, v14, v15
	v_cvt_pk_bf16_f32 v29, v16, v17
	global_store_dwordx2 v2, v[28:29], s[26:27] offset:2560
	v_pk_mul_f32 v[10:11], v[58:59], v[4:5]
	v_pk_mul_f32 v[10:11], v[10:11], v[156:157]
	v_pk_add_f32 v[12:13], v[220:221], v[6:7]
	v_pk_fma_f32 v[14:15], v[10:11], v[12:13], v[188:189]
	v_pk_mul_f32 v[10:11], v[60:61], v[4:5]
	v_pk_mul_f32 v[10:11], v[10:11], v[158:159]
	v_pk_add_f32 v[12:13], v[222:223], v[6:7]
	v_pk_fma_f32 v[16:17], v[10:11], v[12:13], v[190:191]
	v_cvt_pk_bf16_f32 v30, v14, v15
	v_cvt_pk_bf16_f32 v31, v16, v17
	global_store_dwordx2 v2, v[30:31], s[26:27] offset:3072
	v_pk_mul_f32 v[10:11], v[62:63], v[4:5]
	v_pk_mul_f32 v[10:11], v[10:11], v[160:161]
	v_pk_add_f32 v[12:13], v[224:225], v[6:7]
	v_pk_fma_f32 v[14:15], v[10:11], v[12:13], v[192:193]
	v_pk_mul_f32 v[10:11], v[64:65], v[4:5]
	v_pk_mul_f32 v[10:11], v[10:11], v[162:163]
	v_pk_add_f32 v[12:13], v[226:227], v[6:7]
	v_pk_fma_f32 v[16:17], v[10:11], v[12:13], v[194:195]
	v_cvt_pk_bf16_f32 v32, v14, v15
	v_cvt_pk_bf16_f32 v33, v16, v17
	global_store_dwordx2 v2, v[32:33], s[26:27] offset:3584
	s_lshr_b32 s16, s10, 10
	s_add_u32 s16, s16, 2
	s_add_u32 s17, s16, 0
	s_mul_i32 s17, s17, 49152
	s_add_u32 s17, s17, 0x10404000
	s_add_u32 s28, s90, s17
	s_addc_u32 s29, s91, 0
	s_add_u32 s17, s16, 0
	s_mul_i32 s17, s17, 49152
	s_add_u32 s17, s17, 0x10406000
	s_add_u32 s30, s90, s17
	s_addc_u32 s31, s91, 0
	s_add_u32 s32, s30, 0x2000
	s_addc_u32 s33, s31, 0
	s_add_u32 s18, s0, 0x1000
	s_addc_u32 s19, s1, 0
	global_load_dwordx4 v[130:133], v1, s[0:1]
	global_load_dwordx4 v[134:137], v1, s[0:1] offset:1024
	global_load_dwordx4 v[138:141], v1, s[0:1] offset:2048
	global_load_dwordx4 v[142:145], v1, s[0:1] offset:3072
	global_load_dwordx4 v[146:149], v1, s[18:19]
	global_load_dwordx4 v[150:153], v1, s[18:19] offset:1024
	global_load_dwordx4 v[156:159], v1, s[18:19] offset:2048
	global_load_dwordx4 v[160:163], v1, s[18:19] offset:3072
	s_add_u32 s18, s28, 0x1000
	s_addc_u32 s19, s29, 0
	global_load_dwordx4 v[164:167], v1, s[28:29]
	global_load_dwordx4 v[168:171], v1, s[28:29] offset:1024
	global_load_dwordx4 v[172:175], v1, s[28:29] offset:2048
	global_load_dwordx4 v[176:179], v1, s[28:29] offset:3072
	global_load_dwordx4 v[180:183], v1, s[18:19]
	global_load_dwordx4 v[184:187], v1, s[18:19] offset:1024
	global_load_dwordx4 v[188:191], v1, s[18:19] offset:2048
	global_load_dwordx4 v[192:195], v1, s[18:19] offset:3072
	s_add_u32 s12, s10, 6144
	s_lshl_b32 s13, s12, 13
	s_lshl_b32 s14, s12, 12
	s_add_u32 s24, s4, s13
	s_addc_u32 s25, s5, 0
	s_add_u32 s34, s24, 0x1000
	s_addc_u32 s35, s25, 0
	s_add_u32 s26, s90, 0x11918000
	s_addc_u32 s27, s91, 0
	s_add_u32 s26, s26, s14
	s_addc_u32 s27, s27, 0
	s_waitcnt vmcnt(63)
	v_mov_b32_e32 v8, 0
	v_lshlrev_b32_e32 v10, 16, v114
	v_and_b32_e32 v11, 0xffff0000, v114
	v_fmac_f32_e32 v8, v10, v10
	v_fmac_f32_e32 v8, v11, v11
	v_lshlrev_b32_e32 v10, 16, v115
	v_and_b32_e32 v11, 0xffff0000, v115
	v_fmac_f32_e32 v8, v10, v10
	v_fmac_f32_e32 v8, v11, v11
	v_lshlrev_b32_e32 v10, 16, v116
	v_and_b32_e32 v11, 0xffff0000, v116
	v_fmac_f32_e32 v8, v10, v10
	v_fmac_f32_e32 v8, v11, v11
	v_lshlrev_b32_e32 v10, 16, v117
	v_and_b32_e32 v11, 0xffff0000, v117
	v_fmac_f32_e32 v8, v10, v10
	v_fmac_f32_e32 v8, v11, v11
	v_lshlrev_b32_e32 v10, 16, v118
	v_and_b32_e32 v11, 0xffff0000, v118
	v_fmac_f32_e32 v8, v10, v10
	v_fmac_f32_e32 v8, v11, v11
	v_lshlrev_b32_e32 v10, 16, v119
	v_and_b32_e32 v11, 0xffff0000, v119
	v_fmac_f32_e32 v8, v10, v10
	v_fmac_f32_e32 v8, v11, v11
	v_lshlrev_b32_e32 v10, 16, v120
	v_and_b32_e32 v11, 0xffff0000, v120
	v_fmac_f32_e32 v8, v10, v10
	v_fmac_f32_e32 v8, v11, v11
	v_lshlrev_b32_e32 v10, 16, v121
	v_and_b32_e32 v11, 0xffff0000, v121
	v_fmac_f32_e32 v8, v10, v10
	v_fmac_f32_e32 v8, v11, v11
	v_lshlrev_b32_e32 v10, 16, v122
	v_and_b32_e32 v11, 0xffff0000, v122
	v_fmac_f32_e32 v8, v10, v10
	v_fmac_f32_e32 v8, v11, v11
	v_lshlrev_b32_e32 v10, 16, v123
	v_and_b32_e32 v11, 0xffff0000, v123
	v_fmac_f32_e32 v8, v10, v10
	v_fmac_f32_e32 v8, v11, v11
	v_lshlrev_b32_e32 v10, 16, v124
	v_and_b32_e32 v11, 0xffff0000, v124
	v_fmac_f32_e32 v8, v10, v10
	v_fmac_f32_e32 v8, v11, v11
	v_lshlrev_b32_e32 v10, 16, v125
	v_and_b32_e32 v11, 0xffff0000, v125
	v_fmac_f32_e32 v8, v10, v10
	v_fmac_f32_e32 v8, v11, v11
	v_lshlrev_b32_e32 v10, 16, v126
	v_and_b32_e32 v11, 0xffff0000, v126
	v_fmac_f32_e32 v8, v10, v10
	v_fmac_f32_e32 v8, v11, v11
	v_lshlrev_b32_e32 v10, 16, v127
	v_and_b32_e32 v11, 0xffff0000, v127
	v_fmac_f32_e32 v8, v10, v10
	v_fmac_f32_e32 v8, v11, v11
	v_lshlrev_b32_e32 v10, 16, v128
	v_and_b32_e32 v11, 0xffff0000, v128
	v_fmac_f32_e32 v8, v10, v10
	v_fmac_f32_e32 v8, v11, v11
	v_lshlrev_b32_e32 v10, 16, v129
	v_and_b32_e32 v11, 0xffff0000, v129
	v_fmac_f32_e32 v8, v10, v10
	v_fmac_f32_e32 v8, v11, v11
	s_nop 1
	v_add_f32_dpp v8, v8, v8 quad_perm:[1,0,3,2] row_mask:0xf bank_mask:0xf
	s_nop 1
	v_add_f32_dpp v8, v8, v8 quad_perm:[2,3,0,1] row_mask:0xf bank_mask:0xf
	s_nop 1
	v_add_f32_dpp v8, v8, v8 row_ror:4 row_mask:0xf bank_mask:0xf
	s_nop 1
	v_add_f32_dpp v8, v8, v8 row_ror:8 row_mask:0xf bank_mask:0xf
	s_nop 1
	v_readlane_b32 s42, v8, 0
	v_readlane_b32 s43, v8, 16
	v_readlane_b32 s44, v8, 32
	v_readlane_b32 s45, v8, 48
	s_nop 1
	v_mov_b32_e32 v8, s42
	v_add_f32_e32 v8, s43, v8
	v_add_f32_e32 v8, s44, v8
	v_add_f32_e32 v8, s45, v8
	v_mov_b32_e32 v4, s41
	v_fmac_f32_e32 v4, s40, v8
	v_rsq_f32_e32 v4, v4
	s_nop 0
	v_mov_b32_e32 v5, v4
	s_waitcnt vmcnt(56)
	s_waitcnt vmcnt(0)
	v_mov_b32_e32 v8, 0
	v_lshlrev_b32_e32 v10, 16, v114
	v_and_b32_e32 v11, 0xffff0000, v114
	v_pk_mul_f32 v[10:11], v[10:11], v[4:5]
	v_pk_mul_f32 v[10:11], v[10:11], v[130:131]
	v_pk_fma_f32 v[66:67], v[164:165], v[10:11], v[66:67]
	v_lshlrev_b32_e32 v10, 16, v115
	v_and_b32_e32 v11, 0xffff0000, v115
	v_pk_mul_f32 v[10:11], v[10:11], v[4:5]
	v_pk_mul_f32 v[10:11], v[10:11], v[132:133]
	v_pk_fma_f32 v[68:69], v[166:167], v[10:11], v[68:69]
	global_store_dwordx4 v1, v[66:69], s[24:25] nt
	v_fmac_f32_e32 v8, v66, v66
	v_fmac_f32_e32 v8, v67, v67
	v_fmac_f32_e32 v8, v68, v68
	v_fmac_f32_e32 v8, v69, v69
	v_lshlrev_b32_e32 v10, 16, v116
	v_and_b32_e32 v11, 0xffff0000, v116
	v_pk_mul_f32 v[10:11], v[10:11], v[4:5]
	v_pk_mul_f32 v[10:11], v[10:11], v[134:135]
	v_pk_fma_f32 v[70:71], v[168:169], v[10:11], v[70:71]
	v_lshlrev_b32_e32 v10, 16, v117
	v_and_b32_e32 v11, 0xffff0000, v117
	v_pk_mul_f32 v[10:11], v[10:11], v[4:5]
	v_pk_mul_f32 v[10:11], v[10:11], v[136:137]
	v_pk_fma_f32 v[72:73], v[170:171], v[10:11], v[72:73]
	global_store_dwordx4 v1, v[70:73], s[24:25] offset:1024 nt
	v_fmac_f32_e32 v8, v70, v70
	v_fmac_f32_e32 v8, v71, v71
	v_fmac_f32_e32 v8, v72, v72
	v_fmac_f32_e32 v8, v73, v73
	v_lshlrev_b32_e32 v10, 16, v118
	v_and_b32_e32 v11, 0xffff0000, v118
	v_pk_mul_f32 v[10:11], v[10:11], v[4:5]
	v_pk_mul_f32 v[10:11], v[10:11], v[138:139]
	v_pk_fma_f32 v[74:75], v[172:173], v[10:11], v[74:75]
	v_lshlrev_b32_e32 v10, 16, v119
	v_and_b32_e32 v11, 0xffff0000, v119
	v_pk_mul_f32 v[10:11], v[10:11], v[4:5]
	v_pk_mul_f32 v[10:11], v[10:11], v[140:141]
	v_pk_fma_f32 v[76:77], v[174:175], v[10:11], v[76:77]
	global_store_dwordx4 v1, v[74:77], s[24:25] offset:2048 nt
	v_fmac_f32_e32 v8, v74, v74
	v_fmac_f32_e32 v8, v75, v75
	v_fmac_f32_e32 v8, v76, v76
	v_fmac_f32_e32 v8, v77, v77
	v_lshlrev_b32_e32 v10, 16, v120
	v_and_b32_e32 v11, 0xffff0000, v120
	v_pk_mul_f32 v[10:11], v[10:11], v[4:5]
	v_pk_mul_f32 v[10:11], v[10:11], v[142:143]
	v_pk_fma_f32 v[78:79], v[176:177], v[10:11], v[78:79]
	v_lshlrev_b32_e32 v10, 16, v121
	v_and_b32_e32 v11, 0xffff0000, v121
	v_pk_mul_f32 v[10:11], v[10:11], v[4:5]
	v_pk_mul_f32 v[10:11], v[10:11], v[144:145]
	v_pk_fma_f32 v[80:81], v[178:179], v[10:11], v[80:81]
	global_store_dwordx4 v1, v[78:81], s[24:25] offset:3072 nt
	v_fmac_f32_e32 v8, v78, v78
	v_fmac_f32_e32 v8, v79, v79
	v_fmac_f32_e32 v8, v80, v80
	v_fmac_f32_e32 v8, v81, v81
	v_lshlrev_b32_e32 v10, 16, v122
	v_and_b32_e32 v11, 0xffff0000, v122
	v_pk_mul_f32 v[10:11], v[10:11], v[4:5]
	v_pk_mul_f32 v[10:11], v[10:11], v[146:147]
	v_pk_fma_f32 v[82:83], v[180:181], v[10:11], v[82:83]
	v_lshlrev_b32_e32 v10, 16, v123
	v_and_b32_e32 v11, 0xffff0000, v123
	v_pk_mul_f32 v[10:11], v[10:11], v[4:5]
	v_pk_mul_f32 v[10:11], v[10:11], v[148:149]
	v_pk_fma_f32 v[84:85], v[182:183], v[10:11], v[84:85]
	global_store_dwordx4 v1, v[82:85], s[34:35] nt
	v_fmac_f32_e32 v8, v82, v82
	v_fmac_f32_e32 v8, v83, v83
	v_fmac_f32_e32 v8, v84, v84
	v_fmac_f32_e32 v8, v85, v85
	v_lshlrev_b32_e32 v10, 16, v124
	v_and_b32_e32 v11, 0xffff0000, v124
	v_pk_mul_f32 v[10:11], v[10:11], v[4:5]
	v_pk_mul_f32 v[10:11], v[10:11], v[150:151]
	v_pk_fma_f32 v[86:87], v[184:185], v[10:11], v[86:87]
	v_lshlrev_b32_e32 v10, 16, v125
	v_and_b32_e32 v11, 0xffff0000, v125
	v_pk_mul_f32 v[10:11], v[10:11], v[4:5]
	v_pk_mul_f32 v[10:11], v[10:11], v[152:153]
	v_pk_fma_f32 v[88:89], v[186:187], v[10:11], v[88:89]
	global_store_dwordx4 v1, v[86:89], s[34:35] offset:1024 nt
	v_fmac_f32_e32 v8, v86, v86
	v_fmac_f32_e32 v8, v87, v87
	v_fmac_f32_e32 v8, v88, v88
	v_fmac_f32_e32 v8, v89, v89
	v_lshlrev_b32_e32 v10, 16, v126
	v_and_b32_e32 v11, 0xffff0000, v126
	v_pk_mul_f32 v[10:11], v[10:11], v[4:5]
	v_pk_mul_f32 v[10:11], v[10:11], v[156:157]
	v_pk_fma_f32 v[90:91], v[188:189], v[10:11], v[90:91]
	v_lshlrev_b32_e32 v10, 16, v127
	v_and_b32_e32 v11, 0xffff0000, v127
	v_pk_mul_f32 v[10:11], v[10:11], v[4:5]
	v_pk_mul_f32 v[10:11], v[10:11], v[158:159]
	v_pk_fma_f32 v[92:93], v[190:191], v[10:11], v[92:93]
	global_store_dwordx4 v1, v[90:93], s[34:35] offset:2048 nt
	v_fmac_f32_e32 v8, v90, v90
	v_fmac_f32_e32 v8, v91, v91
	v_fmac_f32_e32 v8, v92, v92
	v_fmac_f32_e32 v8, v93, v93
	v_lshlrev_b32_e32 v10, 16, v128
	v_and_b32_e32 v11, 0xffff0000, v128
	v_pk_mul_f32 v[10:11], v[10:11], v[4:5]
	v_pk_mul_f32 v[10:11], v[10:11], v[160:161]
	v_pk_fma_f32 v[94:95], v[192:193], v[10:11], v[94:95]
	v_lshlrev_b32_e32 v10, 16, v129
	v_and_b32_e32 v11, 0xffff0000, v129
	v_pk_mul_f32 v[10:11], v[10:11], v[4:5]
	v_pk_mul_f32 v[10:11], v[10:11], v[162:163]
	v_pk_fma_f32 v[96:97], v[194:195], v[10:11], v[96:97]
	global_store_dwordx4 v1, v[94:97], s[34:35] offset:3072 nt
	v_fmac_f32_e32 v8, v94, v94
	v_fmac_f32_e32 v8, v95, v95
	v_fmac_f32_e32 v8, v96, v96
	v_fmac_f32_e32 v8, v97, v97
	s_add_u32 s18, s2, 0x1000
	s_addc_u32 s19, s3, 0
	global_load_dwordx4 v[130:133], v1, s[2:3]
	global_load_dwordx4 v[134:137], v1, s[2:3] offset:1024
	global_load_dwordx4 v[138:141], v1, s[2:3] offset:2048
	global_load_dwordx4 v[142:145], v1, s[2:3] offset:3072
	global_load_dwordx4 v[146:149], v1, s[18:19]
	global_load_dwordx4 v[150:153], v1, s[18:19] offset:1024
	global_load_dwordx4 v[156:159], v1, s[18:19] offset:2048
	global_load_dwordx4 v[160:163], v1, s[18:19] offset:3072
	s_add_u32 s18, s30, 0x1000
	s_addc_u32 s19, s31, 0
	global_load_dwordx4 v[164:167], v1, s[30:31]
	global_load_dwordx4 v[168:171], v1, s[30:31] offset:1024
	global_load_dwordx4 v[172:175], v1, s[30:31] offset:2048
	global_load_dwordx4 v[176:179], v1, s[30:31] offset:3072
	global_load_dwordx4 v[180:183], v1, s[18:19]
	global_load_dwordx4 v[184:187], v1, s[18:19] offset:1024
	global_load_dwordx4 v[188:191], v1, s[18:19] offset:2048
	global_load_dwordx4 v[192:195], v1, s[18:19] offset:3072
	s_add_u32 s18, s32, 0x1000
	s_addc_u32 s19, s33, 0
	global_load_dwordx4 v[196:199], v1, s[32:33]
	global_load_dwordx4 v[200:203], v1, s[32:33] offset:1024
	global_load_dwordx4 v[204:207], v1, s[32:33] offset:2048
	global_load_dwordx4 v[208:211], v1, s[32:33] offset:3072
	global_load_dwordx4 v[212:215], v1, s[18:19]
	global_load_dwordx4 v[216:219], v1, s[18:19] offset:1024
	global_load_dwordx4 v[220:223], v1, s[18:19] offset:2048
	global_load_dwordx4 v[224:227], v1, s[18:19] offset:3072
	s_nop 1
	v_add_f32_dpp v8, v8, v8 quad_perm:[1,0,3,2] row_mask:0xf bank_mask:0xf
	s_nop 1
	v_add_f32_dpp v8, v8, v8 quad_perm:[2,3,0,1] row_mask:0xf bank_mask:0xf
	s_nop 1
	v_add_f32_dpp v8, v8, v8 row_ror:4 row_mask:0xf bank_mask:0xf
	s_nop 1
	v_add_f32_dpp v8, v8, v8 row_ror:8 row_mask:0xf bank_mask:0xf
	s_nop 1
	v_readlane_b32 s42, v8, 0
	v_readlane_b32 s43, v8, 16
	v_readlane_b32 s44, v8, 32
	v_readlane_b32 s45, v8, 48
	s_nop 1
	v_mov_b32_e32 v8, s42
	v_add_f32_e32 v8, s43, v8
	v_add_f32_e32 v8, s44, v8
	v_add_f32_e32 v8, s45, v8
	v_mov_b32_e32 v4, s41
	v_fmac_f32_e32 v4, s40, v8
	v_rsq_f32_e32 v4, v4
	s_nop 0
	v_mov_b32_e32 v5, v4
	s_waitcnt vmcnt(0)
	v_pk_mul_f32 v[10:11], v[66:67], v[4:5]
	v_pk_mul_f32 v[10:11], v[10:11], v[130:131]
	v_pk_add_f32 v[12:13], v[196:197], v[6:7]
	v_pk_fma_f32 v[14:15], v[10:11], v[12:13], v[164:165]
	v_pk_mul_f32 v[10:11], v[68:69], v[4:5]
	v_pk_mul_f32 v[10:11], v[10:11], v[132:133]
	v_pk_add_f32 v[12:13], v[198:199], v[6:7]
	v_pk_fma_f32 v[16:17], v[10:11], v[12:13], v[166:167]
	v_cvt_pk_bf16_f32 v26, v14, v15
	v_cvt_pk_bf16_f32 v27, v16, v17
	global_store_dwordx2 v2, v[26:27], s[26:27]
	v_pk_mul_f32 v[10:11], v[70:71], v[4:5]
	v_pk_mul_f32 v[10:11], v[10:11], v[134:135]
	v_pk_add_f32 v[12:13], v[200:201], v[6:7]
	v_pk_fma_f32 v[14:15], v[10:11], v[12:13], v[168:169]
	v_pk_mul_f32 v[10:11], v[72:73], v[4:5]
	v_pk_mul_f32 v[10:11], v[10:11], v[136:137]
	v_pk_add_f32 v[12:13], v[202:203], v[6:7]
	v_pk_fma_f32 v[16:17], v[10:11], v[12:13], v[170:171]
	v_cvt_pk_bf16_f32 v28, v14, v15
	v_cvt_pk_bf16_f32 v29, v16, v17
	global_store_dwordx2 v2, v[28:29], s[26:27] offset:512
	v_pk_mul_f32 v[10:11], v[74:75], v[4:5]
	v_pk_mul_f32 v[10:11], v[10:11], v[138:139]
	v_pk_add_f32 v[12:13], v[204:205], v[6:7]
	v_pk_fma_f32 v[14:15], v[10:11], v[12:13], v[172:173]
	v_pk_mul_f32 v[10:11], v[76:77], v[4:5]
	v_pk_mul_f32 v[10:11], v[10:11], v[140:141]
	v_pk_add_f32 v[12:13], v[206:207], v[6:7]
	v_pk_fma_f32 v[16:17], v[10:11], v[12:13], v[174:175]
	v_cvt_pk_bf16_f32 v30, v14, v15
	v_cvt_pk_bf16_f32 v31, v16, v17
	global_store_dwordx2 v2, v[30:31], s[26:27] offset:1024
	v_pk_mul_f32 v[10:11], v[78:79], v[4:5]
	v_pk_mul_f32 v[10:11], v[10:11], v[142:143]
	v_pk_add_f32 v[12:13], v[208:209], v[6:7]
	v_pk_fma_f32 v[14:15], v[10:11], v[12:13], v[176:177]
	v_pk_mul_f32 v[10:11], v[80:81], v[4:5]
	v_pk_mul_f32 v[10:11], v[10:11], v[144:145]
	v_pk_add_f32 v[12:13], v[210:211], v[6:7]
	v_pk_fma_f32 v[16:17], v[10:11], v[12:13], v[178:179]
	v_cvt_pk_bf16_f32 v32, v14, v15
	v_cvt_pk_bf16_f32 v33, v16, v17
	global_store_dwordx2 v2, v[32:33], s[26:27] offset:1536
	v_pk_mul_f32 v[10:11], v[82:83], v[4:5]
	v_pk_mul_f32 v[10:11], v[10:11], v[146:147]
	v_pk_add_f32 v[12:13], v[212:213], v[6:7]
	v_pk_fma_f32 v[14:15], v[10:11], v[12:13], v[180:181]
	v_pk_mul_f32 v[10:11], v[84:85], v[4:5]
	v_pk_mul_f32 v[10:11], v[10:11], v[148:149]
	v_pk_add_f32 v[12:13], v[214:215], v[6:7]
	v_pk_fma_f32 v[16:17], v[10:11], v[12:13], v[182:183]
	v_cvt_pk_bf16_f32 v26, v14, v15
	v_cvt_pk_bf16_f32 v27, v16, v17
	global_store_dwordx2 v2, v[26:27], s[26:27] offset:2048
	v_pk_mul_f32 v[10:11], v[86:87], v[4:5]
	v_pk_mul_f32 v[10:11], v[10:11], v[150:151]
	v_pk_add_f32 v[12:13], v[216:217], v[6:7]
	v_pk_fma_f32 v[14:15], v[10:11], v[12:13], v[184:185]
	v_pk_mul_f32 v[10:11], v[88:89], v[4:5]
	v_pk_mul_f32 v[10:11], v[10:11], v[152:153]
	v_pk_add_f32 v[12:13], v[218:219], v[6:7]
	v_pk_fma_f32 v[16:17], v[10:11], v[12:13], v[186:187]
	v_cvt_pk_bf16_f32 v28, v14, v15
	v_cvt_pk_bf16_f32 v29, v16, v17
	global_store_dwordx2 v2, v[28:29], s[26:27] offset:2560
	v_pk_mul_f32 v[10:11], v[90:91], v[4:5]
	v_pk_mul_f32 v[10:11], v[10:11], v[156:157]
	v_pk_add_f32 v[12:13], v[220:221], v[6:7]
	v_pk_fma_f32 v[14:15], v[10:11], v[12:13], v[188:189]
	v_pk_mul_f32 v[10:11], v[92:93], v[4:5]
	v_pk_mul_f32 v[10:11], v[10:11], v[158:159]
	v_pk_add_f32 v[12:13], v[222:223], v[6:7]
	v_pk_fma_f32 v[16:17], v[10:11], v[12:13], v[190:191]
	v_cvt_pk_bf16_f32 v30, v14, v15
	v_cvt_pk_bf16_f32 v31, v16, v17
	global_store_dwordx2 v2, v[30:31], s[26:27] offset:3072
	v_pk_mul_f32 v[10:11], v[94:95], v[4:5]
	v_pk_mul_f32 v[10:11], v[10:11], v[160:161]
	v_pk_add_f32 v[12:13], v[224:225], v[6:7]
	v_pk_fma_f32 v[14:15], v[10:11], v[12:13], v[192:193]
	v_pk_mul_f32 v[10:11], v[96:97], v[4:5]
	v_pk_mul_f32 v[10:11], v[10:11], v[162:163]
	v_pk_add_f32 v[12:13], v[226:227], v[6:7]
	v_pk_fma_f32 v[16:17], v[10:11], v[12:13], v[194:195]
	v_cvt_pk_bf16_f32 v32, v14, v15
	v_cvt_pk_bf16_f32 v33, v16, v17
	global_store_dwordx2 v2, v[32:33], s[26:27] offset:3584
	s_waitcnt vmcnt(0)
	s_branch .LBB0_1094

.LBB0_1493:
.LBB0_1494:
	s_waitcnt vmcnt(0) lgkmcnt(0)
	s_load_dwordx2 s[0:1], s[92:93], 0x50
	s_load_dwordx2 s[2:3], s[92:93], 0x38
	s_load_dwordx2 s[4:5], s[92:93], 0xf0
	v_and_b32_e32 v2, 63, v154
	v_lshlrev_b32_e32 v1, 4, v2
	v_lshlrev_b32_e32 v2, 3, v2
	v_mov_b32_e32 v6, 1.0
	v_mov_b32_e32 v7, 1.0
	s_mov_b32 s40, 0x3a000000
	s_mov_b32 s41, 0x358637bd
	v_readfirstlane_b32 s10, v154
	s_lshr_b32 s10, s10, 6
	s_lshl_b32 s12, s96, 3
	s_add_u32 s10, s10, s12
	s_waitcnt lgkmcnt(0)
	s_add_u32 s2, s2, 0x2000
	s_addc_u32 s3, s3, 0
	s_add_u32 s12, s10, 0
	s_lshl_b32 s13, s12, 13
	s_lshl_b32 s14, s12, 12
	s_add_u32 s20, s4, s13
	s_addc_u32 s21, s5, 0
	s_add_u32 s22, s90, 0x28918000
	s_addc_u32 s23, s91, 0
	s_add_u32 s22, s22, s14
	s_addc_u32 s23, s23, 0
	global_load_dwordx2 v[98:99], v2, s[22:23] nt
	global_load_dwordx2 v[100:101], v2, s[22:23] offset:512 nt
	global_load_dwordx2 v[102:103], v2, s[22:23] offset:1024 nt
	global_load_dwordx2 v[104:105], v2, s[22:23] offset:1536 nt
	global_load_dwordx2 v[106:107], v2, s[22:23] offset:2048 nt
	global_load_dwordx2 v[108:109], v2, s[22:23] offset:2560 nt
	global_load_dwordx2 v[110:111], v2, s[22:23] offset:3072 nt
	global_load_dwordx2 v[112:113], v2, s[22:23] offset:3584 nt
	s_add_u32 s36, s20, 0x1000
	s_addc_u32 s37, s21, 0
	global_load_dwordx4 v[34:37], v1, s[20:21] nt
	global_load_dwordx4 v[38:41], v1, s[20:21] offset:1024 nt
	global_load_dwordx4 v[42:45], v1, s[20:21] offset:2048 nt
	global_load_dwordx4 v[46:49], v1, s[20:21] offset:3072 nt
	global_load_dwordx4 v[50:53], v1, s[36:37] nt
	global_load_dwordx4 v[54:57], v1, s[36:37] offset:1024 nt
	global_load_dwordx4 v[58:61], v1, s[36:37] offset:2048 nt
	global_load_dwordx4 v[62:65], v1, s[36:37] offset:3072 nt
	s_mov_b32 s16, 4
	s_add_u32 s17, s16, 0
	s_mul_i32 s17, s17, 49152
	s_add_u32 s17, s17, 0x1040a000
	s_add_u32 s28, s90, s17
	s_addc_u32 s29, s91, 0
	s_add_u32 s17, s16, 5
	s_mul_i32 s17, s17, 49152
	s_add_u32 s17, s17, 0x10400000
	s_add_u32 s30, s90, s17
	s_addc_u32 s31, s91, 0
	s_add_u32 s32, s30, 0x2000
	s_addc_u32 s33, s31, 0
	s_add_u32 s18, s0, 0x1000
	s_addc_u32 s19, s1, 0
	global_load_dwordx4 v[130:133], v1, s[0:1]
	global_load_dwordx4 v[134:137], v1, s[0:1] offset:1024
	global_load_dwordx4 v[138:141], v1, s[0:1] offset:2048
	global_load_dwordx4 v[142:145], v1, s[0:1] offset:3072
	global_load_dwordx4 v[146:149], v1, s[18:19]
	global_load_dwordx4 v[150:153], v1, s[18:19] offset:1024
	global_load_dwordx4 v[156:159], v1, s[18:19] offset:2048
	global_load_dwordx4 v[160:163], v1, s[18:19] offset:3072
	s_add_u32 s18, s28, 0x1000
	s_addc_u32 s19, s29, 0
	global_load_dwordx4 v[164:167], v1, s[28:29]
	global_load_dwordx4 v[168:171], v1, s[28:29] offset:1024
	global_load_dwordx4 v[172:175], v1, s[28:29] offset:2048
	global_load_dwordx4 v[176:179], v1, s[28:29] offset:3072
	global_load_dwordx4 v[180:183], v1, s[18:19]
	global_load_dwordx4 v[184:187], v1, s[18:19] offset:1024
	global_load_dwordx4 v[188:191], v1, s[18:19] offset:2048
	global_load_dwordx4 v[192:195], v1, s[18:19] offset:3072
	s_add_u32 s12, s10, 2048
	s_lshl_b32 s13, s12, 13
	s_lshl_b32 s14, s12, 12
	s_add_u32 s20, s4, s13
	s_addc_u32 s21, s5, 0
	s_add_u32 s22, s90, 0x28918000
	s_addc_u32 s23, s91, 0
	s_add_u32 s22, s22, s14
	s_addc_u32 s23, s23, 0
	global_load_dwordx2 v[114:115], v2, s[22:23] nt
	global_load_dwordx2 v[116:117], v2, s[22:23] offset:512 nt
	global_load_dwordx2 v[118:119], v2, s[22:23] offset:1024 nt
	global_load_dwordx2 v[120:121], v2, s[22:23] offset:1536 nt
	global_load_dwordx2 v[122:123], v2, s[22:23] offset:2048 nt
	global_load_dwordx2 v[124:125], v2, s[22:23] offset:2560 nt
	global_load_dwordx2 v[126:127], v2, s[22:23] offset:3072 nt
	global_load_dwordx2 v[128:129], v2, s[22:23] offset:3584 nt
	s_add_u32 s36, s20, 0x1000
	s_addc_u32 s37, s21, 0
	global_load_dwordx4 v[66:69], v1, s[20:21] nt
	global_load_dwordx4 v[70:73], v1, s[20:21] offset:1024 nt
	global_load_dwordx4 v[74:77], v1, s[20:21] offset:2048 nt
	global_load_dwordx4 v[78:81], v1, s[20:21] offset:3072 nt
	global_load_dwordx4 v[82:85], v1, s[36:37] nt
	global_load_dwordx4 v[86:89], v1, s[36:37] offset:1024 nt
	global_load_dwordx4 v[90:93], v1, s[36:37] offset:2048 nt
	global_load_dwordx4 v[94:97], v1, s[36:37] offset:3072 nt
	s_add_u32 s12, s10, 0
	s_lshl_b32 s13, s12, 13
	s_lshl_b32 s14, s12, 12
	s_add_u32 s24, s4, s13
	s_addc_u32 s25, s5, 0
	s_add_u32 s34, s24, 0x1000
	s_addc_u32 s35, s25, 0
	s_add_u32 s26, s90, 0x11918000
	s_addc_u32 s27, s91, 0
	s_add_u32 s26, s26, s14
	s_addc_u32 s27, s27, 0
	s_waitcnt vmcnt(40)
	v_mov_b32_e32 v8, 0
	v_lshlrev_b32_e32 v10, 16, v98
	v_and_b32_e32 v11, 0xffff0000, v98
	v_fmac_f32_e32 v8, v10, v10
	v_fmac_f32_e32 v8, v11, v11
	v_lshlrev_b32_e32 v10, 16, v99
	v_and_b32_e32 v11, 0xffff0000, v99
	v_fmac_f32_e32 v8, v10, v10
	v_fmac_f32_e32 v8, v11, v11
	v_lshlrev_b32_e32 v10, 16, v100
	v_and_b32_e32 v11, 0xffff0000, v100
	v_fmac_f32_e32 v8, v10, v10
	v_fmac_f32_e32 v8, v11, v11
	v_lshlrev_b32_e32 v10, 16, v101
	v_and_b32_e32 v11, 0xffff0000, v101
	v_fmac_f32_e32 v8, v10, v10
	v_fmac_f32_e32 v8, v11, v11
	v_lshlrev_b32_e32 v10, 16, v102
	v_and_b32_e32 v11, 0xffff0000, v102
	v_fmac_f32_e32 v8, v10, v10
	v_fmac_f32_e32 v8, v11, v11
	v_lshlrev_b32_e32 v10, 16, v103
	v_and_b32_e32 v11, 0xffff0000, v103
	v_fmac_f32_e32 v8, v10, v10
	v_fmac_f32_e32 v8, v11, v11
	v_lshlrev_b32_e32 v10, 16, v104
	v_and_b32_e32 v11, 0xffff0000, v104
	v_fmac_f32_e32 v8, v10, v10
	v_fmac_f32_e32 v8, v11, v11
	v_lshlrev_b32_e32 v10, 16, v105
	v_and_b32_e32 v11, 0xffff0000, v105
	v_fmac_f32_e32 v8, v10, v10
	v_fmac_f32_e32 v8, v11, v11
	v_lshlrev_b32_e32 v10, 16, v106
	v_and_b32_e32 v11, 0xffff0000, v106
	v_fmac_f32_e32 v8, v10, v10
	v_fmac_f32_e32 v8, v11, v11
	v_lshlrev_b32_e32 v10, 16, v107
	v_and_b32_e32 v11, 0xffff0000, v107
	v_fmac_f32_e32 v8, v10, v10
	v_fmac_f32_e32 v8, v11, v11
	v_lshlrev_b32_e32 v10, 16, v108
	v_and_b32_e32 v11, 0xffff0000, v108
	v_fmac_f32_e32 v8, v10, v10
	v_fmac_f32_e32 v8, v11, v11
	v_lshlrev_b32_e32 v10, 16, v109
	v_and_b32_e32 v11, 0xffff0000, v109
	v_fmac_f32_e32 v8, v10, v10
	v_fmac_f32_e32 v8, v11, v11
	v_lshlrev_b32_e32 v10, 16, v110
	v_and_b32_e32 v11, 0xffff0000, v110
	v_fmac_f32_e32 v8, v10, v10
	v_fmac_f32_e32 v8, v11, v11
	v_lshlrev_b32_e32 v10, 16, v111
	v_and_b32_e32 v11, 0xffff0000, v111
	v_fmac_f32_e32 v8, v10, v10
	v_fmac_f32_e32 v8, v11, v11
	v_lshlrev_b32_e32 v10, 16, v112
	v_and_b32_e32 v11, 0xffff0000, v112
	v_fmac_f32_e32 v8, v10, v10
	v_fmac_f32_e32 v8, v11, v11
	v_lshlrev_b32_e32 v10, 16, v113
	v_and_b32_e32 v11, 0xffff0000, v113
	v_fmac_f32_e32 v8, v10, v10
	v_fmac_f32_e32 v8, v11, v11
	s_nop 1
	v_add_f32_dpp v8, v8, v8 quad_perm:[1,0,3,2] row_mask:0xf bank_mask:0xf
	s_nop 1
	v_add_f32_dpp v8, v8, v8 quad_perm:[2,3,0,1] row_mask:0xf bank_mask:0xf
	s_nop 1
	v_add_f32_dpp v8, v8, v8 row_ror:4 row_mask:0xf bank_mask:0xf
	s_nop 1
	v_add_f32_dpp v8, v8, v8 row_ror:8 row_mask:0xf bank_mask:0xf
	s_nop 1
	v_readlane_b32 s42, v8, 0
	v_readlane_b32 s43, v8, 16
	v_readlane_b32 s44, v8, 32
	v_readlane_b32 s45, v8, 48
	s_nop 1
	v_mov_b32_e32 v8, s42
	v_add_f32_e32 v8, s43, v8
	v_add_f32_e32 v8, s44, v8
	v_add_f32_e32 v8, s45, v8
	v_mov_b32_e32 v4, s41
	v_fmac_f32_e32 v4, s40, v8
	v_rsq_f32_e32 v4, v4
	s_nop 0
	v_mov_b32_e32 v5, v4
	s_waitcnt vmcnt(32)
	s_waitcnt vmcnt(16)
	v_mov_b32_e32 v8, 0
	v_lshlrev_b32_e32 v10, 16, v98
	v_and_b32_e32 v11, 0xffff0000, v98
	v_pk_mul_f32 v[10:11], v[10:11], v[4:5]
	v_pk_mul_f32 v[10:11], v[10:11], v[130:131]
	v_pk_fma_f32 v[34:35], v[164:165], v[10:11], v[34:35]
	v_lshlrev_b32_e32 v10, 16, v99
	v_and_b32_e32 v11, 0xffff0000, v99
	v_pk_mul_f32 v[10:11], v[10:11], v[4:5]
	v_pk_mul_f32 v[10:11], v[10:11], v[132:133]
	v_pk_fma_f32 v[36:37], v[166:167], v[10:11], v[36:37]
	global_store_dwordx4 v1, v[34:37], s[24:25] nt
	v_fmac_f32_e32 v8, v34, v34
	v_fmac_f32_e32 v8, v35, v35
	v_fmac_f32_e32 v8, v36, v36
	v_fmac_f32_e32 v8, v37, v37
	v_lshlrev_b32_e32 v10, 16, v100
	v_and_b32_e32 v11, 0xffff0000, v100
	v_pk_mul_f32 v[10:11], v[10:11], v[4:5]
	v_pk_mul_f32 v[10:11], v[10:11], v[134:135]
	v_pk_fma_f32 v[38:39], v[168:169], v[10:11], v[38:39]
	v_lshlrev_b32_e32 v10, 16, v101
	v_and_b32_e32 v11, 0xffff0000, v101
	v_pk_mul_f32 v[10:11], v[10:11], v[4:5]
	v_pk_mul_f32 v[10:11], v[10:11], v[136:137]
	v_pk_fma_f32 v[40:41], v[170:171], v[10:11], v[40:41]
	global_store_dwordx4 v1, v[38:41], s[24:25] offset:1024 nt
	v_fmac_f32_e32 v8, v38, v38
	v_fmac_f32_e32 v8, v39, v39
	v_fmac_f32_e32 v8, v40, v40
	v_fmac_f32_e32 v8, v41, v41
	v_lshlrev_b32_e32 v10, 16, v102
	v_and_b32_e32 v11, 0xffff0000, v102
	v_pk_mul_f32 v[10:11], v[10:11], v[4:5]
	v_pk_mul_f32 v[10:11], v[10:11], v[138:139]
	v_pk_fma_f32 v[42:43], v[172:173], v[10:11], v[42:43]
	v_lshlrev_b32_e32 v10, 16, v103
	v_and_b32_e32 v11, 0xffff0000, v103
	v_pk_mul_f32 v[10:11], v[10:11], v[4:5]
	v_pk_mul_f32 v[10:11], v[10:11], v[140:141]
	v_pk_fma_f32 v[44:45], v[174:175], v[10:11], v[44:45]
	global_store_dwordx4 v1, v[42:45], s[24:25] offset:2048 nt
	v_fmac_f32_e32 v8, v42, v42
	v_fmac_f32_e32 v8, v43, v43
	v_fmac_f32_e32 v8, v44, v44
	v_fmac_f32_e32 v8, v45, v45
	v_lshlrev_b32_e32 v10, 16, v104
	v_and_b32_e32 v11, 0xffff0000, v104
	v_pk_mul_f32 v[10:11], v[10:11], v[4:5]
	v_pk_mul_f32 v[10:11], v[10:11], v[142:143]
	v_pk_fma_f32 v[46:47], v[176:177], v[10:11], v[46:47]
	v_lshlrev_b32_e32 v10, 16, v105
	v_and_b32_e32 v11, 0xffff0000, v105
	v_pk_mul_f32 v[10:11], v[10:11], v[4:5]
	v_pk_mul_f32 v[10:11], v[10:11], v[144:145]
	v_pk_fma_f32 v[48:49], v[178:179], v[10:11], v[48:49]
	global_store_dwordx4 v1, v[46:49], s[24:25] offset:3072 nt
	v_fmac_f32_e32 v8, v46, v46
	v_fmac_f32_e32 v8, v47, v47
	v_fmac_f32_e32 v8, v48, v48
	v_fmac_f32_e32 v8, v49, v49
	v_lshlrev_b32_e32 v10, 16, v106
	v_and_b32_e32 v11, 0xffff0000, v106
	v_pk_mul_f32 v[10:11], v[10:11], v[4:5]
	v_pk_mul_f32 v[10:11], v[10:11], v[146:147]
	v_pk_fma_f32 v[50:51], v[180:181], v[10:11], v[50:51]
	v_lshlrev_b32_e32 v10, 16, v107
	v_and_b32_e32 v11, 0xffff0000, v107
	v_pk_mul_f32 v[10:11], v[10:11], v[4:5]
	v_pk_mul_f32 v[10:11], v[10:11], v[148:149]
	v_pk_fma_f32 v[52:53], v[182:183], v[10:11], v[52:53]
	global_store_dwordx4 v1, v[50:53], s[34:35] nt
	v_fmac_f32_e32 v8, v50, v50
	v_fmac_f32_e32 v8, v51, v51
	v_fmac_f32_e32 v8, v52, v52
	v_fmac_f32_e32 v8, v53, v53
	v_lshlrev_b32_e32 v10, 16, v108
	v_and_b32_e32 v11, 0xffff0000, v108
	v_pk_mul_f32 v[10:11], v[10:11], v[4:5]
	v_pk_mul_f32 v[10:11], v[10:11], v[150:151]
	v_pk_fma_f32 v[54:55], v[184:185], v[10:11], v[54:55]
	v_lshlrev_b32_e32 v10, 16, v109
	v_and_b32_e32 v11, 0xffff0000, v109
	v_pk_mul_f32 v[10:11], v[10:11], v[4:5]
	v_pk_mul_f32 v[10:11], v[10:11], v[152:153]
	v_pk_fma_f32 v[56:57], v[186:187], v[10:11], v[56:57]
	global_store_dwordx4 v1, v[54:57], s[34:35] offset:1024 nt
	v_fmac_f32_e32 v8, v54, v54
	v_fmac_f32_e32 v8, v55, v55
	v_fmac_f32_e32 v8, v56, v56
	v_fmac_f32_e32 v8, v57, v57
	v_lshlrev_b32_e32 v10, 16, v110
	v_and_b32_e32 v11, 0xffff0000, v110
	v_pk_mul_f32 v[10:11], v[10:11], v[4:5]
	v_pk_mul_f32 v[10:11], v[10:11], v[156:157]
	v_pk_fma_f32 v[58:59], v[188:189], v[10:11], v[58:59]
	v_lshlrev_b32_e32 v10, 16, v111
	v_and_b32_e32 v11, 0xffff0000, v111
	v_pk_mul_f32 v[10:11], v[10:11], v[4:5]
	v_pk_mul_f32 v[10:11], v[10:11], v[158:159]
	v_pk_fma_f32 v[60:61], v[190:191], v[10:11], v[60:61]
	global_store_dwordx4 v1, v[58:61], s[34:35] offset:2048 nt
	v_fmac_f32_e32 v8, v58, v58
	v_fmac_f32_e32 v8, v59, v59
	v_fmac_f32_e32 v8, v60, v60
	v_fmac_f32_e32 v8, v61, v61
	v_lshlrev_b32_e32 v10, 16, v112
	v_and_b32_e32 v11, 0xffff0000, v112
	v_pk_mul_f32 v[10:11], v[10:11], v[4:5]
	v_pk_mul_f32 v[10:11], v[10:11], v[160:161]
	v_pk_fma_f32 v[62:63], v[192:193], v[10:11], v[62:63]
	v_lshlrev_b32_e32 v10, 16, v113
	v_and_b32_e32 v11, 0xffff0000, v113
	v_pk_mul_f32 v[10:11], v[10:11], v[4:5]
	v_pk_mul_f32 v[10:11], v[10:11], v[162:163]
	v_pk_fma_f32 v[64:65], v[194:195], v[10:11], v[64:65]
	global_store_dwordx4 v1, v[62:65], s[34:35] offset:3072 nt
	v_fmac_f32_e32 v8, v62, v62
	v_fmac_f32_e32 v8, v63, v63
	v_fmac_f32_e32 v8, v64, v64
	v_fmac_f32_e32 v8, v65, v65
	s_add_u32 s18, s2, 0x1000
	s_addc_u32 s19, s3, 0
	global_load_dwordx4 v[130:133], v1, s[2:3]
	global_load_dwordx4 v[134:137], v1, s[2:3] offset:1024
	global_load_dwordx4 v[138:141], v1, s[2:3] offset:2048
	global_load_dwordx4 v[142:145], v1, s[2:3] offset:3072
	global_load_dwordx4 v[146:149], v1, s[18:19]
	global_load_dwordx4 v[150:153], v1, s[18:19] offset:1024
	global_load_dwordx4 v[156:159], v1, s[18:19] offset:2048
	global_load_dwordx4 v[160:163], v1, s[18:19] offset:3072
	s_add_u32 s18, s30, 0x1000
	s_addc_u32 s19, s31, 0
	global_load_dwordx4 v[164:167], v1, s[30:31]
	global_load_dwordx4 v[168:171], v1, s[30:31] offset:1024
	global_load_dwordx4 v[172:175], v1, s[30:31] offset:2048
	global_load_dwordx4 v[176:179], v1, s[30:31] offset:3072
	global_load_dwordx4 v[180:183], v1, s[18:19]
	global_load_dwordx4 v[184:187], v1, s[18:19] offset:1024
	global_load_dwordx4 v[188:191], v1, s[18:19] offset:2048
	global_load_dwordx4 v[192:195], v1, s[18:19] offset:3072
	s_add_u32 s18, s32, 0x1000
	s_addc_u32 s19, s33, 0
	global_load_dwordx4 v[196:199], v1, s[32:33]
	global_load_dwordx4 v[200:203], v1, s[32:33] offset:1024
	global_load_dwordx4 v[204:207], v1, s[32:33] offset:2048
	global_load_dwordx4 v[208:211], v1, s[32:33] offset:3072
	global_load_dwordx4 v[212:215], v1, s[18:19]
	global_load_dwordx4 v[216:219], v1, s[18:19] offset:1024
	global_load_dwordx4 v[220:223], v1, s[18:19] offset:2048
	global_load_dwordx4 v[224:227], v1, s[18:19] offset:3072
	s_nop 1
	v_add_f32_dpp v8, v8, v8 quad_perm:[1,0,3,2] row_mask:0xf bank_mask:0xf
	s_nop 1
	v_add_f32_dpp v8, v8, v8 quad_perm:[2,3,0,1] row_mask:0xf bank_mask:0xf
	s_nop 1
	v_add_f32_dpp v8, v8, v8 row_ror:4 row_mask:0xf bank_mask:0xf
	s_nop 1
	v_add_f32_dpp v8, v8, v8 row_ror:8 row_mask:0xf bank_mask:0xf
	s_nop 1
	v_readlane_b32 s42, v8, 0
	v_readlane_b32 s43, v8, 16
	v_readlane_b32 s44, v8, 32
	v_readlane_b32 s45, v8, 48
	s_nop 1
	v_mov_b32_e32 v8, s42
	v_add_f32_e32 v8, s43, v8
	v_add_f32_e32 v8, s44, v8
	v_add_f32_e32 v8, s45, v8
	v_mov_b32_e32 v4, s41
	v_fmac_f32_e32 v4, s40, v8
	v_rsq_f32_e32 v4, v4
	s_nop 0
	v_mov_b32_e32 v5, v4
	s_waitcnt vmcnt(0)
	v_pk_mul_f32 v[10:11], v[34:35], v[4:5]
	v_pk_mul_f32 v[10:11], v[10:11], v[130:131]
	v_pk_add_f32 v[12:13], v[196:197], v[6:7]
	v_pk_fma_f32 v[14:15], v[10:11], v[12:13], v[164:165]
	v_pk_mul_f32 v[10:11], v[36:37], v[4:5]
	v_pk_mul_f32 v[10:11], v[10:11], v[132:133]
	v_pk_add_f32 v[12:13], v[198:199], v[6:7]
	v_pk_fma_f32 v[16:17], v[10:11], v[12:13], v[166:167]
	v_cvt_pk_bf16_f32 v26, v14, v15
	v_cvt_pk_bf16_f32 v27, v16, v17
	global_store_dwordx2 v2, v[26:27], s[26:27]
	v_pk_mul_f32 v[10:11], v[38:39], v[4:5]
	v_pk_mul_f32 v[10:11], v[10:11], v[134:135]
	v_pk_add_f32 v[12:13], v[200:201], v[6:7]
	v_pk_fma_f32 v[14:15], v[10:11], v[12:13], v[168:169]
	v_pk_mul_f32 v[10:11], v[40:41], v[4:5]
	v_pk_mul_f32 v[10:11], v[10:11], v[136:137]
	v_pk_add_f32 v[12:13], v[202:203], v[6:7]
	v_pk_fma_f32 v[16:17], v[10:11], v[12:13], v[170:171]
	v_cvt_pk_bf16_f32 v28, v14, v15
	v_cvt_pk_bf16_f32 v29, v16, v17
	global_store_dwordx2 v2, v[28:29], s[26:27] offset:512
	v_pk_mul_f32 v[10:11], v[42:43], v[4:5]
	v_pk_mul_f32 v[10:11], v[10:11], v[138:139]
	v_pk_add_f32 v[12:13], v[204:205], v[6:7]
	v_pk_fma_f32 v[14:15], v[10:11], v[12:13], v[172:173]
	v_pk_mul_f32 v[10:11], v[44:45], v[4:5]
	v_pk_mul_f32 v[10:11], v[10:11], v[140:141]
	v_pk_add_f32 v[12:13], v[206:207], v[6:7]
	v_pk_fma_f32 v[16:17], v[10:11], v[12:13], v[174:175]
	v_cvt_pk_bf16_f32 v30, v14, v15
	v_cvt_pk_bf16_f32 v31, v16, v17
	global_store_dwordx2 v2, v[30:31], s[26:27] offset:1024
	v_pk_mul_f32 v[10:11], v[46:47], v[4:5]
	v_pk_mul_f32 v[10:11], v[10:11], v[142:143]
	v_pk_add_f32 v[12:13], v[208:209], v[6:7]
	v_pk_fma_f32 v[14:15], v[10:11], v[12:13], v[176:177]
	v_pk_mul_f32 v[10:11], v[48:49], v[4:5]
	v_pk_mul_f32 v[10:11], v[10:11], v[144:145]
	v_pk_add_f32 v[12:13], v[210:211], v[6:7]
	v_pk_fma_f32 v[16:17], v[10:11], v[12:13], v[178:179]
	v_cvt_pk_bf16_f32 v32, v14, v15
	v_cvt_pk_bf16_f32 v33, v16, v17
	global_store_dwordx2 v2, v[32:33], s[26:27] offset:1536
	v_pk_mul_f32 v[10:11], v[50:51], v[4:5]
	v_pk_mul_f32 v[10:11], v[10:11], v[146:147]
	v_pk_add_f32 v[12:13], v[212:213], v[6:7]
	v_pk_fma_f32 v[14:15], v[10:11], v[12:13], v[180:181]
	v_pk_mul_f32 v[10:11], v[52:53], v[4:5]
	v_pk_mul_f32 v[10:11], v[10:11], v[148:149]
	v_pk_add_f32 v[12:13], v[214:215], v[6:7]
	v_pk_fma_f32 v[16:17], v[10:11], v[12:13], v[182:183]
	v_cvt_pk_bf16_f32 v26, v14, v15
	v_cvt_pk_bf16_f32 v27, v16, v17
	global_store_dwordx2 v2, v[26:27], s[26:27] offset:2048
	v_pk_mul_f32 v[10:11], v[54:55], v[4:5]
	v_pk_mul_f32 v[10:11], v[10:11], v[150:151]
	v_pk_add_f32 v[12:13], v[216:217], v[6:7]
	v_pk_fma_f32 v[14:15], v[10:11], v[12:13], v[184:185]
	v_pk_mul_f32 v[10:11], v[56:57], v[4:5]
	v_pk_mul_f32 v[10:11], v[10:11], v[152:153]
	v_pk_add_f32 v[12:13], v[218:219], v[6:7]
	v_pk_fma_f32 v[16:17], v[10:11], v[12:13], v[186:187]
	v_cvt_pk_bf16_f32 v28, v14, v15
	v_cvt_pk_bf16_f32 v29, v16, v17
	global_store_dwordx2 v2, v[28:29], s[26:27] offset:2560
	v_pk_mul_f32 v[10:11], v[58:59], v[4:5]
	v_pk_mul_f32 v[10:11], v[10:11], v[156:157]
	v_pk_add_f32 v[12:13], v[220:221], v[6:7]
	v_pk_fma_f32 v[14:15], v[10:11], v[12:13], v[188:189]
	v_pk_mul_f32 v[10:11], v[60:61], v[4:5]
	v_pk_mul_f32 v[10:11], v[10:11], v[158:159]
	v_pk_add_f32 v[12:13], v[222:223], v[6:7]
	v_pk_fma_f32 v[16:17], v[10:11], v[12:13], v[190:191]
	v_cvt_pk_bf16_f32 v30, v14, v15
	v_cvt_pk_bf16_f32 v31, v16, v17
	global_store_dwordx2 v2, v[30:31], s[26:27] offset:3072
	v_pk_mul_f32 v[10:11], v[62:63], v[4:5]
	v_pk_mul_f32 v[10:11], v[10:11], v[160:161]
	v_pk_add_f32 v[12:13], v[224:225], v[6:7]
	v_pk_fma_f32 v[14:15], v[10:11], v[12:13], v[192:193]
	v_pk_mul_f32 v[10:11], v[64:65], v[4:5]
	v_pk_mul_f32 v[10:11], v[10:11], v[162:163]
	v_pk_add_f32 v[12:13], v[226:227], v[6:7]
	v_pk_fma_f32 v[16:17], v[10:11], v[12:13], v[194:195]
	v_cvt_pk_bf16_f32 v32, v14, v15
	v_cvt_pk_bf16_f32 v33, v16, v17
	global_store_dwordx2 v2, v[32:33], s[26:27] offset:3584
	s_mov_b32 s16, 4
	s_add_u32 s17, s16, 0
	s_mul_i32 s17, s17, 49152
	s_add_u32 s17, s17, 0x1040a000
	s_add_u32 s28, s90, s17
	s_addc_u32 s29, s91, 0
	s_add_u32 s17, s16, 5
	s_mul_i32 s17, s17, 49152
	s_add_u32 s17, s17, 0x10400000
	s_add_u32 s30, s90, s17
	s_addc_u32 s31, s91, 0
	s_add_u32 s32, s30, 0x2000
	s_addc_u32 s33, s31, 0
	s_add_u32 s18, s0, 0x1000
	s_addc_u32 s19, s1, 0
	global_load_dwordx4 v[130:133], v1, s[0:1]
	global_load_dwordx4 v[134:137], v1, s[0:1] offset:1024
	global_load_dwordx4 v[138:141], v1, s[0:1] offset:2048
	global_load_dwordx4 v[142:145], v1, s[0:1] offset:3072
	global_load_dwordx4 v[146:149], v1, s[18:19]
	global_load_dwordx4 v[150:153], v1, s[18:19] offset:1024
	global_load_dwordx4 v[156:159], v1, s[18:19] offset:2048
	global_load_dwordx4 v[160:163], v1, s[18:19] offset:3072
	s_add_u32 s18, s28, 0x1000
	s_addc_u32 s19, s29, 0
	global_load_dwordx4 v[164:167], v1, s[28:29]
	global_load_dwordx4 v[168:171], v1, s[28:29] offset:1024
	global_load_dwordx4 v[172:175], v1, s[28:29] offset:2048
	global_load_dwordx4 v[176:179], v1, s[28:29] offset:3072
	global_load_dwordx4 v[180:183], v1, s[18:19]
	global_load_dwordx4 v[184:187], v1, s[18:19] offset:1024
	global_load_dwordx4 v[188:191], v1, s[18:19] offset:2048
	global_load_dwordx4 v[192:195], v1, s[18:19] offset:3072
	s_add_u32 s12, s10, 4096
	s_lshl_b32 s13, s12, 13
	s_lshl_b32 s14, s12, 12
	s_add_u32 s20, s4, s13
	s_addc_u32 s21, s5, 0
	s_add_u32 s22, s90, 0x28918000
	s_addc_u32 s23, s91, 0
	s_add_u32 s22, s22, s14
	s_addc_u32 s23, s23, 0
	global_load_dwordx2 v[98:99], v2, s[22:23] nt
	global_load_dwordx2 v[100:101], v2, s[22:23] offset:512 nt
	global_load_dwordx2 v[102:103], v2, s[22:23] offset:1024 nt
	global_load_dwordx2 v[104:105], v2, s[22:23] offset:1536 nt
	global_load_dwordx2 v[106:107], v2, s[22:23] offset:2048 nt
	global_load_dwordx2 v[108:109], v2, s[22:23] offset:2560 nt
	global_load_dwordx2 v[110:111], v2, s[22:23] offset:3072 nt
	global_load_dwordx2 v[112:113], v2, s[22:23] offset:3584 nt
	s_add_u32 s36, s20, 0x1000
	s_addc_u32 s37, s21, 0
	global_load_dwordx4 v[34:37], v1, s[20:21] nt
	global_load_dwordx4 v[38:41], v1, s[20:21] offset:1024 nt
	global_load_dwordx4 v[42:45], v1, s[20:21] offset:2048 nt
	global_load_dwordx4 v[46:49], v1, s[20:21] offset:3072 nt
	global_load_dwordx4 v[50:53], v1, s[36:37] nt
	global_load_dwordx4 v[54:57], v1, s[36:37] offset:1024 nt
	global_load_dwordx4 v[58:61], v1, s[36:37] offset:2048 nt
	global_load_dwordx4 v[62:65], v1, s[36:37] offset:3072 nt
	s_add_u32 s12, s10, 2048
	s_lshl_b32 s13, s12, 13
	s_lshl_b32 s14, s12, 12
	s_add_u32 s24, s4, s13
	s_addc_u32 s25, s5, 0
	s_add_u32 s34, s24, 0x1000
	s_addc_u32 s35, s25, 0
	s_add_u32 s26, s90, 0x11918000
	s_addc_u32 s27, s91, 0
	s_add_u32 s26, s26, s14
	s_addc_u32 s27, s27, 0
	s_waitcnt vmcnt(63)
	v_mov_b32_e32 v8, 0
	v_lshlrev_b32_e32 v10, 16, v114
	v_and_b32_e32 v11, 0xffff0000, v114
	v_fmac_f32_e32 v8, v10, v10
	v_fmac_f32_e32 v8, v11, v11
	v_lshlrev_b32_e32 v10, 16, v115
	v_and_b32_e32 v11, 0xffff0000, v115
	v_fmac_f32_e32 v8, v10, v10
	v_fmac_f32_e32 v8, v11, v11
	v_lshlrev_b32_e32 v10, 16, v116
	v_and_b32_e32 v11, 0xffff0000, v116
	v_fmac_f32_e32 v8, v10, v10
	v_fmac_f32_e32 v8, v11, v11
	v_lshlrev_b32_e32 v10, 16, v117
	v_and_b32_e32 v11, 0xffff0000, v117
	v_fmac_f32_e32 v8, v10, v10
	v_fmac_f32_e32 v8, v11, v11
	v_lshlrev_b32_e32 v10, 16, v118
	v_and_b32_e32 v11, 0xffff0000, v118
	v_fmac_f32_e32 v8, v10, v10
	v_fmac_f32_e32 v8, v11, v11
	v_lshlrev_b32_e32 v10, 16, v119
	v_and_b32_e32 v11, 0xffff0000, v119
	v_fmac_f32_e32 v8, v10, v10
	v_fmac_f32_e32 v8, v11, v11
	v_lshlrev_b32_e32 v10, 16, v120
	v_and_b32_e32 v11, 0xffff0000, v120
	v_fmac_f32_e32 v8, v10, v10
	v_fmac_f32_e32 v8, v11, v11
	v_lshlrev_b32_e32 v10, 16, v121
	v_and_b32_e32 v11, 0xffff0000, v121
	v_fmac_f32_e32 v8, v10, v10
	v_fmac_f32_e32 v8, v11, v11
	v_lshlrev_b32_e32 v10, 16, v122
	v_and_b32_e32 v11, 0xffff0000, v122
	v_fmac_f32_e32 v8, v10, v10
	v_fmac_f32_e32 v8, v11, v11
	v_lshlrev_b32_e32 v10, 16, v123
	v_and_b32_e32 v11, 0xffff0000, v123
	v_fmac_f32_e32 v8, v10, v10
	v_fmac_f32_e32 v8, v11, v11
	v_lshlrev_b32_e32 v10, 16, v124
	v_and_b32_e32 v11, 0xffff0000, v124
	v_fmac_f32_e32 v8, v10, v10
	v_fmac_f32_e32 v8, v11, v11
	v_lshlrev_b32_e32 v10, 16, v125
	v_and_b32_e32 v11, 0xffff0000, v125
	v_fmac_f32_e32 v8, v10, v10
	v_fmac_f32_e32 v8, v11, v11
	v_lshlrev_b32_e32 v10, 16, v126
	v_and_b32_e32 v11, 0xffff0000, v126
	v_fmac_f32_e32 v8, v10, v10
	v_fmac_f32_e32 v8, v11, v11
	v_lshlrev_b32_e32 v10, 16, v127
	v_and_b32_e32 v11, 0xffff0000, v127
	v_fmac_f32_e32 v8, v10, v10
	v_fmac_f32_e32 v8, v11, v11
	v_lshlrev_b32_e32 v10, 16, v128
	v_and_b32_e32 v11, 0xffff0000, v128
	v_fmac_f32_e32 v8, v10, v10
	v_fmac_f32_e32 v8, v11, v11
	v_lshlrev_b32_e32 v10, 16, v129
	v_and_b32_e32 v11, 0xffff0000, v129
	v_fmac_f32_e32 v8, v10, v10
	v_fmac_f32_e32 v8, v11, v11
	s_nop 1
	v_add_f32_dpp v8, v8, v8 quad_perm:[1,0,3,2] row_mask:0xf bank_mask:0xf
	s_nop 1
	v_add_f32_dpp v8, v8, v8 quad_perm:[2,3,0,1] row_mask:0xf bank_mask:0xf
	s_nop 1
	v_add_f32_dpp v8, v8, v8 row_ror:4 row_mask:0xf bank_mask:0xf
	s_nop 1
	v_add_f32_dpp v8, v8, v8 row_ror:8 row_mask:0xf bank_mask:0xf
	s_nop 1
	v_readlane_b32 s42, v8, 0
	v_readlane_b32 s43, v8, 16
	v_readlane_b32 s44, v8, 32
	v_readlane_b32 s45, v8, 48
	s_nop 1
	v_mov_b32_e32 v8, s42
	v_add_f32_e32 v8, s43, v8
	v_add_f32_e32 v8, s44, v8
	v_add_f32_e32 v8, s45, v8
	v_mov_b32_e32 v4, s41
	v_fmac_f32_e32 v4, s40, v8
	v_rsq_f32_e32 v4, v4
	s_nop 0
	v_mov_b32_e32 v5, v4
	s_waitcnt vmcnt(63)
	s_waitcnt vmcnt(16)
	v_mov_b32_e32 v8, 0
	v_lshlrev_b32_e32 v10, 16, v114
	v_and_b32_e32 v11, 0xffff0000, v114
	v_pk_mul_f32 v[10:11], v[10:11], v[4:5]
	v_pk_mul_f32 v[10:11], v[10:11], v[130:131]
	v_pk_fma_f32 v[66:67], v[164:165], v[10:11], v[66:67]
	v_lshlrev_b32_e32 v10, 16, v115
	v_and_b32_e32 v11, 0xffff0000, v115
	v_pk_mul_f32 v[10:11], v[10:11], v[4:5]
	v_pk_mul_f32 v[10:11], v[10:11], v[132:133]
	v_pk_fma_f32 v[68:69], v[166:167], v[10:11], v[68:69]
	global_store_dwordx4 v1, v[66:69], s[24:25] nt
	v_fmac_f32_e32 v8, v66, v66
	v_fmac_f32_e32 v8, v67, v67
	v_fmac_f32_e32 v8, v68, v68
	v_fmac_f32_e32 v8, v69, v69
	v_lshlrev_b32_e32 v10, 16, v116
	v_and_b32_e32 v11, 0xffff0000, v116
	v_pk_mul_f32 v[10:11], v[10:11], v[4:5]
	v_pk_mul_f32 v[10:11], v[10:11], v[134:135]
	v_pk_fma_f32 v[70:71], v[168:169], v[10:11], v[70:71]
	v_lshlrev_b32_e32 v10, 16, v117
	v_and_b32_e32 v11, 0xffff0000, v117
	v_pk_mul_f32 v[10:11], v[10:11], v[4:5]
	v_pk_mul_f32 v[10:11], v[10:11], v[136:137]
	v_pk_fma_f32 v[72:73], v[170:171], v[10:11], v[72:73]
	global_store_dwordx4 v1, v[70:73], s[24:25] offset:1024 nt
	v_fmac_f32_e32 v8, v70, v70
	v_fmac_f32_e32 v8, v71, v71
	v_fmac_f32_e32 v8, v72, v72
	v_fmac_f32_e32 v8, v73, v73
	v_lshlrev_b32_e32 v10, 16, v118
	v_and_b32_e32 v11, 0xffff0000, v118
	v_pk_mul_f32 v[10:11], v[10:11], v[4:5]
	v_pk_mul_f32 v[10:11], v[10:11], v[138:139]
	v_pk_fma_f32 v[74:75], v[172:173], v[10:11], v[74:75]
	v_lshlrev_b32_e32 v10, 16, v119
	v_and_b32_e32 v11, 0xffff0000, v119
	v_pk_mul_f32 v[10:11], v[10:11], v[4:5]
	v_pk_mul_f32 v[10:11], v[10:11], v[140:141]
	v_pk_fma_f32 v[76:77], v[174:175], v[10:11], v[76:77]
	global_store_dwordx4 v1, v[74:77], s[24:25] offset:2048 nt
	v_fmac_f32_e32 v8, v74, v74
	v_fmac_f32_e32 v8, v75, v75
	v_fmac_f32_e32 v8, v76, v76
	v_fmac_f32_e32 v8, v77, v77
	v_lshlrev_b32_e32 v10, 16, v120
	v_and_b32_e32 v11, 0xffff0000, v120
	v_pk_mul_f32 v[10:11], v[10:11], v[4:5]
	v_pk_mul_f32 v[10:11], v[10:11], v[142:143]
	v_pk_fma_f32 v[78:79], v[176:177], v[10:11], v[78:79]
	v_lshlrev_b32_e32 v10, 16, v121
	v_and_b32_e32 v11, 0xffff0000, v121
	v_pk_mul_f32 v[10:11], v[10:11], v[4:5]
	v_pk_mul_f32 v[10:11], v[10:11], v[144:145]
	v_pk_fma_f32 v[80:81], v[178:179], v[10:11], v[80:81]
	global_store_dwordx4 v1, v[78:81], s[24:25] offset:3072 nt
	v_fmac_f32_e32 v8, v78, v78
	v_fmac_f32_e32 v8, v79, v79
	v_fmac_f32_e32 v8, v80, v80
	v_fmac_f32_e32 v8, v81, v81
	v_lshlrev_b32_e32 v10, 16, v122
	v_and_b32_e32 v11, 0xffff0000, v122
	v_pk_mul_f32 v[10:11], v[10:11], v[4:5]
	v_pk_mul_f32 v[10:11], v[10:11], v[146:147]
	v_pk_fma_f32 v[82:83], v[180:181], v[10:11], v[82:83]
	v_lshlrev_b32_e32 v10, 16, v123
	v_and_b32_e32 v11, 0xffff0000, v123
	v_pk_mul_f32 v[10:11], v[10:11], v[4:5]
	v_pk_mul_f32 v[10:11], v[10:11], v[148:149]
	v_pk_fma_f32 v[84:85], v[182:183], v[10:11], v[84:85]
	global_store_dwordx4 v1, v[82:85], s[34:35] nt
	v_fmac_f32_e32 v8, v82, v82
	v_fmac_f32_e32 v8, v83, v83
	v_fmac_f32_e32 v8, v84, v84
	v_fmac_f32_e32 v8, v85, v85
	v_lshlrev_b32_e32 v10, 16, v124
	v_and_b32_e32 v11, 0xffff0000, v124
	v_pk_mul_f32 v[10:11], v[10:11], v[4:5]
	v_pk_mul_f32 v[10:11], v[10:11], v[150:151]
	v_pk_fma_f32 v[86:87], v[184:185], v[10:11], v[86:87]
	v_lshlrev_b32_e32 v10, 16, v125
	v_and_b32_e32 v11, 0xffff0000, v125
	v_pk_mul_f32 v[10:11], v[10:11], v[4:5]
	v_pk_mul_f32 v[10:11], v[10:11], v[152:153]
	v_pk_fma_f32 v[88:89], v[186:187], v[10:11], v[88:89]
	global_store_dwordx4 v1, v[86:89], s[34:35] offset:1024 nt
	v_fmac_f32_e32 v8, v86, v86
	v_fmac_f32_e32 v8, v87, v87
	v_fmac_f32_e32 v8, v88, v88
	v_fmac_f32_e32 v8, v89, v89
	v_lshlrev_b32_e32 v10, 16, v126
	v_and_b32_e32 v11, 0xffff0000, v126
	v_pk_mul_f32 v[10:11], v[10:11], v[4:5]
	v_pk_mul_f32 v[10:11], v[10:11], v[156:157]
	v_pk_fma_f32 v[90:91], v[188:189], v[10:11], v[90:91]
	v_lshlrev_b32_e32 v10, 16, v127
	v_and_b32_e32 v11, 0xffff0000, v127
	v_pk_mul_f32 v[10:11], v[10:11], v[4:5]
	v_pk_mul_f32 v[10:11], v[10:11], v[158:159]
	v_pk_fma_f32 v[92:93], v[190:191], v[10:11], v[92:93]
	global_store_dwordx4 v1, v[90:93], s[34:35] offset:2048 nt
	v_fmac_f32_e32 v8, v90, v90
	v_fmac_f32_e32 v8, v91, v91
	v_fmac_f32_e32 v8, v92, v92
	v_fmac_f32_e32 v8, v93, v93
	v_lshlrev_b32_e32 v10, 16, v128
	v_and_b32_e32 v11, 0xffff0000, v128
	v_pk_mul_f32 v[10:11], v[10:11], v[4:5]
	v_pk_mul_f32 v[10:11], v[10:11], v[160:161]
	v_pk_fma_f32 v[94:95], v[192:193], v[10:11], v[94:95]
	v_lshlrev_b32_e32 v10, 16, v129
	v_and_b32_e32 v11, 0xffff0000, v129
	v_pk_mul_f32 v[10:11], v[10:11], v[4:5]
	v_pk_mul_f32 v[10:11], v[10:11], v[162:163]
	v_pk_fma_f32 v[96:97], v[194:195], v[10:11], v[96:97]
	global_store_dwordx4 v1, v[94:97], s[34:35] offset:3072 nt
	v_fmac_f32_e32 v8, v94, v94
	v_fmac_f32_e32 v8, v95, v95
	v_fmac_f32_e32 v8, v96, v96
	v_fmac_f32_e32 v8, v97, v97
	s_add_u32 s18, s2, 0x1000
	s_addc_u32 s19, s3, 0
	global_load_dwordx4 v[130:133], v1, s[2:3]
	global_load_dwordx4 v[134:137], v1, s[2:3] offset:1024
	global_load_dwordx4 v[138:141], v1, s[2:3] offset:2048
	global_load_dwordx4 v[142:145], v1, s[2:3] offset:3072
	global_load_dwordx4 v[146:149], v1, s[18:19]
	global_load_dwordx4 v[150:153], v1, s[18:19] offset:1024
	global_load_dwordx4 v[156:159], v1, s[18:19] offset:2048
	global_load_dwordx4 v[160:163], v1, s[18:19] offset:3072
	s_add_u32 s18, s30, 0x1000
	s_addc_u32 s19, s31, 0
	global_load_dwordx4 v[164:167], v1, s[30:31]
	global_load_dwordx4 v[168:171], v1, s[30:31] offset:1024
	global_load_dwordx4 v[172:175], v1, s[30:31] offset:2048
	global_load_dwordx4 v[176:179], v1, s[30:31] offset:3072
	global_load_dwordx4 v[180:183], v1, s[18:19]
	global_load_dwordx4 v[184:187], v1, s[18:19] offset:1024
	global_load_dwordx4 v[188:191], v1, s[18:19] offset:2048
	global_load_dwordx4 v[192:195], v1, s[18:19] offset:3072
	s_add_u32 s18, s32, 0x1000
	s_addc_u32 s19, s33, 0
	global_load_dwordx4 v[196:199], v1, s[32:33]
	global_load_dwordx4 v[200:203], v1, s[32:33] offset:1024
	global_load_dwordx4 v[204:207], v1, s[32:33] offset:2048
	global_load_dwordx4 v[208:211], v1, s[32:33] offset:3072
	global_load_dwordx4 v[212:215], v1, s[18:19]
	global_load_dwordx4 v[216:219], v1, s[18:19] offset:1024
	global_load_dwordx4 v[220:223], v1, s[18:19] offset:2048
	global_load_dwordx4 v[224:227], v1, s[18:19] offset:3072
	s_nop 1
	v_add_f32_dpp v8, v8, v8 quad_perm:[1,0,3,2] row_mask:0xf bank_mask:0xf
	s_nop 1
	v_add_f32_dpp v8, v8, v8 quad_perm:[2,3,0,1] row_mask:0xf bank_mask:0xf
	s_nop 1
	v_add_f32_dpp v8, v8, v8 row_ror:4 row_mask:0xf bank_mask:0xf
	s_nop 1
	v_add_f32_dpp v8, v8, v8 row_ror:8 row_mask:0xf bank_mask:0xf
	s_nop 1
	v_readlane_b32 s42, v8, 0
	v_readlane_b32 s43, v8, 16
	v_readlane_b32 s44, v8, 32
	v_readlane_b32 s45, v8, 48
	s_nop 1
	v_mov_b32_e32 v8, s42
	v_add_f32_e32 v8, s43, v8
	v_add_f32_e32 v8, s44, v8
	v_add_f32_e32 v8, s45, v8
	v_mov_b32_e32 v4, s41
	v_fmac_f32_e32 v4, s40, v8
	v_rsq_f32_e32 v4, v4
	s_nop 0
	v_mov_b32_e32 v5, v4
	s_waitcnt vmcnt(0)
	v_pk_mul_f32 v[10:11], v[66:67], v[4:5]
	v_pk_mul_f32 v[10:11], v[10:11], v[130:131]
	v_pk_add_f32 v[12:13], v[196:197], v[6:7]
	v_pk_fma_f32 v[14:15], v[10:11], v[12:13], v[164:165]
	v_pk_mul_f32 v[10:11], v[68:69], v[4:5]
	v_pk_mul_f32 v[10:11], v[10:11], v[132:133]
	v_pk_add_f32 v[12:13], v[198:199], v[6:7]
	v_pk_fma_f32 v[16:17], v[10:11], v[12:13], v[166:167]
	v_cvt_pk_bf16_f32 v26, v14, v15
	v_cvt_pk_bf16_f32 v27, v16, v17
	global_store_dwordx2 v2, v[26:27], s[26:27]
	v_pk_mul_f32 v[10:11], v[70:71], v[4:5]
	v_pk_mul_f32 v[10:11], v[10:11], v[134:135]
	v_pk_add_f32 v[12:13], v[200:201], v[6:7]
	v_pk_fma_f32 v[14:15], v[10:11], v[12:13], v[168:169]
	v_pk_mul_f32 v[10:11], v[72:73], v[4:5]
	v_pk_mul_f32 v[10:11], v[10:11], v[136:137]
	v_pk_add_f32 v[12:13], v[202:203], v[6:7]
	v_pk_fma_f32 v[16:17], v[10:11], v[12:13], v[170:171]
	v_cvt_pk_bf16_f32 v28, v14, v15
	v_cvt_pk_bf16_f32 v29, v16, v17
	global_store_dwordx2 v2, v[28:29], s[26:27] offset:512
	v_pk_mul_f32 v[10:11], v[74:75], v[4:5]
	v_pk_mul_f32 v[10:11], v[10:11], v[138:139]
	v_pk_add_f32 v[12:13], v[204:205], v[6:7]
	v_pk_fma_f32 v[14:15], v[10:11], v[12:13], v[172:173]
	v_pk_mul_f32 v[10:11], v[76:77], v[4:5]
	v_pk_mul_f32 v[10:11], v[10:11], v[140:141]
	v_pk_add_f32 v[12:13], v[206:207], v[6:7]
	v_pk_fma_f32 v[16:17], v[10:11], v[12:13], v[174:175]
	v_cvt_pk_bf16_f32 v30, v14, v15
	v_cvt_pk_bf16_f32 v31, v16, v17
	global_store_dwordx2 v2, v[30:31], s[26:27] offset:1024
	v_pk_mul_f32 v[10:11], v[78:79], v[4:5]
	v_pk_mul_f32 v[10:11], v[10:11], v[142:143]
	v_pk_add_f32 v[12:13], v[208:209], v[6:7]
	v_pk_fma_f32 v[14:15], v[10:11], v[12:13], v[176:177]
	v_pk_mul_f32 v[10:11], v[80:81], v[4:5]
	v_pk_mul_f32 v[10:11], v[10:11], v[144:145]
	v_pk_add_f32 v[12:13], v[210:211], v[6:7]
	v_pk_fma_f32 v[16:17], v[10:11], v[12:13], v[178:179]
	v_cvt_pk_bf16_f32 v32, v14, v15
	v_cvt_pk_bf16_f32 v33, v16, v17
	global_store_dwordx2 v2, v[32:33], s[26:27] offset:1536
	v_pk_mul_f32 v[10:11], v[82:83], v[4:5]
	v_pk_mul_f32 v[10:11], v[10:11], v[146:147]
	v_pk_add_f32 v[12:13], v[212:213], v[6:7]
	v_pk_fma_f32 v[14:15], v[10:11], v[12:13], v[180:181]
	v_pk_mul_f32 v[10:11], v[84:85], v[4:5]
	v_pk_mul_f32 v[10:11], v[10:11], v[148:149]
	v_pk_add_f32 v[12:13], v[214:215], v[6:7]
	v_pk_fma_f32 v[16:17], v[10:11], v[12:13], v[182:183]
	v_cvt_pk_bf16_f32 v26, v14, v15
	v_cvt_pk_bf16_f32 v27, v16, v17
	global_store_dwordx2 v2, v[26:27], s[26:27] offset:2048
	v_pk_mul_f32 v[10:11], v[86:87], v[4:5]
	v_pk_mul_f32 v[10:11], v[10:11], v[150:151]
	v_pk_add_f32 v[12:13], v[216:217], v[6:7]
	v_pk_fma_f32 v[14:15], v[10:11], v[12:13], v[184:185]
	v_pk_mul_f32 v[10:11], v[88:89], v[4:5]
	v_pk_mul_f32 v[10:11], v[10:11], v[152:153]
	v_pk_add_f32 v[12:13], v[218:219], v[6:7]
	v_pk_fma_f32 v[16:17], v[10:11], v[12:13], v[186:187]
	v_cvt_pk_bf16_f32 v28, v14, v15
	v_cvt_pk_bf16_f32 v29, v16, v17
	global_store_dwordx2 v2, v[28:29], s[26:27] offset:2560
	v_pk_mul_f32 v[10:11], v[90:91], v[4:5]
	v_pk_mul_f32 v[10:11], v[10:11], v[156:157]
	v_pk_add_f32 v[12:13], v[220:221], v[6:7]
	v_pk_fma_f32 v[14:15], v[10:11], v[12:13], v[188:189]
	v_pk_mul_f32 v[10:11], v[92:93], v[4:5]
	v_pk_mul_f32 v[10:11], v[10:11], v[158:159]
	v_pk_add_f32 v[12:13], v[222:223], v[6:7]
	v_pk_fma_f32 v[16:17], v[10:11], v[12:13], v[190:191]
	v_cvt_pk_bf16_f32 v30, v14, v15
	v_cvt_pk_bf16_f32 v31, v16, v17
	global_store_dwordx2 v2, v[30:31], s[26:27] offset:3072
	v_pk_mul_f32 v[10:11], v[94:95], v[4:5]
	v_pk_mul_f32 v[10:11], v[10:11], v[160:161]
	v_pk_add_f32 v[12:13], v[224:225], v[6:7]
	v_pk_fma_f32 v[14:15], v[10:11], v[12:13], v[192:193]
	v_pk_mul_f32 v[10:11], v[96:97], v[4:5]
	v_pk_mul_f32 v[10:11], v[10:11], v[162:163]
	v_pk_add_f32 v[12:13], v[226:227], v[6:7]
	v_pk_fma_f32 v[16:17], v[10:11], v[12:13], v[194:195]
	v_cvt_pk_bf16_f32 v32, v14, v15
	v_cvt_pk_bf16_f32 v33, v16, v17
	global_store_dwordx2 v2, v[32:33], s[26:27] offset:3584
	s_lshr_b32 s16, s10, 10
	s_add_u32 s17, s16, 0
	s_mul_i32 s17, s17, 49152
	s_add_u32 s17, s17, 0x1040a000
	s_add_u32 s28, s90, s17
	s_addc_u32 s29, s91, 0
	s_add_u32 s17, s16, 5
	s_mul_i32 s17, s17, 49152
	s_add_u32 s17, s17, 0x10400000
	s_add_u32 s30, s90, s17
	s_addc_u32 s31, s91, 0
	s_add_u32 s32, s30, 0x2000
	s_addc_u32 s33, s31, 0
	s_add_u32 s18, s0, 0x1000
	s_addc_u32 s19, s1, 0
	global_load_dwordx4 v[130:133], v1, s[0:1]
	global_load_dwordx4 v[134:137], v1, s[0:1] offset:1024
	global_load_dwordx4 v[138:141], v1, s[0:1] offset:2048
	global_load_dwordx4 v[142:145], v1, s[0:1] offset:3072
	global_load_dwordx4 v[146:149], v1, s[18:19]
	global_load_dwordx4 v[150:153], v1, s[18:19] offset:1024
	global_load_dwordx4 v[156:159], v1, s[18:19] offset:2048
	global_load_dwordx4 v[160:163], v1, s[18:19] offset:3072
	s_add_u32 s18, s28, 0x1000
	s_addc_u32 s19, s29, 0
	global_load_dwordx4 v[164:167], v1, s[28:29]
	global_load_dwordx4 v[168:171], v1, s[28:29] offset:1024
	global_load_dwordx4 v[172:175], v1, s[28:29] offset:2048
	global_load_dwordx4 v[176:179], v1, s[28:29] offset:3072
	global_load_dwordx4 v[180:183], v1, s[18:19]
	global_load_dwordx4 v[184:187], v1, s[18:19] offset:1024
	global_load_dwordx4 v[188:191], v1, s[18:19] offset:2048
	global_load_dwordx4 v[192:195], v1, s[18:19] offset:3072
	s_add_u32 s12, s10, 6144
	s_lshl_b32 s13, s12, 13
	s_lshl_b32 s14, s12, 12
	s_add_u32 s20, s4, s13
	s_addc_u32 s21, s5, 0
	s_add_u32 s22, s90, 0x28918000
	s_addc_u32 s23, s91, 0
	s_add_u32 s22, s22, s14
	s_addc_u32 s23, s23, 0
	global_load_dwordx2 v[114:115], v2, s[22:23] nt
	global_load_dwordx2 v[116:117], v2, s[22:23] offset:512 nt
	global_load_dwordx2 v[118:119], v2, s[22:23] offset:1024 nt
	global_load_dwordx2 v[120:121], v2, s[22:23] offset:1536 nt
	global_load_dwordx2 v[122:123], v2, s[22:23] offset:2048 nt
	global_load_dwordx2 v[124:125], v2, s[22:23] offset:2560 nt
	global_load_dwordx2 v[126:127], v2, s[22:23] offset:3072 nt
	global_load_dwordx2 v[128:129], v2, s[22:23] offset:3584 nt
	s_add_u32 s36, s20, 0x1000
	s_addc_u32 s37, s21, 0
	global_load_dwordx4 v[66:69], v1, s[20:21] nt
	global_load_dwordx4 v[70:73], v1, s[20:21] offset:1024 nt
	global_load_dwordx4 v[74:77], v1, s[20:21] offset:2048 nt
	global_load_dwordx4 v[78:81], v1, s[20:21] offset:3072 nt
	global_load_dwordx4 v[82:85], v1, s[36:37] nt
	global_load_dwordx4 v[86:89], v1, s[36:37] offset:1024 nt
	global_load_dwordx4 v[90:93], v1, s[36:37] offset:2048 nt
	global_load_dwordx4 v[94:97], v1, s[36:37] offset:3072 nt
	s_add_u32 s12, s10, 4096
	s_lshl_b32 s13, s12, 13
	s_lshl_b32 s14, s12, 12
	s_add_u32 s24, s4, s13
	s_addc_u32 s25, s5, 0
	s_add_u32 s34, s24, 0x1000
	s_addc_u32 s35, s25, 0
	s_add_u32 s26, s90, 0x11918000
	s_addc_u32 s27, s91, 0
	s_add_u32 s26, s26, s14
	s_addc_u32 s27, s27, 0
	s_waitcnt vmcnt(63)
	v_mov_b32_e32 v8, 0
	v_lshlrev_b32_e32 v10, 16, v98
	v_and_b32_e32 v11, 0xffff0000, v98
	v_fmac_f32_e32 v8, v10, v10
	v_fmac_f32_e32 v8, v11, v11
	v_lshlrev_b32_e32 v10, 16, v99
	v_and_b32_e32 v11, 0xffff0000, v99
	v_fmac_f32_e32 v8, v10, v10
	v_fmac_f32_e32 v8, v11, v11
	v_lshlrev_b32_e32 v10, 16, v100
	v_and_b32_e32 v11, 0xffff0000, v100
	v_fmac_f32_e32 v8, v10, v10
	v_fmac_f32_e32 v8, v11, v11
	v_lshlrev_b32_e32 v10, 16, v101
	v_and_b32_e32 v11, 0xffff0000, v101
	v_fmac_f32_e32 v8, v10, v10
	v_fmac_f32_e32 v8, v11, v11
	v_lshlrev_b32_e32 v10, 16, v102
	v_and_b32_e32 v11, 0xffff0000, v102
	v_fmac_f32_e32 v8, v10, v10
	v_fmac_f32_e32 v8, v11, v11
	v_lshlrev_b32_e32 v10, 16, v103
	v_and_b32_e32 v11, 0xffff0000, v103
	v_fmac_f32_e32 v8, v10, v10
	v_fmac_f32_e32 v8, v11, v11
	v_lshlrev_b32_e32 v10, 16, v104
	v_and_b32_e32 v11, 0xffff0000, v104
	v_fmac_f32_e32 v8, v10, v10
	v_fmac_f32_e32 v8, v11, v11
	v_lshlrev_b32_e32 v10, 16, v105
	v_and_b32_e32 v11, 0xffff0000, v105
	v_fmac_f32_e32 v8, v10, v10
	v_fmac_f32_e32 v8, v11, v11
	v_lshlrev_b32_e32 v10, 16, v106
	v_and_b32_e32 v11, 0xffff0000, v106
	v_fmac_f32_e32 v8, v10, v10
	v_fmac_f32_e32 v8, v11, v11
	v_lshlrev_b32_e32 v10, 16, v107
	v_and_b32_e32 v11, 0xffff0000, v107
	v_fmac_f32_e32 v8, v10, v10
	v_fmac_f32_e32 v8, v11, v11
	v_lshlrev_b32_e32 v10, 16, v108
	v_and_b32_e32 v11, 0xffff0000, v108
	v_fmac_f32_e32 v8, v10, v10
	v_fmac_f32_e32 v8, v11, v11
	v_lshlrev_b32_e32 v10, 16, v109
	v_and_b32_e32 v11, 0xffff0000, v109
	v_fmac_f32_e32 v8, v10, v10
	v_fmac_f32_e32 v8, v11, v11
	v_lshlrev_b32_e32 v10, 16, v110
	v_and_b32_e32 v11, 0xffff0000, v110
	v_fmac_f32_e32 v8, v10, v10
	v_fmac_f32_e32 v8, v11, v11
	v_lshlrev_b32_e32 v10, 16, v111
	v_and_b32_e32 v11, 0xffff0000, v111
	v_fmac_f32_e32 v8, v10, v10
	v_fmac_f32_e32 v8, v11, v11
	v_lshlrev_b32_e32 v10, 16, v112
	v_and_b32_e32 v11, 0xffff0000, v112
	v_fmac_f32_e32 v8, v10, v10
	v_fmac_f32_e32 v8, v11, v11
	v_lshlrev_b32_e32 v10, 16, v113
	v_and_b32_e32 v11, 0xffff0000, v113
	v_fmac_f32_e32 v8, v10, v10
	v_fmac_f32_e32 v8, v11, v11
	s_nop 1
	v_add_f32_dpp v8, v8, v8 quad_perm:[1,0,3,2] row_mask:0xf bank_mask:0xf
	s_nop 1
	v_add_f32_dpp v8, v8, v8 quad_perm:[2,3,0,1] row_mask:0xf bank_mask:0xf
	s_nop 1
	v_add_f32_dpp v8, v8, v8 row_ror:4 row_mask:0xf bank_mask:0xf
	s_nop 1
	v_add_f32_dpp v8, v8, v8 row_ror:8 row_mask:0xf bank_mask:0xf
	s_nop 1
	v_readlane_b32 s42, v8, 0
	v_readlane_b32 s43, v8, 16
	v_readlane_b32 s44, v8, 32
	v_readlane_b32 s45, v8, 48
	s_nop 1
	v_mov_b32_e32 v8, s42
	v_add_f32_e32 v8, s43, v8
	v_add_f32_e32 v8, s44, v8
	v_add_f32_e32 v8, s45, v8
	v_mov_b32_e32 v4, s41
	v_fmac_f32_e32 v4, s40, v8
	v_rsq_f32_e32 v4, v4
	s_nop 0
	v_mov_b32_e32 v5, v4
	s_waitcnt vmcnt(63)
	s_waitcnt vmcnt(16)
	v_mov_b32_e32 v8, 0
	v_lshlrev_b32_e32 v10, 16, v98
	v_and_b32_e32 v11, 0xffff0000, v98
	v_pk_mul_f32 v[10:11], v[10:11], v[4:5]
	v_pk_mul_f32 v[10:11], v[10:11], v[130:131]
	v_pk_fma_f32 v[34:35], v[164:165], v[10:11], v[34:35]
	v_lshlrev_b32_e32 v10, 16, v99
	v_and_b32_e32 v11, 0xffff0000, v99
	v_pk_mul_f32 v[10:11], v[10:11], v[4:5]
	v_pk_mul_f32 v[10:11], v[10:11], v[132:133]
	v_pk_fma_f32 v[36:37], v[166:167], v[10:11], v[36:37]
	global_store_dwordx4 v1, v[34:37], s[24:25] nt
	v_fmac_f32_e32 v8, v34, v34
	v_fmac_f32_e32 v8, v35, v35
	v_fmac_f32_e32 v8, v36, v36
	v_fmac_f32_e32 v8, v37, v37
	v_lshlrev_b32_e32 v10, 16, v100
	v_and_b32_e32 v11, 0xffff0000, v100
	v_pk_mul_f32 v[10:11], v[10:11], v[4:5]
	v_pk_mul_f32 v[10:11], v[10:11], v[134:135]
	v_pk_fma_f32 v[38:39], v[168:169], v[10:11], v[38:39]
	v_lshlrev_b32_e32 v10, 16, v101
	v_and_b32_e32 v11, 0xffff0000, v101
	v_pk_mul_f32 v[10:11], v[10:11], v[4:5]
	v_pk_mul_f32 v[10:11], v[10:11], v[136:137]
	v_pk_fma_f32 v[40:41], v[170:171], v[10:11], v[40:41]
	global_store_dwordx4 v1, v[38:41], s[24:25] offset:1024 nt
	v_fmac_f32_e32 v8, v38, v38
	v_fmac_f32_e32 v8, v39, v39
	v_fmac_f32_e32 v8, v40, v40
	v_fmac_f32_e32 v8, v41, v41
	v_lshlrev_b32_e32 v10, 16, v102
	v_and_b32_e32 v11, 0xffff0000, v102
	v_pk_mul_f32 v[10:11], v[10:11], v[4:5]
	v_pk_mul_f32 v[10:11], v[10:11], v[138:139]
	v_pk_fma_f32 v[42:43], v[172:173], v[10:11], v[42:43]
	v_lshlrev_b32_e32 v10, 16, v103
	v_and_b32_e32 v11, 0xffff0000, v103
	v_pk_mul_f32 v[10:11], v[10:11], v[4:5]
	v_pk_mul_f32 v[10:11], v[10:11], v[140:141]
	v_pk_fma_f32 v[44:45], v[174:175], v[10:11], v[44:45]
	global_store_dwordx4 v1, v[42:45], s[24:25] offset:2048 nt
	v_fmac_f32_e32 v8, v42, v42
	v_fmac_f32_e32 v8, v43, v43
	v_fmac_f32_e32 v8, v44, v44
	v_fmac_f32_e32 v8, v45, v45
	v_lshlrev_b32_e32 v10, 16, v104
	v_and_b32_e32 v11, 0xffff0000, v104
	v_pk_mul_f32 v[10:11], v[10:11], v[4:5]
	v_pk_mul_f32 v[10:11], v[10:11], v[142:143]
	v_pk_fma_f32 v[46:47], v[176:177], v[10:11], v[46:47]
	v_lshlrev_b32_e32 v10, 16, v105
	v_and_b32_e32 v11, 0xffff0000, v105
	v_pk_mul_f32 v[10:11], v[10:11], v[4:5]
	v_pk_mul_f32 v[10:11], v[10:11], v[144:145]
	v_pk_fma_f32 v[48:49], v[178:179], v[10:11], v[48:49]
	global_store_dwordx4 v1, v[46:49], s[24:25] offset:3072 nt
	v_fmac_f32_e32 v8, v46, v46
	v_fmac_f32_e32 v8, v47, v47
	v_fmac_f32_e32 v8, v48, v48
	v_fmac_f32_e32 v8, v49, v49
	v_lshlrev_b32_e32 v10, 16, v106
	v_and_b32_e32 v11, 0xffff0000, v106
	v_pk_mul_f32 v[10:11], v[10:11], v[4:5]
	v_pk_mul_f32 v[10:11], v[10:11], v[146:147]
	v_pk_fma_f32 v[50:51], v[180:181], v[10:11], v[50:51]
	v_lshlrev_b32_e32 v10, 16, v107
	v_and_b32_e32 v11, 0xffff0000, v107
	v_pk_mul_f32 v[10:11], v[10:11], v[4:5]
	v_pk_mul_f32 v[10:11], v[10:11], v[148:149]
	v_pk_fma_f32 v[52:53], v[182:183], v[10:11], v[52:53]
	global_store_dwordx4 v1, v[50:53], s[34:35] nt
	v_fmac_f32_e32 v8, v50, v50
	v_fmac_f32_e32 v8, v51, v51
	v_fmac_f32_e32 v8, v52, v52
	v_fmac_f32_e32 v8, v53, v53
	v_lshlrev_b32_e32 v10, 16, v108
	v_and_b32_e32 v11, 0xffff0000, v108
	v_pk_mul_f32 v[10:11], v[10:11], v[4:5]
	v_pk_mul_f32 v[10:11], v[10:11], v[150:151]
	v_pk_fma_f32 v[54:55], v[184:185], v[10:11], v[54:55]
	v_lshlrev_b32_e32 v10, 16, v109
	v_and_b32_e32 v11, 0xffff0000, v109
	v_pk_mul_f32 v[10:11], v[10:11], v[4:5]
	v_pk_mul_f32 v[10:11], v[10:11], v[152:153]
	v_pk_fma_f32 v[56:57], v[186:187], v[10:11], v[56:57]
	global_store_dwordx4 v1, v[54:57], s[34:35] offset:1024 nt
	v_fmac_f32_e32 v8, v54, v54
	v_fmac_f32_e32 v8, v55, v55
	v_fmac_f32_e32 v8, v56, v56
	v_fmac_f32_e32 v8, v57, v57
	v_lshlrev_b32_e32 v10, 16, v110
	v_and_b32_e32 v11, 0xffff0000, v110
	v_pk_mul_f32 v[10:11], v[10:11], v[4:5]
	v_pk_mul_f32 v[10:11], v[10:11], v[156:157]
	v_pk_fma_f32 v[58:59], v[188:189], v[10:11], v[58:59]
	v_lshlrev_b32_e32 v10, 16, v111
	v_and_b32_e32 v11, 0xffff0000, v111
	v_pk_mul_f32 v[10:11], v[10:11], v[4:5]
	v_pk_mul_f32 v[10:11], v[10:11], v[158:159]
	v_pk_fma_f32 v[60:61], v[190:191], v[10:11], v[60:61]
	global_store_dwordx4 v1, v[58:61], s[34:35] offset:2048 nt
	v_fmac_f32_e32 v8, v58, v58
	v_fmac_f32_e32 v8, v59, v59
	v_fmac_f32_e32 v8, v60, v60
	v_fmac_f32_e32 v8, v61, v61
	v_lshlrev_b32_e32 v10, 16, v112
	v_and_b32_e32 v11, 0xffff0000, v112
	v_pk_mul_f32 v[10:11], v[10:11], v[4:5]
	v_pk_mul_f32 v[10:11], v[10:11], v[160:161]
	v_pk_fma_f32 v[62:63], v[192:193], v[10:11], v[62:63]
	v_lshlrev_b32_e32 v10, 16, v113
	v_and_b32_e32 v11, 0xffff0000, v113
	v_pk_mul_f32 v[10:11], v[10:11], v[4:5]
	v_pk_mul_f32 v[10:11], v[10:11], v[162:163]
	v_pk_fma_f32 v[64:65], v[194:195], v[10:11], v[64:65]
	global_store_dwordx4 v1, v[62:65], s[34:35] offset:3072 nt
	v_fmac_f32_e32 v8, v62, v62
	v_fmac_f32_e32 v8, v63, v63
	v_fmac_f32_e32 v8, v64, v64
	v_fmac_f32_e32 v8, v65, v65
	s_add_u32 s18, s2, 0x1000
	s_addc_u32 s19, s3, 0
	global_load_dwordx4 v[130:133], v1, s[2:3]
	global_load_dwordx4 v[134:137], v1, s[2:3] offset:1024
	global_load_dwordx4 v[138:141], v1, s[2:3] offset:2048
	global_load_dwordx4 v[142:145], v1, s[2:3] offset:3072
	global_load_dwordx4 v[146:149], v1, s[18:19]
	global_load_dwordx4 v[150:153], v1, s[18:19] offset:1024
	global_load_dwordx4 v[156:159], v1, s[18:19] offset:2048
	global_load_dwordx4 v[160:163], v1, s[18:19] offset:3072
	s_add_u32 s18, s30, 0x1000
	s_addc_u32 s19, s31, 0
	global_load_dwordx4 v[164:167], v1, s[30:31]
	global_load_dwordx4 v[168:171], v1, s[30:31] offset:1024
	global_load_dwordx4 v[172:175], v1, s[30:31] offset:2048
	global_load_dwordx4 v[176:179], v1, s[30:31] offset:3072
	global_load_dwordx4 v[180:183], v1, s[18:19]
	global_load_dwordx4 v[184:187], v1, s[18:19] offset:1024
	global_load_dwordx4 v[188:191], v1, s[18:19] offset:2048
	global_load_dwordx4 v[192:195], v1, s[18:19] offset:3072
	s_add_u32 s18, s32, 0x1000
	s_addc_u32 s19, s33, 0
	global_load_dwordx4 v[196:199], v1, s[32:33]
	global_load_dwordx4 v[200:203], v1, s[32:33] offset:1024
	global_load_dwordx4 v[204:207], v1, s[32:33] offset:2048
	global_load_dwordx4 v[208:211], v1, s[32:33] offset:3072
	global_load_dwordx4 v[212:215], v1, s[18:19]
	global_load_dwordx4 v[216:219], v1, s[18:19] offset:1024
	global_load_dwordx4 v[220:223], v1, s[18:19] offset:2048
	global_load_dwordx4 v[224:227], v1, s[18:19] offset:3072
	s_nop 1
	v_add_f32_dpp v8, v8, v8 quad_perm:[1,0,3,2] row_mask:0xf bank_mask:0xf
	s_nop 1
	v_add_f32_dpp v8, v8, v8 quad_perm:[2,3,0,1] row_mask:0xf bank_mask:0xf
	s_nop 1
	v_add_f32_dpp v8, v8, v8 row_ror:4 row_mask:0xf bank_mask:0xf
	s_nop 1
	v_add_f32_dpp v8, v8, v8 row_ror:8 row_mask:0xf bank_mask:0xf
	s_nop 1
	v_readlane_b32 s42, v8, 0
	v_readlane_b32 s43, v8, 16
	v_readlane_b32 s44, v8, 32
	v_readlane_b32 s45, v8, 48
	s_nop 1
	v_mov_b32_e32 v8, s42
	v_add_f32_e32 v8, s43, v8
	v_add_f32_e32 v8, s44, v8
	v_add_f32_e32 v8, s45, v8
	v_mov_b32_e32 v4, s41
	v_fmac_f32_e32 v4, s40, v8
	v_rsq_f32_e32 v4, v4
	s_nop 0
	v_mov_b32_e32 v5, v4
	s_waitcnt vmcnt(0)
	v_pk_mul_f32 v[10:11], v[34:35], v[4:5]
	v_pk_mul_f32 v[10:11], v[10:11], v[130:131]
	v_pk_add_f32 v[12:13], v[196:197], v[6:7]
	v_pk_fma_f32 v[14:15], v[10:11], v[12:13], v[164:165]
	v_pk_mul_f32 v[10:11], v[36:37], v[4:5]
	v_pk_mul_f32 v[10:11], v[10:11], v[132:133]
	v_pk_add_f32 v[12:13], v[198:199], v[6:7]
	v_pk_fma_f32 v[16:17], v[10:11], v[12:13], v[166:167]
	v_cvt_pk_bf16_f32 v26, v14, v15
	v_cvt_pk_bf16_f32 v27, v16, v17
	global_store_dwordx2 v2, v[26:27], s[26:27]
	v_pk_mul_f32 v[10:11], v[38:39], v[4:5]
	v_pk_mul_f32 v[10:11], v[10:11], v[134:135]
	v_pk_add_f32 v[12:13], v[200:201], v[6:7]
	v_pk_fma_f32 v[14:15], v[10:11], v[12:13], v[168:169]
	v_pk_mul_f32 v[10:11], v[40:41], v[4:5]
	v_pk_mul_f32 v[10:11], v[10:11], v[136:137]
	v_pk_add_f32 v[12:13], v[202:203], v[6:7]
	v_pk_fma_f32 v[16:17], v[10:11], v[12:13], v[170:171]
	v_cvt_pk_bf16_f32 v28, v14, v15
	v_cvt_pk_bf16_f32 v29, v16, v17
	global_store_dwordx2 v2, v[28:29], s[26:27] offset:512
	v_pk_mul_f32 v[10:11], v[42:43], v[4:5]
	v_pk_mul_f32 v[10:11], v[10:11], v[138:139]
	v_pk_add_f32 v[12:13], v[204:205], v[6:7]
	v_pk_fma_f32 v[14:15], v[10:11], v[12:13], v[172:173]
	v_pk_mul_f32 v[10:11], v[44:45], v[4:5]
	v_pk_mul_f32 v[10:11], v[10:11], v[140:141]
	v_pk_add_f32 v[12:13], v[206:207], v[6:7]
	v_pk_fma_f32 v[16:17], v[10:11], v[12:13], v[174:175]
	v_cvt_pk_bf16_f32 v30, v14, v15
	v_cvt_pk_bf16_f32 v31, v16, v17
	global_store_dwordx2 v2, v[30:31], s[26:27] offset:1024
	v_pk_mul_f32 v[10:11], v[46:47], v[4:5]
	v_pk_mul_f32 v[10:11], v[10:11], v[142:143]
	v_pk_add_f32 v[12:13], v[208:209], v[6:7]
	v_pk_fma_f32 v[14:15], v[10:11], v[12:13], v[176:177]
	v_pk_mul_f32 v[10:11], v[48:49], v[4:5]
	v_pk_mul_f32 v[10:11], v[10:11], v[144:145]
	v_pk_add_f32 v[12:13], v[210:211], v[6:7]
	v_pk_fma_f32 v[16:17], v[10:11], v[12:13], v[178:179]
	v_cvt_pk_bf16_f32 v32, v14, v15
	v_cvt_pk_bf16_f32 v33, v16, v17
	global_store_dwordx2 v2, v[32:33], s[26:27] offset:1536
	v_pk_mul_f32 v[10:11], v[50:51], v[4:5]
	v_pk_mul_f32 v[10:11], v[10:11], v[146:147]
	v_pk_add_f32 v[12:13], v[212:213], v[6:7]
	v_pk_fma_f32 v[14:15], v[10:11], v[12:13], v[180:181]
	v_pk_mul_f32 v[10:11], v[52:53], v[4:5]
	v_pk_mul_f32 v[10:11], v[10:11], v[148:149]
	v_pk_add_f32 v[12:13], v[214:215], v[6:7]
	v_pk_fma_f32 v[16:17], v[10:11], v[12:13], v[182:183]
	v_cvt_pk_bf16_f32 v26, v14, v15
	v_cvt_pk_bf16_f32 v27, v16, v17
	global_store_dwordx2 v2, v[26:27], s[26:27] offset:2048
	v_pk_mul_f32 v[10:11], v[54:55], v[4:5]
	v_pk_mul_f32 v[10:11], v[10:11], v[150:151]
	v_pk_add_f32 v[12:13], v[216:217], v[6:7]
	v_pk_fma_f32 v[14:15], v[10:11], v[12:13], v[184:185]
	v_pk_mul_f32 v[10:11], v[56:57], v[4:5]
	v_pk_mul_f32 v[10:11], v[10:11], v[152:153]
	v_pk_add_f32 v[12:13], v[218:219], v[6:7]
	v_pk_fma_f32 v[16:17], v[10:11], v[12:13], v[186:187]
	v_cvt_pk_bf16_f32 v28, v14, v15
	v_cvt_pk_bf16_f32 v29, v16, v17
	global_store_dwordx2 v2, v[28:29], s[26:27] offset:2560
	v_pk_mul_f32 v[10:11], v[58:59], v[4:5]
	v_pk_mul_f32 v[10:11], v[10:11], v[156:157]
	v_pk_add_f32 v[12:13], v[220:221], v[6:7]
	v_pk_fma_f32 v[14:15], v[10:11], v[12:13], v[188:189]
	v_pk_mul_f32 v[10:11], v[60:61], v[4:5]
	v_pk_mul_f32 v[10:11], v[10:11], v[158:159]
	v_pk_add_f32 v[12:13], v[222:223], v[6:7]
	v_pk_fma_f32 v[16:17], v[10:11], v[12:13], v[190:191]
	v_cvt_pk_bf16_f32 v30, v14, v15
	v_cvt_pk_bf16_f32 v31, v16, v17
	global_store_dwordx2 v2, v[30:31], s[26:27] offset:3072
	v_pk_mul_f32 v[10:11], v[62:63], v[4:5]
	v_pk_mul_f32 v[10:11], v[10:11], v[160:161]
	v_pk_add_f32 v[12:13], v[224:225], v[6:7]
	v_pk_fma_f32 v[14:15], v[10:11], v[12:13], v[192:193]
	v_pk_mul_f32 v[10:11], v[64:65], v[4:5]
	v_pk_mul_f32 v[10:11], v[10:11], v[162:163]
	v_pk_add_f32 v[12:13], v[226:227], v[6:7]
	v_pk_fma_f32 v[16:17], v[10:11], v[12:13], v[194:195]
	v_cvt_pk_bf16_f32 v32, v14, v15
	v_cvt_pk_bf16_f32 v33, v16, v17
	global_store_dwordx2 v2, v[32:33], s[26:27] offset:3584
	s_lshr_b32 s16, s10, 10
	s_add_u32 s16, s16, 2
	s_add_u32 s17, s16, 0
	s_mul_i32 s17, s17, 49152
	s_add_u32 s17, s17, 0x1040a000
	s_add_u32 s28, s90, s17
	s_addc_u32 s29, s91, 0
	s_add_u32 s17, s16, 5
	s_mul_i32 s17, s17, 49152
	s_add_u32 s17, s17, 0x10400000
	s_add_u32 s30, s90, s17
	s_addc_u32 s31, s91, 0
	s_add_u32 s32, s30, 0x2000
	s_addc_u32 s33, s31, 0
	s_add_u32 s18, s0, 0x1000
	s_addc_u32 s19, s1, 0
	global_load_dwordx4 v[130:133], v1, s[0:1]
	global_load_dwordx4 v[134:137], v1, s[0:1] offset:1024
	global_load_dwordx4 v[138:141], v1, s[0:1] offset:2048
	global_load_dwordx4 v[142:145], v1, s[0:1] offset:3072
	global_load_dwordx4 v[146:149], v1, s[18:19]
	global_load_dwordx4 v[150:153], v1, s[18:19] offset:1024
	global_load_dwordx4 v[156:159], v1, s[18:19] offset:2048
	global_load_dwordx4 v[160:163], v1, s[18:19] offset:3072
	s_add_u32 s18, s28, 0x1000
	s_addc_u32 s19, s29, 0
	global_load_dwordx4 v[164:167], v1, s[28:29]
	global_load_dwordx4 v[168:171], v1, s[28:29] offset:1024
	global_load_dwordx4 v[172:175], v1, s[28:29] offset:2048
	global_load_dwordx4 v[176:179], v1, s[28:29] offset:3072
	global_load_dwordx4 v[180:183], v1, s[18:19]
	global_load_dwordx4 v[184:187], v1, s[18:19] offset:1024
	global_load_dwordx4 v[188:191], v1, s[18:19] offset:2048
	global_load_dwordx4 v[192:195], v1, s[18:19] offset:3072
	s_add_u32 s12, s10, 6144
	s_lshl_b32 s13, s12, 13
	s_lshl_b32 s14, s12, 12
	s_add_u32 s24, s4, s13
	s_addc_u32 s25, s5, 0
	s_add_u32 s34, s24, 0x1000
	s_addc_u32 s35, s25, 0
	s_add_u32 s26, s90, 0x11918000
	s_addc_u32 s27, s91, 0
	s_add_u32 s26, s26, s14
	s_addc_u32 s27, s27, 0
	s_waitcnt vmcnt(63)
	v_mov_b32_e32 v8, 0
	v_lshlrev_b32_e32 v10, 16, v114
	v_and_b32_e32 v11, 0xffff0000, v114
	v_fmac_f32_e32 v8, v10, v10
	v_fmac_f32_e32 v8, v11, v11
	v_lshlrev_b32_e32 v10, 16, v115
	v_and_b32_e32 v11, 0xffff0000, v115
	v_fmac_f32_e32 v8, v10, v10
	v_fmac_f32_e32 v8, v11, v11
	v_lshlrev_b32_e32 v10, 16, v116
	v_and_b32_e32 v11, 0xffff0000, v116
	v_fmac_f32_e32 v8, v10, v10
	v_fmac_f32_e32 v8, v11, v11
	v_lshlrev_b32_e32 v10, 16, v117
	v_and_b32_e32 v11, 0xffff0000, v117
	v_fmac_f32_e32 v8, v10, v10
	v_fmac_f32_e32 v8, v11, v11
	v_lshlrev_b32_e32 v10, 16, v118
	v_and_b32_e32 v11, 0xffff0000, v118
	v_fmac_f32_e32 v8, v10, v10
	v_fmac_f32_e32 v8, v11, v11
	v_lshlrev_b32_e32 v10, 16, v119
	v_and_b32_e32 v11, 0xffff0000, v119
	v_fmac_f32_e32 v8, v10, v10
	v_fmac_f32_e32 v8, v11, v11
	v_lshlrev_b32_e32 v10, 16, v120
	v_and_b32_e32 v11, 0xffff0000, v120
	v_fmac_f32_e32 v8, v10, v10
	v_fmac_f32_e32 v8, v11, v11
	v_lshlrev_b32_e32 v10, 16, v121
	v_and_b32_e32 v11, 0xffff0000, v121
	v_fmac_f32_e32 v8, v10, v10
	v_fmac_f32_e32 v8, v11, v11
	v_lshlrev_b32_e32 v10, 16, v122
	v_and_b32_e32 v11, 0xffff0000, v122
	v_fmac_f32_e32 v8, v10, v10
	v_fmac_f32_e32 v8, v11, v11
	v_lshlrev_b32_e32 v10, 16, v123
	v_and_b32_e32 v11, 0xffff0000, v123
	v_fmac_f32_e32 v8, v10, v10
	v_fmac_f32_e32 v8, v11, v11
	v_lshlrev_b32_e32 v10, 16, v124
	v_and_b32_e32 v11, 0xffff0000, v124
	v_fmac_f32_e32 v8, v10, v10
	v_fmac_f32_e32 v8, v11, v11
	v_lshlrev_b32_e32 v10, 16, v125
	v_and_b32_e32 v11, 0xffff0000, v125
	v_fmac_f32_e32 v8, v10, v10
	v_fmac_f32_e32 v8, v11, v11
	v_lshlrev_b32_e32 v10, 16, v126
	v_and_b32_e32 v11, 0xffff0000, v126
	v_fmac_f32_e32 v8, v10, v10
	v_fmac_f32_e32 v8, v11, v11
	v_lshlrev_b32_e32 v10, 16, v127
	v_and_b32_e32 v11, 0xffff0000, v127
	v_fmac_f32_e32 v8, v10, v10
	v_fmac_f32_e32 v8, v11, v11
	v_lshlrev_b32_e32 v10, 16, v128
	v_and_b32_e32 v11, 0xffff0000, v128
	v_fmac_f32_e32 v8, v10, v10
	v_fmac_f32_e32 v8, v11, v11
	v_lshlrev_b32_e32 v10, 16, v129
	v_and_b32_e32 v11, 0xffff0000, v129
	v_fmac_f32_e32 v8, v10, v10
	v_fmac_f32_e32 v8, v11, v11
	s_nop 1
	v_add_f32_dpp v8, v8, v8 quad_perm:[1,0,3,2] row_mask:0xf bank_mask:0xf
	s_nop 1
	v_add_f32_dpp v8, v8, v8 quad_perm:[2,3,0,1] row_mask:0xf bank_mask:0xf
	s_nop 1
	v_add_f32_dpp v8, v8, v8 row_ror:4 row_mask:0xf bank_mask:0xf
	s_nop 1
	v_add_f32_dpp v8, v8, v8 row_ror:8 row_mask:0xf bank_mask:0xf
	s_nop 1
	v_readlane_b32 s42, v8, 0
	v_readlane_b32 s43, v8, 16
	v_readlane_b32 s44, v8, 32
	v_readlane_b32 s45, v8, 48
	s_nop 1
	v_mov_b32_e32 v8, s42
	v_add_f32_e32 v8, s43, v8
	v_add_f32_e32 v8, s44, v8
	v_add_f32_e32 v8, s45, v8
	v_mov_b32_e32 v4, s41
	v_fmac_f32_e32 v4, s40, v8
	v_rsq_f32_e32 v4, v4
	s_nop 0
	v_mov_b32_e32 v5, v4
	s_waitcnt vmcnt(56)
	s_waitcnt vmcnt(0)
	v_mov_b32_e32 v8, 0
	v_lshlrev_b32_e32 v10, 16, v114
	v_and_b32_e32 v11, 0xffff0000, v114
	v_pk_mul_f32 v[10:11], v[10:11], v[4:5]
	v_pk_mul_f32 v[10:11], v[10:11], v[130:131]
	v_pk_fma_f32 v[66:67], v[164:165], v[10:11], v[66:67]
	v_lshlrev_b32_e32 v10, 16, v115
	v_and_b32_e32 v11, 0xffff0000, v115
	v_pk_mul_f32 v[10:11], v[10:11], v[4:5]
	v_pk_mul_f32 v[10:11], v[10:11], v[132:133]
	v_pk_fma_f32 v[68:69], v[166:167], v[10:11], v[68:69]
	global_store_dwordx4 v1, v[66:69], s[24:25] nt
	v_fmac_f32_e32 v8, v66, v66
	v_fmac_f32_e32 v8, v67, v67
	v_fmac_f32_e32 v8, v68, v68
	v_fmac_f32_e32 v8, v69, v69
	v_lshlrev_b32_e32 v10, 16, v116
	v_and_b32_e32 v11, 0xffff0000, v116
	v_pk_mul_f32 v[10:11], v[10:11], v[4:5]
	v_pk_mul_f32 v[10:11], v[10:11], v[134:135]
	v_pk_fma_f32 v[70:71], v[168:169], v[10:11], v[70:71]
	v_lshlrev_b32_e32 v10, 16, v117
	v_and_b32_e32 v11, 0xffff0000, v117
	v_pk_mul_f32 v[10:11], v[10:11], v[4:5]
	v_pk_mul_f32 v[10:11], v[10:11], v[136:137]
	v_pk_fma_f32 v[72:73], v[170:171], v[10:11], v[72:73]
	global_store_dwordx4 v1, v[70:73], s[24:25] offset:1024 nt
	v_fmac_f32_e32 v8, v70, v70
	v_fmac_f32_e32 v8, v71, v71
	v_fmac_f32_e32 v8, v72, v72
	v_fmac_f32_e32 v8, v73, v73
	v_lshlrev_b32_e32 v10, 16, v118
	v_and_b32_e32 v11, 0xffff0000, v118
	v_pk_mul_f32 v[10:11], v[10:11], v[4:5]
	v_pk_mul_f32 v[10:11], v[10:11], v[138:139]
	v_pk_fma_f32 v[74:75], v[172:173], v[10:11], v[74:75]
	v_lshlrev_b32_e32 v10, 16, v119
	v_and_b32_e32 v11, 0xffff0000, v119
	v_pk_mul_f32 v[10:11], v[10:11], v[4:5]
	v_pk_mul_f32 v[10:11], v[10:11], v[140:141]
	v_pk_fma_f32 v[76:77], v[174:175], v[10:11], v[76:77]
	global_store_dwordx4 v1, v[74:77], s[24:25] offset:2048 nt
	v_fmac_f32_e32 v8, v74, v74
	v_fmac_f32_e32 v8, v75, v75
	v_fmac_f32_e32 v8, v76, v76
	v_fmac_f32_e32 v8, v77, v77
	v_lshlrev_b32_e32 v10, 16, v120
	v_and_b32_e32 v11, 0xffff0000, v120
	v_pk_mul_f32 v[10:11], v[10:11], v[4:5]
	v_pk_mul_f32 v[10:11], v[10:11], v[142:143]
	v_pk_fma_f32 v[78:79], v[176:177], v[10:11], v[78:79]
	v_lshlrev_b32_e32 v10, 16, v121
	v_and_b32_e32 v11, 0xffff0000, v121
	v_pk_mul_f32 v[10:11], v[10:11], v[4:5]
	v_pk_mul_f32 v[10:11], v[10:11], v[144:145]
	v_pk_fma_f32 v[80:81], v[178:179], v[10:11], v[80:81]
	global_store_dwordx4 v1, v[78:81], s[24:25] offset:3072 nt
	v_fmac_f32_e32 v8, v78, v78
	v_fmac_f32_e32 v8, v79, v79
	v_fmac_f32_e32 v8, v80, v80
	v_fmac_f32_e32 v8, v81, v81
	v_lshlrev_b32_e32 v10, 16, v122
	v_and_b32_e32 v11, 0xffff0000, v122
	v_pk_mul_f32 v[10:11], v[10:11], v[4:5]
	v_pk_mul_f32 v[10:11], v[10:11], v[146:147]
	v_pk_fma_f32 v[82:83], v[180:181], v[10:11], v[82:83]
	v_lshlrev_b32_e32 v10, 16, v123
	v_and_b32_e32 v11, 0xffff0000, v123
	v_pk_mul_f32 v[10:11], v[10:11], v[4:5]
	v_pk_mul_f32 v[10:11], v[10:11], v[148:149]
	v_pk_fma_f32 v[84:85], v[182:183], v[10:11], v[84:85]
	global_store_dwordx4 v1, v[82:85], s[34:35] nt
	v_fmac_f32_e32 v8, v82, v82
	v_fmac_f32_e32 v8, v83, v83
	v_fmac_f32_e32 v8, v84, v84
	v_fmac_f32_e32 v8, v85, v85
	v_lshlrev_b32_e32 v10, 16, v124
	v_and_b32_e32 v11, 0xffff0000, v124
	v_pk_mul_f32 v[10:11], v[10:11], v[4:5]
	v_pk_mul_f32 v[10:11], v[10:11], v[150:151]
	v_pk_fma_f32 v[86:87], v[184:185], v[10:11], v[86:87]
	v_lshlrev_b32_e32 v10, 16, v125
	v_and_b32_e32 v11, 0xffff0000, v125
	v_pk_mul_f32 v[10:11], v[10:11], v[4:5]
	v_pk_mul_f32 v[10:11], v[10:11], v[152:153]
	v_pk_fma_f32 v[88:89], v[186:187], v[10:11], v[88:89]
	global_store_dwordx4 v1, v[86:89], s[34:35] offset:1024 nt
	v_fmac_f32_e32 v8, v86, v86
	v_fmac_f32_e32 v8, v87, v87
	v_fmac_f32_e32 v8, v88, v88
	v_fmac_f32_e32 v8, v89, v89
	v_lshlrev_b32_e32 v10, 16, v126
	v_and_b32_e32 v11, 0xffff0000, v126
	v_pk_mul_f32 v[10:11], v[10:11], v[4:5]
	v_pk_mul_f32 v[10:11], v[10:11], v[156:157]
	v_pk_fma_f32 v[90:91], v[188:189], v[10:11], v[90:91]
	v_lshlrev_b32_e32 v10, 16, v127
	v_and_b32_e32 v11, 0xffff0000, v127
	v_pk_mul_f32 v[10:11], v[10:11], v[4:5]
	v_pk_mul_f32 v[10:11], v[10:11], v[158:159]
	v_pk_fma_f32 v[92:93], v[190:191], v[10:11], v[92:93]
	global_store_dwordx4 v1, v[90:93], s[34:35] offset:2048 nt
	v_fmac_f32_e32 v8, v90, v90
	v_fmac_f32_e32 v8, v91, v91
	v_fmac_f32_e32 v8, v92, v92
	v_fmac_f32_e32 v8, v93, v93
	v_lshlrev_b32_e32 v10, 16, v128
	v_and_b32_e32 v11, 0xffff0000, v128
	v_pk_mul_f32 v[10:11], v[10:11], v[4:5]
	v_pk_mul_f32 v[10:11], v[10:11], v[160:161]
	v_pk_fma_f32 v[94:95], v[192:193], v[10:11], v[94:95]
	v_lshlrev_b32_e32 v10, 16, v129
	v_and_b32_e32 v11, 0xffff0000, v129
	v_pk_mul_f32 v[10:11], v[10:11], v[4:5]
	v_pk_mul_f32 v[10:11], v[10:11], v[162:163]
	v_pk_fma_f32 v[96:97], v[194:195], v[10:11], v[96:97]
	global_store_dwordx4 v1, v[94:97], s[34:35] offset:3072 nt
	v_fmac_f32_e32 v8, v94, v94
	v_fmac_f32_e32 v8, v95, v95
	v_fmac_f32_e32 v8, v96, v96
	v_fmac_f32_e32 v8, v97, v97
	s_add_u32 s18, s2, 0x1000
	s_addc_u32 s19, s3, 0
	global_load_dwordx4 v[130:133], v1, s[2:3]
	global_load_dwordx4 v[134:137], v1, s[2:3] offset:1024
	global_load_dwordx4 v[138:141], v1, s[2:3] offset:2048
	global_load_dwordx4 v[142:145], v1, s[2:3] offset:3072
	global_load_dwordx4 v[146:149], v1, s[18:19]
	global_load_dwordx4 v[150:153], v1, s[18:19] offset:1024
	global_load_dwordx4 v[156:159], v1, s[18:19] offset:2048
	global_load_dwordx4 v[160:163], v1, s[18:19] offset:3072
	s_add_u32 s18, s30, 0x1000
	s_addc_u32 s19, s31, 0
	global_load_dwordx4 v[164:167], v1, s[30:31]
	global_load_dwordx4 v[168:171], v1, s[30:31] offset:1024
	global_load_dwordx4 v[172:175], v1, s[30:31] offset:2048
	global_load_dwordx4 v[176:179], v1, s[30:31] offset:3072
	global_load_dwordx4 v[180:183], v1, s[18:19]
	global_load_dwordx4 v[184:187], v1, s[18:19] offset:1024
	global_load_dwordx4 v[188:191], v1, s[18:19] offset:2048
	global_load_dwordx4 v[192:195], v1, s[18:19] offset:3072
	s_add_u32 s18, s32, 0x1000
	s_addc_u32 s19, s33, 0
	global_load_dwordx4 v[196:199], v1, s[32:33]
	global_load_dwordx4 v[200:203], v1, s[32:33] offset:1024
	global_load_dwordx4 v[204:207], v1, s[32:33] offset:2048
	global_load_dwordx4 v[208:211], v1, s[32:33] offset:3072
	global_load_dwordx4 v[212:215], v1, s[18:19]
	global_load_dwordx4 v[216:219], v1, s[18:19] offset:1024
	global_load_dwordx4 v[220:223], v1, s[18:19] offset:2048
	global_load_dwordx4 v[224:227], v1, s[18:19] offset:3072
	s_nop 1
	v_add_f32_dpp v8, v8, v8 quad_perm:[1,0,3,2] row_mask:0xf bank_mask:0xf
	s_nop 1
	v_add_f32_dpp v8, v8, v8 quad_perm:[2,3,0,1] row_mask:0xf bank_mask:0xf
	s_nop 1
	v_add_f32_dpp v8, v8, v8 row_ror:4 row_mask:0xf bank_mask:0xf
	s_nop 1
	v_add_f32_dpp v8, v8, v8 row_ror:8 row_mask:0xf bank_mask:0xf
	s_nop 1
	v_readlane_b32 s42, v8, 0
	v_readlane_b32 s43, v8, 16
	v_readlane_b32 s44, v8, 32
	v_readlane_b32 s45, v8, 48
	s_nop 1
	v_mov_b32_e32 v8, s42
	v_add_f32_e32 v8, s43, v8
	v_add_f32_e32 v8, s44, v8
	v_add_f32_e32 v8, s45, v8
	v_mov_b32_e32 v4, s41
	v_fmac_f32_e32 v4, s40, v8
	v_rsq_f32_e32 v4, v4
	s_nop 0
	v_mov_b32_e32 v5, v4
	s_waitcnt vmcnt(0)
	v_pk_mul_f32 v[10:11], v[66:67], v[4:5]
	v_pk_mul_f32 v[10:11], v[10:11], v[130:131]
	v_pk_add_f32 v[12:13], v[196:197], v[6:7]
	v_pk_fma_f32 v[14:15], v[10:11], v[12:13], v[164:165]
	v_pk_mul_f32 v[10:11], v[68:69], v[4:5]
	v_pk_mul_f32 v[10:11], v[10:11], v[132:133]
	v_pk_add_f32 v[12:13], v[198:199], v[6:7]
	v_pk_fma_f32 v[16:17], v[10:11], v[12:13], v[166:167]
	v_cvt_pk_bf16_f32 v26, v14, v15
	v_cvt_pk_bf16_f32 v27, v16, v17
	global_store_dwordx2 v2, v[26:27], s[26:27]
	v_pk_mul_f32 v[10:11], v[70:71], v[4:5]
	v_pk_mul_f32 v[10:11], v[10:11], v[134:135]
	v_pk_add_f32 v[12:13], v[200:201], v[6:7]
	v_pk_fma_f32 v[14:15], v[10:11], v[12:13], v[168:169]
	v_pk_mul_f32 v[10:11], v[72:73], v[4:5]
	v_pk_mul_f32 v[10:11], v[10:11], v[136:137]
	v_pk_add_f32 v[12:13], v[202:203], v[6:7]
	v_pk_fma_f32 v[16:17], v[10:11], v[12:13], v[170:171]
	v_cvt_pk_bf16_f32 v28, v14, v15
	v_cvt_pk_bf16_f32 v29, v16, v17
	global_store_dwordx2 v2, v[28:29], s[26:27] offset:512
	v_pk_mul_f32 v[10:11], v[74:75], v[4:5]
	v_pk_mul_f32 v[10:11], v[10:11], v[138:139]
	v_pk_add_f32 v[12:13], v[204:205], v[6:7]
	v_pk_fma_f32 v[14:15], v[10:11], v[12:13], v[172:173]
	v_pk_mul_f32 v[10:11], v[76:77], v[4:5]
	v_pk_mul_f32 v[10:11], v[10:11], v[140:141]
	v_pk_add_f32 v[12:13], v[206:207], v[6:7]
	v_pk_fma_f32 v[16:17], v[10:11], v[12:13], v[174:175]
	v_cvt_pk_bf16_f32 v30, v14, v15
	v_cvt_pk_bf16_f32 v31, v16, v17
	global_store_dwordx2 v2, v[30:31], s[26:27] offset:1024
	v_pk_mul_f32 v[10:11], v[78:79], v[4:5]
	v_pk_mul_f32 v[10:11], v[10:11], v[142:143]
	v_pk_add_f32 v[12:13], v[208:209], v[6:7]
	v_pk_fma_f32 v[14:15], v[10:11], v[12:13], v[176:177]
	v_pk_mul_f32 v[10:11], v[80:81], v[4:5]
	v_pk_mul_f32 v[10:11], v[10:11], v[144:145]
	v_pk_add_f32 v[12:13], v[210:211], v[6:7]
	v_pk_fma_f32 v[16:17], v[10:11], v[12:13], v[178:179]
	v_cvt_pk_bf16_f32 v32, v14, v15
	v_cvt_pk_bf16_f32 v33, v16, v17
	global_store_dwordx2 v2, v[32:33], s[26:27] offset:1536
	v_pk_mul_f32 v[10:11], v[82:83], v[4:5]
	v_pk_mul_f32 v[10:11], v[10:11], v[146:147]
	v_pk_add_f32 v[12:13], v[212:213], v[6:7]
	v_pk_fma_f32 v[14:15], v[10:11], v[12:13], v[180:181]
	v_pk_mul_f32 v[10:11], v[84:85], v[4:5]
	v_pk_mul_f32 v[10:11], v[10:11], v[148:149]
	v_pk_add_f32 v[12:13], v[214:215], v[6:7]
	v_pk_fma_f32 v[16:17], v[10:11], v[12:13], v[182:183]
	v_cvt_pk_bf16_f32 v26, v14, v15
	v_cvt_pk_bf16_f32 v27, v16, v17
	global_store_dwordx2 v2, v[26:27], s[26:27] offset:2048
	v_pk_mul_f32 v[10:11], v[86:87], v[4:5]
	v_pk_mul_f32 v[10:11], v[10:11], v[150:151]
	v_pk_add_f32 v[12:13], v[216:217], v[6:7]
	v_pk_fma_f32 v[14:15], v[10:11], v[12:13], v[184:185]
	v_pk_mul_f32 v[10:11], v[88:89], v[4:5]
	v_pk_mul_f32 v[10:11], v[10:11], v[152:153]
	v_pk_add_f32 v[12:13], v[218:219], v[6:7]
	v_pk_fma_f32 v[16:17], v[10:11], v[12:13], v[186:187]
	v_cvt_pk_bf16_f32 v28, v14, v15
	v_cvt_pk_bf16_f32 v29, v16, v17
	global_store_dwordx2 v2, v[28:29], s[26:27] offset:2560
	v_pk_mul_f32 v[10:11], v[90:91], v[4:5]
	v_pk_mul_f32 v[10:11], v[10:11], v[156:157]
	v_pk_add_f32 v[12:13], v[220:221], v[6:7]
	v_pk_fma_f32 v[14:15], v[10:11], v[12:13], v[188:189]
	v_pk_mul_f32 v[10:11], v[92:93], v[4:5]
	v_pk_mul_f32 v[10:11], v[10:11], v[158:159]
	v_pk_add_f32 v[12:13], v[222:223], v[6:7]
	v_pk_fma_f32 v[16:17], v[10:11], v[12:13], v[190:191]
	v_cvt_pk_bf16_f32 v30, v14, v15
	v_cvt_pk_bf16_f32 v31, v16, v17
	global_store_dwordx2 v2, v[30:31], s[26:27] offset:3072
	v_pk_mul_f32 v[10:11], v[94:95], v[4:5]
	v_pk_mul_f32 v[10:11], v[10:11], v[160:161]
	v_pk_add_f32 v[12:13], v[224:225], v[6:7]
	v_pk_fma_f32 v[14:15], v[10:11], v[12:13], v[192:193]
	v_pk_mul_f32 v[10:11], v[96:97], v[4:5]
	v_pk_mul_f32 v[10:11], v[10:11], v[162:163]
	v_pk_add_f32 v[12:13], v[226:227], v[6:7]
	v_pk_fma_f32 v[16:17], v[10:11], v[12:13], v[194:195]
	v_cvt_pk_bf16_f32 v32, v14, v15
	v_cvt_pk_bf16_f32 v33, v16, v17
	global_store_dwordx2 v2, v[32:33], s[26:27] offset:3584
	s_waitcnt vmcnt(0)
	s_branch .LBB0_1498

.LBB0_2326:
.LBB0_2327:
	s_waitcnt vmcnt(0) lgkmcnt(0)
	s_load_dwordx2 s[0:1], s[92:93], 0x40
	s_load_dwordx2 s[2:3], s[92:93], 0x48
	s_load_dwordx2 s[4:5], s[92:93], 0xf0
	v_and_b32_e32 v2, 63, v154
	v_lshlrev_b32_e32 v1, 4, v2
	v_lshlrev_b32_e32 v2, 3, v2
	v_mov_b32_e32 v6, 1.0
	v_mov_b32_e32 v7, 1.0
	s_mov_b32 s40, 0x3a000000
	s_mov_b32 s41, 0x358637bd
	v_readfirstlane_b32 s10, v154
	s_lshr_b32 s10, s10, 6
	s_lshl_b32 s12, s96, 3
	s_add_u32 s10, s10, s12
	s_waitcnt lgkmcnt(0)
	s_add_u32 s0, s0, 0x2000
	s_addc_u32 s1, s1, 0
	s_add_u32 s2, s2, 0x2000
	s_addc_u32 s3, s3, 0
	s_add_u32 s12, s10, 0
	s_lshl_b32 s13, s12, 13
	s_lshl_b32 s14, s12, 12
	s_add_u32 s20, s4, s13
	s_addc_u32 s21, s5, 0
	s_add_u32 s22, s90, 0x21918000
	s_addc_u32 s23, s91, 0
	s_add_u32 s22, s22, s14
	s_addc_u32 s23, s23, 0
	global_load_dwordx2 v[98:99], v2, s[22:23] nt
	global_load_dwordx2 v[100:101], v2, s[22:23] offset:512 nt
	global_load_dwordx2 v[102:103], v2, s[22:23] offset:1024 nt
	global_load_dwordx2 v[104:105], v2, s[22:23] offset:1536 nt
	global_load_dwordx2 v[106:107], v2, s[22:23] offset:2048 nt
	global_load_dwordx2 v[108:109], v2, s[22:23] offset:2560 nt
	global_load_dwordx2 v[110:111], v2, s[22:23] offset:3072 nt
	global_load_dwordx2 v[112:113], v2, s[22:23] offset:3584 nt
	s_add_u32 s36, s20, 0x1000
	s_addc_u32 s37, s21, 0
	global_load_dwordx4 v[34:37], v1, s[20:21] nt
	global_load_dwordx4 v[38:41], v1, s[20:21] offset:1024 nt
	global_load_dwordx4 v[42:45], v1, s[20:21] offset:2048 nt
	global_load_dwordx4 v[46:49], v1, s[20:21] offset:3072 nt
	global_load_dwordx4 v[50:53], v1, s[36:37] nt
	global_load_dwordx4 v[54:57], v1, s[36:37] offset:1024 nt
	global_load_dwordx4 v[58:61], v1, s[36:37] offset:2048 nt
	global_load_dwordx4 v[62:65], v1, s[36:37] offset:3072 nt
	s_mov_b32 s16, 4
	s_add_u32 s17, s16, 5
	s_mul_i32 s17, s17, 49152
	s_add_u32 s17, s17, 0x10404000
	s_add_u32 s28, s90, s17
	s_addc_u32 s29, s91, 0
	s_add_u32 s17, s16, 5
	s_mul_i32 s17, s17, 49152
	s_add_u32 s17, s17, 0x10406000
	s_add_u32 s30, s90, s17
	s_addc_u32 s31, s91, 0
	s_add_u32 s32, s30, 0x2000
	s_addc_u32 s33, s31, 0
	s_add_u32 s18, s0, 0x1000
	s_addc_u32 s19, s1, 0
	global_load_dwordx4 v[130:133], v1, s[0:1]
	global_load_dwordx4 v[134:137], v1, s[0:1] offset:1024
	global_load_dwordx4 v[138:141], v1, s[0:1] offset:2048
	global_load_dwordx4 v[142:145], v1, s[0:1] offset:3072
	global_load_dwordx4 v[146:149], v1, s[18:19]
	global_load_dwordx4 v[150:153], v1, s[18:19] offset:1024
	global_load_dwordx4 v[156:159], v1, s[18:19] offset:2048
	global_load_dwordx4 v[160:163], v1, s[18:19] offset:3072
	s_add_u32 s18, s28, 0x1000
	s_addc_u32 s19, s29, 0
	global_load_dwordx4 v[164:167], v1, s[28:29]
	global_load_dwordx4 v[168:171], v1, s[28:29] offset:1024
	global_load_dwordx4 v[172:175], v1, s[28:29] offset:2048
	global_load_dwordx4 v[176:179], v1, s[28:29] offset:3072
	global_load_dwordx4 v[180:183], v1, s[18:19]
	global_load_dwordx4 v[184:187], v1, s[18:19] offset:1024
	global_load_dwordx4 v[188:191], v1, s[18:19] offset:2048
	global_load_dwordx4 v[192:195], v1, s[18:19] offset:3072
	s_add_u32 s12, s10, 2048
	s_lshl_b32 s13, s12, 13
	s_lshl_b32 s14, s12, 12
	s_add_u32 s20, s4, s13
	s_addc_u32 s21, s5, 0
	s_add_u32 s22, s90, 0x21918000
	s_addc_u32 s23, s91, 0
	s_add_u32 s22, s22, s14
	s_addc_u32 s23, s23, 0
	global_load_dwordx2 v[114:115], v2, s[22:23] nt
	global_load_dwordx2 v[116:117], v2, s[22:23] offset:512 nt
	global_load_dwordx2 v[118:119], v2, s[22:23] offset:1024 nt
	global_load_dwordx2 v[120:121], v2, s[22:23] offset:1536 nt
	global_load_dwordx2 v[122:123], v2, s[22:23] offset:2048 nt
	global_load_dwordx2 v[124:125], v2, s[22:23] offset:2560 nt
	global_load_dwordx2 v[126:127], v2, s[22:23] offset:3072 nt
	global_load_dwordx2 v[128:129], v2, s[22:23] offset:3584 nt
	s_add_u32 s36, s20, 0x1000
	s_addc_u32 s37, s21, 0
	global_load_dwordx4 v[66:69], v1, s[20:21] nt
	global_load_dwordx4 v[70:73], v1, s[20:21] offset:1024 nt
	global_load_dwordx4 v[74:77], v1, s[20:21] offset:2048 nt
	global_load_dwordx4 v[78:81], v1, s[20:21] offset:3072 nt
	global_load_dwordx4 v[82:85], v1, s[36:37] nt
	global_load_dwordx4 v[86:89], v1, s[36:37] offset:1024 nt
	global_load_dwordx4 v[90:93], v1, s[36:37] offset:2048 nt
	global_load_dwordx4 v[94:97], v1, s[36:37] offset:3072 nt
	s_add_u32 s12, s10, 0
	s_lshl_b32 s13, s12, 13
	s_lshl_b32 s14, s12, 12
	s_add_u32 s24, s4, s13
	s_addc_u32 s25, s5, 0
	s_add_u32 s34, s24, 0x1000
	s_addc_u32 s35, s25, 0
	s_add_u32 s26, s90, 0x11918000
	s_addc_u32 s27, s91, 0
	s_add_u32 s26, s26, s14
	s_addc_u32 s27, s27, 0
	s_waitcnt vmcnt(40)
	v_mov_b32_e32 v8, 0
	v_lshlrev_b32_e32 v10, 16, v98
	v_and_b32_e32 v11, 0xffff0000, v98
	v_fmac_f32_e32 v8, v10, v10
	v_fmac_f32_e32 v8, v11, v11
	v_lshlrev_b32_e32 v10, 16, v99
	v_and_b32_e32 v11, 0xffff0000, v99
	v_fmac_f32_e32 v8, v10, v10
	v_fmac_f32_e32 v8, v11, v11
	v_lshlrev_b32_e32 v10, 16, v100
	v_and_b32_e32 v11, 0xffff0000, v100
	v_fmac_f32_e32 v8, v10, v10
	v_fmac_f32_e32 v8, v11, v11
	v_lshlrev_b32_e32 v10, 16, v101
	v_and_b32_e32 v11, 0xffff0000, v101
	v_fmac_f32_e32 v8, v10, v10
	v_fmac_f32_e32 v8, v11, v11
	v_lshlrev_b32_e32 v10, 16, v102
	v_and_b32_e32 v11, 0xffff0000, v102
	v_fmac_f32_e32 v8, v10, v10
	v_fmac_f32_e32 v8, v11, v11
	v_lshlrev_b32_e32 v10, 16, v103
	v_and_b32_e32 v11, 0xffff0000, v103
	v_fmac_f32_e32 v8, v10, v10
	v_fmac_f32_e32 v8, v11, v11
	v_lshlrev_b32_e32 v10, 16, v104
	v_and_b32_e32 v11, 0xffff0000, v104
	v_fmac_f32_e32 v8, v10, v10
	v_fmac_f32_e32 v8, v11, v11
	v_lshlrev_b32_e32 v10, 16, v105
	v_and_b32_e32 v11, 0xffff0000, v105
	v_fmac_f32_e32 v8, v10, v10
	v_fmac_f32_e32 v8, v11, v11
	v_lshlrev_b32_e32 v10, 16, v106
	v_and_b32_e32 v11, 0xffff0000, v106
	v_fmac_f32_e32 v8, v10, v10
	v_fmac_f32_e32 v8, v11, v11
	v_lshlrev_b32_e32 v10, 16, v107
	v_and_b32_e32 v11, 0xffff0000, v107
	v_fmac_f32_e32 v8, v10, v10
	v_fmac_f32_e32 v8, v11, v11
	v_lshlrev_b32_e32 v10, 16, v108
	v_and_b32_e32 v11, 0xffff0000, v108
	v_fmac_f32_e32 v8, v10, v10
	v_fmac_f32_e32 v8, v11, v11
	v_lshlrev_b32_e32 v10, 16, v109
	v_and_b32_e32 v11, 0xffff0000, v109
	v_fmac_f32_e32 v8, v10, v10
	v_fmac_f32_e32 v8, v11, v11
	v_lshlrev_b32_e32 v10, 16, v110
	v_and_b32_e32 v11, 0xffff0000, v110
	v_fmac_f32_e32 v8, v10, v10
	v_fmac_f32_e32 v8, v11, v11
	v_lshlrev_b32_e32 v10, 16, v111
	v_and_b32_e32 v11, 0xffff0000, v111
	v_fmac_f32_e32 v8, v10, v10
	v_fmac_f32_e32 v8, v11, v11
	v_lshlrev_b32_e32 v10, 16, v112
	v_and_b32_e32 v11, 0xffff0000, v112
	v_fmac_f32_e32 v8, v10, v10
	v_fmac_f32_e32 v8, v11, v11
	v_lshlrev_b32_e32 v10, 16, v113
	v_and_b32_e32 v11, 0xffff0000, v113
	v_fmac_f32_e32 v8, v10, v10
	v_fmac_f32_e32 v8, v11, v11
	s_nop 1
	v_add_f32_dpp v8, v8, v8 quad_perm:[1,0,3,2] row_mask:0xf bank_mask:0xf
	s_nop 1
	v_add_f32_dpp v8, v8, v8 quad_perm:[2,3,0,1] row_mask:0xf bank_mask:0xf
	s_nop 1
	v_add_f32_dpp v8, v8, v8 row_ror:4 row_mask:0xf bank_mask:0xf
	s_nop 1
	v_add_f32_dpp v8, v8, v8 row_ror:8 row_mask:0xf bank_mask:0xf
	s_nop 1
	v_readlane_b32 s42, v8, 0
	v_readlane_b32 s43, v8, 16
	v_readlane_b32 s44, v8, 32
	v_readlane_b32 s45, v8, 48
	s_nop 1
	v_mov_b32_e32 v8, s42
	v_add_f32_e32 v8, s43, v8
	v_add_f32_e32 v8, s44, v8
	v_add_f32_e32 v8, s45, v8
	v_mov_b32_e32 v4, s41
	v_fmac_f32_e32 v4, s40, v8
	v_rsq_f32_e32 v4, v4
	s_nop 0
	v_mov_b32_e32 v5, v4
	s_waitcnt vmcnt(32)
	s_waitcnt vmcnt(16)
	v_mov_b32_e32 v8, 0
	v_lshlrev_b32_e32 v10, 16, v98
	v_and_b32_e32 v11, 0xffff0000, v98
	v_pk_mul_f32 v[10:11], v[10:11], v[4:5]
	v_pk_mul_f32 v[10:11], v[10:11], v[130:131]
	v_pk_fma_f32 v[34:35], v[164:165], v[10:11], v[34:35]
	v_lshlrev_b32_e32 v10, 16, v99
	v_and_b32_e32 v11, 0xffff0000, v99
	v_pk_mul_f32 v[10:11], v[10:11], v[4:5]
	v_pk_mul_f32 v[10:11], v[10:11], v[132:133]
	v_pk_fma_f32 v[36:37], v[166:167], v[10:11], v[36:37]
	global_store_dwordx4 v1, v[34:37], s[24:25] nt
	v_fmac_f32_e32 v8, v34, v34
	v_fmac_f32_e32 v8, v35, v35
	v_fmac_f32_e32 v8, v36, v36
	v_fmac_f32_e32 v8, v37, v37
	v_lshlrev_b32_e32 v10, 16, v100
	v_and_b32_e32 v11, 0xffff0000, v100
	v_pk_mul_f32 v[10:11], v[10:11], v[4:5]
	v_pk_mul_f32 v[10:11], v[10:11], v[134:135]
	v_pk_fma_f32 v[38:39], v[168:169], v[10:11], v[38:39]
	v_lshlrev_b32_e32 v10, 16, v101
	v_and_b32_e32 v11, 0xffff0000, v101
	v_pk_mul_f32 v[10:11], v[10:11], v[4:5]
	v_pk_mul_f32 v[10:11], v[10:11], v[136:137]
	v_pk_fma_f32 v[40:41], v[170:171], v[10:11], v[40:41]
	global_store_dwordx4 v1, v[38:41], s[24:25] offset:1024 nt
	v_fmac_f32_e32 v8, v38, v38
	v_fmac_f32_e32 v8, v39, v39
	v_fmac_f32_e32 v8, v40, v40
	v_fmac_f32_e32 v8, v41, v41
	v_lshlrev_b32_e32 v10, 16, v102
	v_and_b32_e32 v11, 0xffff0000, v102
	v_pk_mul_f32 v[10:11], v[10:11], v[4:5]
	v_pk_mul_f32 v[10:11], v[10:11], v[138:139]
	v_pk_fma_f32 v[42:43], v[172:173], v[10:11], v[42:43]
	v_lshlrev_b32_e32 v10, 16, v103
	v_and_b32_e32 v11, 0xffff0000, v103
	v_pk_mul_f32 v[10:11], v[10:11], v[4:5]
	v_pk_mul_f32 v[10:11], v[10:11], v[140:141]
	v_pk_fma_f32 v[44:45], v[174:175], v[10:11], v[44:45]
	global_store_dwordx4 v1, v[42:45], s[24:25] offset:2048 nt
	v_fmac_f32_e32 v8, v42, v42
	v_fmac_f32_e32 v8, v43, v43
	v_fmac_f32_e32 v8, v44, v44
	v_fmac_f32_e32 v8, v45, v45
	v_lshlrev_b32_e32 v10, 16, v104
	v_and_b32_e32 v11, 0xffff0000, v104
	v_pk_mul_f32 v[10:11], v[10:11], v[4:5]
	v_pk_mul_f32 v[10:11], v[10:11], v[142:143]
	v_pk_fma_f32 v[46:47], v[176:177], v[10:11], v[46:47]
	v_lshlrev_b32_e32 v10, 16, v105
	v_and_b32_e32 v11, 0xffff0000, v105
	v_pk_mul_f32 v[10:11], v[10:11], v[4:5]
	v_pk_mul_f32 v[10:11], v[10:11], v[144:145]
	v_pk_fma_f32 v[48:49], v[178:179], v[10:11], v[48:49]
	global_store_dwordx4 v1, v[46:49], s[24:25] offset:3072 nt
	v_fmac_f32_e32 v8, v46, v46
	v_fmac_f32_e32 v8, v47, v47
	v_fmac_f32_e32 v8, v48, v48
	v_fmac_f32_e32 v8, v49, v49
	v_lshlrev_b32_e32 v10, 16, v106
	v_and_b32_e32 v11, 0xffff0000, v106
	v_pk_mul_f32 v[10:11], v[10:11], v[4:5]
	v_pk_mul_f32 v[10:11], v[10:11], v[146:147]
	v_pk_fma_f32 v[50:51], v[180:181], v[10:11], v[50:51]
	v_lshlrev_b32_e32 v10, 16, v107
	v_and_b32_e32 v11, 0xffff0000, v107
	v_pk_mul_f32 v[10:11], v[10:11], v[4:5]
	v_pk_mul_f32 v[10:11], v[10:11], v[148:149]
	v_pk_fma_f32 v[52:53], v[182:183], v[10:11], v[52:53]
	global_store_dwordx4 v1, v[50:53], s[34:35] nt
	v_fmac_f32_e32 v8, v50, v50
	v_fmac_f32_e32 v8, v51, v51
	v_fmac_f32_e32 v8, v52, v52
	v_fmac_f32_e32 v8, v53, v53
	v_lshlrev_b32_e32 v10, 16, v108
	v_and_b32_e32 v11, 0xffff0000, v108
	v_pk_mul_f32 v[10:11], v[10:11], v[4:5]
	v_pk_mul_f32 v[10:11], v[10:11], v[150:151]
	v_pk_fma_f32 v[54:55], v[184:185], v[10:11], v[54:55]
	v_lshlrev_b32_e32 v10, 16, v109
	v_and_b32_e32 v11, 0xffff0000, v109
	v_pk_mul_f32 v[10:11], v[10:11], v[4:5]
	v_pk_mul_f32 v[10:11], v[10:11], v[152:153]
	v_pk_fma_f32 v[56:57], v[186:187], v[10:11], v[56:57]
	global_store_dwordx4 v1, v[54:57], s[34:35] offset:1024 nt
	v_fmac_f32_e32 v8, v54, v54
	v_fmac_f32_e32 v8, v55, v55
	v_fmac_f32_e32 v8, v56, v56
	v_fmac_f32_e32 v8, v57, v57
	v_lshlrev_b32_e32 v10, 16, v110
	v_and_b32_e32 v11, 0xffff0000, v110
	v_pk_mul_f32 v[10:11], v[10:11], v[4:5]
	v_pk_mul_f32 v[10:11], v[10:11], v[156:157]
	v_pk_fma_f32 v[58:59], v[188:189], v[10:11], v[58:59]
	v_lshlrev_b32_e32 v10, 16, v111
	v_and_b32_e32 v11, 0xffff0000, v111
	v_pk_mul_f32 v[10:11], v[10:11], v[4:5]
	v_pk_mul_f32 v[10:11], v[10:11], v[158:159]
	v_pk_fma_f32 v[60:61], v[190:191], v[10:11], v[60:61]
	global_store_dwordx4 v1, v[58:61], s[34:35] offset:2048 nt
	v_fmac_f32_e32 v8, v58, v58
	v_fmac_f32_e32 v8, v59, v59
	v_fmac_f32_e32 v8, v60, v60
	v_fmac_f32_e32 v8, v61, v61
	v_lshlrev_b32_e32 v10, 16, v112
	v_and_b32_e32 v11, 0xffff0000, v112
	v_pk_mul_f32 v[10:11], v[10:11], v[4:5]
	v_pk_mul_f32 v[10:11], v[10:11], v[160:161]
	v_pk_fma_f32 v[62:63], v[192:193], v[10:11], v[62:63]
	v_lshlrev_b32_e32 v10, 16, v113
	v_and_b32_e32 v11, 0xffff0000, v113
	v_pk_mul_f32 v[10:11], v[10:11], v[4:5]
	v_pk_mul_f32 v[10:11], v[10:11], v[162:163]
	v_pk_fma_f32 v[64:65], v[194:195], v[10:11], v[64:65]
	global_store_dwordx4 v1, v[62:65], s[34:35] offset:3072 nt
	v_fmac_f32_e32 v8, v62, v62
	v_fmac_f32_e32 v8, v63, v63
	v_fmac_f32_e32 v8, v64, v64
	v_fmac_f32_e32 v8, v65, v65
	s_add_u32 s18, s2, 0x1000
	s_addc_u32 s19, s3, 0
	global_load_dwordx4 v[130:133], v1, s[2:3]
	global_load_dwordx4 v[134:137], v1, s[2:3] offset:1024
	global_load_dwordx4 v[138:141], v1, s[2:3] offset:2048
	global_load_dwordx4 v[142:145], v1, s[2:3] offset:3072
	global_load_dwordx4 v[146:149], v1, s[18:19]
	global_load_dwordx4 v[150:153], v1, s[18:19] offset:1024
	global_load_dwordx4 v[156:159], v1, s[18:19] offset:2048
	global_load_dwordx4 v[160:163], v1, s[18:19] offset:3072
	s_add_u32 s18, s30, 0x1000
	s_addc_u32 s19, s31, 0
	global_load_dwordx4 v[164:167], v1, s[30:31]
	global_load_dwordx4 v[168:171], v1, s[30:31] offset:1024
	global_load_dwordx4 v[172:175], v1, s[30:31] offset:2048
	global_load_dwordx4 v[176:179], v1, s[30:31] offset:3072
	global_load_dwordx4 v[180:183], v1, s[18:19]
	global_load_dwordx4 v[184:187], v1, s[18:19] offset:1024
	global_load_dwordx4 v[188:191], v1, s[18:19] offset:2048
	global_load_dwordx4 v[192:195], v1, s[18:19] offset:3072
	s_add_u32 s18, s32, 0x1000
	s_addc_u32 s19, s33, 0
	global_load_dwordx4 v[196:199], v1, s[32:33]
	global_load_dwordx4 v[200:203], v1, s[32:33] offset:1024
	global_load_dwordx4 v[204:207], v1, s[32:33] offset:2048
	global_load_dwordx4 v[208:211], v1, s[32:33] offset:3072
	global_load_dwordx4 v[212:215], v1, s[18:19]
	global_load_dwordx4 v[216:219], v1, s[18:19] offset:1024
	global_load_dwordx4 v[220:223], v1, s[18:19] offset:2048
	global_load_dwordx4 v[224:227], v1, s[18:19] offset:3072
	s_nop 1
	v_add_f32_dpp v8, v8, v8 quad_perm:[1,0,3,2] row_mask:0xf bank_mask:0xf
	s_nop 1
	v_add_f32_dpp v8, v8, v8 quad_perm:[2,3,0,1] row_mask:0xf bank_mask:0xf
	s_nop 1
	v_add_f32_dpp v8, v8, v8 row_ror:4 row_mask:0xf bank_mask:0xf
	s_nop 1
	v_add_f32_dpp v8, v8, v8 row_ror:8 row_mask:0xf bank_mask:0xf
	s_nop 1
	v_readlane_b32 s42, v8, 0
	v_readlane_b32 s43, v8, 16
	v_readlane_b32 s44, v8, 32
	v_readlane_b32 s45, v8, 48
	s_nop 1
	v_mov_b32_e32 v8, s42
	v_add_f32_e32 v8, s43, v8
	v_add_f32_e32 v8, s44, v8
	v_add_f32_e32 v8, s45, v8
	v_mov_b32_e32 v4, s41
	v_fmac_f32_e32 v4, s40, v8
	v_rsq_f32_e32 v4, v4
	s_nop 0
	v_mov_b32_e32 v5, v4
	s_waitcnt vmcnt(0)
	v_pk_mul_f32 v[10:11], v[34:35], v[4:5]
	v_pk_mul_f32 v[10:11], v[10:11], v[130:131]
	v_pk_add_f32 v[12:13], v[196:197], v[6:7]
	v_pk_fma_f32 v[14:15], v[10:11], v[12:13], v[164:165]
	v_pk_mul_f32 v[10:11], v[36:37], v[4:5]
	v_pk_mul_f32 v[10:11], v[10:11], v[132:133]
	v_pk_add_f32 v[12:13], v[198:199], v[6:7]
	v_pk_fma_f32 v[16:17], v[10:11], v[12:13], v[166:167]
	v_cvt_pk_bf16_f32 v26, v14, v15
	v_cvt_pk_bf16_f32 v27, v16, v17
	global_store_dwordx2 v2, v[26:27], s[26:27]
	v_pk_mul_f32 v[10:11], v[38:39], v[4:5]
	v_pk_mul_f32 v[10:11], v[10:11], v[134:135]
	v_pk_add_f32 v[12:13], v[200:201], v[6:7]
	v_pk_fma_f32 v[14:15], v[10:11], v[12:13], v[168:169]
	v_pk_mul_f32 v[10:11], v[40:41], v[4:5]
	v_pk_mul_f32 v[10:11], v[10:11], v[136:137]
	v_pk_add_f32 v[12:13], v[202:203], v[6:7]
	v_pk_fma_f32 v[16:17], v[10:11], v[12:13], v[170:171]
	v_cvt_pk_bf16_f32 v28, v14, v15
	v_cvt_pk_bf16_f32 v29, v16, v17
	global_store_dwordx2 v2, v[28:29], s[26:27] offset:512
	v_pk_mul_f32 v[10:11], v[42:43], v[4:5]
	v_pk_mul_f32 v[10:11], v[10:11], v[138:139]
	v_pk_add_f32 v[12:13], v[204:205], v[6:7]
	v_pk_fma_f32 v[14:15], v[10:11], v[12:13], v[172:173]
	v_pk_mul_f32 v[10:11], v[44:45], v[4:5]
	v_pk_mul_f32 v[10:11], v[10:11], v[140:141]
	v_pk_add_f32 v[12:13], v[206:207], v[6:7]
	v_pk_fma_f32 v[16:17], v[10:11], v[12:13], v[174:175]
	v_cvt_pk_bf16_f32 v30, v14, v15
	v_cvt_pk_bf16_f32 v31, v16, v17
	global_store_dwordx2 v2, v[30:31], s[26:27] offset:1024
	v_pk_mul_f32 v[10:11], v[46:47], v[4:5]
	v_pk_mul_f32 v[10:11], v[10:11], v[142:143]
	v_pk_add_f32 v[12:13], v[208:209], v[6:7]
	v_pk_fma_f32 v[14:15], v[10:11], v[12:13], v[176:177]
	v_pk_mul_f32 v[10:11], v[48:49], v[4:5]
	v_pk_mul_f32 v[10:11], v[10:11], v[144:145]
	v_pk_add_f32 v[12:13], v[210:211], v[6:7]
	v_pk_fma_f32 v[16:17], v[10:11], v[12:13], v[178:179]
	v_cvt_pk_bf16_f32 v32, v14, v15
	v_cvt_pk_bf16_f32 v33, v16, v17
	global_store_dwordx2 v2, v[32:33], s[26:27] offset:1536
	v_pk_mul_f32 v[10:11], v[50:51], v[4:5]
	v_pk_mul_f32 v[10:11], v[10:11], v[146:147]
	v_pk_add_f32 v[12:13], v[212:213], v[6:7]
	v_pk_fma_f32 v[14:15], v[10:11], v[12:13], v[180:181]
	v_pk_mul_f32 v[10:11], v[52:53], v[4:5]
	v_pk_mul_f32 v[10:11], v[10:11], v[148:149]
	v_pk_add_f32 v[12:13], v[214:215], v[6:7]
	v_pk_fma_f32 v[16:17], v[10:11], v[12:13], v[182:183]
	v_cvt_pk_bf16_f32 v26, v14, v15
	v_cvt_pk_bf16_f32 v27, v16, v17
	global_store_dwordx2 v2, v[26:27], s[26:27] offset:2048
	v_pk_mul_f32 v[10:11], v[54:55], v[4:5]
	v_pk_mul_f32 v[10:11], v[10:11], v[150:151]
	v_pk_add_f32 v[12:13], v[216:217], v[6:7]
	v_pk_fma_f32 v[14:15], v[10:11], v[12:13], v[184:185]
	v_pk_mul_f32 v[10:11], v[56:57], v[4:5]
	v_pk_mul_f32 v[10:11], v[10:11], v[152:153]
	v_pk_add_f32 v[12:13], v[218:219], v[6:7]
	v_pk_fma_f32 v[16:17], v[10:11], v[12:13], v[186:187]
	v_cvt_pk_bf16_f32 v28, v14, v15
	v_cvt_pk_bf16_f32 v29, v16, v17
	global_store_dwordx2 v2, v[28:29], s[26:27] offset:2560
	v_pk_mul_f32 v[10:11], v[58:59], v[4:5]
	v_pk_mul_f32 v[10:11], v[10:11], v[156:157]
	v_pk_add_f32 v[12:13], v[220:221], v[6:7]
	v_pk_fma_f32 v[14:15], v[10:11], v[12:13], v[188:189]
	v_pk_mul_f32 v[10:11], v[60:61], v[4:5]
	v_pk_mul_f32 v[10:11], v[10:11], v[158:159]
	v_pk_add_f32 v[12:13], v[222:223], v[6:7]
	v_pk_fma_f32 v[16:17], v[10:11], v[12:13], v[190:191]
	v_cvt_pk_bf16_f32 v30, v14, v15
	v_cvt_pk_bf16_f32 v31, v16, v17
	global_store_dwordx2 v2, v[30:31], s[26:27] offset:3072
	v_pk_mul_f32 v[10:11], v[62:63], v[4:5]
	v_pk_mul_f32 v[10:11], v[10:11], v[160:161]
	v_pk_add_f32 v[12:13], v[224:225], v[6:7]
	v_pk_fma_f32 v[14:15], v[10:11], v[12:13], v[192:193]
	v_pk_mul_f32 v[10:11], v[64:65], v[4:5]
	v_pk_mul_f32 v[10:11], v[10:11], v[162:163]
	v_pk_add_f32 v[12:13], v[226:227], v[6:7]
	v_pk_fma_f32 v[16:17], v[10:11], v[12:13], v[194:195]
	v_cvt_pk_bf16_f32 v32, v14, v15
	v_cvt_pk_bf16_f32 v33, v16, v17
	global_store_dwordx2 v2, v[32:33], s[26:27] offset:3584
	s_mov_b32 s16, 4
	s_add_u32 s17, s16, 5
	s_mul_i32 s17, s17, 49152
	s_add_u32 s17, s17, 0x10404000
	s_add_u32 s28, s90, s17
	s_addc_u32 s29, s91, 0
	s_add_u32 s17, s16, 5
	s_mul_i32 s17, s17, 49152
	s_add_u32 s17, s17, 0x10406000
	s_add_u32 s30, s90, s17
	s_addc_u32 s31, s91, 0
	s_add_u32 s32, s30, 0x2000
	s_addc_u32 s33, s31, 0
	s_add_u32 s18, s0, 0x1000
	s_addc_u32 s19, s1, 0
	global_load_dwordx4 v[130:133], v1, s[0:1]
	global_load_dwordx4 v[134:137], v1, s[0:1] offset:1024
	global_load_dwordx4 v[138:141], v1, s[0:1] offset:2048
	global_load_dwordx4 v[142:145], v1, s[0:1] offset:3072
	global_load_dwordx4 v[146:149], v1, s[18:19]
	global_load_dwordx4 v[150:153], v1, s[18:19] offset:1024
	global_load_dwordx4 v[156:159], v1, s[18:19] offset:2048
	global_load_dwordx4 v[160:163], v1, s[18:19] offset:3072
	s_add_u32 s18, s28, 0x1000
	s_addc_u32 s19, s29, 0
	global_load_dwordx4 v[164:167], v1, s[28:29]
	global_load_dwordx4 v[168:171], v1, s[28:29] offset:1024
	global_load_dwordx4 v[172:175], v1, s[28:29] offset:2048
	global_load_dwordx4 v[176:179], v1, s[28:29] offset:3072
	global_load_dwordx4 v[180:183], v1, s[18:19]
	global_load_dwordx4 v[184:187], v1, s[18:19] offset:1024
	global_load_dwordx4 v[188:191], v1, s[18:19] offset:2048
	global_load_dwordx4 v[192:195], v1, s[18:19] offset:3072
	s_add_u32 s12, s10, 4096
	s_lshl_b32 s13, s12, 13
	s_lshl_b32 s14, s12, 12
	s_add_u32 s20, s4, s13
	s_addc_u32 s21, s5, 0
	s_add_u32 s22, s90, 0x21918000
	s_addc_u32 s23, s91, 0
	s_add_u32 s22, s22, s14
	s_addc_u32 s23, s23, 0
	global_load_dwordx2 v[98:99], v2, s[22:23] nt
	global_load_dwordx2 v[100:101], v2, s[22:23] offset:512 nt
	global_load_dwordx2 v[102:103], v2, s[22:23] offset:1024 nt
	global_load_dwordx2 v[104:105], v2, s[22:23] offset:1536 nt
	global_load_dwordx2 v[106:107], v2, s[22:23] offset:2048 nt
	global_load_dwordx2 v[108:109], v2, s[22:23] offset:2560 nt
	global_load_dwordx2 v[110:111], v2, s[22:23] offset:3072 nt
	global_load_dwordx2 v[112:113], v2, s[22:23] offset:3584 nt
	s_add_u32 s36, s20, 0x1000
	s_addc_u32 s37, s21, 0
	global_load_dwordx4 v[34:37], v1, s[20:21] nt
	global_load_dwordx4 v[38:41], v1, s[20:21] offset:1024 nt
	global_load_dwordx4 v[42:45], v1, s[20:21] offset:2048 nt
	global_load_dwordx4 v[46:49], v1, s[20:21] offset:3072 nt
	global_load_dwordx4 v[50:53], v1, s[36:37] nt
	global_load_dwordx4 v[54:57], v1, s[36:37] offset:1024 nt
	global_load_dwordx4 v[58:61], v1, s[36:37] offset:2048 nt
	global_load_dwordx4 v[62:65], v1, s[36:37] offset:3072 nt
	s_add_u32 s12, s10, 2048
	s_lshl_b32 s13, s12, 13
	s_lshl_b32 s14, s12, 12
	s_add_u32 s24, s4, s13
	s_addc_u32 s25, s5, 0
	s_add_u32 s34, s24, 0x1000
	s_addc_u32 s35, s25, 0
	s_add_u32 s26, s90, 0x11918000
	s_addc_u32 s27, s91, 0
	s_add_u32 s26, s26, s14
	s_addc_u32 s27, s27, 0
	s_waitcnt vmcnt(63)
	v_mov_b32_e32 v8, 0
	v_lshlrev_b32_e32 v10, 16, v114
	v_and_b32_e32 v11, 0xffff0000, v114
	v_fmac_f32_e32 v8, v10, v10
	v_fmac_f32_e32 v8, v11, v11
	v_lshlrev_b32_e32 v10, 16, v115
	v_and_b32_e32 v11, 0xffff0000, v115
	v_fmac_f32_e32 v8, v10, v10
	v_fmac_f32_e32 v8, v11, v11
	v_lshlrev_b32_e32 v10, 16, v116
	v_and_b32_e32 v11, 0xffff0000, v116
	v_fmac_f32_e32 v8, v10, v10
	v_fmac_f32_e32 v8, v11, v11
	v_lshlrev_b32_e32 v10, 16, v117
	v_and_b32_e32 v11, 0xffff0000, v117
	v_fmac_f32_e32 v8, v10, v10
	v_fmac_f32_e32 v8, v11, v11
	v_lshlrev_b32_e32 v10, 16, v118
	v_and_b32_e32 v11, 0xffff0000, v118
	v_fmac_f32_e32 v8, v10, v10
	v_fmac_f32_e32 v8, v11, v11
	v_lshlrev_b32_e32 v10, 16, v119
	v_and_b32_e32 v11, 0xffff0000, v119
	v_fmac_f32_e32 v8, v10, v10
	v_fmac_f32_e32 v8, v11, v11
	v_lshlrev_b32_e32 v10, 16, v120
	v_and_b32_e32 v11, 0xffff0000, v120
	v_fmac_f32_e32 v8, v10, v10
	v_fmac_f32_e32 v8, v11, v11
	v_lshlrev_b32_e32 v10, 16, v121
	v_and_b32_e32 v11, 0xffff0000, v121
	v_fmac_f32_e32 v8, v10, v10
	v_fmac_f32_e32 v8, v11, v11
	v_lshlrev_b32_e32 v10, 16, v122
	v_and_b32_e32 v11, 0xffff0000, v122
	v_fmac_f32_e32 v8, v10, v10
	v_fmac_f32_e32 v8, v11, v11
	v_lshlrev_b32_e32 v10, 16, v123
	v_and_b32_e32 v11, 0xffff0000, v123
	v_fmac_f32_e32 v8, v10, v10
	v_fmac_f32_e32 v8, v11, v11
	v_lshlrev_b32_e32 v10, 16, v124
	v_and_b32_e32 v11, 0xffff0000, v124
	v_fmac_f32_e32 v8, v10, v10
	v_fmac_f32_e32 v8, v11, v11
	v_lshlrev_b32_e32 v10, 16, v125
	v_and_b32_e32 v11, 0xffff0000, v125
	v_fmac_f32_e32 v8, v10, v10
	v_fmac_f32_e32 v8, v11, v11
	v_lshlrev_b32_e32 v10, 16, v126
	v_and_b32_e32 v11, 0xffff0000, v126
	v_fmac_f32_e32 v8, v10, v10
	v_fmac_f32_e32 v8, v11, v11
	v_lshlrev_b32_e32 v10, 16, v127
	v_and_b32_e32 v11, 0xffff0000, v127
	v_fmac_f32_e32 v8, v10, v10
	v_fmac_f32_e32 v8, v11, v11
	v_lshlrev_b32_e32 v10, 16, v128
	v_and_b32_e32 v11, 0xffff0000, v128
	v_fmac_f32_e32 v8, v10, v10
	v_fmac_f32_e32 v8, v11, v11
	v_lshlrev_b32_e32 v10, 16, v129
	v_and_b32_e32 v11, 0xffff0000, v129
	v_fmac_f32_e32 v8, v10, v10
	v_fmac_f32_e32 v8, v11, v11
	s_nop 1
	v_add_f32_dpp v8, v8, v8 quad_perm:[1,0,3,2] row_mask:0xf bank_mask:0xf
	s_nop 1
	v_add_f32_dpp v8, v8, v8 quad_perm:[2,3,0,1] row_mask:0xf bank_mask:0xf
	s_nop 1
	v_add_f32_dpp v8, v8, v8 row_ror:4 row_mask:0xf bank_mask:0xf
	s_nop 1
	v_add_f32_dpp v8, v8, v8 row_ror:8 row_mask:0xf bank_mask:0xf
	s_nop 1
	v_readlane_b32 s42, v8, 0
	v_readlane_b32 s43, v8, 16
	v_readlane_b32 s44, v8, 32
	v_readlane_b32 s45, v8, 48
	s_nop 1
	v_mov_b32_e32 v8, s42
	v_add_f32_e32 v8, s43, v8
	v_add_f32_e32 v8, s44, v8
	v_add_f32_e32 v8, s45, v8
	v_mov_b32_e32 v4, s41
	v_fmac_f32_e32 v4, s40, v8
	v_rsq_f32_e32 v4, v4
	s_nop 0
	v_mov_b32_e32 v5, v4
	s_waitcnt vmcnt(63)
	s_waitcnt vmcnt(16)
	v_mov_b32_e32 v8, 0
	v_lshlrev_b32_e32 v10, 16, v114
	v_and_b32_e32 v11, 0xffff0000, v114
	v_pk_mul_f32 v[10:11], v[10:11], v[4:5]
	v_pk_mul_f32 v[10:11], v[10:11], v[130:131]
	v_pk_fma_f32 v[66:67], v[164:165], v[10:11], v[66:67]
	v_lshlrev_b32_e32 v10, 16, v115
	v_and_b32_e32 v11, 0xffff0000, v115
	v_pk_mul_f32 v[10:11], v[10:11], v[4:5]
	v_pk_mul_f32 v[10:11], v[10:11], v[132:133]
	v_pk_fma_f32 v[68:69], v[166:167], v[10:11], v[68:69]
	global_store_dwordx4 v1, v[66:69], s[24:25] nt
	v_fmac_f32_e32 v8, v66, v66
	v_fmac_f32_e32 v8, v67, v67
	v_fmac_f32_e32 v8, v68, v68
	v_fmac_f32_e32 v8, v69, v69
	v_lshlrev_b32_e32 v10, 16, v116
	v_and_b32_e32 v11, 0xffff0000, v116
	v_pk_mul_f32 v[10:11], v[10:11], v[4:5]
	v_pk_mul_f32 v[10:11], v[10:11], v[134:135]
	v_pk_fma_f32 v[70:71], v[168:169], v[10:11], v[70:71]
	v_lshlrev_b32_e32 v10, 16, v117
	v_and_b32_e32 v11, 0xffff0000, v117
	v_pk_mul_f32 v[10:11], v[10:11], v[4:5]
	v_pk_mul_f32 v[10:11], v[10:11], v[136:137]
	v_pk_fma_f32 v[72:73], v[170:171], v[10:11], v[72:73]
	global_store_dwordx4 v1, v[70:73], s[24:25] offset:1024 nt
	v_fmac_f32_e32 v8, v70, v70
	v_fmac_f32_e32 v8, v71, v71
	v_fmac_f32_e32 v8, v72, v72
	v_fmac_f32_e32 v8, v73, v73
	v_lshlrev_b32_e32 v10, 16, v118
	v_and_b32_e32 v11, 0xffff0000, v118
	v_pk_mul_f32 v[10:11], v[10:11], v[4:5]
	v_pk_mul_f32 v[10:11], v[10:11], v[138:139]
	v_pk_fma_f32 v[74:75], v[172:173], v[10:11], v[74:75]
	v_lshlrev_b32_e32 v10, 16, v119
	v_and_b32_e32 v11, 0xffff0000, v119
	v_pk_mul_f32 v[10:11], v[10:11], v[4:5]
	v_pk_mul_f32 v[10:11], v[10:11], v[140:141]
	v_pk_fma_f32 v[76:77], v[174:175], v[10:11], v[76:77]
	global_store_dwordx4 v1, v[74:77], s[24:25] offset:2048 nt
	v_fmac_f32_e32 v8, v74, v74
	v_fmac_f32_e32 v8, v75, v75
	v_fmac_f32_e32 v8, v76, v76
	v_fmac_f32_e32 v8, v77, v77
	v_lshlrev_b32_e32 v10, 16, v120
	v_and_b32_e32 v11, 0xffff0000, v120
	v_pk_mul_f32 v[10:11], v[10:11], v[4:5]
	v_pk_mul_f32 v[10:11], v[10:11], v[142:143]
	v_pk_fma_f32 v[78:79], v[176:177], v[10:11], v[78:79]
	v_lshlrev_b32_e32 v10, 16, v121
	v_and_b32_e32 v11, 0xffff0000, v121
	v_pk_mul_f32 v[10:11], v[10:11], v[4:5]
	v_pk_mul_f32 v[10:11], v[10:11], v[144:145]
	v_pk_fma_f32 v[80:81], v[178:179], v[10:11], v[80:81]
	global_store_dwordx4 v1, v[78:81], s[24:25] offset:3072 nt
	v_fmac_f32_e32 v8, v78, v78
	v_fmac_f32_e32 v8, v79, v79
	v_fmac_f32_e32 v8, v80, v80
	v_fmac_f32_e32 v8, v81, v81
	v_lshlrev_b32_e32 v10, 16, v122
	v_and_b32_e32 v11, 0xffff0000, v122
	v_pk_mul_f32 v[10:11], v[10:11], v[4:5]
	v_pk_mul_f32 v[10:11], v[10:11], v[146:147]
	v_pk_fma_f32 v[82:83], v[180:181], v[10:11], v[82:83]
	v_lshlrev_b32_e32 v10, 16, v123
	v_and_b32_e32 v11, 0xffff0000, v123
	v_pk_mul_f32 v[10:11], v[10:11], v[4:5]
	v_pk_mul_f32 v[10:11], v[10:11], v[148:149]
	v_pk_fma_f32 v[84:85], v[182:183], v[10:11], v[84:85]
	global_store_dwordx4 v1, v[82:85], s[34:35] nt
	v_fmac_f32_e32 v8, v82, v82
	v_fmac_f32_e32 v8, v83, v83
	v_fmac_f32_e32 v8, v84, v84
	v_fmac_f32_e32 v8, v85, v85
	v_lshlrev_b32_e32 v10, 16, v124
	v_and_b32_e32 v11, 0xffff0000, v124
	v_pk_mul_f32 v[10:11], v[10:11], v[4:5]
	v_pk_mul_f32 v[10:11], v[10:11], v[150:151]
	v_pk_fma_f32 v[86:87], v[184:185], v[10:11], v[86:87]
	v_lshlrev_b32_e32 v10, 16, v125
	v_and_b32_e32 v11, 0xffff0000, v125
	v_pk_mul_f32 v[10:11], v[10:11], v[4:5]
	v_pk_mul_f32 v[10:11], v[10:11], v[152:153]
	v_pk_fma_f32 v[88:89], v[186:187], v[10:11], v[88:89]
	global_store_dwordx4 v1, v[86:89], s[34:35] offset:1024 nt
	v_fmac_f32_e32 v8, v86, v86
	v_fmac_f32_e32 v8, v87, v87
	v_fmac_f32_e32 v8, v88, v88
	v_fmac_f32_e32 v8, v89, v89
	v_lshlrev_b32_e32 v10, 16, v126
	v_and_b32_e32 v11, 0xffff0000, v126
	v_pk_mul_f32 v[10:11], v[10:11], v[4:5]
	v_pk_mul_f32 v[10:11], v[10:11], v[156:157]
	v_pk_fma_f32 v[90:91], v[188:189], v[10:11], v[90:91]
	v_lshlrev_b32_e32 v10, 16, v127
	v_and_b32_e32 v11, 0xffff0000, v127
	v_pk_mul_f32 v[10:11], v[10:11], v[4:5]
	v_pk_mul_f32 v[10:11], v[10:11], v[158:159]
	v_pk_fma_f32 v[92:93], v[190:191], v[10:11], v[92:93]
	global_store_dwordx4 v1, v[90:93], s[34:35] offset:2048 nt
	v_fmac_f32_e32 v8, v90, v90
	v_fmac_f32_e32 v8, v91, v91
	v_fmac_f32_e32 v8, v92, v92
	v_fmac_f32_e32 v8, v93, v93
	v_lshlrev_b32_e32 v10, 16, v128
	v_and_b32_e32 v11, 0xffff0000, v128
	v_pk_mul_f32 v[10:11], v[10:11], v[4:5]
	v_pk_mul_f32 v[10:11], v[10:11], v[160:161]
	v_pk_fma_f32 v[94:95], v[192:193], v[10:11], v[94:95]
	v_lshlrev_b32_e32 v10, 16, v129
	v_and_b32_e32 v11, 0xffff0000, v129
	v_pk_mul_f32 v[10:11], v[10:11], v[4:5]
	v_pk_mul_f32 v[10:11], v[10:11], v[162:163]
	v_pk_fma_f32 v[96:97], v[194:195], v[10:11], v[96:97]
	global_store_dwordx4 v1, v[94:97], s[34:35] offset:3072 nt
	v_fmac_f32_e32 v8, v94, v94
	v_fmac_f32_e32 v8, v95, v95
	v_fmac_f32_e32 v8, v96, v96
	v_fmac_f32_e32 v8, v97, v97
	s_add_u32 s18, s2, 0x1000
	s_addc_u32 s19, s3, 0
	global_load_dwordx4 v[130:133], v1, s[2:3]
	global_load_dwordx4 v[134:137], v1, s[2:3] offset:1024
	global_load_dwordx4 v[138:141], v1, s[2:3] offset:2048
	global_load_dwordx4 v[142:145], v1, s[2:3] offset:3072
	global_load_dwordx4 v[146:149], v1, s[18:19]
	global_load_dwordx4 v[150:153], v1, s[18:19] offset:1024
	global_load_dwordx4 v[156:159], v1, s[18:19] offset:2048
	global_load_dwordx4 v[160:163], v1, s[18:19] offset:3072
	s_add_u32 s18, s30, 0x1000
	s_addc_u32 s19, s31, 0
	global_load_dwordx4 v[164:167], v1, s[30:31]
	global_load_dwordx4 v[168:171], v1, s[30:31] offset:1024
	global_load_dwordx4 v[172:175], v1, s[30:31] offset:2048
	global_load_dwordx4 v[176:179], v1, s[30:31] offset:3072
	global_load_dwordx4 v[180:183], v1, s[18:19]
	global_load_dwordx4 v[184:187], v1, s[18:19] offset:1024
	global_load_dwordx4 v[188:191], v1, s[18:19] offset:2048
	global_load_dwordx4 v[192:195], v1, s[18:19] offset:3072
	s_add_u32 s18, s32, 0x1000
	s_addc_u32 s19, s33, 0
	global_load_dwordx4 v[196:199], v1, s[32:33]
	global_load_dwordx4 v[200:203], v1, s[32:33] offset:1024
	global_load_dwordx4 v[204:207], v1, s[32:33] offset:2048
	global_load_dwordx4 v[208:211], v1, s[32:33] offset:3072
	global_load_dwordx4 v[212:215], v1, s[18:19]
	global_load_dwordx4 v[216:219], v1, s[18:19] offset:1024
	global_load_dwordx4 v[220:223], v1, s[18:19] offset:2048
	global_load_dwordx4 v[224:227], v1, s[18:19] offset:3072
	s_nop 1
	v_add_f32_dpp v8, v8, v8 quad_perm:[1,0,3,2] row_mask:0xf bank_mask:0xf
	s_nop 1
	v_add_f32_dpp v8, v8, v8 quad_perm:[2,3,0,1] row_mask:0xf bank_mask:0xf
	s_nop 1
	v_add_f32_dpp v8, v8, v8 row_ror:4 row_mask:0xf bank_mask:0xf
	s_nop 1
	v_add_f32_dpp v8, v8, v8 row_ror:8 row_mask:0xf bank_mask:0xf
	s_nop 1
	v_readlane_b32 s42, v8, 0
	v_readlane_b32 s43, v8, 16
	v_readlane_b32 s44, v8, 32
	v_readlane_b32 s45, v8, 48
	s_nop 1
	v_mov_b32_e32 v8, s42
	v_add_f32_e32 v8, s43, v8
	v_add_f32_e32 v8, s44, v8
	v_add_f32_e32 v8, s45, v8
	v_mov_b32_e32 v4, s41
	v_fmac_f32_e32 v4, s40, v8
	v_rsq_f32_e32 v4, v4
	s_nop 0
	v_mov_b32_e32 v5, v4
	s_waitcnt vmcnt(0)
	v_pk_mul_f32 v[10:11], v[66:67], v[4:5]
	v_pk_mul_f32 v[10:11], v[10:11], v[130:131]
	v_pk_add_f32 v[12:13], v[196:197], v[6:7]
	v_pk_fma_f32 v[14:15], v[10:11], v[12:13], v[164:165]
	v_pk_mul_f32 v[10:11], v[68:69], v[4:5]
	v_pk_mul_f32 v[10:11], v[10:11], v[132:133]
	v_pk_add_f32 v[12:13], v[198:199], v[6:7]
	v_pk_fma_f32 v[16:17], v[10:11], v[12:13], v[166:167]
	v_cvt_pk_bf16_f32 v26, v14, v15
	v_cvt_pk_bf16_f32 v27, v16, v17
	global_store_dwordx2 v2, v[26:27], s[26:27]
	v_pk_mul_f32 v[10:11], v[70:71], v[4:5]
	v_pk_mul_f32 v[10:11], v[10:11], v[134:135]
	v_pk_add_f32 v[12:13], v[200:201], v[6:7]
	v_pk_fma_f32 v[14:15], v[10:11], v[12:13], v[168:169]
	v_pk_mul_f32 v[10:11], v[72:73], v[4:5]
	v_pk_mul_f32 v[10:11], v[10:11], v[136:137]
	v_pk_add_f32 v[12:13], v[202:203], v[6:7]
	v_pk_fma_f32 v[16:17], v[10:11], v[12:13], v[170:171]
	v_cvt_pk_bf16_f32 v28, v14, v15
	v_cvt_pk_bf16_f32 v29, v16, v17
	global_store_dwordx2 v2, v[28:29], s[26:27] offset:512
	v_pk_mul_f32 v[10:11], v[74:75], v[4:5]
	v_pk_mul_f32 v[10:11], v[10:11], v[138:139]
	v_pk_add_f32 v[12:13], v[204:205], v[6:7]
	v_pk_fma_f32 v[14:15], v[10:11], v[12:13], v[172:173]
	v_pk_mul_f32 v[10:11], v[76:77], v[4:5]
	v_pk_mul_f32 v[10:11], v[10:11], v[140:141]
	v_pk_add_f32 v[12:13], v[206:207], v[6:7]
	v_pk_fma_f32 v[16:17], v[10:11], v[12:13], v[174:175]
	v_cvt_pk_bf16_f32 v30, v14, v15
	v_cvt_pk_bf16_f32 v31, v16, v17
	global_store_dwordx2 v2, v[30:31], s[26:27] offset:1024
	v_pk_mul_f32 v[10:11], v[78:79], v[4:5]
	v_pk_mul_f32 v[10:11], v[10:11], v[142:143]
	v_pk_add_f32 v[12:13], v[208:209], v[6:7]
	v_pk_fma_f32 v[14:15], v[10:11], v[12:13], v[176:177]
	v_pk_mul_f32 v[10:11], v[80:81], v[4:5]
	v_pk_mul_f32 v[10:11], v[10:11], v[144:145]
	v_pk_add_f32 v[12:13], v[210:211], v[6:7]
	v_pk_fma_f32 v[16:17], v[10:11], v[12:13], v[178:179]
	v_cvt_pk_bf16_f32 v32, v14, v15
	v_cvt_pk_bf16_f32 v33, v16, v17
	global_store_dwordx2 v2, v[32:33], s[26:27] offset:1536
	v_pk_mul_f32 v[10:11], v[82:83], v[4:5]
	v_pk_mul_f32 v[10:11], v[10:11], v[146:147]
	v_pk_add_f32 v[12:13], v[212:213], v[6:7]
	v_pk_fma_f32 v[14:15], v[10:11], v[12:13], v[180:181]
	v_pk_mul_f32 v[10:11], v[84:85], v[4:5]
	v_pk_mul_f32 v[10:11], v[10:11], v[148:149]
	v_pk_add_f32 v[12:13], v[214:215], v[6:7]
	v_pk_fma_f32 v[16:17], v[10:11], v[12:13], v[182:183]
	v_cvt_pk_bf16_f32 v26, v14, v15
	v_cvt_pk_bf16_f32 v27, v16, v17
	global_store_dwordx2 v2, v[26:27], s[26:27] offset:2048
	v_pk_mul_f32 v[10:11], v[86:87], v[4:5]
	v_pk_mul_f32 v[10:11], v[10:11], v[150:151]
	v_pk_add_f32 v[12:13], v[216:217], v[6:7]
	v_pk_fma_f32 v[14:15], v[10:11], v[12:13], v[184:185]
	v_pk_mul_f32 v[10:11], v[88:89], v[4:5]
	v_pk_mul_f32 v[10:11], v[10:11], v[152:153]
	v_pk_add_f32 v[12:13], v[218:219], v[6:7]
	v_pk_fma_f32 v[16:17], v[10:11], v[12:13], v[186:187]
	v_cvt_pk_bf16_f32 v28, v14, v15
	v_cvt_pk_bf16_f32 v29, v16, v17
	global_store_dwordx2 v2, v[28:29], s[26:27] offset:2560
	v_pk_mul_f32 v[10:11], v[90:91], v[4:5]
	v_pk_mul_f32 v[10:11], v[10:11], v[156:157]
	v_pk_add_f32 v[12:13], v[220:221], v[6:7]
	v_pk_fma_f32 v[14:15], v[10:11], v[12:13], v[188:189]
	v_pk_mul_f32 v[10:11], v[92:93], v[4:5]
	v_pk_mul_f32 v[10:11], v[10:11], v[158:159]
	v_pk_add_f32 v[12:13], v[222:223], v[6:7]
	v_pk_fma_f32 v[16:17], v[10:11], v[12:13], v[190:191]
	v_cvt_pk_bf16_f32 v30, v14, v15
	v_cvt_pk_bf16_f32 v31, v16, v17
	global_store_dwordx2 v2, v[30:31], s[26:27] offset:3072
	v_pk_mul_f32 v[10:11], v[94:95], v[4:5]
	v_pk_mul_f32 v[10:11], v[10:11], v[160:161]
	v_pk_add_f32 v[12:13], v[224:225], v[6:7]
	v_pk_fma_f32 v[14:15], v[10:11], v[12:13], v[192:193]
	v_pk_mul_f32 v[10:11], v[96:97], v[4:5]
	v_pk_mul_f32 v[10:11], v[10:11], v[162:163]
	v_pk_add_f32 v[12:13], v[226:227], v[6:7]
	v_pk_fma_f32 v[16:17], v[10:11], v[12:13], v[194:195]
	v_cvt_pk_bf16_f32 v32, v14, v15
	v_cvt_pk_bf16_f32 v33, v16, v17
	global_store_dwordx2 v2, v[32:33], s[26:27] offset:3584
	s_lshr_b32 s16, s10, 10
	s_add_u32 s17, s16, 5
	s_mul_i32 s17, s17, 49152
	s_add_u32 s17, s17, 0x10404000
	s_add_u32 s28, s90, s17
	s_addc_u32 s29, s91, 0
	s_add_u32 s17, s16, 5
	s_mul_i32 s17, s17, 49152
	s_add_u32 s17, s17, 0x10406000
	s_add_u32 s30, s90, s17
	s_addc_u32 s31, s91, 0
	s_add_u32 s32, s30, 0x2000
	s_addc_u32 s33, s31, 0
	s_add_u32 s18, s0, 0x1000
	s_addc_u32 s19, s1, 0
	global_load_dwordx4 v[130:133], v1, s[0:1]
	global_load_dwordx4 v[134:137], v1, s[0:1] offset:1024
	global_load_dwordx4 v[138:141], v1, s[0:1] offset:2048
	global_load_dwordx4 v[142:145], v1, s[0:1] offset:3072
	global_load_dwordx4 v[146:149], v1, s[18:19]
	global_load_dwordx4 v[150:153], v1, s[18:19] offset:1024
	global_load_dwordx4 v[156:159], v1, s[18:19] offset:2048
	global_load_dwordx4 v[160:163], v1, s[18:19] offset:3072
	s_add_u32 s18, s28, 0x1000
	s_addc_u32 s19, s29, 0
	global_load_dwordx4 v[164:167], v1, s[28:29]
	global_load_dwordx4 v[168:171], v1, s[28:29] offset:1024
	global_load_dwordx4 v[172:175], v1, s[28:29] offset:2048
	global_load_dwordx4 v[176:179], v1, s[28:29] offset:3072
	global_load_dwordx4 v[180:183], v1, s[18:19]
	global_load_dwordx4 v[184:187], v1, s[18:19] offset:1024
	global_load_dwordx4 v[188:191], v1, s[18:19] offset:2048
	global_load_dwordx4 v[192:195], v1, s[18:19] offset:3072
	s_add_u32 s12, s10, 6144
	s_lshl_b32 s13, s12, 13
	s_lshl_b32 s14, s12, 12
	s_add_u32 s20, s4, s13
	s_addc_u32 s21, s5, 0
	s_add_u32 s22, s90, 0x21918000
	s_addc_u32 s23, s91, 0
	s_add_u32 s22, s22, s14
	s_addc_u32 s23, s23, 0
	global_load_dwordx2 v[114:115], v2, s[22:23] nt
	global_load_dwordx2 v[116:117], v2, s[22:23] offset:512 nt
	global_load_dwordx2 v[118:119], v2, s[22:23] offset:1024 nt
	global_load_dwordx2 v[120:121], v2, s[22:23] offset:1536 nt
	global_load_dwordx2 v[122:123], v2, s[22:23] offset:2048 nt
	global_load_dwordx2 v[124:125], v2, s[22:23] offset:2560 nt
	global_load_dwordx2 v[126:127], v2, s[22:23] offset:3072 nt
	global_load_dwordx2 v[128:129], v2, s[22:23] offset:3584 nt
	s_add_u32 s36, s20, 0x1000
	s_addc_u32 s37, s21, 0
	global_load_dwordx4 v[66:69], v1, s[20:21] nt
	global_load_dwordx4 v[70:73], v1, s[20:21] offset:1024 nt
	global_load_dwordx4 v[74:77], v1, s[20:21] offset:2048 nt
	global_load_dwordx4 v[78:81], v1, s[20:21] offset:3072 nt
	global_load_dwordx4 v[82:85], v1, s[36:37] nt
	global_load_dwordx4 v[86:89], v1, s[36:37] offset:1024 nt
	global_load_dwordx4 v[90:93], v1, s[36:37] offset:2048 nt
	global_load_dwordx4 v[94:97], v1, s[36:37] offset:3072 nt
	s_add_u32 s12, s10, 4096
	s_lshl_b32 s13, s12, 13
	s_lshl_b32 s14, s12, 12
	s_add_u32 s24, s4, s13
	s_addc_u32 s25, s5, 0
	s_add_u32 s34, s24, 0x1000
	s_addc_u32 s35, s25, 0
	s_add_u32 s26, s90, 0x11918000
	s_addc_u32 s27, s91, 0
	s_add_u32 s26, s26, s14
	s_addc_u32 s27, s27, 0
	s_waitcnt vmcnt(63)
	v_mov_b32_e32 v8, 0
	v_lshlrev_b32_e32 v10, 16, v98
	v_and_b32_e32 v11, 0xffff0000, v98
	v_fmac_f32_e32 v8, v10, v10
	v_fmac_f32_e32 v8, v11, v11
	v_lshlrev_b32_e32 v10, 16, v99
	v_and_b32_e32 v11, 0xffff0000, v99
	v_fmac_f32_e32 v8, v10, v10
	v_fmac_f32_e32 v8, v11, v11
	v_lshlrev_b32_e32 v10, 16, v100
	v_and_b32_e32 v11, 0xffff0000, v100
	v_fmac_f32_e32 v8, v10, v10
	v_fmac_f32_e32 v8, v11, v11
	v_lshlrev_b32_e32 v10, 16, v101
	v_and_b32_e32 v11, 0xffff0000, v101
	v_fmac_f32_e32 v8, v10, v10
	v_fmac_f32_e32 v8, v11, v11
	v_lshlrev_b32_e32 v10, 16, v102
	v_and_b32_e32 v11, 0xffff0000, v102
	v_fmac_f32_e32 v8, v10, v10
	v_fmac_f32_e32 v8, v11, v11
	v_lshlrev_b32_e32 v10, 16, v103
	v_and_b32_e32 v11, 0xffff0000, v103
	v_fmac_f32_e32 v8, v10, v10
	v_fmac_f32_e32 v8, v11, v11
	v_lshlrev_b32_e32 v10, 16, v104
	v_and_b32_e32 v11, 0xffff0000, v104
	v_fmac_f32_e32 v8, v10, v10
	v_fmac_f32_e32 v8, v11, v11
	v_lshlrev_b32_e32 v10, 16, v105
	v_and_b32_e32 v11, 0xffff0000, v105
	v_fmac_f32_e32 v8, v10, v10
	v_fmac_f32_e32 v8, v11, v11
	v_lshlrev_b32_e32 v10, 16, v106
	v_and_b32_e32 v11, 0xffff0000, v106
	v_fmac_f32_e32 v8, v10, v10
	v_fmac_f32_e32 v8, v11, v11
	v_lshlrev_b32_e32 v10, 16, v107
	v_and_b32_e32 v11, 0xffff0000, v107
	v_fmac_f32_e32 v8, v10, v10
	v_fmac_f32_e32 v8, v11, v11
	v_lshlrev_b32_e32 v10, 16, v108
	v_and_b32_e32 v11, 0xffff0000, v108
	v_fmac_f32_e32 v8, v10, v10
	v_fmac_f32_e32 v8, v11, v11
	v_lshlrev_b32_e32 v10, 16, v109
	v_and_b32_e32 v11, 0xffff0000, v109
	v_fmac_f32_e32 v8, v10, v10
	v_fmac_f32_e32 v8, v11, v11
	v_lshlrev_b32_e32 v10, 16, v110
	v_and_b32_e32 v11, 0xffff0000, v110
	v_fmac_f32_e32 v8, v10, v10
	v_fmac_f32_e32 v8, v11, v11
	v_lshlrev_b32_e32 v10, 16, v111
	v_and_b32_e32 v11, 0xffff0000, v111
	v_fmac_f32_e32 v8, v10, v10
	v_fmac_f32_e32 v8, v11, v11
	v_lshlrev_b32_e32 v10, 16, v112
	v_and_b32_e32 v11, 0xffff0000, v112
	v_fmac_f32_e32 v8, v10, v10
	v_fmac_f32_e32 v8, v11, v11
	v_lshlrev_b32_e32 v10, 16, v113
	v_and_b32_e32 v11, 0xffff0000, v113
	v_fmac_f32_e32 v8, v10, v10
	v_fmac_f32_e32 v8, v11, v11
	s_nop 1
	v_add_f32_dpp v8, v8, v8 quad_perm:[1,0,3,2] row_mask:0xf bank_mask:0xf
	s_nop 1
	v_add_f32_dpp v8, v8, v8 quad_perm:[2,3,0,1] row_mask:0xf bank_mask:0xf
	s_nop 1
	v_add_f32_dpp v8, v8, v8 row_ror:4 row_mask:0xf bank_mask:0xf
	s_nop 1
	v_add_f32_dpp v8, v8, v8 row_ror:8 row_mask:0xf bank_mask:0xf
	s_nop 1
	v_readlane_b32 s42, v8, 0
	v_readlane_b32 s43, v8, 16
	v_readlane_b32 s44, v8, 32
	v_readlane_b32 s45, v8, 48
	s_nop 1
	v_mov_b32_e32 v8, s42
	v_add_f32_e32 v8, s43, v8
	v_add_f32_e32 v8, s44, v8
	v_add_f32_e32 v8, s45, v8
	v_mov_b32_e32 v4, s41
	v_fmac_f32_e32 v4, s40, v8
	v_rsq_f32_e32 v4, v4
	s_nop 0
	v_mov_b32_e32 v5, v4
	s_waitcnt vmcnt(63)
	s_waitcnt vmcnt(16)
	v_mov_b32_e32 v8, 0
	v_lshlrev_b32_e32 v10, 16, v98
	v_and_b32_e32 v11, 0xffff0000, v98
	v_pk_mul_f32 v[10:11], v[10:11], v[4:5]
	v_pk_mul_f32 v[10:11], v[10:11], v[130:131]
	v_pk_fma_f32 v[34:35], v[164:165], v[10:11], v[34:35]
	v_lshlrev_b32_e32 v10, 16, v99
	v_and_b32_e32 v11, 0xffff0000, v99
	v_pk_mul_f32 v[10:11], v[10:11], v[4:5]
	v_pk_mul_f32 v[10:11], v[10:11], v[132:133]
	v_pk_fma_f32 v[36:37], v[166:167], v[10:11], v[36:37]
	global_store_dwordx4 v1, v[34:37], s[24:25] nt
	v_fmac_f32_e32 v8, v34, v34
	v_fmac_f32_e32 v8, v35, v35
	v_fmac_f32_e32 v8, v36, v36
	v_fmac_f32_e32 v8, v37, v37
	v_lshlrev_b32_e32 v10, 16, v100
	v_and_b32_e32 v11, 0xffff0000, v100
	v_pk_mul_f32 v[10:11], v[10:11], v[4:5]
	v_pk_mul_f32 v[10:11], v[10:11], v[134:135]
	v_pk_fma_f32 v[38:39], v[168:169], v[10:11], v[38:39]
	v_lshlrev_b32_e32 v10, 16, v101
	v_and_b32_e32 v11, 0xffff0000, v101
	v_pk_mul_f32 v[10:11], v[10:11], v[4:5]
	v_pk_mul_f32 v[10:11], v[10:11], v[136:137]
	v_pk_fma_f32 v[40:41], v[170:171], v[10:11], v[40:41]
	global_store_dwordx4 v1, v[38:41], s[24:25] offset:1024 nt
	v_fmac_f32_e32 v8, v38, v38
	v_fmac_f32_e32 v8, v39, v39
	v_fmac_f32_e32 v8, v40, v40
	v_fmac_f32_e32 v8, v41, v41
	v_lshlrev_b32_e32 v10, 16, v102
	v_and_b32_e32 v11, 0xffff0000, v102
	v_pk_mul_f32 v[10:11], v[10:11], v[4:5]
	v_pk_mul_f32 v[10:11], v[10:11], v[138:139]
	v_pk_fma_f32 v[42:43], v[172:173], v[10:11], v[42:43]
	v_lshlrev_b32_e32 v10, 16, v103
	v_and_b32_e32 v11, 0xffff0000, v103
	v_pk_mul_f32 v[10:11], v[10:11], v[4:5]
	v_pk_mul_f32 v[10:11], v[10:11], v[140:141]
	v_pk_fma_f32 v[44:45], v[174:175], v[10:11], v[44:45]
	global_store_dwordx4 v1, v[42:45], s[24:25] offset:2048 nt
	v_fmac_f32_e32 v8, v42, v42
	v_fmac_f32_e32 v8, v43, v43
	v_fmac_f32_e32 v8, v44, v44
	v_fmac_f32_e32 v8, v45, v45
	v_lshlrev_b32_e32 v10, 16, v104
	v_and_b32_e32 v11, 0xffff0000, v104
	v_pk_mul_f32 v[10:11], v[10:11], v[4:5]
	v_pk_mul_f32 v[10:11], v[10:11], v[142:143]
	v_pk_fma_f32 v[46:47], v[176:177], v[10:11], v[46:47]
	v_lshlrev_b32_e32 v10, 16, v105
	v_and_b32_e32 v11, 0xffff0000, v105
	v_pk_mul_f32 v[10:11], v[10:11], v[4:5]
	v_pk_mul_f32 v[10:11], v[10:11], v[144:145]
	v_pk_fma_f32 v[48:49], v[178:179], v[10:11], v[48:49]
	global_store_dwordx4 v1, v[46:49], s[24:25] offset:3072 nt
	v_fmac_f32_e32 v8, v46, v46
	v_fmac_f32_e32 v8, v47, v47
	v_fmac_f32_e32 v8, v48, v48
	v_fmac_f32_e32 v8, v49, v49
	v_lshlrev_b32_e32 v10, 16, v106
	v_and_b32_e32 v11, 0xffff0000, v106
	v_pk_mul_f32 v[10:11], v[10:11], v[4:5]
	v_pk_mul_f32 v[10:11], v[10:11], v[146:147]
	v_pk_fma_f32 v[50:51], v[180:181], v[10:11], v[50:51]
	v_lshlrev_b32_e32 v10, 16, v107
	v_and_b32_e32 v11, 0xffff0000, v107
	v_pk_mul_f32 v[10:11], v[10:11], v[4:5]
	v_pk_mul_f32 v[10:11], v[10:11], v[148:149]
	v_pk_fma_f32 v[52:53], v[182:183], v[10:11], v[52:53]
	global_store_dwordx4 v1, v[50:53], s[34:35] nt
	v_fmac_f32_e32 v8, v50, v50
	v_fmac_f32_e32 v8, v51, v51
	v_fmac_f32_e32 v8, v52, v52
	v_fmac_f32_e32 v8, v53, v53
	v_lshlrev_b32_e32 v10, 16, v108
	v_and_b32_e32 v11, 0xffff0000, v108
	v_pk_mul_f32 v[10:11], v[10:11], v[4:5]
	v_pk_mul_f32 v[10:11], v[10:11], v[150:151]
	v_pk_fma_f32 v[54:55], v[184:185], v[10:11], v[54:55]
	v_lshlrev_b32_e32 v10, 16, v109
	v_and_b32_e32 v11, 0xffff0000, v109
	v_pk_mul_f32 v[10:11], v[10:11], v[4:5]
	v_pk_mul_f32 v[10:11], v[10:11], v[152:153]
	v_pk_fma_f32 v[56:57], v[186:187], v[10:11], v[56:57]
	global_store_dwordx4 v1, v[54:57], s[34:35] offset:1024 nt
	v_fmac_f32_e32 v8, v54, v54
	v_fmac_f32_e32 v8, v55, v55
	v_fmac_f32_e32 v8, v56, v56
	v_fmac_f32_e32 v8, v57, v57
	v_lshlrev_b32_e32 v10, 16, v110
	v_and_b32_e32 v11, 0xffff0000, v110
	v_pk_mul_f32 v[10:11], v[10:11], v[4:5]
	v_pk_mul_f32 v[10:11], v[10:11], v[156:157]
	v_pk_fma_f32 v[58:59], v[188:189], v[10:11], v[58:59]
	v_lshlrev_b32_e32 v10, 16, v111
	v_and_b32_e32 v11, 0xffff0000, v111
	v_pk_mul_f32 v[10:11], v[10:11], v[4:5]
	v_pk_mul_f32 v[10:11], v[10:11], v[158:159]
	v_pk_fma_f32 v[60:61], v[190:191], v[10:11], v[60:61]
	global_store_dwordx4 v1, v[58:61], s[34:35] offset:2048 nt
	v_fmac_f32_e32 v8, v58, v58
	v_fmac_f32_e32 v8, v59, v59
	v_fmac_f32_e32 v8, v60, v60
	v_fmac_f32_e32 v8, v61, v61
	v_lshlrev_b32_e32 v10, 16, v112
	v_and_b32_e32 v11, 0xffff0000, v112
	v_pk_mul_f32 v[10:11], v[10:11], v[4:5]
	v_pk_mul_f32 v[10:11], v[10:11], v[160:161]
	v_pk_fma_f32 v[62:63], v[192:193], v[10:11], v[62:63]
	v_lshlrev_b32_e32 v10, 16, v113
	v_and_b32_e32 v11, 0xffff0000, v113
	v_pk_mul_f32 v[10:11], v[10:11], v[4:5]
	v_pk_mul_f32 v[10:11], v[10:11], v[162:163]
	v_pk_fma_f32 v[64:65], v[194:195], v[10:11], v[64:65]
	global_store_dwordx4 v1, v[62:65], s[34:35] offset:3072 nt
	v_fmac_f32_e32 v8, v62, v62
	v_fmac_f32_e32 v8, v63, v63
	v_fmac_f32_e32 v8, v64, v64
	v_fmac_f32_e32 v8, v65, v65
	s_add_u32 s18, s2, 0x1000
	s_addc_u32 s19, s3, 0
	global_load_dwordx4 v[130:133], v1, s[2:3]
	global_load_dwordx4 v[134:137], v1, s[2:3] offset:1024
	global_load_dwordx4 v[138:141], v1, s[2:3] offset:2048
	global_load_dwordx4 v[142:145], v1, s[2:3] offset:3072
	global_load_dwordx4 v[146:149], v1, s[18:19]
	global_load_dwordx4 v[150:153], v1, s[18:19] offset:1024
	global_load_dwordx4 v[156:159], v1, s[18:19] offset:2048
	global_load_dwordx4 v[160:163], v1, s[18:19] offset:3072
	s_add_u32 s18, s30, 0x1000
	s_addc_u32 s19, s31, 0
	global_load_dwordx4 v[164:167], v1, s[30:31]
	global_load_dwordx4 v[168:171], v1, s[30:31] offset:1024
	global_load_dwordx4 v[172:175], v1, s[30:31] offset:2048
	global_load_dwordx4 v[176:179], v1, s[30:31] offset:3072
	global_load_dwordx4 v[180:183], v1, s[18:19]
	global_load_dwordx4 v[184:187], v1, s[18:19] offset:1024
	global_load_dwordx4 v[188:191], v1, s[18:19] offset:2048
	global_load_dwordx4 v[192:195], v1, s[18:19] offset:3072
	s_add_u32 s18, s32, 0x1000
	s_addc_u32 s19, s33, 0
	global_load_dwordx4 v[196:199], v1, s[32:33]
	global_load_dwordx4 v[200:203], v1, s[32:33] offset:1024
	global_load_dwordx4 v[204:207], v1, s[32:33] offset:2048
	global_load_dwordx4 v[208:211], v1, s[32:33] offset:3072
	global_load_dwordx4 v[212:215], v1, s[18:19]
	global_load_dwordx4 v[216:219], v1, s[18:19] offset:1024
	global_load_dwordx4 v[220:223], v1, s[18:19] offset:2048
	global_load_dwordx4 v[224:227], v1, s[18:19] offset:3072
	s_nop 1
	v_add_f32_dpp v8, v8, v8 quad_perm:[1,0,3,2] row_mask:0xf bank_mask:0xf
	s_nop 1
	v_add_f32_dpp v8, v8, v8 quad_perm:[2,3,0,1] row_mask:0xf bank_mask:0xf
	s_nop 1
	v_add_f32_dpp v8, v8, v8 row_ror:4 row_mask:0xf bank_mask:0xf
	s_nop 1
	v_add_f32_dpp v8, v8, v8 row_ror:8 row_mask:0xf bank_mask:0xf
	s_nop 1
	v_readlane_b32 s42, v8, 0
	v_readlane_b32 s43, v8, 16
	v_readlane_b32 s44, v8, 32
	v_readlane_b32 s45, v8, 48
	s_nop 1
	v_mov_b32_e32 v8, s42
	v_add_f32_e32 v8, s43, v8
	v_add_f32_e32 v8, s44, v8
	v_add_f32_e32 v8, s45, v8
	v_mov_b32_e32 v4, s41
	v_fmac_f32_e32 v4, s40, v8
	v_rsq_f32_e32 v4, v4
	s_nop 0
	v_mov_b32_e32 v5, v4
	s_waitcnt vmcnt(0)
	v_pk_mul_f32 v[10:11], v[34:35], v[4:5]
	v_pk_mul_f32 v[10:11], v[10:11], v[130:131]
	v_pk_add_f32 v[12:13], v[196:197], v[6:7]
	v_pk_fma_f32 v[14:15], v[10:11], v[12:13], v[164:165]
	v_pk_mul_f32 v[10:11], v[36:37], v[4:5]
	v_pk_mul_f32 v[10:11], v[10:11], v[132:133]
	v_pk_add_f32 v[12:13], v[198:199], v[6:7]
	v_pk_fma_f32 v[16:17], v[10:11], v[12:13], v[166:167]
	v_cvt_pk_bf16_f32 v26, v14, v15
	v_cvt_pk_bf16_f32 v27, v16, v17
	global_store_dwordx2 v2, v[26:27], s[26:27]
	v_pk_mul_f32 v[10:11], v[38:39], v[4:5]
	v_pk_mul_f32 v[10:11], v[10:11], v[134:135]
	v_pk_add_f32 v[12:13], v[200:201], v[6:7]
	v_pk_fma_f32 v[14:15], v[10:11], v[12:13], v[168:169]
	v_pk_mul_f32 v[10:11], v[40:41], v[4:5]
	v_pk_mul_f32 v[10:11], v[10:11], v[136:137]
	v_pk_add_f32 v[12:13], v[202:203], v[6:7]
	v_pk_fma_f32 v[16:17], v[10:11], v[12:13], v[170:171]
	v_cvt_pk_bf16_f32 v28, v14, v15
	v_cvt_pk_bf16_f32 v29, v16, v17
	global_store_dwordx2 v2, v[28:29], s[26:27] offset:512
	v_pk_mul_f32 v[10:11], v[42:43], v[4:5]
	v_pk_mul_f32 v[10:11], v[10:11], v[138:139]
	v_pk_add_f32 v[12:13], v[204:205], v[6:7]
	v_pk_fma_f32 v[14:15], v[10:11], v[12:13], v[172:173]
	v_pk_mul_f32 v[10:11], v[44:45], v[4:5]
	v_pk_mul_f32 v[10:11], v[10:11], v[140:141]
	v_pk_add_f32 v[12:13], v[206:207], v[6:7]
	v_pk_fma_f32 v[16:17], v[10:11], v[12:13], v[174:175]
	v_cvt_pk_bf16_f32 v30, v14, v15
	v_cvt_pk_bf16_f32 v31, v16, v17
	global_store_dwordx2 v2, v[30:31], s[26:27] offset:1024
	v_pk_mul_f32 v[10:11], v[46:47], v[4:5]
	v_pk_mul_f32 v[10:11], v[10:11], v[142:143]
	v_pk_add_f32 v[12:13], v[208:209], v[6:7]
	v_pk_fma_f32 v[14:15], v[10:11], v[12:13], v[176:177]
	v_pk_mul_f32 v[10:11], v[48:49], v[4:5]
	v_pk_mul_f32 v[10:11], v[10:11], v[144:145]
	v_pk_add_f32 v[12:13], v[210:211], v[6:7]
	v_pk_fma_f32 v[16:17], v[10:11], v[12:13], v[178:179]
	v_cvt_pk_bf16_f32 v32, v14, v15
	v_cvt_pk_bf16_f32 v33, v16, v17
	global_store_dwordx2 v2, v[32:33], s[26:27] offset:1536
	v_pk_mul_f32 v[10:11], v[50:51], v[4:5]
	v_pk_mul_f32 v[10:11], v[10:11], v[146:147]
	v_pk_add_f32 v[12:13], v[212:213], v[6:7]
	v_pk_fma_f32 v[14:15], v[10:11], v[12:13], v[180:181]
	v_pk_mul_f32 v[10:11], v[52:53], v[4:5]
	v_pk_mul_f32 v[10:11], v[10:11], v[148:149]
	v_pk_add_f32 v[12:13], v[214:215], v[6:7]
	v_pk_fma_f32 v[16:17], v[10:11], v[12:13], v[182:183]
	v_cvt_pk_bf16_f32 v26, v14, v15
	v_cvt_pk_bf16_f32 v27, v16, v17
	global_store_dwordx2 v2, v[26:27], s[26:27] offset:2048
	v_pk_mul_f32 v[10:11], v[54:55], v[4:5]
	v_pk_mul_f32 v[10:11], v[10:11], v[150:151]
	v_pk_add_f32 v[12:13], v[216:217], v[6:7]
	v_pk_fma_f32 v[14:15], v[10:11], v[12:13], v[184:185]
	v_pk_mul_f32 v[10:11], v[56:57], v[4:5]
	v_pk_mul_f32 v[10:11], v[10:11], v[152:153]
	v_pk_add_f32 v[12:13], v[218:219], v[6:7]
	v_pk_fma_f32 v[16:17], v[10:11], v[12:13], v[186:187]
	v_cvt_pk_bf16_f32 v28, v14, v15
	v_cvt_pk_bf16_f32 v29, v16, v17
	global_store_dwordx2 v2, v[28:29], s[26:27] offset:2560
	v_pk_mul_f32 v[10:11], v[58:59], v[4:5]
	v_pk_mul_f32 v[10:11], v[10:11], v[156:157]
	v_pk_add_f32 v[12:13], v[220:221], v[6:7]
	v_pk_fma_f32 v[14:15], v[10:11], v[12:13], v[188:189]
	v_pk_mul_f32 v[10:11], v[60:61], v[4:5]
	v_pk_mul_f32 v[10:11], v[10:11], v[158:159]
	v_pk_add_f32 v[12:13], v[222:223], v[6:7]
	v_pk_fma_f32 v[16:17], v[10:11], v[12:13], v[190:191]
	v_cvt_pk_bf16_f32 v30, v14, v15
	v_cvt_pk_bf16_f32 v31, v16, v17
	global_store_dwordx2 v2, v[30:31], s[26:27] offset:3072
	v_pk_mul_f32 v[10:11], v[62:63], v[4:5]
	v_pk_mul_f32 v[10:11], v[10:11], v[160:161]
	v_pk_add_f32 v[12:13], v[224:225], v[6:7]
	v_pk_fma_f32 v[14:15], v[10:11], v[12:13], v[192:193]
	v_pk_mul_f32 v[10:11], v[64:65], v[4:5]
	v_pk_mul_f32 v[10:11], v[10:11], v[162:163]
	v_pk_add_f32 v[12:13], v[226:227], v[6:7]
	v_pk_fma_f32 v[16:17], v[10:11], v[12:13], v[194:195]
	v_cvt_pk_bf16_f32 v32, v14, v15
	v_cvt_pk_bf16_f32 v33, v16, v17
	global_store_dwordx2 v2, v[32:33], s[26:27] offset:3584
	s_lshr_b32 s16, s10, 10
	s_add_u32 s16, s16, 2
	s_add_u32 s17, s16, 5
	s_mul_i32 s17, s17, 49152
	s_add_u32 s17, s17, 0x10404000
	s_add_u32 s28, s90, s17
	s_addc_u32 s29, s91, 0
	s_add_u32 s17, s16, 5
	s_mul_i32 s17, s17, 49152
	s_add_u32 s17, s17, 0x10406000
	s_add_u32 s30, s90, s17
	s_addc_u32 s31, s91, 0
	s_add_u32 s32, s30, 0x2000
	s_addc_u32 s33, s31, 0
	s_add_u32 s18, s0, 0x1000
	s_addc_u32 s19, s1, 0
	global_load_dwordx4 v[130:133], v1, s[0:1]
	global_load_dwordx4 v[134:137], v1, s[0:1] offset:1024
	global_load_dwordx4 v[138:141], v1, s[0:1] offset:2048
	global_load_dwordx4 v[142:145], v1, s[0:1] offset:3072
	global_load_dwordx4 v[146:149], v1, s[18:19]
	global_load_dwordx4 v[150:153], v1, s[18:19] offset:1024
	global_load_dwordx4 v[156:159], v1, s[18:19] offset:2048
	global_load_dwordx4 v[160:163], v1, s[18:19] offset:3072
	s_add_u32 s18, s28, 0x1000
	s_addc_u32 s19, s29, 0
	global_load_dwordx4 v[164:167], v1, s[28:29]
	global_load_dwordx4 v[168:171], v1, s[28:29] offset:1024
	global_load_dwordx4 v[172:175], v1, s[28:29] offset:2048
	global_load_dwordx4 v[176:179], v1, s[28:29] offset:3072
	global_load_dwordx4 v[180:183], v1, s[18:19]
	global_load_dwordx4 v[184:187], v1, s[18:19] offset:1024
	global_load_dwordx4 v[188:191], v1, s[18:19] offset:2048
	global_load_dwordx4 v[192:195], v1, s[18:19] offset:3072
	s_add_u32 s12, s10, 6144
	s_lshl_b32 s13, s12, 13
	s_lshl_b32 s14, s12, 12
	s_add_u32 s24, s4, s13
	s_addc_u32 s25, s5, 0
	s_add_u32 s34, s24, 0x1000
	s_addc_u32 s35, s25, 0
	s_add_u32 s26, s90, 0x11918000
	s_addc_u32 s27, s91, 0
	s_add_u32 s26, s26, s14
	s_addc_u32 s27, s27, 0
	s_waitcnt vmcnt(63)
	v_mov_b32_e32 v8, 0
	v_lshlrev_b32_e32 v10, 16, v114
	v_and_b32_e32 v11, 0xffff0000, v114
	v_fmac_f32_e32 v8, v10, v10
	v_fmac_f32_e32 v8, v11, v11
	v_lshlrev_b32_e32 v10, 16, v115
	v_and_b32_e32 v11, 0xffff0000, v115
	v_fmac_f32_e32 v8, v10, v10
	v_fmac_f32_e32 v8, v11, v11
	v_lshlrev_b32_e32 v10, 16, v116
	v_and_b32_e32 v11, 0xffff0000, v116
	v_fmac_f32_e32 v8, v10, v10
	v_fmac_f32_e32 v8, v11, v11
	v_lshlrev_b32_e32 v10, 16, v117
	v_and_b32_e32 v11, 0xffff0000, v117
	v_fmac_f32_e32 v8, v10, v10
	v_fmac_f32_e32 v8, v11, v11
	v_lshlrev_b32_e32 v10, 16, v118
	v_and_b32_e32 v11, 0xffff0000, v118
	v_fmac_f32_e32 v8, v10, v10
	v_fmac_f32_e32 v8, v11, v11
	v_lshlrev_b32_e32 v10, 16, v119
	v_and_b32_e32 v11, 0xffff0000, v119
	v_fmac_f32_e32 v8, v10, v10
	v_fmac_f32_e32 v8, v11, v11
	v_lshlrev_b32_e32 v10, 16, v120
	v_and_b32_e32 v11, 0xffff0000, v120
	v_fmac_f32_e32 v8, v10, v10
	v_fmac_f32_e32 v8, v11, v11
	v_lshlrev_b32_e32 v10, 16, v121
	v_and_b32_e32 v11, 0xffff0000, v121
	v_fmac_f32_e32 v8, v10, v10
	v_fmac_f32_e32 v8, v11, v11
	v_lshlrev_b32_e32 v10, 16, v122
	v_and_b32_e32 v11, 0xffff0000, v122
	v_fmac_f32_e32 v8, v10, v10
	v_fmac_f32_e32 v8, v11, v11
	v_lshlrev_b32_e32 v10, 16, v123
	v_and_b32_e32 v11, 0xffff0000, v123
	v_fmac_f32_e32 v8, v10, v10
	v_fmac_f32_e32 v8, v11, v11
	v_lshlrev_b32_e32 v10, 16, v124
	v_and_b32_e32 v11, 0xffff0000, v124
	v_fmac_f32_e32 v8, v10, v10
	v_fmac_f32_e32 v8, v11, v11
	v_lshlrev_b32_e32 v10, 16, v125
	v_and_b32_e32 v11, 0xffff0000, v125
	v_fmac_f32_e32 v8, v10, v10
	v_fmac_f32_e32 v8, v11, v11
	v_lshlrev_b32_e32 v10, 16, v126
	v_and_b32_e32 v11, 0xffff0000, v126
	v_fmac_f32_e32 v8, v10, v10
	v_fmac_f32_e32 v8, v11, v11
	v_lshlrev_b32_e32 v10, 16, v127
	v_and_b32_e32 v11, 0xffff0000, v127
	v_fmac_f32_e32 v8, v10, v10
	v_fmac_f32_e32 v8, v11, v11
	v_lshlrev_b32_e32 v10, 16, v128
	v_and_b32_e32 v11, 0xffff0000, v128
	v_fmac_f32_e32 v8, v10, v10
	v_fmac_f32_e32 v8, v11, v11
	v_lshlrev_b32_e32 v10, 16, v129
	v_and_b32_e32 v11, 0xffff0000, v129
	v_fmac_f32_e32 v8, v10, v10
	v_fmac_f32_e32 v8, v11, v11
	s_nop 1
	v_add_f32_dpp v8, v8, v8 quad_perm:[1,0,3,2] row_mask:0xf bank_mask:0xf
	s_nop 1
	v_add_f32_dpp v8, v8, v8 quad_perm:[2,3,0,1] row_mask:0xf bank_mask:0xf
	s_nop 1
	v_add_f32_dpp v8, v8, v8 row_ror:4 row_mask:0xf bank_mask:0xf
	s_nop 1
	v_add_f32_dpp v8, v8, v8 row_ror:8 row_mask:0xf bank_mask:0xf
	s_nop 1
	v_readlane_b32 s42, v8, 0
	v_readlane_b32 s43, v8, 16
	v_readlane_b32 s44, v8, 32
	v_readlane_b32 s45, v8, 48
	s_nop 1
	v_mov_b32_e32 v8, s42
	v_add_f32_e32 v8, s43, v8
	v_add_f32_e32 v8, s44, v8
	v_add_f32_e32 v8, s45, v8
	v_mov_b32_e32 v4, s41
	v_fmac_f32_e32 v4, s40, v8
	v_rsq_f32_e32 v4, v4
	s_nop 0
	v_mov_b32_e32 v5, v4
	s_waitcnt vmcnt(56)
	s_waitcnt vmcnt(0)
	v_mov_b32_e32 v8, 0
	v_lshlrev_b32_e32 v10, 16, v114
	v_and_b32_e32 v11, 0xffff0000, v114
	v_pk_mul_f32 v[10:11], v[10:11], v[4:5]
	v_pk_mul_f32 v[10:11], v[10:11], v[130:131]
	v_pk_fma_f32 v[66:67], v[164:165], v[10:11], v[66:67]
	v_lshlrev_b32_e32 v10, 16, v115
	v_and_b32_e32 v11, 0xffff0000, v115
	v_pk_mul_f32 v[10:11], v[10:11], v[4:5]
	v_pk_mul_f32 v[10:11], v[10:11], v[132:133]
	v_pk_fma_f32 v[68:69], v[166:167], v[10:11], v[68:69]
	global_store_dwordx4 v1, v[66:69], s[24:25] nt
	v_fmac_f32_e32 v8, v66, v66
	v_fmac_f32_e32 v8, v67, v67
	v_fmac_f32_e32 v8, v68, v68
	v_fmac_f32_e32 v8, v69, v69
	v_lshlrev_b32_e32 v10, 16, v116
	v_and_b32_e32 v11, 0xffff0000, v116
	v_pk_mul_f32 v[10:11], v[10:11], v[4:5]
	v_pk_mul_f32 v[10:11], v[10:11], v[134:135]
	v_pk_fma_f32 v[70:71], v[168:169], v[10:11], v[70:71]
	v_lshlrev_b32_e32 v10, 16, v117
	v_and_b32_e32 v11, 0xffff0000, v117
	v_pk_mul_f32 v[10:11], v[10:11], v[4:5]
	v_pk_mul_f32 v[10:11], v[10:11], v[136:137]
	v_pk_fma_f32 v[72:73], v[170:171], v[10:11], v[72:73]
	global_store_dwordx4 v1, v[70:73], s[24:25] offset:1024 nt
	v_fmac_f32_e32 v8, v70, v70
	v_fmac_f32_e32 v8, v71, v71
	v_fmac_f32_e32 v8, v72, v72
	v_fmac_f32_e32 v8, v73, v73
	v_lshlrev_b32_e32 v10, 16, v118
	v_and_b32_e32 v11, 0xffff0000, v118
	v_pk_mul_f32 v[10:11], v[10:11], v[4:5]
	v_pk_mul_f32 v[10:11], v[10:11], v[138:139]
	v_pk_fma_f32 v[74:75], v[172:173], v[10:11], v[74:75]
	v_lshlrev_b32_e32 v10, 16, v119
	v_and_b32_e32 v11, 0xffff0000, v119
	v_pk_mul_f32 v[10:11], v[10:11], v[4:5]
	v_pk_mul_f32 v[10:11], v[10:11], v[140:141]
	v_pk_fma_f32 v[76:77], v[174:175], v[10:11], v[76:77]
	global_store_dwordx4 v1, v[74:77], s[24:25] offset:2048 nt
	v_fmac_f32_e32 v8, v74, v74
	v_fmac_f32_e32 v8, v75, v75
	v_fmac_f32_e32 v8, v76, v76
	v_fmac_f32_e32 v8, v77, v77
	v_lshlrev_b32_e32 v10, 16, v120
	v_and_b32_e32 v11, 0xffff0000, v120
	v_pk_mul_f32 v[10:11], v[10:11], v[4:5]
	v_pk_mul_f32 v[10:11], v[10:11], v[142:143]
	v_pk_fma_f32 v[78:79], v[176:177], v[10:11], v[78:79]
	v_lshlrev_b32_e32 v10, 16, v121
	v_and_b32_e32 v11, 0xffff0000, v121
	v_pk_mul_f32 v[10:11], v[10:11], v[4:5]
	v_pk_mul_f32 v[10:11], v[10:11], v[144:145]
	v_pk_fma_f32 v[80:81], v[178:179], v[10:11], v[80:81]
	global_store_dwordx4 v1, v[78:81], s[24:25] offset:3072 nt
	v_fmac_f32_e32 v8, v78, v78
	v_fmac_f32_e32 v8, v79, v79
	v_fmac_f32_e32 v8, v80, v80
	v_fmac_f32_e32 v8, v81, v81
	v_lshlrev_b32_e32 v10, 16, v122
	v_and_b32_e32 v11, 0xffff0000, v122
	v_pk_mul_f32 v[10:11], v[10:11], v[4:5]
	v_pk_mul_f32 v[10:11], v[10:11], v[146:147]
	v_pk_fma_f32 v[82:83], v[180:181], v[10:11], v[82:83]
	v_lshlrev_b32_e32 v10, 16, v123
	v_and_b32_e32 v11, 0xffff0000, v123
	v_pk_mul_f32 v[10:11], v[10:11], v[4:5]
	v_pk_mul_f32 v[10:11], v[10:11], v[148:149]
	v_pk_fma_f32 v[84:85], v[182:183], v[10:11], v[84:85]
	global_store_dwordx4 v1, v[82:85], s[34:35] nt
	v_fmac_f32_e32 v8, v82, v82
	v_fmac_f32_e32 v8, v83, v83
	v_fmac_f32_e32 v8, v84, v84
	v_fmac_f32_e32 v8, v85, v85
	v_lshlrev_b32_e32 v10, 16, v124
	v_and_b32_e32 v11, 0xffff0000, v124
	v_pk_mul_f32 v[10:11], v[10:11], v[4:5]
	v_pk_mul_f32 v[10:11], v[10:11], v[150:151]
	v_pk_fma_f32 v[86:87], v[184:185], v[10:11], v[86:87]
	v_lshlrev_b32_e32 v10, 16, v125
	v_and_b32_e32 v11, 0xffff0000, v125
	v_pk_mul_f32 v[10:11], v[10:11], v[4:5]
	v_pk_mul_f32 v[10:11], v[10:11], v[152:153]
	v_pk_fma_f32 v[88:89], v[186:187], v[10:11], v[88:89]
	global_store_dwordx4 v1, v[86:89], s[34:35] offset:1024 nt
	v_fmac_f32_e32 v8, v86, v86
	v_fmac_f32_e32 v8, v87, v87
	v_fmac_f32_e32 v8, v88, v88
	v_fmac_f32_e32 v8, v89, v89
	v_lshlrev_b32_e32 v10, 16, v126
	v_and_b32_e32 v11, 0xffff0000, v126
	v_pk_mul_f32 v[10:11], v[10:11], v[4:5]
	v_pk_mul_f32 v[10:11], v[10:11], v[156:157]
	v_pk_fma_f32 v[90:91], v[188:189], v[10:11], v[90:91]
	v_lshlrev_b32_e32 v10, 16, v127
	v_and_b32_e32 v11, 0xffff0000, v127
	v_pk_mul_f32 v[10:11], v[10:11], v[4:5]
	v_pk_mul_f32 v[10:11], v[10:11], v[158:159]
	v_pk_fma_f32 v[92:93], v[190:191], v[10:11], v[92:93]
	global_store_dwordx4 v1, v[90:93], s[34:35] offset:2048 nt
	v_fmac_f32_e32 v8, v90, v90
	v_fmac_f32_e32 v8, v91, v91
	v_fmac_f32_e32 v8, v92, v92
	v_fmac_f32_e32 v8, v93, v93
	v_lshlrev_b32_e32 v10, 16, v128
	v_and_b32_e32 v11, 0xffff0000, v128
	v_pk_mul_f32 v[10:11], v[10:11], v[4:5]
	v_pk_mul_f32 v[10:11], v[10:11], v[160:161]
	v_pk_fma_f32 v[94:95], v[192:193], v[10:11], v[94:95]
	v_lshlrev_b32_e32 v10, 16, v129
	v_and_b32_e32 v11, 0xffff0000, v129
	v_pk_mul_f32 v[10:11], v[10:11], v[4:5]
	v_pk_mul_f32 v[10:11], v[10:11], v[162:163]
	v_pk_fma_f32 v[96:97], v[194:195], v[10:11], v[96:97]
	global_store_dwordx4 v1, v[94:97], s[34:35] offset:3072 nt
	v_fmac_f32_e32 v8, v94, v94
	v_fmac_f32_e32 v8, v95, v95
	v_fmac_f32_e32 v8, v96, v96
	v_fmac_f32_e32 v8, v97, v97
	s_add_u32 s18, s2, 0x1000
	s_addc_u32 s19, s3, 0
	global_load_dwordx4 v[130:133], v1, s[2:3]
	global_load_dwordx4 v[134:137], v1, s[2:3] offset:1024
	global_load_dwordx4 v[138:141], v1, s[2:3] offset:2048
	global_load_dwordx4 v[142:145], v1, s[2:3] offset:3072
	global_load_dwordx4 v[146:149], v1, s[18:19]
	global_load_dwordx4 v[150:153], v1, s[18:19] offset:1024
	global_load_dwordx4 v[156:159], v1, s[18:19] offset:2048
	global_load_dwordx4 v[160:163], v1, s[18:19] offset:3072
	s_add_u32 s18, s30, 0x1000
	s_addc_u32 s19, s31, 0
	global_load_dwordx4 v[164:167], v1, s[30:31]
	global_load_dwordx4 v[168:171], v1, s[30:31] offset:1024
	global_load_dwordx4 v[172:175], v1, s[30:31] offset:2048
	global_load_dwordx4 v[176:179], v1, s[30:31] offset:3072
	global_load_dwordx4 v[180:183], v1, s[18:19]
	global_load_dwordx4 v[184:187], v1, s[18:19] offset:1024
	global_load_dwordx4 v[188:191], v1, s[18:19] offset:2048
	global_load_dwordx4 v[192:195], v1, s[18:19] offset:3072
	s_add_u32 s18, s32, 0x1000
	s_addc_u32 s19, s33, 0
	global_load_dwordx4 v[196:199], v1, s[32:33]
	global_load_dwordx4 v[200:203], v1, s[32:33] offset:1024
	global_load_dwordx4 v[204:207], v1, s[32:33] offset:2048
	global_load_dwordx4 v[208:211], v1, s[32:33] offset:3072
	global_load_dwordx4 v[212:215], v1, s[18:19]
	global_load_dwordx4 v[216:219], v1, s[18:19] offset:1024
	global_load_dwordx4 v[220:223], v1, s[18:19] offset:2048
	global_load_dwordx4 v[224:227], v1, s[18:19] offset:3072
	s_nop 1
	v_add_f32_dpp v8, v8, v8 quad_perm:[1,0,3,2] row_mask:0xf bank_mask:0xf
	s_nop 1
	v_add_f32_dpp v8, v8, v8 quad_perm:[2,3,0,1] row_mask:0xf bank_mask:0xf
	s_nop 1
	v_add_f32_dpp v8, v8, v8 row_ror:4 row_mask:0xf bank_mask:0xf
	s_nop 1
	v_add_f32_dpp v8, v8, v8 row_ror:8 row_mask:0xf bank_mask:0xf
	s_nop 1
	v_readlane_b32 s42, v8, 0
	v_readlane_b32 s43, v8, 16
	v_readlane_b32 s44, v8, 32
	v_readlane_b32 s45, v8, 48
	s_nop 1
	v_mov_b32_e32 v8, s42
	v_add_f32_e32 v8, s43, v8
	v_add_f32_e32 v8, s44, v8
	v_add_f32_e32 v8, s45, v8
	v_mov_b32_e32 v4, s41
	v_fmac_f32_e32 v4, s40, v8
	v_rsq_f32_e32 v4, v4
	s_nop 0
	v_mov_b32_e32 v5, v4
	s_waitcnt vmcnt(0)
	v_pk_mul_f32 v[10:11], v[66:67], v[4:5]
	v_pk_mul_f32 v[10:11], v[10:11], v[130:131]
	v_pk_add_f32 v[12:13], v[196:197], v[6:7]
	v_pk_fma_f32 v[14:15], v[10:11], v[12:13], v[164:165]
	v_pk_mul_f32 v[10:11], v[68:69], v[4:5]
	v_pk_mul_f32 v[10:11], v[10:11], v[132:133]
	v_pk_add_f32 v[12:13], v[198:199], v[6:7]
	v_pk_fma_f32 v[16:17], v[10:11], v[12:13], v[166:167]
	v_cvt_pk_bf16_f32 v26, v14, v15
	v_cvt_pk_bf16_f32 v27, v16, v17
	global_store_dwordx2 v2, v[26:27], s[26:27]
	v_pk_mul_f32 v[10:11], v[70:71], v[4:5]
	v_pk_mul_f32 v[10:11], v[10:11], v[134:135]
	v_pk_add_f32 v[12:13], v[200:201], v[6:7]
	v_pk_fma_f32 v[14:15], v[10:11], v[12:13], v[168:169]
	v_pk_mul_f32 v[10:11], v[72:73], v[4:5]
	v_pk_mul_f32 v[10:11], v[10:11], v[136:137]
	v_pk_add_f32 v[12:13], v[202:203], v[6:7]
	v_pk_fma_f32 v[16:17], v[10:11], v[12:13], v[170:171]
	v_cvt_pk_bf16_f32 v28, v14, v15
	v_cvt_pk_bf16_f32 v29, v16, v17
	global_store_dwordx2 v2, v[28:29], s[26:27] offset:512
	v_pk_mul_f32 v[10:11], v[74:75], v[4:5]
	v_pk_mul_f32 v[10:11], v[10:11], v[138:139]
	v_pk_add_f32 v[12:13], v[204:205], v[6:7]
	v_pk_fma_f32 v[14:15], v[10:11], v[12:13], v[172:173]
	v_pk_mul_f32 v[10:11], v[76:77], v[4:5]
	v_pk_mul_f32 v[10:11], v[10:11], v[140:141]
	v_pk_add_f32 v[12:13], v[206:207], v[6:7]
	v_pk_fma_f32 v[16:17], v[10:11], v[12:13], v[174:175]
	v_cvt_pk_bf16_f32 v30, v14, v15
	v_cvt_pk_bf16_f32 v31, v16, v17
	global_store_dwordx2 v2, v[30:31], s[26:27] offset:1024
	v_pk_mul_f32 v[10:11], v[78:79], v[4:5]
	v_pk_mul_f32 v[10:11], v[10:11], v[142:143]
	v_pk_add_f32 v[12:13], v[208:209], v[6:7]
	v_pk_fma_f32 v[14:15], v[10:11], v[12:13], v[176:177]
	v_pk_mul_f32 v[10:11], v[80:81], v[4:5]
	v_pk_mul_f32 v[10:11], v[10:11], v[144:145]
	v_pk_add_f32 v[12:13], v[210:211], v[6:7]
	v_pk_fma_f32 v[16:17], v[10:11], v[12:13], v[178:179]
	v_cvt_pk_bf16_f32 v32, v14, v15
	v_cvt_pk_bf16_f32 v33, v16, v17
	global_store_dwordx2 v2, v[32:33], s[26:27] offset:1536
	v_pk_mul_f32 v[10:11], v[82:83], v[4:5]
	v_pk_mul_f32 v[10:11], v[10:11], v[146:147]
	v_pk_add_f32 v[12:13], v[212:213], v[6:7]
	v_pk_fma_f32 v[14:15], v[10:11], v[12:13], v[180:181]
	v_pk_mul_f32 v[10:11], v[84:85], v[4:5]
	v_pk_mul_f32 v[10:11], v[10:11], v[148:149]
	v_pk_add_f32 v[12:13], v[214:215], v[6:7]
	v_pk_fma_f32 v[16:17], v[10:11], v[12:13], v[182:183]
	v_cvt_pk_bf16_f32 v26, v14, v15
	v_cvt_pk_bf16_f32 v27, v16, v17
	global_store_dwordx2 v2, v[26:27], s[26:27] offset:2048
	v_pk_mul_f32 v[10:11], v[86:87], v[4:5]
	v_pk_mul_f32 v[10:11], v[10:11], v[150:151]
	v_pk_add_f32 v[12:13], v[216:217], v[6:7]
	v_pk_fma_f32 v[14:15], v[10:11], v[12:13], v[184:185]
	v_pk_mul_f32 v[10:11], v[88:89], v[4:5]
	v_pk_mul_f32 v[10:11], v[10:11], v[152:153]
	v_pk_add_f32 v[12:13], v[218:219], v[6:7]
	v_pk_fma_f32 v[16:17], v[10:11], v[12:13], v[186:187]
	v_cvt_pk_bf16_f32 v28, v14, v15
	v_cvt_pk_bf16_f32 v29, v16, v17
	global_store_dwordx2 v2, v[28:29], s[26:27] offset:2560
	v_pk_mul_f32 v[10:11], v[90:91], v[4:5]
	v_pk_mul_f32 v[10:11], v[10:11], v[156:157]
	v_pk_add_f32 v[12:13], v[220:221], v[6:7]
	v_pk_fma_f32 v[14:15], v[10:11], v[12:13], v[188:189]
	v_pk_mul_f32 v[10:11], v[92:93], v[4:5]
	v_pk_mul_f32 v[10:11], v[10:11], v[158:159]
	v_pk_add_f32 v[12:13], v[222:223], v[6:7]
	v_pk_fma_f32 v[16:17], v[10:11], v[12:13], v[190:191]
	v_cvt_pk_bf16_f32 v30, v14, v15
	v_cvt_pk_bf16_f32 v31, v16, v17
	global_store_dwordx2 v2, v[30:31], s[26:27] offset:3072
	v_pk_mul_f32 v[10:11], v[94:95], v[4:5]
	v_pk_mul_f32 v[10:11], v[10:11], v[160:161]
	v_pk_add_f32 v[12:13], v[224:225], v[6:7]
	v_pk_fma_f32 v[14:15], v[10:11], v[12:13], v[192:193]
	v_pk_mul_f32 v[10:11], v[96:97], v[4:5]
	v_pk_mul_f32 v[10:11], v[10:11], v[162:163]
	v_pk_add_f32 v[12:13], v[226:227], v[6:7]
	v_pk_fma_f32 v[16:17], v[10:11], v[12:13], v[194:195]
	v_cvt_pk_bf16_f32 v32, v14, v15
	v_cvt_pk_bf16_f32 v33, v16, v17
	global_store_dwordx2 v2, v[32:33], s[26:27] offset:3584
	s_waitcnt vmcnt(0)
	s_branch .LBB0_2331

.LBB0_2730:
.LBB0_2731:
	s_waitcnt vmcnt(0) lgkmcnt(0)
	s_load_dwordx2 s[0:1], s[92:93], 0x50
	s_load_dwordx2 s[2:3], s[92:93], 0x38
	s_load_dwordx2 s[4:5], s[92:93], 0xf0
	v_and_b32_e32 v2, 63, v154
	v_lshlrev_b32_e32 v1, 4, v2
	v_lshlrev_b32_e32 v2, 3, v2
	v_mov_b32_e32 v6, 1.0
	v_mov_b32_e32 v7, 1.0
	s_mov_b32 s40, 0x3a000000
	s_mov_b32 s41, 0x358637bd
	v_readfirstlane_b32 s10, v154
	s_lshr_b32 s10, s10, 6
	s_lshl_b32 s12, s96, 3
	s_add_u32 s10, s10, s12
	s_waitcnt lgkmcnt(0)
	s_add_u32 s0, s0, 0x2000
	s_addc_u32 s1, s1, 0
	s_add_u32 s12, s10, 0
	s_lshl_b32 s13, s12, 13
	s_lshl_b32 s14, s12, 12
	s_add_u32 s20, s4, s13
	s_addc_u32 s21, s5, 0
	s_add_u32 s22, s90, 0x28918000
	s_addc_u32 s23, s91, 0
	s_add_u32 s22, s22, s14
	s_addc_u32 s23, s23, 0
	global_load_dwordx2 v[98:99], v2, s[22:23] nt
	global_load_dwordx2 v[100:101], v2, s[22:23] offset:512 nt
	global_load_dwordx2 v[102:103], v2, s[22:23] offset:1024 nt
	global_load_dwordx2 v[104:105], v2, s[22:23] offset:1536 nt
	global_load_dwordx2 v[106:107], v2, s[22:23] offset:2048 nt
	global_load_dwordx2 v[108:109], v2, s[22:23] offset:2560 nt
	global_load_dwordx2 v[110:111], v2, s[22:23] offset:3072 nt
	global_load_dwordx2 v[112:113], v2, s[22:23] offset:3584 nt
	s_add_u32 s36, s20, 0x1000
	s_addc_u32 s37, s21, 0
	global_load_dwordx4 v[34:37], v1, s[20:21] nt
	global_load_dwordx4 v[38:41], v1, s[20:21] offset:1024 nt
	global_load_dwordx4 v[42:45], v1, s[20:21] offset:2048 nt
	global_load_dwordx4 v[46:49], v1, s[20:21] offset:3072 nt
	global_load_dwordx4 v[50:53], v1, s[36:37] nt
	global_load_dwordx4 v[54:57], v1, s[36:37] offset:1024 nt
	global_load_dwordx4 v[58:61], v1, s[36:37] offset:2048 nt
	global_load_dwordx4 v[62:65], v1, s[36:37] offset:3072 nt
	s_mov_b32 s16, 4
	s_add_u32 s17, s16, 5
	s_mul_i32 s17, s17, 49152
	s_add_u32 s17, s17, 0x1040a000
	s_add_u32 s28, s90, s17
	s_addc_u32 s29, s91, 0
	s_add_u32 s18, s0, 0x1000
	s_addc_u32 s19, s1, 0
	global_load_dwordx4 v[130:133], v1, s[0:1]
	global_load_dwordx4 v[134:137], v1, s[0:1] offset:1024
	global_load_dwordx4 v[138:141], v1, s[0:1] offset:2048
	global_load_dwordx4 v[142:145], v1, s[0:1] offset:3072
	global_load_dwordx4 v[146:149], v1, s[18:19]
	global_load_dwordx4 v[150:153], v1, s[18:19] offset:1024
	global_load_dwordx4 v[156:159], v1, s[18:19] offset:2048
	global_load_dwordx4 v[160:163], v1, s[18:19] offset:3072
	s_add_u32 s18, s28, 0x1000
	s_addc_u32 s19, s29, 0
	global_load_dwordx4 v[164:167], v1, s[28:29]
	global_load_dwordx4 v[168:171], v1, s[28:29] offset:1024
	global_load_dwordx4 v[172:175], v1, s[28:29] offset:2048
	global_load_dwordx4 v[176:179], v1, s[28:29] offset:3072
	global_load_dwordx4 v[180:183], v1, s[18:19]
	global_load_dwordx4 v[184:187], v1, s[18:19] offset:1024
	global_load_dwordx4 v[188:191], v1, s[18:19] offset:2048
	global_load_dwordx4 v[192:195], v1, s[18:19] offset:3072
	s_add_u32 s12, s10, 2048
	s_lshl_b32 s13, s12, 13
	s_lshl_b32 s14, s12, 12
	s_add_u32 s20, s4, s13
	s_addc_u32 s21, s5, 0
	s_add_u32 s22, s90, 0x28918000
	s_addc_u32 s23, s91, 0
	s_add_u32 s22, s22, s14
	s_addc_u32 s23, s23, 0
	global_load_dwordx2 v[114:115], v2, s[22:23] nt
	global_load_dwordx2 v[116:117], v2, s[22:23] offset:512 nt
	global_load_dwordx2 v[118:119], v2, s[22:23] offset:1024 nt
	global_load_dwordx2 v[120:121], v2, s[22:23] offset:1536 nt
	global_load_dwordx2 v[122:123], v2, s[22:23] offset:2048 nt
	global_load_dwordx2 v[124:125], v2, s[22:23] offset:2560 nt
	global_load_dwordx2 v[126:127], v2, s[22:23] offset:3072 nt
	global_load_dwordx2 v[128:129], v2, s[22:23] offset:3584 nt
	s_add_u32 s36, s20, 0x1000
	s_addc_u32 s37, s21, 0
	global_load_dwordx4 v[66:69], v1, s[20:21] nt
	global_load_dwordx4 v[70:73], v1, s[20:21] offset:1024 nt
	global_load_dwordx4 v[74:77], v1, s[20:21] offset:2048 nt
	global_load_dwordx4 v[78:81], v1, s[20:21] offset:3072 nt
	global_load_dwordx4 v[82:85], v1, s[36:37] nt
	global_load_dwordx4 v[86:89], v1, s[36:37] offset:1024 nt
	global_load_dwordx4 v[90:93], v1, s[36:37] offset:2048 nt
	global_load_dwordx4 v[94:97], v1, s[36:37] offset:3072 nt
	s_add_u32 s12, s10, 0
	s_lshl_b32 s13, s12, 13
	s_lshl_b32 s14, s12, 12
	s_add_u32 s24, s4, s13
	s_addc_u32 s25, s5, 0
	s_add_u32 s34, s24, 0x1000
	s_addc_u32 s35, s25, 0
	s_add_u32 s26, s90, 0x11918000
	s_addc_u32 s27, s91, 0
	s_add_u32 s26, s26, s14
	s_addc_u32 s27, s27, 0
	s_waitcnt vmcnt(40)
	v_mov_b32_e32 v8, 0
	v_lshlrev_b32_e32 v10, 16, v98
	v_and_b32_e32 v11, 0xffff0000, v98
	v_fmac_f32_e32 v8, v10, v10
	v_fmac_f32_e32 v8, v11, v11
	v_lshlrev_b32_e32 v10, 16, v99
	v_and_b32_e32 v11, 0xffff0000, v99
	v_fmac_f32_e32 v8, v10, v10
	v_fmac_f32_e32 v8, v11, v11
	v_lshlrev_b32_e32 v10, 16, v100
	v_and_b32_e32 v11, 0xffff0000, v100
	v_fmac_f32_e32 v8, v10, v10
	v_fmac_f32_e32 v8, v11, v11
	v_lshlrev_b32_e32 v10, 16, v101
	v_and_b32_e32 v11, 0xffff0000, v101
	v_fmac_f32_e32 v8, v10, v10
	v_fmac_f32_e32 v8, v11, v11
	v_lshlrev_b32_e32 v10, 16, v102
	v_and_b32_e32 v11, 0xffff0000, v102
	v_fmac_f32_e32 v8, v10, v10
	v_fmac_f32_e32 v8, v11, v11
	v_lshlrev_b32_e32 v10, 16, v103
	v_and_b32_e32 v11, 0xffff0000, v103
	v_fmac_f32_e32 v8, v10, v10
	v_fmac_f32_e32 v8, v11, v11
	v_lshlrev_b32_e32 v10, 16, v104
	v_and_b32_e32 v11, 0xffff0000, v104
	v_fmac_f32_e32 v8, v10, v10
	v_fmac_f32_e32 v8, v11, v11
	v_lshlrev_b32_e32 v10, 16, v105
	v_and_b32_e32 v11, 0xffff0000, v105
	v_fmac_f32_e32 v8, v10, v10
	v_fmac_f32_e32 v8, v11, v11
	v_lshlrev_b32_e32 v10, 16, v106
	v_and_b32_e32 v11, 0xffff0000, v106
	v_fmac_f32_e32 v8, v10, v10
	v_fmac_f32_e32 v8, v11, v11
	v_lshlrev_b32_e32 v10, 16, v107
	v_and_b32_e32 v11, 0xffff0000, v107
	v_fmac_f32_e32 v8, v10, v10
	v_fmac_f32_e32 v8, v11, v11
	v_lshlrev_b32_e32 v10, 16, v108
	v_and_b32_e32 v11, 0xffff0000, v108
	v_fmac_f32_e32 v8, v10, v10
	v_fmac_f32_e32 v8, v11, v11
	v_lshlrev_b32_e32 v10, 16, v109
	v_and_b32_e32 v11, 0xffff0000, v109
	v_fmac_f32_e32 v8, v10, v10
	v_fmac_f32_e32 v8, v11, v11
	v_lshlrev_b32_e32 v10, 16, v110
	v_and_b32_e32 v11, 0xffff0000, v110
	v_fmac_f32_e32 v8, v10, v10
	v_fmac_f32_e32 v8, v11, v11
	v_lshlrev_b32_e32 v10, 16, v111
	v_and_b32_e32 v11, 0xffff0000, v111
	v_fmac_f32_e32 v8, v10, v10
	v_fmac_f32_e32 v8, v11, v11
	v_lshlrev_b32_e32 v10, 16, v112
	v_and_b32_e32 v11, 0xffff0000, v112
	v_fmac_f32_e32 v8, v10, v10
	v_fmac_f32_e32 v8, v11, v11
	v_lshlrev_b32_e32 v10, 16, v113
	v_and_b32_e32 v11, 0xffff0000, v113
	v_fmac_f32_e32 v8, v10, v10
	v_fmac_f32_e32 v8, v11, v11
	s_nop 1
	v_add_f32_dpp v8, v8, v8 quad_perm:[1,0,3,2] row_mask:0xf bank_mask:0xf
	s_nop 1
	v_add_f32_dpp v8, v8, v8 quad_perm:[2,3,0,1] row_mask:0xf bank_mask:0xf
	s_nop 1
	v_add_f32_dpp v8, v8, v8 row_ror:4 row_mask:0xf bank_mask:0xf
	s_nop 1
	v_add_f32_dpp v8, v8, v8 row_ror:8 row_mask:0xf bank_mask:0xf
	s_nop 1
	v_readlane_b32 s42, v8, 0
	v_readlane_b32 s43, v8, 16
	v_readlane_b32 s44, v8, 32
	v_readlane_b32 s45, v8, 48
	s_nop 1
	v_mov_b32_e32 v8, s42
	v_add_f32_e32 v8, s43, v8
	v_add_f32_e32 v8, s44, v8
	v_add_f32_e32 v8, s45, v8
	v_mov_b32_e32 v4, s41
	v_fmac_f32_e32 v4, s40, v8
	v_rsq_f32_e32 v4, v4
	s_nop 0
	v_mov_b32_e32 v5, v4
	s_waitcnt vmcnt(32)
	s_waitcnt vmcnt(16)
	v_mov_b32_e32 v8, 0
	v_lshlrev_b32_e32 v10, 16, v98
	v_and_b32_e32 v11, 0xffff0000, v98
	v_pk_mul_f32 v[10:11], v[10:11], v[4:5]
	v_pk_mul_f32 v[10:11], v[10:11], v[130:131]
	v_pk_fma_f32 v[34:35], v[164:165], v[10:11], v[34:35]
	v_lshlrev_b32_e32 v10, 16, v99
	v_and_b32_e32 v11, 0xffff0000, v99
	v_pk_mul_f32 v[10:11], v[10:11], v[4:5]
	v_pk_mul_f32 v[10:11], v[10:11], v[132:133]
	v_pk_fma_f32 v[36:37], v[166:167], v[10:11], v[36:37]
	global_store_dwordx4 v1, v[34:37], s[24:25] nt
	v_lshlrev_b32_e32 v10, 16, v100
	v_and_b32_e32 v11, 0xffff0000, v100
	v_pk_mul_f32 v[10:11], v[10:11], v[4:5]
	v_pk_mul_f32 v[10:11], v[10:11], v[134:135]
	v_pk_fma_f32 v[38:39], v[168:169], v[10:11], v[38:39]
	v_lshlrev_b32_e32 v10, 16, v101
	v_and_b32_e32 v11, 0xffff0000, v101
	v_pk_mul_f32 v[10:11], v[10:11], v[4:5]
	v_pk_mul_f32 v[10:11], v[10:11], v[136:137]
	v_pk_fma_f32 v[40:41], v[170:171], v[10:11], v[40:41]
	global_store_dwordx4 v1, v[38:41], s[24:25] offset:1024 nt
	v_lshlrev_b32_e32 v10, 16, v102
	v_and_b32_e32 v11, 0xffff0000, v102
	v_pk_mul_f32 v[10:11], v[10:11], v[4:5]
	v_pk_mul_f32 v[10:11], v[10:11], v[138:139]
	v_pk_fma_f32 v[42:43], v[172:173], v[10:11], v[42:43]
	v_lshlrev_b32_e32 v10, 16, v103
	v_and_b32_e32 v11, 0xffff0000, v103
	v_pk_mul_f32 v[10:11], v[10:11], v[4:5]
	v_pk_mul_f32 v[10:11], v[10:11], v[140:141]
	v_pk_fma_f32 v[44:45], v[174:175], v[10:11], v[44:45]
	global_store_dwordx4 v1, v[42:45], s[24:25] offset:2048 nt
	v_lshlrev_b32_e32 v10, 16, v104
	v_and_b32_e32 v11, 0xffff0000, v104
	v_pk_mul_f32 v[10:11], v[10:11], v[4:5]
	v_pk_mul_f32 v[10:11], v[10:11], v[142:143]
	v_pk_fma_f32 v[46:47], v[176:177], v[10:11], v[46:47]
	v_lshlrev_b32_e32 v10, 16, v105
	v_and_b32_e32 v11, 0xffff0000, v105
	v_pk_mul_f32 v[10:11], v[10:11], v[4:5]
	v_pk_mul_f32 v[10:11], v[10:11], v[144:145]
	v_pk_fma_f32 v[48:49], v[178:179], v[10:11], v[48:49]
	global_store_dwordx4 v1, v[46:49], s[24:25] offset:3072 nt
	v_lshlrev_b32_e32 v10, 16, v106
	v_and_b32_e32 v11, 0xffff0000, v106
	v_pk_mul_f32 v[10:11], v[10:11], v[4:5]
	v_pk_mul_f32 v[10:11], v[10:11], v[146:147]
	v_pk_fma_f32 v[50:51], v[180:181], v[10:11], v[50:51]
	v_lshlrev_b32_e32 v10, 16, v107
	v_and_b32_e32 v11, 0xffff0000, v107
	v_pk_mul_f32 v[10:11], v[10:11], v[4:5]
	v_pk_mul_f32 v[10:11], v[10:11], v[148:149]
	v_pk_fma_f32 v[52:53], v[182:183], v[10:11], v[52:53]
	global_store_dwordx4 v1, v[50:53], s[34:35] nt
	v_lshlrev_b32_e32 v10, 16, v108
	v_and_b32_e32 v11, 0xffff0000, v108
	v_pk_mul_f32 v[10:11], v[10:11], v[4:5]
	v_pk_mul_f32 v[10:11], v[10:11], v[150:151]
	v_pk_fma_f32 v[54:55], v[184:185], v[10:11], v[54:55]
	v_lshlrev_b32_e32 v10, 16, v109
	v_and_b32_e32 v11, 0xffff0000, v109
	v_pk_mul_f32 v[10:11], v[10:11], v[4:5]
	v_pk_mul_f32 v[10:11], v[10:11], v[152:153]
	v_pk_fma_f32 v[56:57], v[186:187], v[10:11], v[56:57]
	global_store_dwordx4 v1, v[54:57], s[34:35] offset:1024 nt
	v_lshlrev_b32_e32 v10, 16, v110
	v_and_b32_e32 v11, 0xffff0000, v110
	v_pk_mul_f32 v[10:11], v[10:11], v[4:5]
	v_pk_mul_f32 v[10:11], v[10:11], v[156:157]
	v_pk_fma_f32 v[58:59], v[188:189], v[10:11], v[58:59]
	v_lshlrev_b32_e32 v10, 16, v111
	v_and_b32_e32 v11, 0xffff0000, v111
	v_pk_mul_f32 v[10:11], v[10:11], v[4:5]
	v_pk_mul_f32 v[10:11], v[10:11], v[158:159]
	v_pk_fma_f32 v[60:61], v[190:191], v[10:11], v[60:61]
	global_store_dwordx4 v1, v[58:61], s[34:35] offset:2048 nt
	v_lshlrev_b32_e32 v10, 16, v112
	v_and_b32_e32 v11, 0xffff0000, v112
	v_pk_mul_f32 v[10:11], v[10:11], v[4:5]
	v_pk_mul_f32 v[10:11], v[10:11], v[160:161]
	v_pk_fma_f32 v[62:63], v[192:193], v[10:11], v[62:63]
	v_lshlrev_b32_e32 v10, 16, v113
	v_and_b32_e32 v11, 0xffff0000, v113
	v_pk_mul_f32 v[10:11], v[10:11], v[4:5]
	v_pk_mul_f32 v[10:11], v[10:11], v[162:163]
	v_pk_fma_f32 v[64:65], v[194:195], v[10:11], v[64:65]
	global_store_dwordx4 v1, v[62:65], s[34:35] offset:3072 nt
	s_mov_b32 s16, 4
	s_add_u32 s17, s16, 5
	s_mul_i32 s17, s17, 49152
	s_add_u32 s17, s17, 0x1040a000
	s_add_u32 s28, s90, s17
	s_addc_u32 s29, s91, 0
	s_add_u32 s18, s0, 0x1000
	s_addc_u32 s19, s1, 0
	global_load_dwordx4 v[130:133], v1, s[0:1]
	global_load_dwordx4 v[134:137], v1, s[0:1] offset:1024
	global_load_dwordx4 v[138:141], v1, s[0:1] offset:2048
	global_load_dwordx4 v[142:145], v1, s[0:1] offset:3072
	global_load_dwordx4 v[146:149], v1, s[18:19]
	global_load_dwordx4 v[150:153], v1, s[18:19] offset:1024
	global_load_dwordx4 v[156:159], v1, s[18:19] offset:2048
	global_load_dwordx4 v[160:163], v1, s[18:19] offset:3072
	s_add_u32 s18, s28, 0x1000
	s_addc_u32 s19, s29, 0
	global_load_dwordx4 v[164:167], v1, s[28:29]
	global_load_dwordx4 v[168:171], v1, s[28:29] offset:1024
	global_load_dwordx4 v[172:175], v1, s[28:29] offset:2048
	global_load_dwordx4 v[176:179], v1, s[28:29] offset:3072
	global_load_dwordx4 v[180:183], v1, s[18:19]
	global_load_dwordx4 v[184:187], v1, s[18:19] offset:1024
	global_load_dwordx4 v[188:191], v1, s[18:19] offset:2048
	global_load_dwordx4 v[192:195], v1, s[18:19] offset:3072
	s_add_u32 s12, s10, 4096
	s_lshl_b32 s13, s12, 13
	s_lshl_b32 s14, s12, 12
	s_add_u32 s20, s4, s13
	s_addc_u32 s21, s5, 0
	s_add_u32 s22, s90, 0x28918000
	s_addc_u32 s23, s91, 0
	s_add_u32 s22, s22, s14
	s_addc_u32 s23, s23, 0
	global_load_dwordx2 v[98:99], v2, s[22:23] nt
	global_load_dwordx2 v[100:101], v2, s[22:23] offset:512 nt
	global_load_dwordx2 v[102:103], v2, s[22:23] offset:1024 nt
	global_load_dwordx2 v[104:105], v2, s[22:23] offset:1536 nt
	global_load_dwordx2 v[106:107], v2, s[22:23] offset:2048 nt
	global_load_dwordx2 v[108:109], v2, s[22:23] offset:2560 nt
	global_load_dwordx2 v[110:111], v2, s[22:23] offset:3072 nt
	global_load_dwordx2 v[112:113], v2, s[22:23] offset:3584 nt
	s_add_u32 s36, s20, 0x1000
	s_addc_u32 s37, s21, 0
	global_load_dwordx4 v[34:37], v1, s[20:21] nt
	global_load_dwordx4 v[38:41], v1, s[20:21] offset:1024 nt
	global_load_dwordx4 v[42:45], v1, s[20:21] offset:2048 nt
	global_load_dwordx4 v[46:49], v1, s[20:21] offset:3072 nt
	global_load_dwordx4 v[50:53], v1, s[36:37] nt
	global_load_dwordx4 v[54:57], v1, s[36:37] offset:1024 nt
	global_load_dwordx4 v[58:61], v1, s[36:37] offset:2048 nt
	global_load_dwordx4 v[62:65], v1, s[36:37] offset:3072 nt
	s_add_u32 s12, s10, 2048
	s_lshl_b32 s13, s12, 13
	s_lshl_b32 s14, s12, 12
	s_add_u32 s24, s4, s13
	s_addc_u32 s25, s5, 0
	s_add_u32 s34, s24, 0x1000
	s_addc_u32 s35, s25, 0
	s_add_u32 s26, s90, 0x11918000
	s_addc_u32 s27, s91, 0
	s_add_u32 s26, s26, s14
	s_addc_u32 s27, s27, 0
	s_waitcnt vmcnt(48)
	v_mov_b32_e32 v8, 0
	v_lshlrev_b32_e32 v10, 16, v114
	v_and_b32_e32 v11, 0xffff0000, v114
	v_fmac_f32_e32 v8, v10, v10
	v_fmac_f32_e32 v8, v11, v11
	v_lshlrev_b32_e32 v10, 16, v115
	v_and_b32_e32 v11, 0xffff0000, v115
	v_fmac_f32_e32 v8, v10, v10
	v_fmac_f32_e32 v8, v11, v11
	v_lshlrev_b32_e32 v10, 16, v116
	v_and_b32_e32 v11, 0xffff0000, v116
	v_fmac_f32_e32 v8, v10, v10
	v_fmac_f32_e32 v8, v11, v11
	v_lshlrev_b32_e32 v10, 16, v117
	v_and_b32_e32 v11, 0xffff0000, v117
	v_fmac_f32_e32 v8, v10, v10
	v_fmac_f32_e32 v8, v11, v11
	v_lshlrev_b32_e32 v10, 16, v118
	v_and_b32_e32 v11, 0xffff0000, v118
	v_fmac_f32_e32 v8, v10, v10
	v_fmac_f32_e32 v8, v11, v11
	v_lshlrev_b32_e32 v10, 16, v119
	v_and_b32_e32 v11, 0xffff0000, v119
	v_fmac_f32_e32 v8, v10, v10
	v_fmac_f32_e32 v8, v11, v11
	v_lshlrev_b32_e32 v10, 16, v120
	v_and_b32_e32 v11, 0xffff0000, v120
	v_fmac_f32_e32 v8, v10, v10
	v_fmac_f32_e32 v8, v11, v11
	v_lshlrev_b32_e32 v10, 16, v121
	v_and_b32_e32 v11, 0xffff0000, v121
	v_fmac_f32_e32 v8, v10, v10
	v_fmac_f32_e32 v8, v11, v11
	v_lshlrev_b32_e32 v10, 16, v122
	v_and_b32_e32 v11, 0xffff0000, v122
	v_fmac_f32_e32 v8, v10, v10
	v_fmac_f32_e32 v8, v11, v11
	v_lshlrev_b32_e32 v10, 16, v123
	v_and_b32_e32 v11, 0xffff0000, v123
	v_fmac_f32_e32 v8, v10, v10
	v_fmac_f32_e32 v8, v11, v11
	v_lshlrev_b32_e32 v10, 16, v124
	v_and_b32_e32 v11, 0xffff0000, v124
	v_fmac_f32_e32 v8, v10, v10
	v_fmac_f32_e32 v8, v11, v11
	v_lshlrev_b32_e32 v10, 16, v125
	v_and_b32_e32 v11, 0xffff0000, v125
	v_fmac_f32_e32 v8, v10, v10
	v_fmac_f32_e32 v8, v11, v11
	v_lshlrev_b32_e32 v10, 16, v126
	v_and_b32_e32 v11, 0xffff0000, v126
	v_fmac_f32_e32 v8, v10, v10
	v_fmac_f32_e32 v8, v11, v11
	v_lshlrev_b32_e32 v10, 16, v127
	v_and_b32_e32 v11, 0xffff0000, v127
	v_fmac_f32_e32 v8, v10, v10
	v_fmac_f32_e32 v8, v11, v11
	v_lshlrev_b32_e32 v10, 16, v128
	v_and_b32_e32 v11, 0xffff0000, v128
	v_fmac_f32_e32 v8, v10, v10
	v_fmac_f32_e32 v8, v11, v11
	v_lshlrev_b32_e32 v10, 16, v129
	v_and_b32_e32 v11, 0xffff0000, v129
	v_fmac_f32_e32 v8, v10, v10
	v_fmac_f32_e32 v8, v11, v11
	s_nop 1
	v_add_f32_dpp v8, v8, v8 quad_perm:[1,0,3,2] row_mask:0xf bank_mask:0xf
	s_nop 1
	v_add_f32_dpp v8, v8, v8 quad_perm:[2,3,0,1] row_mask:0xf bank_mask:0xf
	s_nop 1
	v_add_f32_dpp v8, v8, v8 row_ror:4 row_mask:0xf bank_mask:0xf
	s_nop 1
	v_add_f32_dpp v8, v8, v8 row_ror:8 row_mask:0xf bank_mask:0xf
	s_nop 1
	v_readlane_b32 s42, v8, 0
	v_readlane_b32 s43, v8, 16
	v_readlane_b32 s44, v8, 32
	v_readlane_b32 s45, v8, 48
	s_nop 1
	v_mov_b32_e32 v8, s42
	v_add_f32_e32 v8, s43, v8
	v_add_f32_e32 v8, s44, v8
	v_add_f32_e32 v8, s45, v8
	v_mov_b32_e32 v4, s41
	v_fmac_f32_e32 v4, s40, v8
	v_rsq_f32_e32 v4, v4
	s_nop 0
	v_mov_b32_e32 v5, v4
	s_waitcnt vmcnt(40)
	s_waitcnt vmcnt(16)
	v_mov_b32_e32 v8, 0
	v_lshlrev_b32_e32 v10, 16, v114
	v_and_b32_e32 v11, 0xffff0000, v114
	v_pk_mul_f32 v[10:11], v[10:11], v[4:5]
	v_pk_mul_f32 v[10:11], v[10:11], v[130:131]
	v_pk_fma_f32 v[66:67], v[164:165], v[10:11], v[66:67]
	v_lshlrev_b32_e32 v10, 16, v115
	v_and_b32_e32 v11, 0xffff0000, v115
	v_pk_mul_f32 v[10:11], v[10:11], v[4:5]
	v_pk_mul_f32 v[10:11], v[10:11], v[132:133]
	v_pk_fma_f32 v[68:69], v[166:167], v[10:11], v[68:69]
	global_store_dwordx4 v1, v[66:69], s[24:25] nt
	v_lshlrev_b32_e32 v10, 16, v116
	v_and_b32_e32 v11, 0xffff0000, v116
	v_pk_mul_f32 v[10:11], v[10:11], v[4:5]
	v_pk_mul_f32 v[10:11], v[10:11], v[134:135]
	v_pk_fma_f32 v[70:71], v[168:169], v[10:11], v[70:71]
	v_lshlrev_b32_e32 v10, 16, v117
	v_and_b32_e32 v11, 0xffff0000, v117
	v_pk_mul_f32 v[10:11], v[10:11], v[4:5]
	v_pk_mul_f32 v[10:11], v[10:11], v[136:137]
	v_pk_fma_f32 v[72:73], v[170:171], v[10:11], v[72:73]
	global_store_dwordx4 v1, v[70:73], s[24:25] offset:1024 nt
	v_lshlrev_b32_e32 v10, 16, v118
	v_and_b32_e32 v11, 0xffff0000, v118
	v_pk_mul_f32 v[10:11], v[10:11], v[4:5]
	v_pk_mul_f32 v[10:11], v[10:11], v[138:139]
	v_pk_fma_f32 v[74:75], v[172:173], v[10:11], v[74:75]
	v_lshlrev_b32_e32 v10, 16, v119
	v_and_b32_e32 v11, 0xffff0000, v119
	v_pk_mul_f32 v[10:11], v[10:11], v[4:5]
	v_pk_mul_f32 v[10:11], v[10:11], v[140:141]
	v_pk_fma_f32 v[76:77], v[174:175], v[10:11], v[76:77]
	global_store_dwordx4 v1, v[74:77], s[24:25] offset:2048 nt
	v_lshlrev_b32_e32 v10, 16, v120
	v_and_b32_e32 v11, 0xffff0000, v120
	v_pk_mul_f32 v[10:11], v[10:11], v[4:5]
	v_pk_mul_f32 v[10:11], v[10:11], v[142:143]
	v_pk_fma_f32 v[78:79], v[176:177], v[10:11], v[78:79]
	v_lshlrev_b32_e32 v10, 16, v121
	v_and_b32_e32 v11, 0xffff0000, v121
	v_pk_mul_f32 v[10:11], v[10:11], v[4:5]
	v_pk_mul_f32 v[10:11], v[10:11], v[144:145]
	v_pk_fma_f32 v[80:81], v[178:179], v[10:11], v[80:81]
	global_store_dwordx4 v1, v[78:81], s[24:25] offset:3072 nt
	v_lshlrev_b32_e32 v10, 16, v122
	v_and_b32_e32 v11, 0xffff0000, v122
	v_pk_mul_f32 v[10:11], v[10:11], v[4:5]
	v_pk_mul_f32 v[10:11], v[10:11], v[146:147]
	v_pk_fma_f32 v[82:83], v[180:181], v[10:11], v[82:83]
	v_lshlrev_b32_e32 v10, 16, v123
	v_and_b32_e32 v11, 0xffff0000, v123
	v_pk_mul_f32 v[10:11], v[10:11], v[4:5]
	v_pk_mul_f32 v[10:11], v[10:11], v[148:149]
	v_pk_fma_f32 v[84:85], v[182:183], v[10:11], v[84:85]
	global_store_dwordx4 v1, v[82:85], s[34:35] nt
	v_lshlrev_b32_e32 v10, 16, v124
	v_and_b32_e32 v11, 0xffff0000, v124
	v_pk_mul_f32 v[10:11], v[10:11], v[4:5]
	v_pk_mul_f32 v[10:11], v[10:11], v[150:151]
	v_pk_fma_f32 v[86:87], v[184:185], v[10:11], v[86:87]
	v_lshlrev_b32_e32 v10, 16, v125
	v_and_b32_e32 v11, 0xffff0000, v125
	v_pk_mul_f32 v[10:11], v[10:11], v[4:5]
	v_pk_mul_f32 v[10:11], v[10:11], v[152:153]
	v_pk_fma_f32 v[88:89], v[186:187], v[10:11], v[88:89]
	global_store_dwordx4 v1, v[86:89], s[34:35] offset:1024 nt
	v_lshlrev_b32_e32 v10, 16, v126
	v_and_b32_e32 v11, 0xffff0000, v126
	v_pk_mul_f32 v[10:11], v[10:11], v[4:5]
	v_pk_mul_f32 v[10:11], v[10:11], v[156:157]
	v_pk_fma_f32 v[90:91], v[188:189], v[10:11], v[90:91]
	v_lshlrev_b32_e32 v10, 16, v127
	v_and_b32_e32 v11, 0xffff0000, v127
	v_pk_mul_f32 v[10:11], v[10:11], v[4:5]
	v_pk_mul_f32 v[10:11], v[10:11], v[158:159]
	v_pk_fma_f32 v[92:93], v[190:191], v[10:11], v[92:93]
	global_store_dwordx4 v1, v[90:93], s[34:35] offset:2048 nt
	v_lshlrev_b32_e32 v10, 16, v128
	v_and_b32_e32 v11, 0xffff0000, v128
	v_pk_mul_f32 v[10:11], v[10:11], v[4:5]
	v_pk_mul_f32 v[10:11], v[10:11], v[160:161]
	v_pk_fma_f32 v[94:95], v[192:193], v[10:11], v[94:95]
	v_lshlrev_b32_e32 v10, 16, v129
	v_and_b32_e32 v11, 0xffff0000, v129
	v_pk_mul_f32 v[10:11], v[10:11], v[4:5]
	v_pk_mul_f32 v[10:11], v[10:11], v[162:163]
	v_pk_fma_f32 v[96:97], v[194:195], v[10:11], v[96:97]
	global_store_dwordx4 v1, v[94:97], s[34:35] offset:3072 nt
	s_lshr_b32 s16, s10, 10
	s_add_u32 s17, s16, 5
	s_mul_i32 s17, s17, 49152
	s_add_u32 s17, s17, 0x1040a000
	s_add_u32 s28, s90, s17
	s_addc_u32 s29, s91, 0
	s_add_u32 s18, s0, 0x1000
	s_addc_u32 s19, s1, 0
	global_load_dwordx4 v[130:133], v1, s[0:1]
	global_load_dwordx4 v[134:137], v1, s[0:1] offset:1024
	global_load_dwordx4 v[138:141], v1, s[0:1] offset:2048
	global_load_dwordx4 v[142:145], v1, s[0:1] offset:3072
	global_load_dwordx4 v[146:149], v1, s[18:19]
	global_load_dwordx4 v[150:153], v1, s[18:19] offset:1024
	global_load_dwordx4 v[156:159], v1, s[18:19] offset:2048
	global_load_dwordx4 v[160:163], v1, s[18:19] offset:3072
	s_add_u32 s18, s28, 0x1000
	s_addc_u32 s19, s29, 0
	global_load_dwordx4 v[164:167], v1, s[28:29]
	global_load_dwordx4 v[168:171], v1, s[28:29] offset:1024
	global_load_dwordx4 v[172:175], v1, s[28:29] offset:2048
	global_load_dwordx4 v[176:179], v1, s[28:29] offset:3072
	global_load_dwordx4 v[180:183], v1, s[18:19]
	global_load_dwordx4 v[184:187], v1, s[18:19] offset:1024
	global_load_dwordx4 v[188:191], v1, s[18:19] offset:2048
	global_load_dwordx4 v[192:195], v1, s[18:19] offset:3072
	s_add_u32 s12, s10, 6144
	s_lshl_b32 s13, s12, 13
	s_lshl_b32 s14, s12, 12
	s_add_u32 s20, s4, s13
	s_addc_u32 s21, s5, 0
	s_add_u32 s22, s90, 0x28918000
	s_addc_u32 s23, s91, 0
	s_add_u32 s22, s22, s14
	s_addc_u32 s23, s23, 0
	global_load_dwordx2 v[114:115], v2, s[22:23] nt
	global_load_dwordx2 v[116:117], v2, s[22:23] offset:512 nt
	global_load_dwordx2 v[118:119], v2, s[22:23] offset:1024 nt
	global_load_dwordx2 v[120:121], v2, s[22:23] offset:1536 nt
	global_load_dwordx2 v[122:123], v2, s[22:23] offset:2048 nt
	global_load_dwordx2 v[124:125], v2, s[22:23] offset:2560 nt
	global_load_dwordx2 v[126:127], v2, s[22:23] offset:3072 nt
	global_load_dwordx2 v[128:129], v2, s[22:23] offset:3584 nt
	s_add_u32 s36, s20, 0x1000
	s_addc_u32 s37, s21, 0
	global_load_dwordx4 v[66:69], v1, s[20:21] nt
	global_load_dwordx4 v[70:73], v1, s[20:21] offset:1024 nt
	global_load_dwordx4 v[74:77], v1, s[20:21] offset:2048 nt
	global_load_dwordx4 v[78:81], v1, s[20:21] offset:3072 nt
	global_load_dwordx4 v[82:85], v1, s[36:37] nt
	global_load_dwordx4 v[86:89], v1, s[36:37] offset:1024 nt
	global_load_dwordx4 v[90:93], v1, s[36:37] offset:2048 nt
	global_load_dwordx4 v[94:97], v1, s[36:37] offset:3072 nt
	s_add_u32 s12, s10, 4096
	s_lshl_b32 s13, s12, 13
	s_lshl_b32 s14, s12, 12
	s_add_u32 s24, s4, s13
	s_addc_u32 s25, s5, 0
	s_add_u32 s34, s24, 0x1000
	s_addc_u32 s35, s25, 0
	s_add_u32 s26, s90, 0x11918000
	s_addc_u32 s27, s91, 0
	s_add_u32 s26, s26, s14
	s_addc_u32 s27, s27, 0
	s_waitcnt vmcnt(48)
	v_mov_b32_e32 v8, 0
	v_lshlrev_b32_e32 v10, 16, v98
	v_and_b32_e32 v11, 0xffff0000, v98
	v_fmac_f32_e32 v8, v10, v10
	v_fmac_f32_e32 v8, v11, v11
	v_lshlrev_b32_e32 v10, 16, v99
	v_and_b32_e32 v11, 0xffff0000, v99
	v_fmac_f32_e32 v8, v10, v10
	v_fmac_f32_e32 v8, v11, v11
	v_lshlrev_b32_e32 v10, 16, v100
	v_and_b32_e32 v11, 0xffff0000, v100
	v_fmac_f32_e32 v8, v10, v10
	v_fmac_f32_e32 v8, v11, v11
	v_lshlrev_b32_e32 v10, 16, v101
	v_and_b32_e32 v11, 0xffff0000, v101
	v_fmac_f32_e32 v8, v10, v10
	v_fmac_f32_e32 v8, v11, v11
	v_lshlrev_b32_e32 v10, 16, v102
	v_and_b32_e32 v11, 0xffff0000, v102
	v_fmac_f32_e32 v8, v10, v10
	v_fmac_f32_e32 v8, v11, v11
	v_lshlrev_b32_e32 v10, 16, v103
	v_and_b32_e32 v11, 0xffff0000, v103
	v_fmac_f32_e32 v8, v10, v10
	v_fmac_f32_e32 v8, v11, v11
	v_lshlrev_b32_e32 v10, 16, v104
	v_and_b32_e32 v11, 0xffff0000, v104
	v_fmac_f32_e32 v8, v10, v10
	v_fmac_f32_e32 v8, v11, v11
	v_lshlrev_b32_e32 v10, 16, v105
	v_and_b32_e32 v11, 0xffff0000, v105
	v_fmac_f32_e32 v8, v10, v10
	v_fmac_f32_e32 v8, v11, v11
	v_lshlrev_b32_e32 v10, 16, v106
	v_and_b32_e32 v11, 0xffff0000, v106
	v_fmac_f32_e32 v8, v10, v10
	v_fmac_f32_e32 v8, v11, v11
	v_lshlrev_b32_e32 v10, 16, v107
	v_and_b32_e32 v11, 0xffff0000, v107
	v_fmac_f32_e32 v8, v10, v10
	v_fmac_f32_e32 v8, v11, v11
	v_lshlrev_b32_e32 v10, 16, v108
	v_and_b32_e32 v11, 0xffff0000, v108
	v_fmac_f32_e32 v8, v10, v10
	v_fmac_f32_e32 v8, v11, v11
	v_lshlrev_b32_e32 v10, 16, v109
	v_and_b32_e32 v11, 0xffff0000, v109
	v_fmac_f32_e32 v8, v10, v10
	v_fmac_f32_e32 v8, v11, v11
	v_lshlrev_b32_e32 v10, 16, v110
	v_and_b32_e32 v11, 0xffff0000, v110
	v_fmac_f32_e32 v8, v10, v10
	v_fmac_f32_e32 v8, v11, v11
	v_lshlrev_b32_e32 v10, 16, v111
	v_and_b32_e32 v11, 0xffff0000, v111
	v_fmac_f32_e32 v8, v10, v10
	v_fmac_f32_e32 v8, v11, v11
	v_lshlrev_b32_e32 v10, 16, v112
	v_and_b32_e32 v11, 0xffff0000, v112
	v_fmac_f32_e32 v8, v10, v10
	v_fmac_f32_e32 v8, v11, v11
	v_lshlrev_b32_e32 v10, 16, v113
	v_and_b32_e32 v11, 0xffff0000, v113
	v_fmac_f32_e32 v8, v10, v10
	v_fmac_f32_e32 v8, v11, v11
	s_nop 1
	v_add_f32_dpp v8, v8, v8 quad_perm:[1,0,3,2] row_mask:0xf bank_mask:0xf
	s_nop 1
	v_add_f32_dpp v8, v8, v8 quad_perm:[2,3,0,1] row_mask:0xf bank_mask:0xf
	s_nop 1
	v_add_f32_dpp v8, v8, v8 row_ror:4 row_mask:0xf bank_mask:0xf
	s_nop 1
	v_add_f32_dpp v8, v8, v8 row_ror:8 row_mask:0xf bank_mask:0xf
	s_nop 1
	v_readlane_b32 s42, v8, 0
	v_readlane_b32 s43, v8, 16
	v_readlane_b32 s44, v8, 32
	v_readlane_b32 s45, v8, 48
	s_nop 1
	v_mov_b32_e32 v8, s42
	v_add_f32_e32 v8, s43, v8
	v_add_f32_e32 v8, s44, v8
	v_add_f32_e32 v8, s45, v8
	v_mov_b32_e32 v4, s41
	v_fmac_f32_e32 v4, s40, v8
	v_rsq_f32_e32 v4, v4
	s_nop 0
	v_mov_b32_e32 v5, v4
	s_waitcnt vmcnt(40)
	s_waitcnt vmcnt(16)
	v_mov_b32_e32 v8, 0
	v_lshlrev_b32_e32 v10, 16, v98
	v_and_b32_e32 v11, 0xffff0000, v98
	v_pk_mul_f32 v[10:11], v[10:11], v[4:5]
	v_pk_mul_f32 v[10:11], v[10:11], v[130:131]
	v_pk_fma_f32 v[34:35], v[164:165], v[10:11], v[34:35]
	v_lshlrev_b32_e32 v10, 16, v99
	v_and_b32_e32 v11, 0xffff0000, v99
	v_pk_mul_f32 v[10:11], v[10:11], v[4:5]
	v_pk_mul_f32 v[10:11], v[10:11], v[132:133]
	v_pk_fma_f32 v[36:37], v[166:167], v[10:11], v[36:37]
	global_store_dwordx4 v1, v[34:37], s[24:25] nt
	v_lshlrev_b32_e32 v10, 16, v100
	v_and_b32_e32 v11, 0xffff0000, v100
	v_pk_mul_f32 v[10:11], v[10:11], v[4:5]
	v_pk_mul_f32 v[10:11], v[10:11], v[134:135]
	v_pk_fma_f32 v[38:39], v[168:169], v[10:11], v[38:39]
	v_lshlrev_b32_e32 v10, 16, v101
	v_and_b32_e32 v11, 0xffff0000, v101
	v_pk_mul_f32 v[10:11], v[10:11], v[4:5]
	v_pk_mul_f32 v[10:11], v[10:11], v[136:137]
	v_pk_fma_f32 v[40:41], v[170:171], v[10:11], v[40:41]
	global_store_dwordx4 v1, v[38:41], s[24:25] offset:1024 nt
	v_lshlrev_b32_e32 v10, 16, v102
	v_and_b32_e32 v11, 0xffff0000, v102
	v_pk_mul_f32 v[10:11], v[10:11], v[4:5]
	v_pk_mul_f32 v[10:11], v[10:11], v[138:139]
	v_pk_fma_f32 v[42:43], v[172:173], v[10:11], v[42:43]
	v_lshlrev_b32_e32 v10, 16, v103
	v_and_b32_e32 v11, 0xffff0000, v103
	v_pk_mul_f32 v[10:11], v[10:11], v[4:5]
	v_pk_mul_f32 v[10:11], v[10:11], v[140:141]
	v_pk_fma_f32 v[44:45], v[174:175], v[10:11], v[44:45]
	global_store_dwordx4 v1, v[42:45], s[24:25] offset:2048 nt
	v_lshlrev_b32_e32 v10, 16, v104
	v_and_b32_e32 v11, 0xffff0000, v104
	v_pk_mul_f32 v[10:11], v[10:11], v[4:5]
	v_pk_mul_f32 v[10:11], v[10:11], v[142:143]
	v_pk_fma_f32 v[46:47], v[176:177], v[10:11], v[46:47]
	v_lshlrev_b32_e32 v10, 16, v105
	v_and_b32_e32 v11, 0xffff0000, v105
	v_pk_mul_f32 v[10:11], v[10:11], v[4:5]
	v_pk_mul_f32 v[10:11], v[10:11], v[144:145]
	v_pk_fma_f32 v[48:49], v[178:179], v[10:11], v[48:49]
	global_store_dwordx4 v1, v[46:49], s[24:25] offset:3072 nt
	v_lshlrev_b32_e32 v10, 16, v106
	v_and_b32_e32 v11, 0xffff0000, v106
	v_pk_mul_f32 v[10:11], v[10:11], v[4:5]
	v_pk_mul_f32 v[10:11], v[10:11], v[146:147]
	v_pk_fma_f32 v[50:51], v[180:181], v[10:11], v[50:51]
	v_lshlrev_b32_e32 v10, 16, v107
	v_and_b32_e32 v11, 0xffff0000, v107
	v_pk_mul_f32 v[10:11], v[10:11], v[4:5]
	v_pk_mul_f32 v[10:11], v[10:11], v[148:149]
	v_pk_fma_f32 v[52:53], v[182:183], v[10:11], v[52:53]
	global_store_dwordx4 v1, v[50:53], s[34:35] nt
	v_lshlrev_b32_e32 v10, 16, v108
	v_and_b32_e32 v11, 0xffff0000, v108
	v_pk_mul_f32 v[10:11], v[10:11], v[4:5]
	v_pk_mul_f32 v[10:11], v[10:11], v[150:151]
	v_pk_fma_f32 v[54:55], v[184:185], v[10:11], v[54:55]
	v_lshlrev_b32_e32 v10, 16, v109
	v_and_b32_e32 v11, 0xffff0000, v109
	v_pk_mul_f32 v[10:11], v[10:11], v[4:5]
	v_pk_mul_f32 v[10:11], v[10:11], v[152:153]
	v_pk_fma_f32 v[56:57], v[186:187], v[10:11], v[56:57]
	global_store_dwordx4 v1, v[54:57], s[34:35] offset:1024 nt
	v_lshlrev_b32_e32 v10, 16, v110
	v_and_b32_e32 v11, 0xffff0000, v110
	v_pk_mul_f32 v[10:11], v[10:11], v[4:5]
	v_pk_mul_f32 v[10:11], v[10:11], v[156:157]
	v_pk_fma_f32 v[58:59], v[188:189], v[10:11], v[58:59]
	v_lshlrev_b32_e32 v10, 16, v111
	v_and_b32_e32 v11, 0xffff0000, v111
	v_pk_mul_f32 v[10:11], v[10:11], v[4:5]
	v_pk_mul_f32 v[10:11], v[10:11], v[158:159]
	v_pk_fma_f32 v[60:61], v[190:191], v[10:11], v[60:61]
	global_store_dwordx4 v1, v[58:61], s[34:35] offset:2048 nt
	v_lshlrev_b32_e32 v10, 16, v112
	v_and_b32_e32 v11, 0xffff0000, v112
	v_pk_mul_f32 v[10:11], v[10:11], v[4:5]
	v_pk_mul_f32 v[10:11], v[10:11], v[160:161]
	v_pk_fma_f32 v[62:63], v[192:193], v[10:11], v[62:63]
	v_lshlrev_b32_e32 v10, 16, v113
	v_and_b32_e32 v11, 0xffff0000, v113
	v_pk_mul_f32 v[10:11], v[10:11], v[4:5]
	v_pk_mul_f32 v[10:11], v[10:11], v[162:163]
	v_pk_fma_f32 v[64:65], v[194:195], v[10:11], v[64:65]
	global_store_dwordx4 v1, v[62:65], s[34:35] offset:3072 nt
	s_lshr_b32 s16, s10, 10
	s_add_u32 s16, s16, 2
	s_add_u32 s17, s16, 5
	s_mul_i32 s17, s17, 49152
	s_add_u32 s17, s17, 0x1040a000
	s_add_u32 s28, s90, s17
	s_addc_u32 s29, s91, 0
	s_add_u32 s18, s0, 0x1000
	s_addc_u32 s19, s1, 0
	global_load_dwordx4 v[130:133], v1, s[0:1]
	global_load_dwordx4 v[134:137], v1, s[0:1] offset:1024
	global_load_dwordx4 v[138:141], v1, s[0:1] offset:2048
	global_load_dwordx4 v[142:145], v1, s[0:1] offset:3072
	global_load_dwordx4 v[146:149], v1, s[18:19]
	global_load_dwordx4 v[150:153], v1, s[18:19] offset:1024
	global_load_dwordx4 v[156:159], v1, s[18:19] offset:2048
	global_load_dwordx4 v[160:163], v1, s[18:19] offset:3072
	s_add_u32 s18, s28, 0x1000
	s_addc_u32 s19, s29, 0
	global_load_dwordx4 v[164:167], v1, s[28:29]
	global_load_dwordx4 v[168:171], v1, s[28:29] offset:1024
	global_load_dwordx4 v[172:175], v1, s[28:29] offset:2048
	global_load_dwordx4 v[176:179], v1, s[28:29] offset:3072
	global_load_dwordx4 v[180:183], v1, s[18:19]
	global_load_dwordx4 v[184:187], v1, s[18:19] offset:1024
	global_load_dwordx4 v[188:191], v1, s[18:19] offset:2048
	global_load_dwordx4 v[192:195], v1, s[18:19] offset:3072
	s_add_u32 s12, s10, 6144
	s_lshl_b32 s13, s12, 13
	s_lshl_b32 s14, s12, 12
	s_add_u32 s24, s4, s13
	s_addc_u32 s25, s5, 0
	s_add_u32 s34, s24, 0x1000
	s_addc_u32 s35, s25, 0
	s_add_u32 s26, s90, 0x11918000
	s_addc_u32 s27, s91, 0
	s_add_u32 s26, s26, s14
	s_addc_u32 s27, s27, 0
	s_waitcnt vmcnt(32)
	v_mov_b32_e32 v8, 0
	v_lshlrev_b32_e32 v10, 16, v114
	v_and_b32_e32 v11, 0xffff0000, v114
	v_fmac_f32_e32 v8, v10, v10
	v_fmac_f32_e32 v8, v11, v11
	v_lshlrev_b32_e32 v10, 16, v115
	v_and_b32_e32 v11, 0xffff0000, v115
	v_fmac_f32_e32 v8, v10, v10
	v_fmac_f32_e32 v8, v11, v11
	v_lshlrev_b32_e32 v10, 16, v116
	v_and_b32_e32 v11, 0xffff0000, v116
	v_fmac_f32_e32 v8, v10, v10
	v_fmac_f32_e32 v8, v11, v11
	v_lshlrev_b32_e32 v10, 16, v117
	v_and_b32_e32 v11, 0xffff0000, v117
	v_fmac_f32_e32 v8, v10, v10
	v_fmac_f32_e32 v8, v11, v11
	v_lshlrev_b32_e32 v10, 16, v118
	v_and_b32_e32 v11, 0xffff0000, v118
	v_fmac_f32_e32 v8, v10, v10
	v_fmac_f32_e32 v8, v11, v11
	v_lshlrev_b32_e32 v10, 16, v119
	v_and_b32_e32 v11, 0xffff0000, v119
	v_fmac_f32_e32 v8, v10, v10
	v_fmac_f32_e32 v8, v11, v11
	v_lshlrev_b32_e32 v10, 16, v120
	v_and_b32_e32 v11, 0xffff0000, v120
	v_fmac_f32_e32 v8, v10, v10
	v_fmac_f32_e32 v8, v11, v11
	v_lshlrev_b32_e32 v10, 16, v121
	v_and_b32_e32 v11, 0xffff0000, v121
	v_fmac_f32_e32 v8, v10, v10
	v_fmac_f32_e32 v8, v11, v11
	v_lshlrev_b32_e32 v10, 16, v122
	v_and_b32_e32 v11, 0xffff0000, v122
	v_fmac_f32_e32 v8, v10, v10
	v_fmac_f32_e32 v8, v11, v11
	v_lshlrev_b32_e32 v10, 16, v123
	v_and_b32_e32 v11, 0xffff0000, v123
	v_fmac_f32_e32 v8, v10, v10
	v_fmac_f32_e32 v8, v11, v11
	v_lshlrev_b32_e32 v10, 16, v124
	v_and_b32_e32 v11, 0xffff0000, v124
	v_fmac_f32_e32 v8, v10, v10
	v_fmac_f32_e32 v8, v11, v11
	v_lshlrev_b32_e32 v10, 16, v125
	v_and_b32_e32 v11, 0xffff0000, v125
	v_fmac_f32_e32 v8, v10, v10
	v_fmac_f32_e32 v8, v11, v11
	v_lshlrev_b32_e32 v10, 16, v126
	v_and_b32_e32 v11, 0xffff0000, v126
	v_fmac_f32_e32 v8, v10, v10
	v_fmac_f32_e32 v8, v11, v11
	v_lshlrev_b32_e32 v10, 16, v127
	v_and_b32_e32 v11, 0xffff0000, v127
	v_fmac_f32_e32 v8, v10, v10
	v_fmac_f32_e32 v8, v11, v11
	v_lshlrev_b32_e32 v10, 16, v128
	v_and_b32_e32 v11, 0xffff0000, v128
	v_fmac_f32_e32 v8, v10, v10
	v_fmac_f32_e32 v8, v11, v11
	v_lshlrev_b32_e32 v10, 16, v129
	v_and_b32_e32 v11, 0xffff0000, v129
	v_fmac_f32_e32 v8, v10, v10
	v_fmac_f32_e32 v8, v11, v11
	s_nop 1
	v_add_f32_dpp v8, v8, v8 quad_perm:[1,0,3,2] row_mask:0xf bank_mask:0xf
	s_nop 1
	v_add_f32_dpp v8, v8, v8 quad_perm:[2,3,0,1] row_mask:0xf bank_mask:0xf
	s_nop 1
	v_add_f32_dpp v8, v8, v8 row_ror:4 row_mask:0xf bank_mask:0xf
	s_nop 1
	v_add_f32_dpp v8, v8, v8 row_ror:8 row_mask:0xf bank_mask:0xf
	s_nop 1
	v_readlane_b32 s42, v8, 0
	v_readlane_b32 s43, v8, 16
	v_readlane_b32 s44, v8, 32
	v_readlane_b32 s45, v8, 48
	s_nop 1
	v_mov_b32_e32 v8, s42
	v_add_f32_e32 v8, s43, v8
	v_add_f32_e32 v8, s44, v8
	v_add_f32_e32 v8, s45, v8
	v_mov_b32_e32 v4, s41
	v_fmac_f32_e32 v4, s40, v8
	v_rsq_f32_e32 v4, v4
	s_nop 0
	v_mov_b32_e32 v5, v4
	s_waitcnt vmcnt(24)
	s_waitcnt vmcnt(0)
	v_mov_b32_e32 v8, 0
	v_lshlrev_b32_e32 v10, 16, v114
	v_and_b32_e32 v11, 0xffff0000, v114
	v_pk_mul_f32 v[10:11], v[10:11], v[4:5]
	v_pk_mul_f32 v[10:11], v[10:11], v[130:131]
	v_pk_fma_f32 v[66:67], v[164:165], v[10:11], v[66:67]
	v_lshlrev_b32_e32 v10, 16, v115
	v_and_b32_e32 v11, 0xffff0000, v115
	v_pk_mul_f32 v[10:11], v[10:11], v[4:5]
	v_pk_mul_f32 v[10:11], v[10:11], v[132:133]
	v_pk_fma_f32 v[68:69], v[166:167], v[10:11], v[68:69]
	global_store_dwordx4 v1, v[66:69], s[24:25] nt
	v_lshlrev_b32_e32 v10, 16, v116
	v_and_b32_e32 v11, 0xffff0000, v116
	v_pk_mul_f32 v[10:11], v[10:11], v[4:5]
	v_pk_mul_f32 v[10:11], v[10:11], v[134:135]
	v_pk_fma_f32 v[70:71], v[168:169], v[10:11], v[70:71]
	v_lshlrev_b32_e32 v10, 16, v117
	v_and_b32_e32 v11, 0xffff0000, v117
	v_pk_mul_f32 v[10:11], v[10:11], v[4:5]
	v_pk_mul_f32 v[10:11], v[10:11], v[136:137]
	v_pk_fma_f32 v[72:73], v[170:171], v[10:11], v[72:73]
	global_store_dwordx4 v1, v[70:73], s[24:25] offset:1024 nt
	v_lshlrev_b32_e32 v10, 16, v118
	v_and_b32_e32 v11, 0xffff0000, v118
	v_pk_mul_f32 v[10:11], v[10:11], v[4:5]
	v_pk_mul_f32 v[10:11], v[10:11], v[138:139]
	v_pk_fma_f32 v[74:75], v[172:173], v[10:11], v[74:75]
	v_lshlrev_b32_e32 v10, 16, v119
	v_and_b32_e32 v11, 0xffff0000, v119
	v_pk_mul_f32 v[10:11], v[10:11], v[4:5]
	v_pk_mul_f32 v[10:11], v[10:11], v[140:141]
	v_pk_fma_f32 v[76:77], v[174:175], v[10:11], v[76:77]
	global_store_dwordx4 v1, v[74:77], s[24:25] offset:2048 nt
	v_lshlrev_b32_e32 v10, 16, v120
	v_and_b32_e32 v11, 0xffff0000, v120
	v_pk_mul_f32 v[10:11], v[10:11], v[4:5]
	v_pk_mul_f32 v[10:11], v[10:11], v[142:143]
	v_pk_fma_f32 v[78:79], v[176:177], v[10:11], v[78:79]
	v_lshlrev_b32_e32 v10, 16, v121
	v_and_b32_e32 v11, 0xffff0000, v121
	v_pk_mul_f32 v[10:11], v[10:11], v[4:5]
	v_pk_mul_f32 v[10:11], v[10:11], v[144:145]
	v_pk_fma_f32 v[80:81], v[178:179], v[10:11], v[80:81]
	global_store_dwordx4 v1, v[78:81], s[24:25] offset:3072 nt
	v_lshlrev_b32_e32 v10, 16, v122
	v_and_b32_e32 v11, 0xffff0000, v122
	v_pk_mul_f32 v[10:11], v[10:11], v[4:5]
	v_pk_mul_f32 v[10:11], v[10:11], v[146:147]
	v_pk_fma_f32 v[82:83], v[180:181], v[10:11], v[82:83]
	v_lshlrev_b32_e32 v10, 16, v123
	v_and_b32_e32 v11, 0xffff0000, v123
	v_pk_mul_f32 v[10:11], v[10:11], v[4:5]
	v_pk_mul_f32 v[10:11], v[10:11], v[148:149]
	v_pk_fma_f32 v[84:85], v[182:183], v[10:11], v[84:85]
	global_store_dwordx4 v1, v[82:85], s[34:35] nt
	v_lshlrev_b32_e32 v10, 16, v124
	v_and_b32_e32 v11, 0xffff0000, v124
	v_pk_mul_f32 v[10:11], v[10:11], v[4:5]
	v_pk_mul_f32 v[10:11], v[10:11], v[150:151]
	v_pk_fma_f32 v[86:87], v[184:185], v[10:11], v[86:87]
	v_lshlrev_b32_e32 v10, 16, v125
	v_and_b32_e32 v11, 0xffff0000, v125
	v_pk_mul_f32 v[10:11], v[10:11], v[4:5]
	v_pk_mul_f32 v[10:11], v[10:11], v[152:153]
	v_pk_fma_f32 v[88:89], v[186:187], v[10:11], v[88:89]
	global_store_dwordx4 v1, v[86:89], s[34:35] offset:1024 nt
	v_lshlrev_b32_e32 v10, 16, v126
	v_and_b32_e32 v11, 0xffff0000, v126
	v_pk_mul_f32 v[10:11], v[10:11], v[4:5]
	v_pk_mul_f32 v[10:11], v[10:11], v[156:157]
	v_pk_fma_f32 v[90:91], v[188:189], v[10:11], v[90:91]
	v_lshlrev_b32_e32 v10, 16, v127
	v_and_b32_e32 v11, 0xffff0000, v127
	v_pk_mul_f32 v[10:11], v[10:11], v[4:5]
	v_pk_mul_f32 v[10:11], v[10:11], v[158:159]
	v_pk_fma_f32 v[92:93], v[190:191], v[10:11], v[92:93]
	global_store_dwordx4 v1, v[90:93], s[34:35] offset:2048 nt
	v_lshlrev_b32_e32 v10, 16, v128
	v_and_b32_e32 v11, 0xffff0000, v128
	v_pk_mul_f32 v[10:11], v[10:11], v[4:5]
	v_pk_mul_f32 v[10:11], v[10:11], v[160:161]
	v_pk_fma_f32 v[94:95], v[192:193], v[10:11], v[94:95]
	v_lshlrev_b32_e32 v10, 16, v129
	v_and_b32_e32 v11, 0xffff0000, v129
	v_pk_mul_f32 v[10:11], v[10:11], v[4:5]
	v_pk_mul_f32 v[10:11], v[10:11], v[162:163]
	v_pk_fma_f32 v[96:97], v[194:195], v[10:11], v[96:97]
	global_store_dwordx4 v1, v[94:97], s[34:35] offset:3072 nt
	s_waitcnt vmcnt(0)
	s_branch .LBB0_2734
